# v5: + attention KV-loop loads via saddr+32bit lane offsets (no per-tile 64-bit address rebuild), redundant waits dropped; GEMM stage loads saddr-form
# speedup vs baseline: 1.0137x; 1.0137x over previous
; #define PG8_STAGE(bufoff, gbase, voff) do { _Pragma("unroll") for (int _i = 0; _i < 2; ++_i) \
;         __builtin_amdgcn_global_load_lds((const unsigned*)((const char*)(gbase) + (voff)[_i]), (LAS unsigned*)(lds + (bufoff) + ldsw + _i * 8192), 16, 0, 0); } while (0)
; #define PG8_WAIT_V(n) asm volatile("s_waitcnt vmcnt(" #n ")" ::: "memory")
; #define PG8_BAR __builtin_amdgcn_s_barrier()
; template <class Epi>
; __device__ __forceinline__ void gemm_phase(LAS unsigned char* lds, const Gemm g, const StaticOrder& S, const Epi& E, int wv) {
;     ...
;     PG8_STAGE(PG8_SB(0, 0), cB, voffB); PG8_STAGE(PG8_SA(0, 0), cA, voffA); PG8_STAGE(PG8_SB(0, 1), cB + hstep, voffB); PG8_STAGE(PG8_SA(0, 1), cA + hstep, voffA);
;     if (wr == 1) PG8_BAR;
;     PG8_WAIT_V(4); PG8_BAR;
;     PG8_STAGE(PG8_SB(1, 0), cB + kstep, voffB); PG8_STAGE(PG8_SA(1, 0), cA + kstep, voffA); PG8_STAGE(PG8_SB(1, 1), cB + hstep + kstep, voffB);
;     PG8_WAIT_V(6); PG8_BAR;
.LBB0_177:
	s_add_u32 s12, s44, 0x1c000000
	s_addc_u32 s13, s45, 0
	s_add_u32 s22, s44, 0x3e900000
	s_addc_u32 s23, s45, 0
	s_add_u32 s42, s44, 0x3f100000
	s_addc_u32 s43, s45, 0
	s_lshl_b64 s[2:3], s[24:25], 2
	s_add_u32 s56, s8, s2
	v_and_b32_e32 v9, 15, v8
	v_and_b32_e32 v10, 48, v8
	v_lshlrev_b32_e32 v8, 2, v8
	s_addc_u32 s57, s9, s3
	v_lshl_or_b32 v9, v9, 6, v10
	v_and_b32_e32 v8, 32, v8
	v_readlane_b32 s2, v254, 7
	v_lshl_add_u64 v[6:7], v[6:7], 0, s[80:81]
	s_add_i32 m0, s47, 0x18000
	s_or_b32 s58, s24, 0x80
	v_bitop3_b32 v10, v9, s2, v8 bitop3:0xde
	v_readlane_b32 s2, v254, 8
	s_waitcnt vmcnt(4)
	s_barrier
	global_load_lds_dwordx4 v[6:7], off
	v_lshl_add_u64 v[2:3], v[2:3], 0, s[80:81]
	s_add_i32 m0, s47, 0x1a000
	s_add_i32 s70, s47, 0x8000
	s_add_i32 s71, s47, 0xa000
	v_bitop3_b32 v161, v9, s2, v8 bitop3:0xde
	global_load_lds_dwordx4 v[2:3], off
	v_lshl_add_u64 v[0:1], v[0:1], 0, s[80:81]
	s_mov_b32 m0, s70
	s_add_u32 s2, s68, 0x18080
	global_load_lds_dwordx4 v[0:1], off
	v_lshl_add_u64 v[0:1], v[4:5], 0, s[80:81]
	s_mov_b32 m0, s71
	s_addc_u32 s3, s69, 0
	global_load_lds_dwordx4 v[0:1], off
	s_add_i32 m0, s47, 0x1c000
	v_writelane_b32 v255, s8, 20
	global_load_lds_dwordx4 v156, s[2:3]
	v_lshl_add_u64 v[0:1], s[2:3], 0, v[152:153]
	s_add_i32 m0, s47, 0x1e000
	v_readlane_b32 s60, v254, 37
	global_load_lds_dwordx4 v[0:1], off
	s_waitcnt vmcnt(6)
	v_writelane_b32 v255, s9, 22
	s_mov_b32 s59, s25
	v_add_u32_e32 v163, 0, v10
	v_readlane_b32 s61, v254, 38
	s_add_i32 s72, s60, s79
	v_readlane_b32 s77, v254, 41
	v_readlane_b32 s78, v254, 40
	s_barrier
	s_branch .LBB0_179

; #define PG8_STAGE(bufoff, gbase, voff) do { _Pragma("unroll") for (int _i = 0; _i < 2; ++_i) \
;         __builtin_amdgcn_global_load_lds((const unsigned*)((const char*)(gbase) + (voff)[_i]), (LAS unsigned*)(lds + (bufoff) + ldsw + _i * 8192), 16, 0, 0); } while (0)
; #define PG8_LDA(dst, b, h) do { _Pragma("unroll") for (int m = 0; m < 4; ++m) _Pragma("unroll") for (int k = 0; k < 2; ++k) dst[m][k] = *(const LAS bf16x8*)(lds + PG8_SA(b, h) + aoff + m * 2048 + k * 1024); } while (0)
; #define PG8_LDB(dst, b, h) do { _Pragma("unroll") for (int n = 0; n < 2; ++n) _Pragma("unroll") for (int k = 0; k < 2; ++k) dst[n][k] = *(const LAS bf16x8*)(lds + PG8_SB(b, h) + boff + n * 2048 + k * 1024); } while (0)
; #define PG8_MMA(ai, bj, At, Bt) do { __builtin_amdgcn_s_setprio(1); _Pragma("unroll") for (int m = 0; m < 4; ++m) _Pragma("unroll") for (int n = 0; n < 2; ++n) _Pragma("unroll") for (int k = 0; k < 2; ++k) \
;         acc[ai][bj][m][n] = __builtin_amdgcn_mfma_f32_16x16x32_bf16(Bt[n][k], At[m][k], acc[ai][bj][m][n], 0, 0, 0); __builtin_amdgcn_s_setprio(0); } while (0)
; #define PG8_WAIT_V(n) asm volatile("s_waitcnt vmcnt(" #n ")" ::: "memory")
; #define PG8_WAIT_L(n) asm volatile("s_waitcnt lgkmcnt(" #n ")" ::: "memory")
; #define PG8_BAR __builtin_amdgcn_s_barrier()
; #define PG8_SCHED __builtin_amdgcn_sched_barrier(0)
; template <class Epi>
; __device__ __forceinline__ void gemm_phase(LAS unsigned char* lds, const Gemm g, const StaticOrder& S, const Epi& E, int wv) {
;     ...
;             PG8_LDB(B0, 0, 0); PG8_SCHED; PG8_LDA(At, 0, 0); PG8_STAGE(PG8_SA(1, 1), a1 + hstep, voffA);
;             PG8_WAIT_L(8); PG8_BAR; PG8_WAIT_L(0); PG8_MMA(0, 0, At, B0); PG8_BAR; PG8_SCHED;
;             PG8_LDB(B1, 0, 1); PG8_STAGE(PG8_SB(0, 0), b2, voffB);
;             PG8_BAR; PG8_WAIT_L(0); PG8_MMA(0, 1, At, B1); PG8_BAR;
;             PG8_LDA(At, 0, 1); PG8_STAGE(PG8_SA(0, 0), a2, voffA);
;             PG8_BAR; PG8_WAIT_L(0); PG8_MMA(1, 0, At, B0); PG8_BAR; PG8_SCHED;
;             PG8_STAGE(PG8_SB(0, 1), b2 + hstep, voffB);
;             PG8_WAIT_V(6); PG8_BAR; PG8_MMA(1, 1, At, B1); PG8_BAR;
.LBB0_185:
	s_add_i32 s96, 0, 0x10000
	v_add_u32_e32 v8, s96, v161
	ds_read_b128 v[10:13], v8
	ds_read_b128 v[14:17], v8 offset:1024
	ds_read_b128 v[18:21], v8 offset:2048
	ds_read_b128 v[22:25], v8 offset:3072
	s_add_u32 s2, s62, 0x18080
	s_addc_u32 s3, s63, 0
	s_add_i32 vcc_hi, s47, 0xc000
	s_mov_b32 m0, vcc_hi
	s_add_i32 s79, s47, 0xe000
	ds_read_b128 v[4:7], v163
	ds_read_b128 v[26:29], v163 offset:1024
	ds_read_b128 v[30:33], v163 offset:2048
	ds_read_b128 v[34:37], v163 offset:3072
	ds_read_b128 v[38:41], v163 offset:4096
	ds_read_b128 v[42:45], v163 offset:5120
	ds_read_b128 v[46:49], v163 offset:6144
	ds_read_b128 v[50:53], v163 offset:7168
	global_load_lds_dwordx4 v158, s[2:3]
	s_mov_b32 m0, s79
	s_nop 0
	global_load_lds_dwordx4 v154, s[2:3]
	s_waitcnt lgkmcnt(8)
	s_barrier
	s_waitcnt lgkmcnt(0)
	s_setprio 1
	v_mfma_f32_16x16x32_bf16 v[0:3], v[10:13], v[4:7], 0
	v_mfma_f32_16x16x32_bf16 v[54:57], v[14:17], v[26:29], v[0:3]
	v_mfma_f32_16x16x32_bf16 v[0:3], v[18:21], v[4:7], 0
	v_mfma_f32_16x16x32_bf16 v[58:61], v[22:25], v[26:29], v[0:3]
	v_mfma_f32_16x16x32_bf16 v[0:3], v[10:13], v[30:33], 0
	v_mfma_f32_16x16x32_bf16 v[62:65], v[14:17], v[34:37], v[0:3]
	v_mfma_f32_16x16x32_bf16 v[0:3], v[18:21], v[30:33], 0
	v_mfma_f32_16x16x32_bf16 v[66:69], v[22:25], v[34:37], v[0:3]
	v_mfma_f32_16x16x32_bf16 v[0:3], v[10:13], v[38:41], 0
	v_mfma_f32_16x16x32_bf16 v[70:73], v[14:17], v[42:45], v[0:3]
	v_mfma_f32_16x16x32_bf16 v[0:3], v[18:21], v[38:41], 0
	v_mfma_f32_16x16x32_bf16 v[74:77], v[22:25], v[42:45], v[0:3]
	v_mfma_f32_16x16x32_bf16 v[0:3], v[10:13], v[46:49], 0
	v_mfma_f32_16x16x32_bf16 v[78:81], v[14:17], v[50:53], v[0:3]
	v_mfma_f32_16x16x32_bf16 v[0:3], v[18:21], v[46:49], 0
	v_mfma_f32_16x16x32_bf16 v[82:85], v[22:25], v[50:53], v[0:3]
	s_setprio 0
	s_barrier
	s_add_i32 s97, 0, 0x14000
	s_nop 3
	v_lshl_add_u64 v[0:1], s[68:69], 0, v[156:157]
	s_mov_b64 s[2:3], 0x100
	s_add_i32 s96, s96, s37
	v_add_u32_e32 v9, s97, v161
	v_lshl_add_u64 v[2:3], v[0:1], 0, s[2:3]
	s_mov_b32 m0, s96
	ds_read_b128 v[86:89], v9
	ds_read_b128 v[90:93], v9 offset:1024
	ds_read_b128 v[94:97], v9 offset:2048
	ds_read_b128 v[98:101], v9 offset:3072
	global_load_lds_dwordx4 v[2:3], off
	v_lshl_add_u64 v[2:3], s[68:69], 0, v[152:153]
	s_add_i32 s85, s96, 0x2000
	v_lshl_add_u64 v[102:103], v[2:3], 0, s[2:3]
	s_mov_b32 m0, s85
	s_nop 0
	global_load_lds_dwordx4 v[102:103], off
	s_barrier
	s_waitcnt lgkmcnt(0)
	s_setprio 1
	v_mfma_f32_16x16x32_bf16 v[102:105], v[86:89], v[4:7], 0
	v_mfma_f32_16x16x32_bf16 v[4:7], v[94:97], v[4:7], 0
	v_mfma_f32_16x16x32_bf16 v[102:105], v[90:93], v[26:29], v[102:105]
	v_mfma_f32_16x16x32_bf16 v[26:29], v[98:101], v[26:29], v[4:7]
	v_mfma_f32_16x16x32_bf16 v[4:7], v[86:89], v[30:33], 0
	v_mfma_f32_16x16x32_bf16 v[106:109], v[90:93], v[34:37], v[4:7]
	v_mfma_f32_16x16x32_bf16 v[4:7], v[94:97], v[30:33], 0
	v_mfma_f32_16x16x32_bf16 v[30:33], v[98:101], v[34:37], v[4:7]
	v_mfma_f32_16x16x32_bf16 v[4:7], v[86:89], v[38:41], 0
	v_mfma_f32_16x16x32_bf16 v[34:37], v[90:93], v[42:45], v[4:7]
	v_mfma_f32_16x16x32_bf16 v[4:7], v[94:97], v[38:41], 0
	v_mfma_f32_16x16x32_bf16 v[38:41], v[98:101], v[42:45], v[4:7]
	v_mfma_f32_16x16x32_bf16 v[4:7], v[86:89], v[46:49], 0
	v_mfma_f32_16x16x32_bf16 v[42:45], v[90:93], v[50:53], v[4:7]
	v_mfma_f32_16x16x32_bf16 v[4:7], v[94:97], v[46:49], 0
	v_mfma_f32_16x16x32_bf16 v[46:49], v[98:101], v[50:53], v[4:7]
	s_setprio 0
	s_nop 5
	v_lshl_add_u64 v[4:5], s[62:63], 0, v[158:159]
	s_mov_b32 m0, s47
	v_lshl_add_u64 v[6:7], v[4:5], 0, s[2:3]
	s_barrier
	ds_read_b128 v[50:53], v163 offset:16384
	ds_read_b128 v[110:113], v163 offset:17408
	ds_read_b128 v[114:117], v163 offset:18432
	ds_read_b128 v[118:121], v163 offset:19456
	ds_read_b128 v[122:125], v163 offset:20480
	ds_read_b128 v[126:129], v163 offset:21504
	ds_read_b128 v[130:133], v163 offset:22528
	ds_read_b128 v[134:137], v163 offset:23552
	global_load_lds_dwordx4 v[6:7], off
	v_lshl_add_u64 v[6:7], s[62:63], 0, v[154:155]
	v_lshl_add_u64 v[138:139], v[6:7], 0, s[2:3]
	s_mov_b32 m0, s50
	s_nop 0
	global_load_lds_dwordx4 v[138:139], off
	s_barrier
	s_waitcnt lgkmcnt(0)
	s_setprio 1
	v_mfma_f32_16x16x32_bf16 v[138:141], v[10:13], v[50:53], 0
	v_mfma_f32_16x16x32_bf16 v[146:149], v[10:13], v[114:117], 0
	v_mfma_f32_16x16x32_bf16 v[168:171], v[10:13], v[122:125], 0
	v_mfma_f32_16x16x32_bf16 v[10:13], v[10:13], v[130:133], 0
	v_mfma_f32_16x16x32_bf16 v[138:141], v[14:17], v[110:113], v[138:141]
	v_mfma_f32_16x16x32_bf16 v[142:145], v[18:21], v[50:53], 0
	v_mfma_f32_16x16x32_bf16 v[146:149], v[14:17], v[118:121], v[146:149]
	v_mfma_f32_16x16x32_bf16 v[164:167], v[18:21], v[114:117], 0
	v_mfma_f32_16x16x32_bf16 v[168:171], v[14:17], v[126:129], v[168:171]
	v_mfma_f32_16x16x32_bf16 v[172:175], v[18:21], v[122:125], 0
	v_mfma_f32_16x16x32_bf16 v[12:15], v[14:17], v[134:137], v[10:13]
	v_mfma_f32_16x16x32_bf16 v[16:19], v[18:21], v[130:133], 0
	v_mfma_f32_16x16x32_bf16 v[164:167], v[22:25], v[118:121], v[164:167]
	v_mfma_f32_16x16x32_bf16 v[172:175], v[22:25], v[126:129], v[172:175]
	v_mfma_f32_16x16x32_bf16 v[16:19], v[22:25], v[134:137], v[16:19]
	v_mfma_f32_16x16x32_bf16 v[142:145], v[22:25], v[110:113], v[142:145]
	s_setprio 0
	s_barrier
	s_add_u32 s2, s68, 0x18100
	s_addc_u32 s3, s69, 0
	s_add_i32 s97, s97, s37
	s_mov_b32 m0, s97
	s_add_i32 s86, s97, 0x2000
	global_load_lds_dwordx4 v156, s[2:3]
	v_lshl_add_u64 v[10:11], s[2:3], 0, v[152:153]
	s_mov_b32 m0, s86
	s_nop 0
	global_load_lds_dwordx4 v[10:11], off
	s_waitcnt vmcnt(6)
	s_barrier
; #define PG8_STAGE(bufoff, gbase, voff) do { _Pragma("unroll") for (int _i = 0; _i < 2; ++_i) \
;         __builtin_amdgcn_global_load_lds((const unsigned*)((const char*)(gbase) + (voff)[_i]), (LAS unsigned*)(lds + (bufoff) + ldsw + _i * 8192), 16, 0, 0); } while (0)
; #define PG8_LDA(dst, b, h) do { _Pragma("unroll") for (int m = 0; m < 4; ++m) _Pragma("unroll") for (int k = 0; k < 2; ++k) dst[m][k] = *(const LAS bf16x8*)(lds + PG8_SA(b, h) + aoff + m * 2048 + k * 1024); } while (0)
; #define PG8_LDB(dst, b, h) do { _Pragma("unroll") for (int n = 0; n < 2; ++n) _Pragma("unroll") for (int k = 0; k < 2; ++k) dst[n][k] = *(const LAS bf16x8*)(lds + PG8_SB(b, h) + boff + n * 2048 + k * 1024); } while (0)
; #define PG8_MMA(ai, bj, At, Bt) do { __builtin_amdgcn_s_setprio(1); _Pragma("unroll") for (int m = 0; m < 4; ++m) _Pragma("unroll") for (int n = 0; n < 2; ++n) _Pragma("unroll") for (int k = 0; k < 2; ++k) \
;         acc[ai][bj][m][n] = __builtin_amdgcn_mfma_f32_16x16x32_bf16(Bt[n][k], At[m][k], acc[ai][bj][m][n], 0, 0, 0); __builtin_amdgcn_s_setprio(0); } while (0)
; #define PG8_WAIT_V(n) asm volatile("s_waitcnt vmcnt(" #n ")" ::: "memory")
; #define PG8_WAIT_L(n) asm volatile("s_waitcnt lgkmcnt(" #n ")" ::: "memory")
; #define PG8_BAR __builtin_amdgcn_s_barrier()
; #define PG8_SCHED __builtin_amdgcn_sched_barrier(0)
; template <class Epi>
; __device__ __forceinline__ void gemm_phase(LAS unsigned char* lds, const Gemm g, const StaticOrder& S, const Epi& E, int wv) {
;     ...
;             PG8_WAIT_V(6); PG8_BAR; PG8_MMA(1, 1, At, B1); PG8_BAR;
;             PG8_LDB(B0, 1, 0); PG8_SCHED; PG8_LDA(At, 1, 0); PG8_STAGE(PG8_SA(0, 1), a2 + hstep, voffA);
;             PG8_WAIT_L(8); PG8_BAR; PG8_WAIT_L(0); PG8_MMA(0, 0, At, B0); PG8_BAR; PG8_SCHED;
;             PG8_LDB(B1, 1, 1); PG8_STAGE(PG8_SB(1, 0), b3, voffB);
;             PG8_BAR; PG8_WAIT_L(0); PG8_MMA(0, 1, At, B1); PG8_BAR;
;             PG8_LDA(At, 1, 1); PG8_STAGE(PG8_SA(1, 0), a3, voffA);
;             PG8_BAR; PG8_WAIT_L(0); PG8_MMA(1, 0, At, B0); PG8_BAR; PG8_SCHED;
	s_setprio 1
	v_mfma_f32_16x16x32_bf16 v[20:23], v[86:89], v[50:53], 0
	v_mfma_f32_16x16x32_bf16 v[50:53], v[94:97], v[50:53], 0
	v_mfma_f32_16x16x32_bf16 v[20:23], v[90:93], v[110:113], v[20:23]
	v_mfma_f32_16x16x32_bf16 v[50:53], v[98:101], v[110:113], v[50:53]
	v_mfma_f32_16x16x32_bf16 v[110:113], v[86:89], v[114:117], 0
	v_mfma_f32_16x16x32_bf16 v[114:117], v[94:97], v[114:117], 0
	v_mfma_f32_16x16x32_bf16 v[110:113], v[90:93], v[118:121], v[110:113]
	v_mfma_f32_16x16x32_bf16 v[114:117], v[98:101], v[118:121], v[114:117]
	v_mfma_f32_16x16x32_bf16 v[118:121], v[86:89], v[122:125], 0
	v_mfma_f32_16x16x32_bf16 v[86:89], v[86:89], v[130:133], 0
	v_mfma_f32_16x16x32_bf16 v[118:121], v[90:93], v[126:129], v[118:121]
	v_mfma_f32_16x16x32_bf16 v[122:125], v[94:97], v[122:125], 0
	v_mfma_f32_16x16x32_bf16 v[86:89], v[90:93], v[134:137], v[86:89]
	v_mfma_f32_16x16x32_bf16 v[90:93], v[94:97], v[130:133], 0
	v_mfma_f32_16x16x32_bf16 v[122:125], v[98:101], v[126:129], v[122:125]
	v_mfma_f32_16x16x32_bf16 v[90:93], v[98:101], v[134:137], v[90:93]
	s_setprio 0
	s_add_i32 vcc_lo, 0, 0x18000
	v_add_u32_e32 v10, vcc_lo, v161
	s_barrier
	ds_read_b128 v[94:97], v10
	ds_read_b128 v[98:101], v10 offset:1024
	ds_read_b128 v[126:129], v10 offset:2048
	ds_read_b128 v[130:133], v10 offset:3072
	s_add_u32 s2, s62, 0x18100
	s_addc_u32 s3, s63, 0
	s_mov_b32 m0, s64
	ds_read_b128 v[134:137], v163 offset:32768
	ds_read_b128 v[176:179], v163 offset:33792
	ds_read_b128 v[180:183], v163 offset:34816
	ds_read_b128 v[184:187], v163 offset:35840
	ds_read_b128 v[188:191], v163 offset:36864
	ds_read_b128 v[192:195], v163 offset:37888
	ds_read_b128 v[196:199], v163 offset:38912
	ds_read_b128 v[200:203], v163 offset:39936
	global_load_lds_dwordx4 v158, s[2:3]
	s_mov_b32 m0, s65
	s_nop 0
	global_load_lds_dwordx4 v154, s[2:3]
	s_waitcnt lgkmcnt(8)
	s_barrier
	s_waitcnt lgkmcnt(0)
	s_setprio 1
	v_mfma_f32_16x16x32_bf16 v[54:57], v[94:97], v[134:137], v[54:57]
	v_mfma_f32_16x16x32_bf16 v[58:61], v[126:129], v[134:137], v[58:61]
	v_mfma_f32_16x16x32_bf16 v[62:65], v[94:97], v[180:183], v[62:65]
	v_mfma_f32_16x16x32_bf16 v[66:69], v[126:129], v[180:183], v[66:69]
	v_mfma_f32_16x16x32_bf16 v[70:73], v[94:97], v[188:191], v[70:73]
	v_mfma_f32_16x16x32_bf16 v[74:77], v[126:129], v[188:191], v[74:77]
	v_mfma_f32_16x16x32_bf16 v[78:81], v[94:97], v[196:199], v[78:81]
	v_mfma_f32_16x16x32_bf16 v[82:85], v[126:129], v[196:199], v[82:85]
	v_mfma_f32_16x16x32_bf16 v[54:57], v[98:101], v[176:179], v[54:57]
	v_mfma_f32_16x16x32_bf16 v[58:61], v[130:133], v[176:179], v[58:61]
	v_mfma_f32_16x16x32_bf16 v[62:65], v[98:101], v[184:187], v[62:65]
	v_mfma_f32_16x16x32_bf16 v[66:69], v[130:133], v[184:187], v[66:69]
	v_mfma_f32_16x16x32_bf16 v[70:73], v[98:101], v[192:195], v[70:73]
	v_mfma_f32_16x16x32_bf16 v[74:77], v[130:133], v[192:195], v[74:77]
	v_mfma_f32_16x16x32_bf16 v[78:81], v[98:101], v[200:203], v[78:81]
	v_mfma_f32_16x16x32_bf16 v[82:85], v[130:133], v[200:203], v[82:85]
	s_setprio 0
	s_barrier
	s_add_i32 s2, 0, 0x1c000
	s_mov_b64 s[14:15], 0x180
	s_add_i32 vcc_lo, vcc_lo, s37
	v_add_u32_e32 v11, s2, v161
	v_lshl_add_u64 v[24:25], v[0:1], 0, s[14:15]
	s_mov_b32 m0, vcc_lo
	s_add_i32 s3, vcc_lo, 0x2000
	ds_read_b128 v[204:207], v11
	ds_read_b128 v[208:211], v11 offset:1024
	ds_read_b128 v[224:227], v11 offset:2048
	ds_read_b128 v[238:241], v11 offset:3072
	global_load_lds_dwordx4 v[24:25], off
	v_lshl_add_u64 v[24:25], v[2:3], 0, s[14:15]
	s_mov_b32 m0, s3
	s_nop 0
	global_load_lds_dwordx4 v[24:25], off
	s_barrier
	s_waitcnt lgkmcnt(0)
	s_setprio 1
	v_mfma_f32_16x16x32_bf16 v[102:105], v[204:207], v[134:137], v[102:105]
	v_mfma_f32_16x16x32_bf16 v[24:27], v[224:227], v[134:137], v[26:29]
	v_mfma_f32_16x16x32_bf16 v[106:109], v[204:207], v[180:183], v[106:109]
	v_mfma_f32_16x16x32_bf16 v[28:31], v[224:227], v[180:183], v[30:33]
	v_mfma_f32_16x16x32_bf16 v[32:35], v[204:207], v[188:191], v[34:37]
	v_mfma_f32_16x16x32_bf16 v[36:39], v[224:227], v[188:191], v[38:41]
	v_mfma_f32_16x16x32_bf16 v[40:43], v[204:207], v[196:199], v[42:45]
	v_mfma_f32_16x16x32_bf16 v[44:47], v[224:227], v[196:199], v[46:49]
	v_mfma_f32_16x16x32_bf16 v[102:105], v[208:211], v[176:179], v[102:105]
	v_mfma_f32_16x16x32_bf16 v[24:27], v[238:241], v[176:179], v[24:27]
	v_mfma_f32_16x16x32_bf16 v[106:109], v[208:211], v[184:187], v[106:109]
	v_mfma_f32_16x16x32_bf16 v[32:35], v[208:211], v[192:195], v[32:35]
	v_mfma_f32_16x16x32_bf16 v[36:39], v[238:241], v[192:195], v[36:39]
	v_mfma_f32_16x16x32_bf16 v[40:43], v[208:211], v[200:203], v[40:43]
	v_mfma_f32_16x16x32_bf16 v[44:47], v[238:241], v[200:203], v[44:47]
	v_mfma_f32_16x16x32_bf16 v[28:31], v[238:241], v[184:187], v[28:31]
	s_setprio 0
	s_mov_b32 m0, s70
	v_lshl_add_u64 v[48:49], v[4:5], 0, s[14:15]
	s_barrier
	ds_read_b128 v[134:137], v163 offset:49152
	ds_read_b128 v[176:179], v163 offset:50176
	ds_read_b128 v[180:183], v163 offset:51200
	ds_read_b128 v[184:187], v163 offset:52224
	ds_read_b128 v[188:191], v163 offset:53248
	ds_read_b128 v[192:195], v163 offset:54272
	ds_read_b128 v[196:199], v163 offset:55296
	ds_read_b128 v[200:203], v163 offset:56320
	global_load_lds_dwordx4 v[48:49], off
	v_lshl_add_u64 v[48:49], v[6:7], 0, s[14:15]
	s_mov_b32 m0, s71
	s_nop 0
	global_load_lds_dwordx4 v[48:49], off
	s_barrier
; #define PG8_STAGE(bufoff, gbase, voff) do { _Pragma("unroll") for (int _i = 0; _i < 2; ++_i) \
;         __builtin_amdgcn_global_load_lds((const unsigned*)((const char*)(gbase) + (voff)[_i]), (LAS unsigned*)(lds + (bufoff) + ldsw + _i * 8192), 16, 0, 0); } while (0)
; #define PG8_LDA(dst, b, h) do { _Pragma("unroll") for (int m = 0; m < 4; ++m) _Pragma("unroll") for (int k = 0; k < 2; ++k) dst[m][k] = *(const LAS bf16x8*)(lds + PG8_SA(b, h) + aoff + m * 2048 + k * 1024); } while (0)
; #define PG8_LDB(dst, b, h) do { _Pragma("unroll") for (int n = 0; n < 2; ++n) _Pragma("unroll") for (int k = 0; k < 2; ++k) dst[n][k] = *(const LAS bf16x8*)(lds + PG8_SB(b, h) + boff + n * 2048 + k * 1024); } while (0)
; #define PG8_WAIT_V(n) asm volatile("s_waitcnt vmcnt(" #n ")" ::: "memory")
; #define PG8_WAIT_L(n) asm volatile("s_waitcnt lgkmcnt(" #n ")" ::: "memory")
; #define PG8_BAR __builtin_amdgcn_s_barrier()
; #define PG8_SCHED __builtin_amdgcn_sched_barrier(0)
; template <class Epi>
; __device__ __forceinline__ void gemm_phase(LAS unsigned char* lds, const Gemm g, const StaticOrder& S, const Epi& E, int wv) {
;     ...
;             PG8_LDB(B0, 0, 0); PG8_SCHED; PG8_LDA(At, 0, 0); PG8_STAGE(PG8_SA(1, 1), a1 + hstep, voffA);
;             PG8_WAIT_L(8); PG8_BAR; PG8_WAIT_L(0); PG8_MMA(0, 0, At, B0); PG8_BAR; PG8_SCHED;
;             PG8_LDB(B1, 0, 1); PG8_STAGE(PG8_SB(0, 0), b2, voffB);
;             PG8_BAR; PG8_WAIT_L(0); PG8_MMA(0, 1, At, B1); PG8_BAR;
;             PG8_LDA(At, 0, 1); PG8_STAGE(PG8_SA(0, 0), a2, voffA);
;             PG8_BAR; PG8_WAIT_L(0); PG8_MMA(1, 0, At, B0); PG8_BAR; PG8_SCHED;
;             PG8_STAGE(PG8_SB(0, 1), b2 + hstep, voffB);
;             PG8_WAIT_V(6); PG8_BAR; PG8_MMA(1, 1, At, B1); PG8_BAR;
;             PG8_LDB(B0, 1, 0); PG8_SCHED; PG8_LDA(At, 1, 0); PG8_STAGE(PG8_SA(0, 1), a2 + hstep, voffA);
;             PG8_WAIT_L(8); PG8_BAR; PG8_WAIT_L(0); PG8_MMA(0, 0, At, B0); PG8_BAR; PG8_SCHED;
;             PG8_LDB(B1, 1, 1); PG8_STAGE(PG8_SB(1, 0), b3, voffB);
;             PG8_BAR; PG8_WAIT_L(0); PG8_MMA(0, 1, At, B1); PG8_BAR;
;             PG8_LDA(At, 1, 1); PG8_STAGE(PG8_SA(1, 0), a3, voffA);
;             PG8_BAR; PG8_WAIT_L(0); PG8_MMA(1, 0, At, B0); PG8_BAR; PG8_SCHED;
;             PG8_STAGE(PG8_SB(1, 1), b3 + hstep, voffB);
;             PG8_WAIT_V(6); PG8_BAR; PG8_MMA(1, 1, At, B1); PG8_BAR;
	s_waitcnt lgkmcnt(0)
	s_setprio 1
	v_mfma_f32_16x16x32_bf16 v[164:167], v[126:129], v[180:183], v[164:167]
	v_mfma_f32_16x16x32_bf16 v[168:171], v[94:97], v[188:191], v[168:171]
	v_mfma_f32_16x16x32_bf16 v[172:175], v[126:129], v[188:191], v[172:175]
	v_mfma_f32_16x16x32_bf16 v[12:15], v[94:97], v[196:199], v[12:15]
	v_mfma_f32_16x16x32_bf16 v[16:19], v[126:129], v[196:199], v[16:19]
	v_mfma_f32_16x16x32_bf16 v[138:141], v[94:97], v[134:137], v[138:141]
	v_mfma_f32_16x16x32_bf16 v[142:145], v[126:129], v[134:137], v[142:145]
	v_mfma_f32_16x16x32_bf16 v[146:149], v[94:97], v[180:183], v[146:149]
	v_mfma_f32_16x16x32_bf16 v[164:167], v[130:133], v[184:187], v[164:167]
	v_mfma_f32_16x16x32_bf16 v[168:171], v[98:101], v[192:195], v[168:171]
	v_mfma_f32_16x16x32_bf16 v[172:175], v[130:133], v[192:195], v[172:175]
	v_mfma_f32_16x16x32_bf16 v[12:15], v[98:101], v[200:203], v[12:15]
	v_mfma_f32_16x16x32_bf16 v[16:19], v[130:133], v[200:203], v[16:19]
	v_mfma_f32_16x16x32_bf16 v[138:141], v[98:101], v[176:179], v[138:141]
	v_mfma_f32_16x16x32_bf16 v[142:145], v[130:133], v[176:179], v[142:145]
	v_mfma_f32_16x16x32_bf16 v[146:149], v[98:101], v[184:187], v[146:149]
	s_setprio 0
	s_barrier
	s_add_u32 s14, s68, 0x18180
	s_addc_u32 s15, s69, 0
	s_add_i32 s2, s2, s37
	s_mov_b32 m0, s2
	s_nop 0
	global_load_lds_dwordx4 v156, s[14:15]
	v_lshl_add_u64 v[48:49], s[14:15], 0, v[152:153]
	s_add_i32 s14, s2, 0x2000
	s_mov_b32 m0, s14
	s_nop 0
	global_load_lds_dwordx4 v[48:49], off
	s_waitcnt vmcnt(6)
	s_barrier
	s_setprio 1
	v_mfma_f32_16x16x32_bf16 v[20:23], v[204:207], v[134:137], v[20:23]
	v_mfma_f32_16x16x32_bf16 v[48:51], v[224:227], v[134:137], v[50:53]
	v_mfma_f32_16x16x32_bf16 v[94:97], v[204:207], v[180:183], v[110:113]
	v_mfma_f32_16x16x32_bf16 v[98:101], v[224:227], v[180:183], v[114:117]
	v_mfma_f32_16x16x32_bf16 v[110:113], v[204:207], v[188:191], v[118:121]
	v_mfma_f32_16x16x32_bf16 v[114:117], v[224:227], v[188:191], v[122:125]
	v_mfma_f32_16x16x32_bf16 v[86:89], v[204:207], v[196:199], v[86:89]
	v_mfma_f32_16x16x32_bf16 v[90:93], v[224:227], v[196:199], v[90:93]
	v_mfma_f32_16x16x32_bf16 v[20:23], v[208:211], v[176:179], v[20:23]
	v_mfma_f32_16x16x32_bf16 v[48:51], v[238:241], v[176:179], v[48:51]
	v_mfma_f32_16x16x32_bf16 v[94:97], v[208:211], v[184:187], v[94:97]
	v_mfma_f32_16x16x32_bf16 v[98:101], v[238:241], v[184:187], v[98:101]
	v_mfma_f32_16x16x32_bf16 v[110:113], v[208:211], v[192:195], v[110:113]
	v_mfma_f32_16x16x32_bf16 v[114:117], v[238:241], v[192:195], v[114:117]
	v_mfma_f32_16x16x32_bf16 v[86:89], v[208:211], v[200:203], v[86:89]
	v_mfma_f32_16x16x32_bf16 v[90:93], v[238:241], v[200:203], v[90:93]
	s_setprio 0
	s_barrier
	ds_read_b128 v[118:121], v8
	ds_read_b128 v[122:125], v8 offset:1024
	ds_read_b128 v[126:129], v8 offset:2048
	ds_read_b128 v[130:133], v8 offset:3072
	s_add_u32 s20, s62, 0x18180
	s_addc_u32 s21, s63, 0
	s_mov_b32 m0, vcc_hi
	ds_read_b128 v[134:137], v163
	ds_read_b128 v[176:179], v163 offset:1024
	ds_read_b128 v[180:183], v163 offset:2048
	ds_read_b128 v[184:187], v163 offset:3072
	ds_read_b128 v[188:191], v163 offset:4096
	ds_read_b128 v[192:195], v163 offset:5120
	ds_read_b128 v[196:199], v163 offset:6144
	ds_read_b128 v[200:203], v163 offset:7168
	global_load_lds_dwordx4 v158, s[20:21]
	s_mov_b32 m0, s79
	s_nop 0
	global_load_lds_dwordx4 v154, s[20:21]
	s_waitcnt lgkmcnt(8)
	s_barrier
	s_waitcnt lgkmcnt(0)
	s_setprio 1
	v_mfma_f32_16x16x32_bf16 v[52:55], v[118:121], v[134:137], v[54:57]
	v_mfma_f32_16x16x32_bf16 v[56:59], v[126:129], v[134:137], v[58:61]
	v_mfma_f32_16x16x32_bf16 v[60:63], v[118:121], v[180:183], v[62:65]
	v_mfma_f32_16x16x32_bf16 v[64:67], v[126:129], v[180:183], v[66:69]
	v_mfma_f32_16x16x32_bf16 v[68:71], v[118:121], v[188:191], v[70:73]
	v_mfma_f32_16x16x32_bf16 v[72:75], v[126:129], v[188:191], v[74:77]
	v_mfma_f32_16x16x32_bf16 v[76:79], v[118:121], v[196:199], v[78:81]
	v_mfma_f32_16x16x32_bf16 v[80:83], v[126:129], v[196:199], v[82:85]
	v_mfma_f32_16x16x32_bf16 v[52:55], v[122:125], v[176:179], v[52:55]
	v_mfma_f32_16x16x32_bf16 v[56:59], v[130:133], v[176:179], v[56:59]
	v_mfma_f32_16x16x32_bf16 v[60:63], v[122:125], v[184:187], v[60:63]
	v_mfma_f32_16x16x32_bf16 v[64:67], v[130:133], v[184:187], v[64:67]
	v_mfma_f32_16x16x32_bf16 v[68:71], v[122:125], v[192:195], v[68:71]
	v_mfma_f32_16x16x32_bf16 v[72:75], v[130:133], v[192:195], v[72:75]
	v_mfma_f32_16x16x32_bf16 v[76:79], v[122:125], v[200:203], v[76:79]
	v_mfma_f32_16x16x32_bf16 v[80:83], v[130:133], v[200:203], v[80:83]
	s_setprio 0
	s_barrier
	s_mov_b64 s[20:21], 0x200
	s_mov_b32 m0, s96
	v_lshl_add_u64 v[84:85], v[0:1], 0, s[20:21]
	ds_read_b128 v[204:207], v9
	ds_read_b128 v[208:211], v9 offset:1024
	ds_read_b128 v[224:227], v9 offset:2048
	ds_read_b128 v[238:241], v9 offset:3072
	global_load_lds_dwordx4 v[84:85], off
	v_lshl_add_u64 v[84:85], v[2:3], 0, s[20:21]
	s_mov_b32 m0, s85
	s_nop 0
	global_load_lds_dwordx4 v[84:85], off
	s_barrier
	s_waitcnt lgkmcnt(0)
	s_setprio 1
	v_mfma_f32_16x16x32_bf16 v[102:105], v[204:207], v[134:137], v[102:105]
	v_mfma_f32_16x16x32_bf16 v[24:27], v[224:227], v[134:137], v[24:27]
	v_mfma_f32_16x16x32_bf16 v[106:109], v[204:207], v[180:183], v[106:109]
	v_mfma_f32_16x16x32_bf16 v[32:35], v[204:207], v[188:191], v[32:35]
	v_mfma_f32_16x16x32_bf16 v[36:39], v[224:227], v[188:191], v[36:39]
	v_mfma_f32_16x16x32_bf16 v[40:43], v[204:207], v[196:199], v[40:43]
	v_mfma_f32_16x16x32_bf16 v[44:47], v[224:227], v[196:199], v[44:47]
	v_mfma_f32_16x16x32_bf16 v[102:105], v[208:211], v[176:179], v[102:105]
	v_mfma_f32_16x16x32_bf16 v[24:27], v[238:241], v[176:179], v[24:27]
	v_mfma_f32_16x16x32_bf16 v[106:109], v[208:211], v[184:187], v[106:109]
	v_mfma_f32_16x16x32_bf16 v[28:31], v[224:227], v[180:183], v[28:31]
	v_mfma_f32_16x16x32_bf16 v[32:35], v[208:211], v[192:195], v[32:35]
	v_mfma_f32_16x16x32_bf16 v[36:39], v[238:241], v[192:195], v[36:39]
	v_mfma_f32_16x16x32_bf16 v[40:43], v[208:211], v[200:203], v[40:43]
	v_mfma_f32_16x16x32_bf16 v[44:47], v[238:241], v[200:203], v[44:47]
	v_mfma_f32_16x16x32_bf16 v[28:31], v[238:241], v[184:187], v[28:31]
	s_setprio 0
	s_mov_b32 m0, s47
	v_lshl_add_u64 v[84:85], v[4:5], 0, s[20:21]
	s_barrier
; #define PG8_STAGE(bufoff, gbase, voff) do { _Pragma("unroll") for (int _i = 0; _i < 2; ++_i) \
;         __builtin_amdgcn_global_load_lds((const unsigned*)((const char*)(gbase) + (voff)[_i]), (LAS unsigned*)(lds + (bufoff) + ldsw + _i * 8192), 16, 0, 0); } while (0)
; #define PG8_LDA(dst, b, h) do { _Pragma("unroll") for (int m = 0; m < 4; ++m) _Pragma("unroll") for (int k = 0; k < 2; ++k) dst[m][k] = *(const LAS bf16x8*)(lds + PG8_SA(b, h) + aoff + m * 2048 + k * 1024); } while (0)
; #define PG8_LDB(dst, b, h) do { _Pragma("unroll") for (int n = 0; n < 2; ++n) _Pragma("unroll") for (int k = 0; k < 2; ++k) dst[n][k] = *(const LAS bf16x8*)(lds + PG8_SB(b, h) + boff + n * 2048 + k * 1024); } while (0)
; #define PG8_WAIT_V(n) asm volatile("s_waitcnt vmcnt(" #n ")" ::: "memory")
; #define PG8_WAIT_L(n) asm volatile("s_waitcnt lgkmcnt(" #n ")" ::: "memory")
; #define PG8_BAR __builtin_amdgcn_s_barrier()
; #define PG8_SCHED __builtin_amdgcn_sched_barrier(0)
; template <class Epi>
; __device__ __forceinline__ void gemm_phase(LAS unsigned char* lds, const Gemm g, const StaticOrder& S, const Epi& E, int wv) {
;     ...
;             PG8_LDB(B0, 0, 0); PG8_SCHED; PG8_LDA(At, 0, 0); PG8_STAGE(PG8_SA(1, 1), a1 + hstep, voffA);
;             PG8_WAIT_L(8); PG8_BAR; PG8_WAIT_L(0); PG8_MMA(0, 0, At, B0); PG8_BAR; PG8_SCHED;
;             PG8_LDB(B1, 0, 1); PG8_STAGE(PG8_SB(0, 0), b2, voffB);
;             PG8_BAR; PG8_WAIT_L(0); PG8_MMA(0, 1, At, B1); PG8_BAR;
;             PG8_LDA(At, 0, 1); PG8_STAGE(PG8_SA(0, 0), a2, voffA);
;             PG8_BAR; PG8_WAIT_L(0); PG8_MMA(1, 0, At, B0); PG8_BAR; PG8_SCHED;
;             PG8_STAGE(PG8_SB(0, 1), b2 + hstep, voffB);
;             PG8_WAIT_V(6); PG8_BAR; PG8_MMA(1, 1, At, B1); PG8_BAR;
;             PG8_LDB(B0, 1, 0); PG8_SCHED; PG8_LDA(At, 1, 0); PG8_STAGE(PG8_SA(0, 1), a2 + hstep, voffA);
;             PG8_WAIT_L(8); PG8_BAR; PG8_WAIT_L(0); PG8_MMA(0, 0, At, B0); PG8_BAR; PG8_SCHED;
;             PG8_LDB(B1, 1, 1); PG8_STAGE(PG8_SB(1, 0), b3, voffB);
;             PG8_BAR; PG8_WAIT_L(0); PG8_MMA(0, 1, At, B1); PG8_BAR;
;             PG8_LDA(At, 1, 1); PG8_STAGE(PG8_SA(1, 0), a3, voffA);
;             PG8_BAR; PG8_WAIT_L(0); PG8_MMA(1, 0, At, B0); PG8_BAR; PG8_SCHED;
;             PG8_STAGE(PG8_SB(1, 1), b3 + hstep, voffB);
;             PG8_WAIT_V(6); PG8_BAR; PG8_MMA(1, 1, At, B1); PG8_BAR;
	ds_read_b128 v[134:137], v163 offset:16384
	ds_read_b128 v[176:179], v163 offset:17408
	ds_read_b128 v[180:183], v163 offset:18432
	ds_read_b128 v[184:187], v163 offset:19456
	ds_read_b128 v[188:191], v163 offset:20480
	ds_read_b128 v[192:195], v163 offset:21504
	ds_read_b128 v[196:199], v163 offset:22528
	ds_read_b128 v[200:203], v163 offset:23552
	global_load_lds_dwordx4 v[84:85], off
	v_lshl_add_u64 v[84:85], v[6:7], 0, s[20:21]
	s_mov_b32 m0, s50
	s_nop 0
	global_load_lds_dwordx4 v[84:85], off
	s_barrier
	s_waitcnt lgkmcnt(0)
	s_setprio 1
	v_mfma_f32_16x16x32_bf16 v[164:167], v[126:129], v[180:183], v[164:167]
	v_mfma_f32_16x16x32_bf16 v[168:171], v[118:121], v[188:191], v[168:171]
	v_mfma_f32_16x16x32_bf16 v[172:175], v[126:129], v[188:191], v[172:175]
	v_mfma_f32_16x16x32_bf16 v[12:15], v[118:121], v[196:199], v[12:15]
	v_mfma_f32_16x16x32_bf16 v[16:19], v[126:129], v[196:199], v[16:19]
	v_mfma_f32_16x16x32_bf16 v[138:141], v[118:121], v[134:137], v[138:141]
	v_mfma_f32_16x16x32_bf16 v[142:145], v[126:129], v[134:137], v[142:145]
	v_mfma_f32_16x16x32_bf16 v[146:149], v[118:121], v[180:183], v[146:149]
	v_mfma_f32_16x16x32_bf16 v[164:167], v[130:133], v[184:187], v[164:167]
	v_mfma_f32_16x16x32_bf16 v[168:171], v[122:125], v[192:195], v[168:171]
	v_mfma_f32_16x16x32_bf16 v[172:175], v[130:133], v[192:195], v[172:175]
	v_mfma_f32_16x16x32_bf16 v[12:15], v[122:125], v[200:203], v[12:15]
	v_mfma_f32_16x16x32_bf16 v[16:19], v[130:133], v[200:203], v[16:19]
	v_mfma_f32_16x16x32_bf16 v[138:141], v[122:125], v[176:179], v[138:141]
	v_mfma_f32_16x16x32_bf16 v[142:145], v[130:133], v[176:179], v[142:145]
	v_mfma_f32_16x16x32_bf16 v[146:149], v[122:125], v[184:187], v[146:149]
	s_setprio 0
	s_barrier
	s_add_u32 s20, s68, 0x18200
	s_addc_u32 s21, s69, 0
	s_mov_b32 m0, s97
	s_nop 0
	global_load_lds_dwordx4 v156, s[20:21]
	s_mov_b32 m0, s86
	s_nop 0
	global_load_lds_dwordx4 v152, s[20:21]
	s_waitcnt vmcnt(6)
	s_barrier
	s_setprio 1
	v_mfma_f32_16x16x32_bf16 v[20:23], v[204:207], v[134:137], v[20:23]
	v_mfma_f32_16x16x32_bf16 v[48:51], v[224:227], v[134:137], v[48:51]
	v_mfma_f32_16x16x32_bf16 v[94:97], v[204:207], v[180:183], v[94:97]
	v_mfma_f32_16x16x32_bf16 v[98:101], v[224:227], v[180:183], v[98:101]
	v_mfma_f32_16x16x32_bf16 v[110:113], v[204:207], v[188:191], v[110:113]
	v_mfma_f32_16x16x32_bf16 v[114:117], v[224:227], v[188:191], v[114:117]
	v_mfma_f32_16x16x32_bf16 v[84:87], v[204:207], v[196:199], v[86:89]
	v_mfma_f32_16x16x32_bf16 v[88:91], v[224:227], v[196:199], v[90:93]
	v_mfma_f32_16x16x32_bf16 v[20:23], v[208:211], v[176:179], v[20:23]
	v_mfma_f32_16x16x32_bf16 v[48:51], v[238:241], v[176:179], v[48:51]
	v_mfma_f32_16x16x32_bf16 v[94:97], v[208:211], v[184:187], v[94:97]
	v_mfma_f32_16x16x32_bf16 v[98:101], v[238:241], v[184:187], v[98:101]
	v_mfma_f32_16x16x32_bf16 v[110:113], v[208:211], v[192:195], v[110:113]
	v_mfma_f32_16x16x32_bf16 v[114:117], v[238:241], v[192:195], v[114:117]
	v_mfma_f32_16x16x32_bf16 v[84:87], v[208:211], v[200:203], v[84:87]
	v_mfma_f32_16x16x32_bf16 v[88:91], v[238:241], v[200:203], v[88:91]
	s_setprio 0
	s_barrier
	ds_read_b128 v[118:121], v10
	ds_read_b128 v[122:125], v10 offset:1024
	ds_read_b128 v[126:129], v10 offset:2048
	ds_read_b128 v[130:133], v10 offset:3072
	s_add_u32 s20, s62, 0x18200
	s_addc_u32 s21, s63, 0
	s_mov_b32 m0, s64
	ds_read_b128 v[134:137], v163 offset:32768
	ds_read_b128 v[176:179], v163 offset:33792
	ds_read_b128 v[180:183], v163 offset:34816
	ds_read_b128 v[184:187], v163 offset:35840
	ds_read_b128 v[188:191], v163 offset:36864
	ds_read_b128 v[192:195], v163 offset:37888
	ds_read_b128 v[196:199], v163 offset:38912
	ds_read_b128 v[200:203], v163 offset:39936
	global_load_lds_dwordx4 v158, s[20:21]
	s_mov_b32 m0, s65
	s_nop 0
	global_load_lds_dwordx4 v154, s[20:21]
	s_waitcnt lgkmcnt(8)
	s_barrier
	s_waitcnt lgkmcnt(0)
	s_setprio 1
	v_mfma_f32_16x16x32_bf16 v[52:55], v[118:121], v[134:137], v[52:55]
	v_mfma_f32_16x16x32_bf16 v[56:59], v[126:129], v[134:137], v[56:59]
	v_mfma_f32_16x16x32_bf16 v[60:63], v[118:121], v[180:183], v[60:63]
	v_mfma_f32_16x16x32_bf16 v[64:67], v[126:129], v[180:183], v[64:67]
	v_mfma_f32_16x16x32_bf16 v[68:71], v[118:121], v[188:191], v[68:71]
	v_mfma_f32_16x16x32_bf16 v[72:75], v[126:129], v[188:191], v[72:75]
	v_mfma_f32_16x16x32_bf16 v[76:79], v[118:121], v[196:199], v[76:79]
	v_mfma_f32_16x16x32_bf16 v[80:83], v[126:129], v[196:199], v[80:83]
	v_mfma_f32_16x16x32_bf16 v[52:55], v[122:125], v[176:179], v[52:55]
	v_mfma_f32_16x16x32_bf16 v[56:59], v[130:133], v[176:179], v[56:59]
	v_mfma_f32_16x16x32_bf16 v[60:63], v[122:125], v[184:187], v[60:63]
	v_mfma_f32_16x16x32_bf16 v[64:67], v[130:133], v[184:187], v[64:67]
	v_mfma_f32_16x16x32_bf16 v[68:71], v[122:125], v[192:195], v[68:71]
	v_mfma_f32_16x16x32_bf16 v[72:75], v[130:133], v[192:195], v[72:75]
	v_mfma_f32_16x16x32_bf16 v[76:79], v[122:125], v[200:203], v[76:79]
	v_mfma_f32_16x16x32_bf16 v[80:83], v[130:133], v[200:203], v[80:83]
	s_setprio 0
	s_barrier
	s_mov_b64 s[20:21], 0x280
	s_mov_b32 m0, vcc_lo
	v_lshl_add_u64 v[0:1], v[0:1], 0, s[20:21]
	ds_read_b128 v[204:207], v11
	ds_read_b128 v[208:211], v11 offset:1024
	ds_read_b128 v[224:227], v11 offset:2048
	ds_read_b128 v[238:241], v11 offset:3072
	global_load_lds_dwordx4 v[0:1], off
	v_lshl_add_u64 v[0:1], v[2:3], 0, s[20:21]
	s_mov_b32 m0, s3
	s_nop 0
	global_load_lds_dwordx4 v[0:1], off
	s_barrier
; #define PG8_STAGE(bufoff, gbase, voff) do { _Pragma("unroll") for (int _i = 0; _i < 2; ++_i) \
;         __builtin_amdgcn_global_load_lds((const unsigned*)((const char*)(gbase) + (voff)[_i]), (LAS unsigned*)(lds + (bufoff) + ldsw + _i * 8192), 16, 0, 0); } while (0)
; #define PG8_LDA(dst, b, h) do { _Pragma("unroll") for (int m = 0; m < 4; ++m) _Pragma("unroll") for (int k = 0; k < 2; ++k) dst[m][k] = *(const LAS bf16x8*)(lds + PG8_SA(b, h) + aoff + m * 2048 + k * 1024); } while (0)
; #define PG8_LDB(dst, b, h) do { _Pragma("unroll") for (int n = 0; n < 2; ++n) _Pragma("unroll") for (int k = 0; k < 2; ++k) dst[n][k] = *(const LAS bf16x8*)(lds + PG8_SB(b, h) + boff + n * 2048 + k * 1024); } while (0)
; #define PG8_WAIT_V(n) asm volatile("s_waitcnt vmcnt(" #n ")" ::: "memory")
; #define PG8_WAIT_L(n) asm volatile("s_waitcnt lgkmcnt(" #n ")" ::: "memory")
; #define PG8_BAR __builtin_amdgcn_s_barrier()
; #define PG8_SCHED __builtin_amdgcn_sched_barrier(0)
; template <class Epi>
; __device__ __forceinline__ void gemm_phase(LAS unsigned char* lds, const Gemm g, const StaticOrder& S, const Epi& E, int wv) {
;     ...
;             PG8_LDB(B0, 0, 0); PG8_SCHED; PG8_LDA(At, 0, 0); PG8_STAGE(PG8_SA(1, 1), a1 + hstep, voffA);
;             PG8_WAIT_L(8); PG8_BAR; PG8_WAIT_L(0); PG8_MMA(0, 0, At, B0); PG8_BAR; PG8_SCHED;
;             PG8_LDB(B1, 0, 1); PG8_STAGE(PG8_SB(0, 0), b2, voffB);
;             PG8_BAR; PG8_WAIT_L(0); PG8_MMA(0, 1, At, B1); PG8_BAR;
;             PG8_LDA(At, 0, 1); PG8_STAGE(PG8_SA(0, 0), a2, voffA);
;             PG8_BAR; PG8_WAIT_L(0); PG8_MMA(1, 0, At, B0); PG8_BAR; PG8_SCHED;
;             PG8_STAGE(PG8_SB(0, 1), b2 + hstep, voffB);
;             PG8_WAIT_V(6); PG8_BAR; PG8_MMA(1, 1, At, B1); PG8_BAR;
;             PG8_LDB(B0, 1, 0); PG8_SCHED; PG8_LDA(At, 1, 0); PG8_STAGE(PG8_SA(0, 1), a2 + hstep, voffA);
;             PG8_WAIT_L(8); PG8_BAR; PG8_WAIT_L(0); PG8_MMA(0, 0, At, B0); PG8_BAR; PG8_SCHED;
;             PG8_LDB(B1, 1, 1); PG8_STAGE(PG8_SB(1, 0), b3, voffB);
;             PG8_BAR; PG8_WAIT_L(0); PG8_MMA(0, 1, At, B1); PG8_BAR;
;             PG8_LDA(At, 1, 1); PG8_STAGE(PG8_SA(1, 0), a3, voffA);
;             PG8_BAR; PG8_WAIT_L(0); PG8_MMA(1, 0, At, B0); PG8_BAR; PG8_SCHED;
;             PG8_STAGE(PG8_SB(1, 1), b3 + hstep, voffB);
;             PG8_WAIT_V(6); PG8_BAR; PG8_MMA(1, 1, At, B1); PG8_BAR;
	s_waitcnt lgkmcnt(0)
	s_setprio 1
	v_mfma_f32_16x16x32_bf16 v[0:3], v[204:207], v[134:137], v[102:105]
	v_mfma_f32_16x16x32_bf16 v[24:27], v[224:227], v[134:137], v[24:27]
	v_mfma_f32_16x16x32_bf16 v[102:105], v[204:207], v[180:183], v[106:109]
	v_mfma_f32_16x16x32_bf16 v[32:35], v[204:207], v[188:191], v[32:35]
	v_mfma_f32_16x16x32_bf16 v[36:39], v[224:227], v[188:191], v[36:39]
	v_mfma_f32_16x16x32_bf16 v[40:43], v[204:207], v[196:199], v[40:43]
	v_mfma_f32_16x16x32_bf16 v[44:47], v[224:227], v[196:199], v[44:47]
	v_mfma_f32_16x16x32_bf16 v[0:3], v[208:211], v[176:179], v[0:3]
	v_mfma_f32_16x16x32_bf16 v[24:27], v[238:241], v[176:179], v[24:27]
	v_mfma_f32_16x16x32_bf16 v[102:105], v[208:211], v[184:187], v[102:105]
	v_mfma_f32_16x16x32_bf16 v[28:31], v[224:227], v[180:183], v[28:31]
	v_mfma_f32_16x16x32_bf16 v[32:35], v[208:211], v[192:195], v[32:35]
	v_mfma_f32_16x16x32_bf16 v[36:39], v[238:241], v[192:195], v[36:39]
	v_mfma_f32_16x16x32_bf16 v[40:43], v[208:211], v[200:203], v[40:43]
	v_mfma_f32_16x16x32_bf16 v[44:47], v[238:241], v[200:203], v[44:47]
	v_mfma_f32_16x16x32_bf16 v[28:31], v[238:241], v[184:187], v[28:31]
	s_setprio 0
	s_mov_b32 m0, s70
	v_lshl_add_u64 v[4:5], v[4:5], 0, s[20:21]
	s_barrier
	ds_read_b128 v[106:109], v163 offset:49152
	ds_read_b128 v[134:137], v163 offset:50176
	ds_read_b128 v[176:179], v163 offset:51200
	ds_read_b128 v[180:183], v163 offset:52224
	ds_read_b128 v[184:187], v163 offset:53248
	ds_read_b128 v[188:191], v163 offset:54272
	ds_read_b128 v[192:195], v163 offset:55296
	ds_read_b128 v[196:199], v163 offset:56320
	global_load_lds_dwordx4 v[4:5], off
	v_lshl_add_u64 v[4:5], v[6:7], 0, s[20:21]
	s_mov_b32 m0, s71
	s_nop 0
	global_load_lds_dwordx4 v[4:5], off
	s_barrier
	s_waitcnt lgkmcnt(0)
	s_setprio 1
	v_mfma_f32_16x16x32_bf16 v[4:7], v[118:121], v[106:109], v[138:141]
	v_mfma_f32_16x16x32_bf16 v[138:141], v[126:129], v[106:109], v[142:145]
	v_mfma_f32_16x16x32_bf16 v[142:145], v[118:121], v[176:179], v[146:149]
	v_mfma_f32_16x16x32_bf16 v[146:149], v[126:129], v[176:179], v[164:167]
	v_mfma_f32_16x16x32_bf16 v[164:167], v[118:121], v[184:187], v[168:171]
	v_mfma_f32_16x16x32_bf16 v[168:171], v[126:129], v[184:187], v[172:175]
	v_mfma_f32_16x16x32_bf16 v[12:15], v[118:121], v[192:195], v[12:15]
	v_mfma_f32_16x16x32_bf16 v[16:19], v[126:129], v[192:195], v[16:19]
	v_mfma_f32_16x16x32_bf16 v[4:7], v[122:125], v[134:137], v[4:7]
	v_mfma_f32_16x16x32_bf16 v[164:167], v[122:125], v[188:191], v[164:167]
	v_mfma_f32_16x16x32_bf16 v[168:171], v[130:133], v[188:191], v[168:171]
	v_mfma_f32_16x16x32_bf16 v[12:15], v[122:125], v[196:199], v[12:15]
	v_mfma_f32_16x16x32_bf16 v[16:19], v[130:133], v[196:199], v[16:19]
	v_mfma_f32_16x16x32_bf16 v[138:141], v[130:133], v[134:137], v[138:141]
	v_mfma_f32_16x16x32_bf16 v[142:145], v[122:125], v[180:183], v[142:145]
	v_mfma_f32_16x16x32_bf16 v[146:149], v[130:133], v[180:183], v[146:149]
	s_setprio 0
	s_barrier
	s_add_u32 s20, s68, 0x18280
	s_addc_u32 s21, s69, 0
	s_mov_b32 m0, s2
	s_nop 0
	global_load_lds_dwordx4 v156, s[20:21]
	s_mov_b32 m0, s14
	s_nop 0
	global_load_lds_dwordx4 v152, s[20:21]
	s_waitcnt vmcnt(6)
	s_barrier
	s_setprio 1
	v_mfma_f32_16x16x32_bf16 v[20:23], v[204:207], v[106:109], v[20:23]
	v_mfma_f32_16x16x32_bf16 v[48:51], v[224:227], v[106:109], v[48:51]
	v_mfma_f32_16x16x32_bf16 v[92:95], v[204:207], v[176:179], v[94:97]
	v_mfma_f32_16x16x32_bf16 v[96:99], v[224:227], v[176:179], v[98:101]
	v_mfma_f32_16x16x32_bf16 v[106:109], v[204:207], v[184:187], v[110:113]
	v_mfma_f32_16x16x32_bf16 v[110:113], v[224:227], v[184:187], v[114:117]
	v_mfma_f32_16x16x32_bf16 v[84:87], v[204:207], v[192:195], v[84:87]
	v_mfma_f32_16x16x32_bf16 v[88:91], v[224:227], v[192:195], v[88:91]
	v_mfma_f32_16x16x32_bf16 v[20:23], v[208:211], v[134:137], v[20:23]
	v_mfma_f32_16x16x32_bf16 v[48:51], v[238:241], v[134:137], v[48:51]
	v_mfma_f32_16x16x32_bf16 v[92:95], v[208:211], v[180:183], v[92:95]
	v_mfma_f32_16x16x32_bf16 v[96:99], v[238:241], v[180:183], v[96:99]
	v_mfma_f32_16x16x32_bf16 v[106:109], v[208:211], v[188:191], v[106:109]
	v_mfma_f32_16x16x32_bf16 v[110:113], v[238:241], v[188:191], v[110:113]
	v_mfma_f32_16x16x32_bf16 v[84:87], v[208:211], v[196:199], v[84:87]
	v_mfma_f32_16x16x32_bf16 v[88:91], v[238:241], v[196:199], v[88:91]
	s_setprio 0
	s_barrier
	ds_read_b128 v[114:117], v8
	ds_read_b128 v[118:121], v8 offset:1024
	ds_read_b128 v[122:125], v8 offset:2048
	ds_read_b128 v[126:129], v8 offset:3072
	s_add_u32 s20, s62, 0x18280
	s_addc_u32 s21, s63, 0
	s_mov_b32 m0, vcc_hi
	ds_read_b128 v[130:133], v163
	ds_read_b128 v[134:137], v163 offset:1024
	ds_read_b128 v[172:175], v163 offset:2048
	ds_read_b128 v[176:179], v163 offset:3072
	ds_read_b128 v[180:183], v163 offset:4096
	ds_read_b128 v[184:187], v163 offset:5120
	ds_read_b128 v[188:191], v163 offset:6144
	ds_read_b128 v[192:195], v163 offset:7168
	global_load_lds_dwordx4 v158, s[20:21]
	s_mov_b32 m0, s79
	s_nop 0
	global_load_lds_dwordx4 v154, s[20:21]
	s_waitcnt lgkmcnt(8)
	s_barrier
	s_waitcnt lgkmcnt(0)
	s_setprio 1
	v_mfma_f32_16x16x32_bf16 v[52:55], v[114:117], v[130:133], v[52:55]
	v_mfma_f32_16x16x32_bf16 v[56:59], v[122:125], v[130:133], v[56:59]
	v_mfma_f32_16x16x32_bf16 v[60:63], v[114:117], v[172:175], v[60:63]
	v_mfma_f32_16x16x32_bf16 v[64:67], v[122:125], v[172:175], v[64:67]
	v_mfma_f32_16x16x32_bf16 v[68:71], v[114:117], v[180:183], v[68:71]
	v_mfma_f32_16x16x32_bf16 v[72:75], v[122:125], v[180:183], v[72:75]
	v_mfma_f32_16x16x32_bf16 v[76:79], v[114:117], v[188:191], v[76:79]
	v_mfma_f32_16x16x32_bf16 v[80:83], v[122:125], v[188:191], v[80:83]
	v_mfma_f32_16x16x32_bf16 v[52:55], v[118:121], v[134:137], v[52:55]
	v_mfma_f32_16x16x32_bf16 v[56:59], v[126:129], v[134:137], v[56:59]
	v_mfma_f32_16x16x32_bf16 v[60:63], v[118:121], v[176:179], v[60:63]
	v_mfma_f32_16x16x32_bf16 v[64:67], v[126:129], v[176:179], v[64:67]
	v_mfma_f32_16x16x32_bf16 v[68:71], v[118:121], v[184:187], v[68:71]
	v_mfma_f32_16x16x32_bf16 v[72:75], v[126:129], v[184:187], v[72:75]
	v_mfma_f32_16x16x32_bf16 v[76:79], v[118:121], v[192:195], v[76:79]
	v_mfma_f32_16x16x32_bf16 v[80:83], v[126:129], v[192:195], v[80:83]
	s_setprio 0
	s_barrier
; #define PG8_STAGE(bufoff, gbase, voff) do { _Pragma("unroll") for (int _i = 0; _i < 2; ++_i) \
;         __builtin_amdgcn_global_load_lds((const unsigned*)((const char*)(gbase) + (voff)[_i]), (LAS unsigned*)(lds + (bufoff) + ldsw + _i * 8192), 16, 0, 0); } while (0)
; #define PG8_LDA(dst, b, h) do { _Pragma("unroll") for (int m = 0; m < 4; ++m) _Pragma("unroll") for (int k = 0; k < 2; ++k) dst[m][k] = *(const LAS bf16x8*)(lds + PG8_SA(b, h) + aoff + m * 2048 + k * 1024); } while (0)
; #define PG8_LDB(dst, b, h) do { _Pragma("unroll") for (int n = 0; n < 2; ++n) _Pragma("unroll") for (int k = 0; k < 2; ++k) dst[n][k] = *(const LAS bf16x8*)(lds + PG8_SB(b, h) + boff + n * 2048 + k * 1024); } while (0)
; #define PG8_WAIT_V(n) asm volatile("s_waitcnt vmcnt(" #n ")" ::: "memory")
; template <class Epi>
; __device__ __forceinline__ void gemm_phase(LAS unsigned char* lds, const Gemm g, const StaticOrder& S, const Epi& E, int wv) {
;     ...
;             const char* a2 = last ? nA : cA + (size_t)(t + 2) * kstep; const char* b2 = last ? nB : cB + (size_t)(t + 2) * kstep;
;             const char* a3 = a2 + kstep; const char* b3 = b2 + kstep;
;             PG8_LDB(B0, 0, 0); PG8_SCHED; PG8_LDA(At, 0, 0); PG8_STAGE(PG8_SA(1, 1), a1 + hstep, voffA);
;             PG8_WAIT_L(8); PG8_BAR; PG8_WAIT_L(0); PG8_MMA(0, 0, At, B0); PG8_BAR; PG8_SCHED;
;             PG8_LDB(B1, 0, 1); PG8_STAGE(PG8_SB(0, 0), b2, voffB);
;             PG8_BAR; PG8_WAIT_L(0); PG8_MMA(0, 1, At, B1); PG8_BAR;
;             PG8_LDA(At, 0, 1); PG8_STAGE(PG8_SA(0, 0), a2, voffA);
;             PG8_BAR; PG8_WAIT_L(0); PG8_MMA(1, 0, At, B0); PG8_BAR; PG8_SCHED;
;             PG8_STAGE(PG8_SB(0, 1), b2 + hstep, voffB);
;             PG8_WAIT_V(6); PG8_BAR; PG8_MMA(1, 1, At, B1); PG8_BAR;
;             PG8_LDB(B0, 1, 0); PG8_SCHED; PG8_LDA(At, 1, 0); PG8_STAGE(PG8_SA(0, 1), a2 + hstep, voffA);
;             PG8_WAIT_L(8); PG8_BAR; PG8_WAIT_L(0); PG8_MMA(0, 0, At, B0); PG8_BAR; PG8_SCHED;
;             PG8_LDB(B1, 1, 1); PG8_STAGE(PG8_SB(1, 0), b3, voffB);
;             PG8_BAR; PG8_WAIT_L(0); PG8_MMA(0, 1, At, B1); PG8_BAR;
;             PG8_LDA(At, 1, 1); PG8_STAGE(PG8_SA(1, 0), a3, voffA);
;             PG8_BAR; PG8_WAIT_L(0); PG8_MMA(1, 0, At, B0); PG8_BAR; PG8_SCHED;
;             PG8_STAGE(PG8_SB(1, 1), b3 + hstep, voffB);
;             PG8_WAIT_V(6); PG8_BAR; PG8_MMA(1, 1, At, B1); PG8_BAR;
	s_mov_b32 m0, s96
	v_lshl_add_u64 v[150:151], s[10:11], 0, v[156:157]
	ds_read_b128 v[196:199], v9
	ds_read_b128 v[200:203], v9 offset:1024
	ds_read_b128 v[204:207], v9 offset:2048
	ds_read_b128 v[208:211], v9 offset:3072
	global_load_lds_dwordx4 v[150:151], off
	v_lshl_add_u64 v[228:229], s[10:11], 0, v[152:153]
	s_mov_b32 m0, s85
	s_nop 0
	global_load_lds_dwordx4 v[228:229], off
	s_barrier
	s_waitcnt lgkmcnt(0)
	s_setprio 1
	v_mfma_f32_16x16x32_bf16 v[0:3], v[196:199], v[130:133], v[0:3]
	v_mfma_f32_16x16x32_bf16 v[24:27], v[204:207], v[130:133], v[24:27]
	v_mfma_f32_16x16x32_bf16 v[40:43], v[196:199], v[188:191], v[40:43]
	v_mfma_f32_16x16x32_bf16 v[0:3], v[200:203], v[134:137], v[0:3]
	v_mfma_f32_16x16x32_bf16 v[24:27], v[208:211], v[134:137], v[24:27]
	v_mfma_f32_16x16x32_bf16 v[32:35], v[196:199], v[180:183], v[32:35]
	v_mfma_f32_16x16x32_bf16 v[36:39], v[204:207], v[180:183], v[36:39]
	v_mfma_f32_16x16x32_bf16 v[134:137], v[200:203], v[192:195], v[40:43]
	v_mfma_f32_16x16x32_bf16 v[40:43], v[204:207], v[188:191], v[44:47]
	v_mfma_f32_16x16x32_bf16 v[100:103], v[196:199], v[172:175], v[102:105]
	v_mfma_f32_16x16x32_bf16 v[28:31], v[204:207], v[172:175], v[28:31]
	v_mfma_f32_16x16x32_bf16 v[32:35], v[200:203], v[184:187], v[32:35]
	v_mfma_f32_16x16x32_bf16 v[36:39], v[208:211], v[184:187], v[36:39]
	v_mfma_f32_16x16x32_bf16 v[172:175], v[208:211], v[192:195], v[40:43]
	v_mfma_f32_16x16x32_bf16 v[130:133], v[200:203], v[176:179], v[100:103]
	v_mfma_f32_16x16x32_bf16 v[28:31], v[208:211], v[176:179], v[28:31]
	s_setprio 0
	s_mov_b32 m0, s47
	v_lshl_add_u64 v[236:237], s[8:9], 0, v[158:159]
	s_barrier
	ds_read_b128 v[40:43], v163 offset:16384
	ds_read_b128 v[44:47], v163 offset:17408
	ds_read_b128 v[100:103], v163 offset:18432
	ds_read_b128 v[176:179], v163 offset:19456
	ds_read_b128 v[180:183], v163 offset:20480
	ds_read_b128 v[184:187], v163 offset:21504
	ds_read_b128 v[188:191], v163 offset:22528
	ds_read_b128 v[192:195], v163 offset:23552
	global_load_lds_dwordx4 v[236:237], off
	v_lshl_add_u64 v[222:223], s[8:9], 0, v[154:155]
	s_mov_b32 m0, s50
	s_nop 0
	global_load_lds_dwordx4 v[222:223], off
	s_barrier
	s_waitcnt lgkmcnt(0)
	s_setprio 1
	v_mfma_f32_16x16x32_bf16 v[4:7], v[114:117], v[40:43], v[4:7]
	v_mfma_f32_16x16x32_bf16 v[164:167], v[114:117], v[180:183], v[164:167]
	v_mfma_f32_16x16x32_bf16 v[168:171], v[122:125], v[180:183], v[168:171]
	v_mfma_f32_16x16x32_bf16 v[12:15], v[114:117], v[188:191], v[12:15]
	v_mfma_f32_16x16x32_bf16 v[16:19], v[122:125], v[188:191], v[16:19]
	v_mfma_f32_16x16x32_bf16 v[4:7], v[118:121], v[44:47], v[4:7]
	v_mfma_f32_16x16x32_bf16 v[138:141], v[122:125], v[40:43], v[138:141]
	v_mfma_f32_16x16x32_bf16 v[142:145], v[114:117], v[100:103], v[142:145]
	v_mfma_f32_16x16x32_bf16 v[146:149], v[122:125], v[100:103], v[146:149]
	v_mfma_f32_16x16x32_bf16 v[164:167], v[118:121], v[184:187], v[164:167]
	v_mfma_f32_16x16x32_bf16 v[168:171], v[126:129], v[184:187], v[168:171]
	v_mfma_f32_16x16x32_bf16 v[12:15], v[118:121], v[192:195], v[12:15]
	v_mfma_f32_16x16x32_bf16 v[16:19], v[126:129], v[192:195], v[16:19]
	v_mfma_f32_16x16x32_bf16 v[138:141], v[126:129], v[44:47], v[138:141]
	v_mfma_f32_16x16x32_bf16 v[142:145], v[118:121], v[176:179], v[142:145]
	v_mfma_f32_16x16x32_bf16 v[146:149], v[126:129], v[176:179], v[146:149]
	s_setprio 0
	s_barrier
	s_add_u32 s20, s10, 0x18000
	s_addc_u32 s21, s11, 0
	s_mov_b32 m0, s97
	s_nop 0
	global_load_lds_dwordx4 v156, s[20:21]
	s_mov_b32 m0, s86
	s_nop 0
	global_load_lds_dwordx4 v152, s[20:21]
	s_waitcnt vmcnt(6)
	s_barrier
	s_setprio 1
	v_mfma_f32_16x16x32_bf16 v[20:23], v[196:199], v[40:43], v[20:23]
	v_mfma_f32_16x16x32_bf16 v[40:43], v[204:207], v[40:43], v[48:51]
	v_mfma_f32_16x16x32_bf16 v[224:227], v[208:211], v[44:47], v[40:43]
	v_mfma_f32_16x16x32_bf16 v[40:43], v[196:199], v[100:103], v[92:95]
	v_mfma_f32_16x16x32_bf16 v[238:241], v[200:203], v[176:179], v[40:43]
	v_mfma_f32_16x16x32_bf16 v[40:43], v[204:207], v[100:103], v[96:99]
	v_mfma_f32_16x16x32_bf16 v[176:179], v[208:211], v[176:179], v[40:43]
	v_mfma_f32_16x16x32_bf16 v[40:43], v[196:199], v[180:183], v[106:109]
	v_mfma_f32_16x16x32_bf16 v[242:245], v[200:203], v[184:187], v[40:43]
	v_mfma_f32_16x16x32_bf16 v[40:43], v[204:207], v[180:183], v[110:113]
	v_mfma_f32_16x16x32_bf16 v[180:183], v[208:211], v[184:187], v[40:43]
	v_mfma_f32_16x16x32_bf16 v[40:43], v[196:199], v[188:191], v[84:87]
	v_mfma_f32_16x16x32_bf16 v[184:187], v[200:203], v[192:195], v[40:43]
	v_mfma_f32_16x16x32_bf16 v[40:43], v[204:207], v[188:191], v[88:91]
	v_mfma_f32_16x16x32_bf16 v[20:23], v[200:203], v[44:47], v[20:23]
	v_mfma_f32_16x16x32_bf16 v[188:191], v[208:211], v[192:195], v[40:43]
	s_setprio 0
	s_barrier
	ds_read_b128 v[192:195], v10
	ds_read_b128 v[196:199], v10 offset:1024
	ds_read_b128 v[200:203], v10 offset:2048
	ds_read_b128 v[204:207], v10 offset:3072
	s_add_u32 s20, s8, 0x18000
	s_addc_u32 s21, s9, 0
	s_mov_b32 m0, s64
	ds_read_b128 v[40:43], v163 offset:32768
	ds_read_b128 v[44:47], v163 offset:33792
	ds_read_b128 v[48:51], v163 offset:34816
	ds_read_b128 v[84:87], v163 offset:35840
	ds_read_b128 v[88:91], v163 offset:36864
	ds_read_b128 v[92:95], v163 offset:37888
	ds_read_b128 v[208:211], v163 offset:38912
	ds_read_b128 v[246:249], v163 offset:39936
	global_load_lds_dwordx4 v158, s[20:21]
	s_mov_b32 m0, s65
	s_nop 0
	global_load_lds_dwordx4 v154, s[20:21]
	s_waitcnt lgkmcnt(8)
	s_barrier
; __device__ __forceinline__ int opaque_lane() { int l = __builtin_amdgcn_mbcnt_hi(~0u, __builtin_amdgcn_mbcnt_lo(~0u, 0u)); asm volatile("" : "+v"(l)); return l; }
; #define PG8_STAGE(bufoff, gbase, voff) do { _Pragma("unroll") for (int _i = 0; _i < 2; ++_i) \
;         __builtin_amdgcn_global_load_lds((const unsigned*)((const char*)(gbase) + (voff)[_i]), (LAS unsigned*)(lds + (bufoff) + ldsw + _i * 8192), 16, 0, 0); } while (0)
; #define PG8_LDA(dst, b, h) do { _Pragma("unroll") for (int m = 0; m < 4; ++m) _Pragma("unroll") for (int k = 0; k < 2; ++k) dst[m][k] = *(const LAS bf16x8*)(lds + PG8_SA(b, h) + aoff + m * 2048 + k * 1024); } while (0)
; #define PG8_LDB(dst, b, h) do { _Pragma("unroll") for (int n = 0; n < 2; ++n) _Pragma("unroll") for (int k = 0; k < 2; ++k) dst[n][k] = *(const LAS bf16x8*)(lds + PG8_SB(b, h) + boff + n * 2048 + k * 1024); } while (0)
; #define PG8_MMA(ai, bj, At, Bt) do { __builtin_amdgcn_s_setprio(1); _Pragma("unroll") for (int m = 0; m < 4; ++m) _Pragma("unroll") for (int n = 0; n < 2; ++n) _Pragma("unroll") for (int k = 0; k < 2; ++k) \
;         acc[ai][bj][m][n] = __builtin_amdgcn_mfma_f32_16x16x32_bf16(Bt[n][k], At[m][k], acc[ai][bj][m][n], 0, 0, 0); __builtin_amdgcn_s_setprio(0); } while (0)
; #define PG8_BAR __builtin_amdgcn_s_barrier()
; template <class Epi>
; __device__ __forceinline__ void gemm_phase(LAS unsigned char* lds, const Gemm g, const StaticOrder& S, const Epi& E, int wv) {
;     ...
;             PG8_WAIT_V(6); PG8_BAR; PG8_MMA(1, 1, At, B1); PG8_BAR;
;             PG8_LDB(B0, 1, 0); PG8_SCHED; PG8_LDA(At, 1, 0); PG8_STAGE(PG8_SA(0, 1), a2 + hstep, voffA);
;             PG8_WAIT_L(8); PG8_BAR; PG8_WAIT_L(0); PG8_MMA(0, 0, At, B0); PG8_BAR; PG8_SCHED;
;             PG8_LDB(B1, 1, 1); PG8_STAGE(PG8_SB(1, 0), b3, voffB);
;             PG8_BAR; PG8_WAIT_L(0); PG8_MMA(0, 1, At, B1); PG8_BAR;
;             PG8_LDA(At, 1, 1); PG8_STAGE(PG8_SA(1, 0), a3, voffA);
;             PG8_BAR; PG8_WAIT_L(0); PG8_MMA(1, 0, At, B0); PG8_BAR; PG8_SCHED;
;             PG8_STAGE(PG8_SB(1, 1), b3 + hstep, voffB);
;             PG8_WAIT_V(6); PG8_BAR; PG8_MMA(1, 1, At, B1); PG8_BAR;
;     __device__ __forceinline__ void operator()(Acc& acc, const Unit& u, int wv) const {
;         const int wr = wv >> 2, wc = wv & 3, ln_ = opaque_lane(), fr = ln_ & 15, fq = ln_ >> 4;
;         const int row0 = u.pm * BM + wr * 64 + fr;
	s_waitcnt lgkmcnt(0)
	s_setprio 1
	v_mfma_f32_16x16x32_bf16 v[52:55], v[192:195], v[40:43], v[52:55]
	v_mfma_f32_16x16x32_bf16 v[124:127], v[196:199], v[44:47], v[52:55]
	v_mfma_f32_16x16x32_bf16 v[52:55], v[200:203], v[40:43], v[56:59]
	v_mfma_f32_16x16x32_bf16 v[120:123], v[204:207], v[44:47], v[52:55]
	v_mfma_f32_16x16x32_bf16 v[52:55], v[192:195], v[48:51], v[60:63]
	v_mfma_f32_16x16x32_bf16 v[116:119], v[196:199], v[84:87], v[52:55]
	v_mfma_f32_16x16x32_bf16 v[52:55], v[200:203], v[48:51], v[64:67]
	v_mfma_f32_16x16x32_bf16 v[112:115], v[204:207], v[84:87], v[52:55]
	v_mfma_f32_16x16x32_bf16 v[52:55], v[192:195], v[88:91], v[68:71]
	v_mfma_f32_16x16x32_bf16 v[108:111], v[196:199], v[92:95], v[52:55]
	v_mfma_f32_16x16x32_bf16 v[52:55], v[200:203], v[88:91], v[72:75]
	v_mfma_f32_16x16x32_bf16 v[104:107], v[204:207], v[92:95], v[52:55]
	v_mfma_f32_16x16x32_bf16 v[52:55], v[192:195], v[208:211], v[76:79]
	v_mfma_f32_16x16x32_bf16 v[100:103], v[196:199], v[246:249], v[52:55]
	v_mfma_f32_16x16x32_bf16 v[52:55], v[200:203], v[208:211], v[80:83]
	v_mfma_f32_16x16x32_bf16 v[96:99], v[204:207], v[246:249], v[52:55]
	s_setprio 0
	s_barrier
	s_mov_b32 m0, vcc_lo
	s_nop 3
	v_lshl_add_u64 v[52:53], v[150:151], 0, s[80:81]
	ds_read_b128 v[250:253], v11
	ds_read_b128 v[214:217], v11 offset:1024
	ds_read_b128 v[218:221], v11 offset:2048
	ds_read_b128 v[8:11], v11 offset:3072
	global_load_lds_dwordx4 v[52:53], off
	v_lshl_add_u64 v[52:53], v[228:229], 0, s[80:81]
	s_mov_b32 m0, s3
	s_nop 0
	global_load_lds_dwordx4 v[52:53], off
	s_barrier
	s_waitcnt lgkmcnt(0)
	s_setprio 1
	v_mfma_f32_16x16x32_bf16 v[0:3], v[250:253], v[40:43], v[0:3]
	v_mfma_f32_16x16x32_bf16 v[60:63], v[214:217], v[44:47], v[0:3]
	v_mfma_f32_16x16x32_bf16 v[0:3], v[218:221], v[40:43], v[24:27]
	v_mfma_f32_16x16x32_bf16 v[56:59], v[8:11], v[44:47], v[0:3]
	v_mfma_f32_16x16x32_bf16 v[0:3], v[250:253], v[48:51], v[130:133]
	v_mfma_f32_16x16x32_bf16 v[52:55], v[214:217], v[84:87], v[0:3]
	v_mfma_f32_16x16x32_bf16 v[0:3], v[218:221], v[48:51], v[28:31]
	v_mfma_f32_16x16x32_bf16 v[48:51], v[8:11], v[84:87], v[0:3]
	v_mfma_f32_16x16x32_bf16 v[0:3], v[250:253], v[88:91], v[32:35]
	v_mfma_f32_16x16x32_bf16 v[44:47], v[214:217], v[92:95], v[0:3]
	v_mfma_f32_16x16x32_bf16 v[0:3], v[218:221], v[88:91], v[36:39]
	v_mfma_f32_16x16x32_bf16 v[40:43], v[8:11], v[92:95], v[0:3]
	v_mfma_f32_16x16x32_bf16 v[0:3], v[250:253], v[208:211], v[134:137]
	v_mfma_f32_16x16x32_bf16 v[36:39], v[214:217], v[246:249], v[0:3]
	v_mfma_f32_16x16x32_bf16 v[0:3], v[218:221], v[208:211], v[172:175]
	v_mfma_f32_16x16x32_bf16 v[32:35], v[8:11], v[246:249], v[0:3]
	s_setprio 0
	s_mov_b32 m0, s70
	v_lshl_add_u64 v[64:65], v[236:237], 0, s[80:81]
	s_barrier
	s_nop 2
	ds_read_b128 v[0:3], v163 offset:49152
	ds_read_b128 v[24:27], v163 offset:50176
	ds_read_b128 v[128:131], v163 offset:51200
	ds_read_b128 v[132:135], v163 offset:52224
	ds_read_b128 v[172:175], v163 offset:53248
	ds_read_b128 v[208:211], v163 offset:54272
	ds_read_b128 v[246:249], v163 offset:55296
	ds_read_b128 v[28:31], v163 offset:56320
	global_load_lds_dwordx4 v[64:65], off
	v_lshl_add_u64 v[64:65], v[222:223], 0, s[80:81]
	s_mov_b32 m0, s71
	s_nop 0
	global_load_lds_dwordx4 v[64:65], off
	s_barrier
	s_waitcnt lgkmcnt(0)
	s_setprio 1
	v_mfma_f32_16x16x32_bf16 v[4:7], v[192:195], v[0:3], v[4:7]
	v_mfma_f32_16x16x32_bf16 v[92:95], v[196:199], v[24:27], v[4:7]
	v_mfma_f32_16x16x32_bf16 v[4:7], v[200:203], v[0:3], v[138:141]
	v_mfma_f32_16x16x32_bf16 v[88:91], v[204:207], v[24:27], v[4:7]
	v_mfma_f32_16x16x32_bf16 v[4:7], v[192:195], v[128:131], v[142:145]
	v_mfma_f32_16x16x32_bf16 v[84:87], v[196:199], v[132:135], v[4:7]
	v_mfma_f32_16x16x32_bf16 v[4:7], v[200:203], v[128:131], v[146:149]
	v_mfma_f32_16x16x32_bf16 v[80:83], v[204:207], v[132:135], v[4:7]
	v_mfma_f32_16x16x32_bf16 v[4:7], v[192:195], v[172:175], v[164:167]
	v_mfma_f32_16x16x32_bf16 v[76:79], v[196:199], v[208:211], v[4:7]
	v_mfma_f32_16x16x32_bf16 v[4:7], v[200:203], v[172:175], v[168:171]
	v_mfma_f32_16x16x32_bf16 v[72:75], v[204:207], v[208:211], v[4:7]
	v_mfma_f32_16x16x32_bf16 v[4:7], v[192:195], v[246:249], v[12:15]
	v_mfma_f32_16x16x32_bf16 v[68:71], v[196:199], v[28:31], v[4:7]
	v_mfma_f32_16x16x32_bf16 v[4:7], v[200:203], v[246:249], v[16:19]
	v_mfma_f32_16x16x32_bf16 v[64:67], v[204:207], v[28:31], v[4:7]
	s_setprio 0
	s_barrier
	s_mov_b32 m0, s2
	s_add_u32 s2, s10, 0x18080
	s_addc_u32 s3, s11, 0
	s_nop 1
	global_load_lds_dwordx4 v156, s[2:3]
	s_mov_b32 m0, s14
	s_nop 0
	global_load_lds_dwordx4 v152, s[2:3]
	s_waitcnt vmcnt(6)
	s_barrier
	s_setprio 1
	v_mfma_f32_16x16x32_bf16 v[4:7], v[250:253], v[0:3], v[20:23]
	v_mfma_f32_16x16x32_bf16 v[0:3], v[218:221], v[0:3], v[224:227]
	v_mfma_f32_16x16x32_bf16 v[196:199], v[214:217], v[24:27], v[4:7]
	v_mfma_f32_16x16x32_bf16 v[24:27], v[8:11], v[24:27], v[0:3]
	v_mfma_f32_16x16x32_bf16 v[0:3], v[250:253], v[128:131], v[238:241]
	v_mfma_f32_16x16x32_bf16 v[20:23], v[214:217], v[132:135], v[0:3]
	v_mfma_f32_16x16x32_bf16 v[0:3], v[218:221], v[128:131], v[176:179]
	v_mfma_f32_16x16x32_bf16 v[16:19], v[8:11], v[132:135], v[0:3]
	v_mfma_f32_16x16x32_bf16 v[0:3], v[250:253], v[172:175], v[242:245]
	v_mfma_f32_16x16x32_bf16 v[12:15], v[214:217], v[208:211], v[0:3]
	v_mfma_f32_16x16x32_bf16 v[0:3], v[218:221], v[172:175], v[180:183]
	v_mfma_f32_16x16x32_bf16 v[192:195], v[8:11], v[208:211], v[0:3]
	v_mfma_f32_16x16x32_bf16 v[0:3], v[250:253], v[246:249], v[184:187]
	v_mfma_f32_16x16x32_bf16 v[4:7], v[214:217], v[28:31], v[0:3]
	v_mfma_f32_16x16x32_bf16 v[0:3], v[218:221], v[246:249], v[188:191]
	v_mfma_f32_16x16x32_bf16 v[0:3], v[8:11], v[28:31], v[0:3]
	s_setprio 0
	s_lshl_b32 s2, s78, 8
	v_readlane_b32 s3, v254, 13
	v_mov_b32_e32 v10, v233
	s_add_i32 s2, s2, s3
	s_barrier
; __device__ __forceinline__ int opaque_lane() { int l = __builtin_amdgcn_mbcnt_hi(~0u, __builtin_amdgcn_mbcnt_lo(~0u, 0u)); asm volatile("" : "+v"(l)); return l; }
;     __device__ __forceinline__ void operator()(Acc& acc, const Unit& u, int wv) const {
;         const int wr = wv >> 2, wc = wv & 3, ln_ = opaque_lane(), fr = ln_ & 15, fq = ln_ >> 4;
;         const int row0 = u.pm * BM + wr * 64 + fr;
;         float sc[8];
; #pragma unroll
;         for (int i = 0; i < 8; ++i) sc[i] = RQ[(size_t)tok0 + row0 + (i >> 2) * HALF + (i & 3) * 16];
; #pragma unroll
;         for (int i = 0; i < 8; ++i) sc[i] = rsqrtf(sc[i] * (1.f / 384.f) + EPS);
; #pragma unroll
;         for (int bj = 0; bj < 2; ++bj) {
;             const int c = u.pn * 256 + bj * 128 + wc * 32 + 8 * fq, o = c % 192; const bool rope = o >= 128; const int i0 = (o - 128) >> 1;
;             if (!rope) {
	s_nop 0
	v_and_or_b32 v174, v10, 15, s2
	v_ashrrev_i32_e32 v175, 31, v174
	v_lshl_add_u64 v[8:9], v[174:175], 2, s[56:57]
	global_load_dword v11, v[8:9], off
	global_load_dword v28, v[8:9], off offset:64
	global_load_dword v29, v[8:9], off offset:128
	global_load_dword v30, v[8:9], off offset:192
	global_load_dword v31, v[8:9], off offset:512
	global_load_dword v128, v[8:9], off offset:576
	global_load_dword v129, v[8:9], off offset:640
	s_nop 0
	global_load_dword v8, v[8:9], off offset:704
	s_lshl_b32 s2, s77, 8
	s_or_b32 s2, s2, s53
	v_or_b32_e32 v188, 16, v174
	v_or_b32_e32 v177, 32, v174
	v_or_b32_e32 v173, 48, v174
	v_add_u32_e32 v171, 0x80, v174
	v_add_u32_e32 v167, 0x90, v174
	v_add_u32_e32 v165, 0xa0, v174
	v_add_u32_e32 v169, 0xb0, v174
	s_waitcnt vmcnt(0)
	v_fmamk_f32 v9, v11, 0x3b2aaaab, v230
	v_cmp_gt_f32_e32 vcc, s89, v9
	v_mul_f32_e32 v11, 0x4b800000, v9
	v_fmamk_f32 v8, v8, 0x3b2aaaab, v230
	v_cndmask_b32_e32 v9, v9, v11, vcc
	v_rsq_f32_e32 v9, v9
	s_nop 0
	v_mul_f32_e32 v11, 0x45800000, v9
	v_cndmask_b32_e32 v176, v9, v11, vcc
	v_fmamk_f32 v9, v28, 0x3b2aaaab, v230
	v_cmp_gt_f32_e32 vcc, s89, v9
	v_mul_f32_e32 v11, 0x4b800000, v9
	s_nop 0
	v_cndmask_b32_e32 v9, v9, v11, vcc
	v_rsq_f32_e32 v9, v9
	s_nop 0
	v_mul_f32_e32 v11, 0x45800000, v9
	v_cndmask_b32_e32 v172, v9, v11, vcc
	v_fmamk_f32 v9, v29, 0x3b2aaaab, v230
	v_cmp_gt_f32_e32 vcc, s89, v9
	v_mul_f32_e32 v11, 0x4b800000, v9
	s_nop 0
	v_cndmask_b32_e32 v9, v9, v11, vcc
	v_rsq_f32_e32 v9, v9
	s_nop 0
	v_mul_f32_e32 v11, 0x45800000, v9
	v_cndmask_b32_e32 v170, v9, v11, vcc
	v_fmamk_f32 v9, v30, 0x3b2aaaab, v230
	v_cmp_gt_f32_e32 vcc, s89, v9
	v_mul_f32_e32 v11, 0x4b800000, v9
	s_nop 0
	v_cndmask_b32_e32 v9, v9, v11, vcc
	v_rsq_f32_e32 v9, v9
	s_nop 0
	v_mul_f32_e32 v11, 0x45800000, v9
	v_cndmask_b32_e32 v168, v9, v11, vcc
	v_fmamk_f32 v9, v31, 0x3b2aaaab, v230
	v_cmp_gt_f32_e32 vcc, s89, v9
	v_mul_f32_e32 v11, 0x4b800000, v9
	s_nop 0
	v_cndmask_b32_e32 v9, v9, v11, vcc
	v_rsq_f32_e32 v9, v9
	s_nop 0
	v_mul_f32_e32 v11, 0x45800000, v9
	v_cndmask_b32_e32 v166, v9, v11, vcc
	v_fmamk_f32 v9, v128, 0x3b2aaaab, v230
	v_cmp_gt_f32_e32 vcc, s89, v9
	v_mul_f32_e32 v11, 0x4b800000, v9
	s_nop 0
	v_cndmask_b32_e32 v9, v9, v11, vcc
	v_rsq_f32_e32 v9, v9
	s_nop 0
	v_mul_f32_e32 v11, 0x45800000, v9
	v_cndmask_b32_e32 v164, v9, v11, vcc
	v_fmamk_f32 v9, v129, 0x3b2aaaab, v230
	v_cmp_gt_f32_e32 vcc, s89, v9
	v_mul_f32_e32 v11, 0x4b800000, v9
	s_nop 0
	v_cndmask_b32_e32 v9, v9, v11, vcc
	v_rsq_f32_e32 v9, v9
	s_nop 0
	v_mul_f32_e32 v11, 0x45800000, v9
	v_cndmask_b32_e32 v162, v9, v11, vcc
	v_cmp_gt_f32_e32 vcc, s89, v8
	v_mul_f32_e32 v9, 0x4b800000, v8
	s_nop 0
	v_cndmask_b32_e32 v8, v8, v9, vcc
	v_rsq_f32_e32 v8, v8
	s_nop 0
	v_mul_f32_e32 v9, 0x45800000, v8
	v_cndmask_b32_e32 v160, v8, v9, vcc
	v_ashrrev_i32_e32 v8, 1, v10
	v_and_b32_e32 v8, -8, v8
	v_add_u32_e32 v178, s2, v8
	s_mov_b32 s2, 0x2aaaaaab
	v_mul_hi_i32 v8, v178, s2
	v_lshrrev_b32_e32 v9, 31, v8
	v_lshrrev_b32_e32 v8, 5, v8
	v_add_u32_e32 v8, v8, v9
	s_movk_i32 s2, 0xc0
	v_mul_lo_u32 v8, v8, s2
	v_sub_u32_e32 v128, v178, v8
	s_movk_i32 s2, 0x80
	v_cmp_gt_i32_e32 vcc, s2, v128
	v_ashrrev_i32_e32 v179, 31, v178
	s_and_saveexec_b64 s[2:3], vcc
	s_xor_b64 s[62:63], exec, s[2:3]
	s_movk_i32 s85, 0x1800
	s_cbranch_execz .LBB0_187
;     __device__ __forceinline__ void operator()(Acc& acc, const Unit& u, int wv) const {
;     ...
;             const int c = u.pn * 256 + bj * 128 + wc * 32 + 8 * fq, o = c % 192; const bool rope = o >= 128; const int i0 = (o - 128) >> 1;
;             if (!rope) {
; #pragma unroll
;                 for (int i = 0; i < 8; ++i) { const int row = row0 + (i >> 2) * HALF + (i & 3) * 16; store8_bf16(Q + (size_t)row * 3072 + c, acc[i >> 2][bj][i & 3][0], acc[i >> 2][bj][i & 3][1], sc[i]); }
	v_mov_b64_e32 v[28:29], s[12:13]
	v_mad_i64_i32 v[8:9], s[2:3], v174, s85, v[28:29]
	v_lshlrev_b64 v[30:31], 1, v[178:179]
	v_lshl_add_u64 v[128:129], v[8:9], 0, v[30:31]
	v_mul_f32_e32 v8, v124, v176
	v_mul_f32_e32 v9, v125, v176
	v_cvt_pk_bf16_f32 v8, v8, v9
	v_mul_f32_e32 v9, v126, v176
	v_mul_f32_e32 v10, v127, v176
	v_cvt_pk_bf16_f32 v9, v9, v10
	v_mul_f32_e32 v10, v120, v176
	v_mul_f32_e32 v11, v121, v176
	v_cvt_pk_bf16_f32 v10, v10, v11
	v_mul_f32_e32 v11, v122, v176
	v_mul_f32_e32 v120, v123, v176
	v_cvt_pk_bf16_f32 v11, v11, v120
	global_store_dwordx4 v[128:129], v[8:11], off
	s_nop 1
	v_mad_i64_i32 v[8:9], s[2:3], v188, s85, v[28:29]
	v_lshl_add_u64 v[120:121], v[8:9], 0, v[30:31]
	v_mul_f32_e32 v8, v116, v172
	v_mul_f32_e32 v9, v117, v172
	v_cvt_pk_bf16_f32 v8, v8, v9
	v_mul_f32_e32 v9, v118, v172
	v_mul_f32_e32 v10, v119, v172
	v_cvt_pk_bf16_f32 v9, v9, v10
	v_mul_f32_e32 v10, v112, v172
	v_mul_f32_e32 v11, v113, v172
	v_cvt_pk_bf16_f32 v10, v10, v11
	v_mul_f32_e32 v11, v114, v172
	v_mul_f32_e32 v112, v115, v172
	v_cvt_pk_bf16_f32 v11, v11, v112
	global_store_dwordx4 v[120:121], v[8:11], off
	s_nop 1
	v_mad_i64_i32 v[8:9], s[2:3], v177, s85, v[28:29]
	v_lshl_add_u64 v[112:113], v[8:9], 0, v[30:31]
	v_mul_f32_e32 v8, v108, v170
	v_mul_f32_e32 v9, v109, v170
	v_cvt_pk_bf16_f32 v8, v8, v9
	v_mul_f32_e32 v9, v110, v170
	v_mul_f32_e32 v10, v111, v170
	v_cvt_pk_bf16_f32 v9, v9, v10
	v_mul_f32_e32 v10, v104, v170
	v_mul_f32_e32 v11, v105, v170
	v_cvt_pk_bf16_f32 v10, v10, v11
	v_mul_f32_e32 v11, v106, v170
	v_mul_f32_e32 v104, v107, v170
	v_cvt_pk_bf16_f32 v11, v11, v104
	global_store_dwordx4 v[112:113], v[8:11], off
	s_nop 1
	v_mad_i64_i32 v[8:9], s[2:3], v173, s85, v[28:29]
	v_lshl_add_u64 v[104:105], v[8:9], 0, v[30:31]
	v_mul_f32_e32 v8, v100, v168
	v_mul_f32_e32 v9, v101, v168
	v_cvt_pk_bf16_f32 v8, v8, v9
	v_mul_f32_e32 v9, v102, v168
	v_mul_f32_e32 v10, v103, v168
	v_cvt_pk_bf16_f32 v9, v9, v10
	v_mul_f32_e32 v10, v96, v168
	v_mul_f32_e32 v11, v97, v168
	v_cvt_pk_bf16_f32 v10, v10, v11
	v_mul_f32_e32 v11, v98, v168
	v_mul_f32_e32 v96, v99, v168
	v_cvt_pk_bf16_f32 v11, v11, v96
	global_store_dwordx4 v[104:105], v[8:11], off
	s_nop 1
	v_mad_i64_i32 v[8:9], s[2:3], v171, s85, v[28:29]
	v_lshl_add_u64 v[96:97], v[8:9], 0, v[30:31]
	v_mul_f32_e32 v8, v92, v166
	v_mul_f32_e32 v9, v93, v166
	v_cvt_pk_bf16_f32 v8, v8, v9
	v_mul_f32_e32 v9, v94, v166
	v_mul_f32_e32 v10, v95, v166
	v_cvt_pk_bf16_f32 v9, v9, v10
	v_mul_f32_e32 v10, v88, v166
	v_mul_f32_e32 v11, v89, v166
	v_cvt_pk_bf16_f32 v10, v10, v11
	v_mul_f32_e32 v11, v90, v166
	v_mul_f32_e32 v88, v91, v166
	v_cvt_pk_bf16_f32 v11, v11, v88
	global_store_dwordx4 v[96:97], v[8:11], off
	s_nop 1
	v_mad_i64_i32 v[8:9], s[2:3], v167, s85, v[28:29]
	v_lshl_add_u64 v[88:89], v[8:9], 0, v[30:31]
	v_mul_f32_e32 v8, v84, v164
	v_mul_f32_e32 v9, v85, v164
	v_cvt_pk_bf16_f32 v8, v8, v9
	v_mul_f32_e32 v9, v86, v164
	v_mul_f32_e32 v10, v87, v164
	v_cvt_pk_bf16_f32 v9, v9, v10
	v_mul_f32_e32 v10, v80, v164
	v_mul_f32_e32 v11, v81, v164
	v_cvt_pk_bf16_f32 v10, v10, v11
	v_mul_f32_e32 v11, v82, v164
	v_mul_f32_e32 v80, v83, v164
	v_cvt_pk_bf16_f32 v11, v11, v80
	global_store_dwordx4 v[88:89], v[8:11], off
	s_nop 1
	v_mad_i64_i32 v[8:9], s[2:3], v165, s85, v[28:29]
	v_lshl_add_u64 v[80:81], v[8:9], 0, v[30:31]
	v_mul_f32_e32 v8, v76, v162
	v_mul_f32_e32 v9, v77, v162
	v_cvt_pk_bf16_f32 v8, v8, v9
	v_mul_f32_e32 v9, v78, v162
	v_mul_f32_e32 v10, v79, v162
	v_cvt_pk_bf16_f32 v9, v9, v10
	v_mul_f32_e32 v10, v72, v162
	v_mul_f32_e32 v11, v73, v162
	v_cvt_pk_bf16_f32 v10, v10, v11
	v_mul_f32_e32 v11, v74, v162
	v_mul_f32_e32 v72, v75, v162
	v_cvt_pk_bf16_f32 v11, v11, v72
	global_store_dwordx4 v[80:81], v[8:11], off
	s_nop 1
	v_mad_i64_i32 v[8:9], s[2:3], v169, s85, v[28:29]
	v_lshl_add_u64 v[28:29], v[8:9], 0, v[30:31]
	v_mul_f32_e32 v8, v68, v160
	v_mul_f32_e32 v9, v69, v160
	v_cvt_pk_bf16_f32 v8, v8, v9
	v_mul_f32_e32 v9, v70, v160
	v_mul_f32_e32 v10, v71, v160
	v_cvt_pk_bf16_f32 v9, v9, v10
	v_mul_f32_e32 v10, v64, v160
	v_mul_f32_e32 v11, v65, v160
	v_cvt_pk_bf16_f32 v10, v10, v11
	v_mul_f32_e32 v11, v66, v160
	v_mul_f32_e32 v30, v67, v160
	v_cvt_pk_bf16_f32 v11, v11, v30
	global_store_dwordx4 v[28:29], v[8:11], off

; #define PG8_STAGE(bufoff, gbase, voff) do { _Pragma("unroll") for (int _i = 0; _i < 2; ++_i) \
;         __builtin_amdgcn_global_load_lds((const unsigned*)((const char*)(gbase) + (voff)[_i]), (LAS unsigned*)(lds + (bufoff) + ldsw + _i * 8192), 16, 0, 0); } while (0)
; #define PG8_WAIT_V(n) asm volatile("s_waitcnt vmcnt(" #n ")" ::: "memory")
; #define PG8_BAR __builtin_amdgcn_s_barrier()
; template <class Epi>
; __device__ __forceinline__ void gemm_phase(LAS unsigned char* lds, const Gemm g, const StaticOrder& S, const Epi& E, int wv) {
;     ...
;     PG8_STAGE(PG8_SB(0, 0), cB, voffB); PG8_STAGE(PG8_SA(0, 0), cA, voffA); PG8_STAGE(PG8_SB(0, 1), cB + hstep, voffB); PG8_STAGE(PG8_SA(0, 1), cA + hstep, voffA);
;     if (wr == 1) PG8_BAR;
;     PG8_WAIT_V(4); PG8_BAR;
;     PG8_STAGE(PG8_SB(1, 0), cB + kstep, voffB); PG8_STAGE(PG8_SA(1, 0), cA + kstep, voffA); PG8_STAGE(PG8_SB(1, 1), cB + hstep + kstep, voffB);
;     PG8_WAIT_V(6); PG8_BAR;
.LBB0_199:
	s_add_u32 s70, s44, 0x28000000
	s_addc_u32 s71, s45, 0
	s_add_u32 s72, s44, 0x30000000
	s_addc_u32 s73, s45, 0
	s_lshl_b64 s[2:3], s[24:25], 2
	s_add_u32 s2, s8, s2
	s_addc_u32 s3, s9, s3
	v_and_b32_e32 v9, 15, v8
	v_and_b32_e32 v10, 48, v8
	v_lshlrev_b32_e32 v8, 2, v8
	s_add_u32 s8, s2, 0x40000
	v_lshl_or_b32 v9, v9, 6, v10
	v_and_b32_e32 v8, 32, v8
	v_readlane_b32 s2, v254, 7
	s_addc_u32 s9, s3, 0
	v_lshl_add_u64 v[6:7], v[6:7], 0, s[80:81]
	v_bitop3_b32 v10, v9, s2, v8 bitop3:0xde
	v_readlane_b32 s2, v254, 8
	s_add_i32 m0, s47, 0x18000
	s_waitcnt vmcnt(4)
	s_barrier
	v_bitop3_b32 v140, v9, s2, v8 bitop3:0xde
	global_load_lds_dwordx4 v[6:7], off
	v_lshl_add_u64 v[2:3], v[2:3], 0, s[80:81]
	s_add_i32 m0, s47, 0x1a000
	s_add_i32 s2, s47, 0x8000
	s_add_i32 s3, s47, 0xa000
	global_load_lds_dwordx4 v[2:3], off
	v_lshl_add_u64 v[0:1], v[0:1], 0, s[80:81]
	s_mov_b32 m0, s2
	s_add_u32 s6, s60, 0x10080
	global_load_lds_dwordx4 v[0:1], off
	v_lshl_add_u64 v[0:1], v[4:5], 0, s[80:81]
	s_mov_b32 m0, s3
	s_addc_u32 s7, s61, 0
	global_load_lds_dwordx4 v[0:1], off
	s_add_i32 m0, s47, 0x1c000
	v_readlane_b32 s10, v254, 37
	global_load_lds_dwordx4 v212, s[6:7]
	v_lshl_add_u64 v[0:1], s[6:7], 0, v[128:129]
	s_add_i32 m0, s47, 0x1e000
	v_readlane_b32 s6, v254, 57
	global_load_lds_dwordx4 v[0:1], off
	s_waitcnt vmcnt(6)
	v_readlane_b32 s11, v254, 38
	s_add_i32 s76, s10, s79
	v_add_u32_e32 v141, 0, v10
	v_readlane_b32 s78, v254, 42
	s_mov_b32 s77, s6
	s_barrier
	v_readlane_b32 s7, v254, 58
	s_branch .LBB0_202

; #define PG8_STAGE(bufoff, gbase, voff) do { _Pragma("unroll") for (int _i = 0; _i < 2; ++_i) \
;         __builtin_amdgcn_global_load_lds((const unsigned*)((const char*)(gbase) + (voff)[_i]), (LAS unsigned*)(lds + (bufoff) + ldsw + _i * 8192), 16, 0, 0); } while (0)
; #define PG8_LDA(dst, b, h) do { _Pragma("unroll") for (int m = 0; m < 4; ++m) _Pragma("unroll") for (int k = 0; k < 2; ++k) dst[m][k] = *(const LAS bf16x8*)(lds + PG8_SA(b, h) + aoff + m * 2048 + k * 1024); } while (0)
; #define PG8_LDB(dst, b, h) do { _Pragma("unroll") for (int n = 0; n < 2; ++n) _Pragma("unroll") for (int k = 0; k < 2; ++k) dst[n][k] = *(const LAS bf16x8*)(lds + PG8_SB(b, h) + boff + n * 2048 + k * 1024); } while (0)
; #define PG8_MMA(ai, bj, At, Bt) do { __builtin_amdgcn_s_setprio(1); _Pragma("unroll") for (int m = 0; m < 4; ++m) _Pragma("unroll") for (int n = 0; n < 2; ++n) _Pragma("unroll") for (int k = 0; k < 2; ++k) \
;         acc[ai][bj][m][n] = __builtin_amdgcn_mfma_f32_16x16x32_bf16(Bt[n][k], At[m][k], acc[ai][bj][m][n], 0, 0, 0); __builtin_amdgcn_s_setprio(0); } while (0)
; #define PG8_WAIT_L(n) asm volatile("s_waitcnt lgkmcnt(" #n ")" ::: "memory")
; template <class Epi>
; __device__ __forceinline__ void gemm_phase(LAS unsigned char* lds, const Gemm g, const StaticOrder& S, const Epi& E, int wv) {
;     ...
;         const bool has_next = S.next(ui + 1, nxt);
;         const char* nA = has_next ? (const char*)g.A + (size_t)nxt.pm * tstep : cA; const char* nB = has_next ? (const char*)g.Bt + (size_t)nxt.pn * tstep : cB;
;         for (int t = 0; t < nt; t += 2) {
;             const bool last = (t == nt - 2);
;             const char* a1 = cA + (size_t)(t + 1) * kstep;
;             const char* a2 = last ? nA : cA + (size_t)(t + 2) * kstep; const char* b2 = last ? nB : cB + (size_t)(t + 2) * kstep;
;             const char* a3 = a2 + kstep; const char* b3 = b2 + kstep;
;             PG8_LDB(B0, 0, 0); PG8_SCHED; PG8_LDA(At, 0, 0); PG8_STAGE(PG8_SA(1, 1), a1 + hstep, voffA);
;             PG8_WAIT_L(8); PG8_BAR; PG8_WAIT_L(0); PG8_MMA(0, 0, At, B0); PG8_BAR; PG8_SCHED;
;             PG8_LDB(B1, 0, 1); PG8_STAGE(PG8_SB(0, 0), b2, voffB);
;             PG8_BAR; PG8_WAIT_L(0); PG8_MMA(0, 1, At, B1); PG8_BAR;
;             PG8_LDA(At, 0, 1); PG8_STAGE(PG8_SA(0, 0), a2, voffA);
;             PG8_BAR; PG8_WAIT_L(0); PG8_MMA(1, 0, At, B0); PG8_BAR; PG8_SCHED;
.LBB0_201:
	s_ashr_i32 s23, s22, 31
	s_lshl_b64 s[20:21], s[22:23], 17
	v_mov_b64_e32 v[0:1], 0x800
	s_add_u32 s42, s14, s20
	v_cmp_lt_i64_e32 vcc, s[10:11], v[0:1]
	s_addc_u32 s43, s15, s21
	s_and_b64 s[20:21], vcc, exec
	s_cselect_b32 s65, s43, s59
	s_cselect_b32 s64, s42, s58
	s_ashr_i32 s13, s12, 31
	s_lshl_b64 s[20:21], s[12:13], 17
	s_add_u32 s56, s35, s20
	s_addc_u32 s57, s46, s21
	s_and_b64 s[20:21], vcc, exec
	s_cselect_b32 s63, s57, s61
	s_cselect_b32 s62, s56, s60
	s_add_i32 s79, 0, 0x10000
	v_add_u32_e32 v208, s79, v140
	ds_read_b128 v[0:3], v208
	ds_read_b128 v[4:7], v208 offset:1024
	ds_read_b128 v[8:11], v208 offset:2048
	ds_read_b128 v[12:15], v208 offset:3072
	s_add_u32 s20, s58, 0x10080
	s_addc_u32 s21, s59, 0
	s_add_i32 s85, s47, 0xc000
	s_mov_b32 m0, s85
	s_add_i32 s13, s47, 0xe000
	ds_read_b128 v[16:19], v141
	ds_read_b128 v[20:23], v141 offset:1024
	ds_read_b128 v[24:27], v141 offset:2048
	ds_read_b128 v[28:31], v141 offset:3072
	ds_read_b128 v[32:35], v141 offset:4096
	ds_read_b128 v[36:39], v141 offset:5120
	ds_read_b128 v[40:43], v141 offset:6144
	ds_read_b128 v[44:47], v141 offset:7168
	global_load_lds_dwordx4 v132, s[20:21]
	s_mov_b32 m0, s13
	s_nop 0
	global_load_lds_dwordx4 v130, s[20:21]
	s_waitcnt lgkmcnt(8)
	s_barrier
	s_waitcnt lgkmcnt(0)
	s_setprio 1
	v_mfma_f32_16x16x32_bf16 v[48:51], v[0:3], v[16:19], 0
	v_mfma_f32_16x16x32_bf16 v[52:55], v[8:11], v[16:19], 0
	v_mfma_f32_16x16x32_bf16 v[56:59], v[0:3], v[24:27], 0
	v_mfma_f32_16x16x32_bf16 v[60:63], v[8:11], v[24:27], 0
	v_mfma_f32_16x16x32_bf16 v[64:67], v[0:3], v[32:35], 0
	v_mfma_f32_16x16x32_bf16 v[68:71], v[8:11], v[32:35], 0
	v_mfma_f32_16x16x32_bf16 v[72:75], v[0:3], v[40:43], 0
	v_mfma_f32_16x16x32_bf16 v[76:79], v[8:11], v[40:43], 0
	v_mfma_f32_16x16x32_bf16 v[48:51], v[4:7], v[20:23], v[48:51]
	v_mfma_f32_16x16x32_bf16 v[52:55], v[12:15], v[20:23], v[52:55]
	v_mfma_f32_16x16x32_bf16 v[56:59], v[4:7], v[28:31], v[56:59]
	v_mfma_f32_16x16x32_bf16 v[60:63], v[12:15], v[28:31], v[60:63]
	v_mfma_f32_16x16x32_bf16 v[64:67], v[4:7], v[36:39], v[64:67]
	v_mfma_f32_16x16x32_bf16 v[68:71], v[12:15], v[36:39], v[68:71]
	v_mfma_f32_16x16x32_bf16 v[72:75], v[4:7], v[44:47], v[72:75]
	v_mfma_f32_16x16x32_bf16 v[76:79], v[12:15], v[44:47], v[76:79]
	s_setprio 0
	s_barrier
	s_add_i32 s86, 0, 0x14000
	v_lshl_add_u64 v[138:139], s[60:61], 0, v[212:213]
	s_mov_b64 s[20:21], 0x100
	s_add_i32 s79, s79, s37
	v_add_u32_e32 v209, s86, v140
	v_lshl_add_u64 v[96:97], v[138:139], 0, s[20:21]
	s_mov_b32 m0, s79
	v_lshl_add_u64 v[202:203], s[60:61], 0, v[128:129]
	s_add_i32 s23, s79, 0x2000
	ds_read_b128 v[80:83], v209
	ds_read_b128 v[84:87], v209 offset:1024
	ds_read_b128 v[88:91], v209 offset:2048
	ds_read_b128 v[92:95], v209 offset:3072
	global_load_lds_dwordx4 v[96:97], off
	v_lshl_add_u64 v[96:97], v[202:203], 0, s[20:21]
	s_mov_b32 m0, s23
	s_nop 0
	global_load_lds_dwordx4 v[96:97], off
	s_barrier
	s_waitcnt lgkmcnt(0)
	s_setprio 1
	v_mfma_f32_16x16x32_bf16 v[96:99], v[80:83], v[16:19], 0
	v_mfma_f32_16x16x32_bf16 v[16:19], v[88:91], v[16:19], 0
	v_mfma_f32_16x16x32_bf16 v[96:99], v[84:87], v[20:23], v[96:99]
	v_mfma_f32_16x16x32_bf16 v[16:19], v[92:95], v[20:23], v[16:19]
	v_mfma_f32_16x16x32_bf16 v[20:23], v[80:83], v[24:27], 0
	v_mfma_f32_16x16x32_bf16 v[24:27], v[88:91], v[24:27], 0
	v_mfma_f32_16x16x32_bf16 v[20:23], v[84:87], v[28:31], v[20:23]
	v_mfma_f32_16x16x32_bf16 v[24:27], v[92:95], v[28:31], v[24:27]
	v_mfma_f32_16x16x32_bf16 v[28:31], v[80:83], v[32:35], 0
	v_mfma_f32_16x16x32_bf16 v[32:35], v[88:91], v[32:35], 0
	v_mfma_f32_16x16x32_bf16 v[28:31], v[84:87], v[36:39], v[28:31]
	v_mfma_f32_16x16x32_bf16 v[32:35], v[92:95], v[36:39], v[32:35]
	v_mfma_f32_16x16x32_bf16 v[36:39], v[80:83], v[40:43], 0
	v_mfma_f32_16x16x32_bf16 v[40:43], v[88:91], v[40:43], 0
	v_mfma_f32_16x16x32_bf16 v[36:39], v[84:87], v[44:47], v[36:39]
	v_mfma_f32_16x16x32_bf16 v[40:43], v[92:95], v[44:47], v[40:43]
	s_setprio 0
	v_lshl_add_u64 v[204:205], s[58:59], 0, v[132:133]
	s_mov_b32 m0, s47
	v_lshl_add_u64 v[134:135], v[204:205], 0, s[20:21]
	v_lshl_add_u64 v[206:207], s[58:59], 0, v[130:131]
	s_barrier
	ds_read_b128 v[44:47], v141 offset:16384
	ds_read_b128 v[100:103], v141 offset:17408
	ds_read_b128 v[104:107], v141 offset:18432
	ds_read_b128 v[108:111], v141 offset:19456
	ds_read_b128 v[112:115], v141 offset:20480
	ds_read_b128 v[116:119], v141 offset:21504
	ds_read_b128 v[120:123], v141 offset:22528
	ds_read_b128 v[124:127], v141 offset:23552
	global_load_lds_dwordx4 v[134:135], off
	v_lshl_add_u64 v[134:135], v[206:207], 0, s[20:21]
	s_mov_b32 m0, s50
	s_nop 0
	global_load_lds_dwordx4 v[134:135], off
	s_barrier
	s_waitcnt lgkmcnt(0)
	s_setprio 1
	v_mfma_f32_16x16x32_bf16 v[134:137], v[0:3], v[44:47], 0
	v_mfma_f32_16x16x32_bf16 v[146:149], v[0:3], v[104:107], 0
	v_mfma_f32_16x16x32_bf16 v[154:157], v[0:3], v[112:115], 0
	v_mfma_f32_16x16x32_bf16 v[0:3], v[0:3], v[120:123], 0
	v_mfma_f32_16x16x32_bf16 v[134:137], v[4:7], v[100:103], v[134:137]
	v_mfma_f32_16x16x32_bf16 v[142:145], v[8:11], v[44:47], 0
	v_mfma_f32_16x16x32_bf16 v[146:149], v[4:7], v[108:111], v[146:149]
	v_mfma_f32_16x16x32_bf16 v[150:153], v[8:11], v[104:107], 0
	v_mfma_f32_16x16x32_bf16 v[154:157], v[4:7], v[116:119], v[154:157]
	v_mfma_f32_16x16x32_bf16 v[158:161], v[8:11], v[112:115], 0
	v_mfma_f32_16x16x32_bf16 v[0:3], v[4:7], v[124:127], v[0:3]
	v_mfma_f32_16x16x32_bf16 v[4:7], v[8:11], v[120:123], 0
	v_mfma_f32_16x16x32_bf16 v[142:145], v[12:15], v[100:103], v[142:145]
	v_mfma_f32_16x16x32_bf16 v[150:153], v[12:15], v[108:111], v[150:153]
	v_mfma_f32_16x16x32_bf16 v[158:161], v[12:15], v[116:119], v[158:161]
	v_mfma_f32_16x16x32_bf16 v[4:7], v[12:15], v[124:127], v[4:7]
	s_setprio 0
	s_barrier
; #define PG8_STAGE(bufoff, gbase, voff) do { _Pragma("unroll") for (int _i = 0; _i < 2; ++_i) \
;         __builtin_amdgcn_global_load_lds((const unsigned*)((const char*)(gbase) + (voff)[_i]), (LAS unsigned*)(lds + (bufoff) + ldsw + _i * 8192), 16, 0, 0); } while (0)
; #define PG8_LDA(dst, b, h) do { _Pragma("unroll") for (int m = 0; m < 4; ++m) _Pragma("unroll") for (int k = 0; k < 2; ++k) dst[m][k] = *(const LAS bf16x8*)(lds + PG8_SA(b, h) + aoff + m * 2048 + k * 1024); } while (0)
; #define PG8_WAIT_V(n) asm volatile("s_waitcnt vmcnt(" #n ")" ::: "memory")
; #define PG8_WAIT_L(n) asm volatile("s_waitcnt lgkmcnt(" #n ")" ::: "memory")
; template <class Epi>
; __device__ __forceinline__ void gemm_phase(LAS unsigned char* lds, const Gemm g, const StaticOrder& S, const Epi& E, int wv) {
;     ...
;         for (int t = 0; t < nt; t += 2) {
;             const bool last = (t == nt - 2);
;             const char* a1 = cA + (size_t)(t + 1) * kstep;
;             const char* a2 = last ? nA : cA + (size_t)(t + 2) * kstep; const char* b2 = last ? nB : cB + (size_t)(t + 2) * kstep;
;             const char* a3 = a2 + kstep; const char* b3 = b2 + kstep;
;             PG8_LDB(B0, 0, 0); PG8_SCHED; PG8_LDA(At, 0, 0); PG8_STAGE(PG8_SA(1, 1), a1 + hstep, voffA);
;             PG8_WAIT_L(8); PG8_BAR; PG8_WAIT_L(0); PG8_MMA(0, 0, At, B0); PG8_BAR; PG8_SCHED;
;             PG8_LDB(B1, 0, 1); PG8_STAGE(PG8_SB(0, 0), b2, voffB);
;             PG8_BAR; PG8_WAIT_L(0); PG8_MMA(0, 1, At, B1); PG8_BAR;
;             PG8_LDA(At, 0, 1); PG8_STAGE(PG8_SA(0, 0), a2, voffA);
;             PG8_BAR; PG8_WAIT_L(0); PG8_MMA(1, 0, At, B0); PG8_BAR; PG8_SCHED;
;             PG8_STAGE(PG8_SB(0, 1), b2 + hstep, voffB);
;             PG8_WAIT_V(6); PG8_BAR; PG8_MMA(1, 1, At, B1); PG8_BAR;
;             PG8_LDB(B0, 1, 0); PG8_SCHED; PG8_LDA(At, 1, 0); PG8_STAGE(PG8_SA(0, 1), a2 + hstep, voffA);
;             PG8_WAIT_L(8); PG8_BAR; PG8_WAIT_L(0); PG8_MMA(0, 0, At, B0); PG8_BAR; PG8_SCHED;
;             PG8_LDB(B1, 1, 1); PG8_STAGE(PG8_SB(1, 0), b3, voffB);
;             PG8_BAR; PG8_WAIT_L(0); PG8_MMA(0, 1, At, B1); PG8_BAR;
;             PG8_LDA(At, 1, 1); PG8_STAGE(PG8_SA(1, 0), a3, voffA);
;             PG8_BAR; PG8_WAIT_L(0); PG8_MMA(1, 0, At, B0); PG8_BAR; PG8_SCHED;
;             PG8_STAGE(PG8_SB(1, 1), b3 + hstep, voffB);
;             PG8_WAIT_V(6); PG8_BAR; PG8_MMA(1, 1, At, B1); PG8_BAR;
	s_add_u32 s20, s60, 0x10100
	s_addc_u32 s21, s61, 0
	s_add_i32 s86, s86, s37
	s_mov_b32 m0, s86
	s_add_i32 s24, s86, 0x2000
	global_load_lds_dwordx4 v212, s[20:21]
	s_mov_b32 m0, s24
	s_nop 0
	global_load_lds_dwordx4 v128, s[20:21]
	s_waitcnt vmcnt(6)
	s_barrier
	s_setprio 1
	v_mfma_f32_16x16x32_bf16 v[8:11], v[80:83], v[44:47], 0
	v_mfma_f32_16x16x32_bf16 v[12:15], v[88:91], v[44:47], 0
	v_mfma_f32_16x16x32_bf16 v[8:11], v[84:87], v[100:103], v[8:11]
	v_mfma_f32_16x16x32_bf16 v[12:15], v[92:95], v[100:103], v[12:15]
	v_mfma_f32_16x16x32_bf16 v[44:47], v[80:83], v[104:107], 0
	v_mfma_f32_16x16x32_bf16 v[100:103], v[88:91], v[104:107], 0
	v_mfma_f32_16x16x32_bf16 v[104:107], v[80:83], v[112:115], 0
	v_mfma_f32_16x16x32_bf16 v[80:83], v[80:83], v[120:123], 0
	v_mfma_f32_16x16x32_bf16 v[44:47], v[84:87], v[108:111], v[44:47]
	v_mfma_f32_16x16x32_bf16 v[100:103], v[92:95], v[108:111], v[100:103]
	v_mfma_f32_16x16x32_bf16 v[104:107], v[84:87], v[116:119], v[104:107]
	v_mfma_f32_16x16x32_bf16 v[108:111], v[88:91], v[112:115], 0
	v_mfma_f32_16x16x32_bf16 v[80:83], v[84:87], v[124:127], v[80:83]
	v_mfma_f32_16x16x32_bf16 v[84:87], v[88:91], v[120:123], 0
	v_mfma_f32_16x16x32_bf16 v[108:111], v[92:95], v[116:119], v[108:111]
	v_mfma_f32_16x16x32_bf16 v[84:87], v[92:95], v[124:127], v[84:87]
	s_setprio 0
	s_add_i32 s97, 0, 0x18000
	v_add_u32_e32 v218, s97, v140
	s_barrier
	ds_read_b128 v[88:91], v218
	ds_read_b128 v[92:95], v218 offset:1024
	ds_read_b128 v[112:115], v218 offset:2048
	ds_read_b128 v[116:119], v218 offset:3072
	s_add_u32 s20, s58, 0x10100
	s_addc_u32 s21, s59, 0
	s_mov_b32 m0, s68
	ds_read_b128 v[120:123], v141 offset:32768
	ds_read_b128 v[124:127], v141 offset:33792
	ds_read_b128 v[162:165], v141 offset:34816
	ds_read_b128 v[166:169], v141 offset:35840
	ds_read_b128 v[170:173], v141 offset:36864
	ds_read_b128 v[174:177], v141 offset:37888
	ds_read_b128 v[178:181], v141 offset:38912
	ds_read_b128 v[182:185], v141 offset:39936
	global_load_lds_dwordx4 v132, s[20:21]
	s_mov_b32 m0, s69
	s_nop 0
	global_load_lds_dwordx4 v130, s[20:21]
	s_waitcnt lgkmcnt(8)
	s_barrier
	s_waitcnt lgkmcnt(0)
	s_setprio 1
	v_mfma_f32_16x16x32_bf16 v[48:51], v[88:91], v[120:123], v[48:51]
	v_mfma_f32_16x16x32_bf16 v[52:55], v[112:115], v[120:123], v[52:55]
	v_mfma_f32_16x16x32_bf16 v[56:59], v[88:91], v[162:165], v[56:59]
	v_mfma_f32_16x16x32_bf16 v[60:63], v[112:115], v[162:165], v[60:63]
	v_mfma_f32_16x16x32_bf16 v[64:67], v[88:91], v[170:173], v[64:67]
	v_mfma_f32_16x16x32_bf16 v[68:71], v[112:115], v[170:173], v[68:71]
	v_mfma_f32_16x16x32_bf16 v[72:75], v[88:91], v[178:181], v[72:75]
	v_mfma_f32_16x16x32_bf16 v[76:79], v[112:115], v[178:181], v[76:79]
	v_mfma_f32_16x16x32_bf16 v[48:51], v[92:95], v[124:127], v[48:51]
	v_mfma_f32_16x16x32_bf16 v[52:55], v[116:119], v[124:127], v[52:55]
	v_mfma_f32_16x16x32_bf16 v[56:59], v[92:95], v[166:169], v[56:59]
	v_mfma_f32_16x16x32_bf16 v[60:63], v[116:119], v[166:169], v[60:63]
	v_mfma_f32_16x16x32_bf16 v[64:67], v[92:95], v[174:177], v[64:67]
	v_mfma_f32_16x16x32_bf16 v[68:71], v[116:119], v[174:177], v[68:71]
	v_mfma_f32_16x16x32_bf16 v[72:75], v[92:95], v[182:185], v[72:75]
	v_mfma_f32_16x16x32_bf16 v[76:79], v[116:119], v[182:185], v[76:79]
	s_setprio 0
	s_barrier
	s_add_i32 vcc_lo, 0, 0x1c000
	s_mov_b64 s[20:21], 0x180
	s_add_i32 s97, s97, s37
	v_add_u32_e32 v236, vcc_lo, v140
	v_lshl_add_u64 v[138:139], v[138:139], 0, s[20:21]
	s_mov_b32 m0, s97
	s_add_i32 s96, s97, 0x2000
	ds_read_b128 v[186:189], v236
	ds_read_b128 v[190:193], v236 offset:1024
	ds_read_b128 v[194:197], v236 offset:2048
	ds_read_b128 v[198:201], v236 offset:3072
	global_load_lds_dwordx4 v[138:139], off
	v_lshl_add_u64 v[138:139], v[202:203], 0, s[20:21]
	s_mov_b32 m0, s96
	s_nop 0
	global_load_lds_dwordx4 v[138:139], off
	s_barrier
	s_waitcnt lgkmcnt(0)
	s_setprio 1
	v_mfma_f32_16x16x32_bf16 v[96:99], v[186:189], v[120:123], v[96:99]
	v_mfma_f32_16x16x32_bf16 v[16:19], v[194:197], v[120:123], v[16:19]
	v_mfma_f32_16x16x32_bf16 v[20:23], v[186:189], v[162:165], v[20:23]
	v_mfma_f32_16x16x32_bf16 v[24:27], v[194:197], v[162:165], v[24:27]
	v_mfma_f32_16x16x32_bf16 v[28:31], v[186:189], v[170:173], v[28:31]
	v_mfma_f32_16x16x32_bf16 v[32:35], v[194:197], v[170:173], v[32:35]
	v_mfma_f32_16x16x32_bf16 v[36:39], v[186:189], v[178:181], v[36:39]
	v_mfma_f32_16x16x32_bf16 v[40:43], v[194:197], v[178:181], v[40:43]
	v_mfma_f32_16x16x32_bf16 v[96:99], v[190:193], v[124:127], v[96:99]
	v_mfma_f32_16x16x32_bf16 v[16:19], v[198:201], v[124:127], v[16:19]
	v_mfma_f32_16x16x32_bf16 v[20:23], v[190:193], v[166:169], v[20:23]
	v_mfma_f32_16x16x32_bf16 v[24:27], v[198:201], v[166:169], v[24:27]
	v_mfma_f32_16x16x32_bf16 v[28:31], v[190:193], v[174:177], v[28:31]
	v_mfma_f32_16x16x32_bf16 v[32:35], v[198:201], v[174:177], v[32:35]
	v_mfma_f32_16x16x32_bf16 v[36:39], v[190:193], v[182:185], v[36:39]
	v_mfma_f32_16x16x32_bf16 v[40:43], v[198:201], v[182:185], v[40:43]
	s_setprio 0
	s_mov_b32 m0, s2
	v_lshl_add_u64 v[138:139], v[204:205], 0, s[20:21]
	s_barrier
	ds_read_b128 v[120:123], v141 offset:49152
	ds_read_b128 v[124:127], v141 offset:50176
	ds_read_b128 v[162:165], v141 offset:51200
	ds_read_b128 v[166:169], v141 offset:52224
	ds_read_b128 v[170:173], v141 offset:53248
	ds_read_b128 v[174:177], v141 offset:54272
	ds_read_b128 v[178:181], v141 offset:55296
	ds_read_b128 v[182:185], v141 offset:56320
	global_load_lds_dwordx4 v[138:139], off
	v_lshl_add_u64 v[138:139], v[206:207], 0, s[20:21]
	s_mov_b32 m0, s3
	s_nop 0
	global_load_lds_dwordx4 v[138:139], off
	s_barrier
; #define PG8_STAGE(bufoff, gbase, voff) do { _Pragma("unroll") for (int _i = 0; _i < 2; ++_i) \
;         __builtin_amdgcn_global_load_lds((const unsigned*)((const char*)(gbase) + (voff)[_i]), (LAS unsigned*)(lds + (bufoff) + ldsw + _i * 8192), 16, 0, 0); } while (0)
; #define PG8_LDA(dst, b, h) do { _Pragma("unroll") for (int m = 0; m < 4; ++m) _Pragma("unroll") for (int k = 0; k < 2; ++k) dst[m][k] = *(const LAS bf16x8*)(lds + PG8_SA(b, h) + aoff + m * 2048 + k * 1024); } while (0)
; #define PG8_WAIT_V(n) asm volatile("s_waitcnt vmcnt(" #n ")" ::: "memory")
; #define PG8_WAIT_L(n) asm volatile("s_waitcnt lgkmcnt(" #n ")" ::: "memory")
; template <class Epi>
; __device__ __forceinline__ void gemm_phase(LAS unsigned char* lds, const Gemm g, const StaticOrder& S, const Epi& E, int wv) {
;     ...
;         for (int t = 0; t < nt; t += 2) {
;             const bool last = (t == nt - 2);
;             const char* a1 = cA + (size_t)(t + 1) * kstep;
;             const char* a2 = last ? nA : cA + (size_t)(t + 2) * kstep; const char* b2 = last ? nB : cB + (size_t)(t + 2) * kstep;
;             const char* a3 = a2 + kstep; const char* b3 = b2 + kstep;
;             PG8_LDB(B0, 0, 0); PG8_SCHED; PG8_LDA(At, 0, 0); PG8_STAGE(PG8_SA(1, 1), a1 + hstep, voffA);
;             PG8_WAIT_L(8); PG8_BAR; PG8_WAIT_L(0); PG8_MMA(0, 0, At, B0); PG8_BAR; PG8_SCHED;
;             PG8_LDB(B1, 0, 1); PG8_STAGE(PG8_SB(0, 0), b2, voffB);
;             PG8_BAR; PG8_WAIT_L(0); PG8_MMA(0, 1, At, B1); PG8_BAR;
;             PG8_LDA(At, 0, 1); PG8_STAGE(PG8_SA(0, 0), a2, voffA);
;             PG8_BAR; PG8_WAIT_L(0); PG8_MMA(1, 0, At, B0); PG8_BAR; PG8_SCHED;
;             PG8_STAGE(PG8_SB(0, 1), b2 + hstep, voffB);
;             PG8_WAIT_V(6); PG8_BAR; PG8_MMA(1, 1, At, B1); PG8_BAR;
;             PG8_LDB(B0, 1, 0); PG8_SCHED; PG8_LDA(At, 1, 0); PG8_STAGE(PG8_SA(0, 1), a2 + hstep, voffA);
;             PG8_WAIT_L(8); PG8_BAR; PG8_WAIT_L(0); PG8_MMA(0, 0, At, B0); PG8_BAR; PG8_SCHED;
;             PG8_LDB(B1, 1, 1); PG8_STAGE(PG8_SB(1, 0), b3, voffB);
;             PG8_BAR; PG8_WAIT_L(0); PG8_MMA(0, 1, At, B1); PG8_BAR;
;             PG8_LDA(At, 1, 1); PG8_STAGE(PG8_SA(1, 0), a3, voffA);
;             PG8_BAR; PG8_WAIT_L(0); PG8_MMA(1, 0, At, B0); PG8_BAR; PG8_SCHED;
;             PG8_STAGE(PG8_SB(1, 1), b3 + hstep, voffB);
;             PG8_WAIT_V(6); PG8_BAR; PG8_MMA(1, 1, At, B1); PG8_BAR;
	s_waitcnt lgkmcnt(0)
	s_setprio 1
	v_mfma_f32_16x16x32_bf16 v[134:137], v[88:91], v[120:123], v[134:137]
	v_mfma_f32_16x16x32_bf16 v[142:145], v[112:115], v[120:123], v[142:145]
	v_mfma_f32_16x16x32_bf16 v[146:149], v[88:91], v[162:165], v[146:149]
	v_mfma_f32_16x16x32_bf16 v[150:153], v[112:115], v[162:165], v[150:153]
	v_mfma_f32_16x16x32_bf16 v[154:157], v[88:91], v[170:173], v[154:157]
	v_mfma_f32_16x16x32_bf16 v[158:161], v[112:115], v[170:173], v[158:161]
	v_mfma_f32_16x16x32_bf16 v[0:3], v[88:91], v[178:181], v[0:3]
	v_mfma_f32_16x16x32_bf16 v[4:7], v[112:115], v[178:181], v[4:7]
	v_mfma_f32_16x16x32_bf16 v[134:137], v[92:95], v[124:127], v[134:137]
	v_mfma_f32_16x16x32_bf16 v[142:145], v[116:119], v[124:127], v[142:145]
	v_mfma_f32_16x16x32_bf16 v[146:149], v[92:95], v[166:169], v[146:149]
	v_mfma_f32_16x16x32_bf16 v[150:153], v[116:119], v[166:169], v[150:153]
	v_mfma_f32_16x16x32_bf16 v[154:157], v[92:95], v[174:177], v[154:157]
	v_mfma_f32_16x16x32_bf16 v[158:161], v[116:119], v[174:177], v[158:161]
	v_mfma_f32_16x16x32_bf16 v[0:3], v[92:95], v[182:185], v[0:3]
	v_mfma_f32_16x16x32_bf16 v[4:7], v[116:119], v[182:185], v[4:7]
	s_setprio 0
	s_barrier
	s_add_u32 s20, s60, 0x10180
	s_addc_u32 s21, s61, 0
	s_add_i32 s61, vcc_lo, s37
	s_mov_b32 m0, s61
	s_add_i32 s60, s61, 0x2000
	global_load_lds_dwordx4 v212, s[20:21]
	s_mov_b32 m0, s60
	s_nop 0
	global_load_lds_dwordx4 v128, s[20:21]
	s_waitcnt vmcnt(6)
	s_barrier
	s_setprio 1
	v_mfma_f32_16x16x32_bf16 v[8:11], v[186:189], v[120:123], v[8:11]
	v_mfma_f32_16x16x32_bf16 v[12:15], v[194:197], v[120:123], v[12:15]
	v_mfma_f32_16x16x32_bf16 v[44:47], v[186:189], v[162:165], v[44:47]
	v_mfma_f32_16x16x32_bf16 v[88:91], v[194:197], v[162:165], v[100:103]
	v_mfma_f32_16x16x32_bf16 v[92:95], v[186:189], v[170:173], v[104:107]
	v_mfma_f32_16x16x32_bf16 v[100:103], v[194:197], v[170:173], v[108:111]
	v_mfma_f32_16x16x32_bf16 v[80:83], v[186:189], v[178:181], v[80:83]
	v_mfma_f32_16x16x32_bf16 v[84:87], v[194:197], v[178:181], v[84:87]
	v_mfma_f32_16x16x32_bf16 v[8:11], v[190:193], v[124:127], v[8:11]
	v_mfma_f32_16x16x32_bf16 v[12:15], v[198:201], v[124:127], v[12:15]
	v_mfma_f32_16x16x32_bf16 v[44:47], v[190:193], v[166:169], v[44:47]
	v_mfma_f32_16x16x32_bf16 v[88:91], v[198:201], v[166:169], v[88:91]
	v_mfma_f32_16x16x32_bf16 v[92:95], v[190:193], v[174:177], v[92:95]
	v_mfma_f32_16x16x32_bf16 v[100:103], v[198:201], v[174:177], v[100:103]
	v_mfma_f32_16x16x32_bf16 v[80:83], v[190:193], v[182:185], v[80:83]
	v_mfma_f32_16x16x32_bf16 v[84:87], v[198:201], v[182:185], v[84:87]
	s_setprio 0
	s_barrier
	ds_read_b128 v[104:107], v208
	ds_read_b128 v[108:111], v208 offset:1024
	ds_read_b128 v[112:115], v208 offset:2048
	ds_read_b128 v[116:119], v208 offset:3072
	s_add_u32 s20, s58, 0x10180
	s_addc_u32 s21, s59, 0
	s_mov_b32 m0, s85
	ds_read_b128 v[120:123], v141
	ds_read_b128 v[124:127], v141 offset:1024
	ds_read_b128 v[162:165], v141 offset:2048
	ds_read_b128 v[166:169], v141 offset:3072
	ds_read_b128 v[170:173], v141 offset:4096
	ds_read_b128 v[174:177], v141 offset:5120
	ds_read_b128 v[178:181], v141 offset:6144
	ds_read_b128 v[182:185], v141 offset:7168
	global_load_lds_dwordx4 v132, s[20:21]
	s_mov_b32 m0, s13
	s_nop 0
	global_load_lds_dwordx4 v130, s[20:21]
	s_waitcnt lgkmcnt(8)
	s_barrier
	s_waitcnt lgkmcnt(0)
	s_setprio 1
	v_mfma_f32_16x16x32_bf16 v[48:51], v[104:107], v[120:123], v[48:51]
	v_mfma_f32_16x16x32_bf16 v[52:55], v[112:115], v[120:123], v[52:55]
	v_mfma_f32_16x16x32_bf16 v[56:59], v[104:107], v[162:165], v[56:59]
	v_mfma_f32_16x16x32_bf16 v[60:63], v[112:115], v[162:165], v[60:63]
	v_mfma_f32_16x16x32_bf16 v[64:67], v[104:107], v[170:173], v[64:67]
	v_mfma_f32_16x16x32_bf16 v[68:71], v[112:115], v[170:173], v[68:71]
	v_mfma_f32_16x16x32_bf16 v[72:75], v[104:107], v[178:181], v[72:75]
	v_mfma_f32_16x16x32_bf16 v[76:79], v[112:115], v[178:181], v[76:79]
	v_mfma_f32_16x16x32_bf16 v[48:51], v[108:111], v[124:127], v[48:51]
	v_mfma_f32_16x16x32_bf16 v[52:55], v[116:119], v[124:127], v[52:55]
	v_mfma_f32_16x16x32_bf16 v[56:59], v[108:111], v[166:169], v[56:59]
	v_mfma_f32_16x16x32_bf16 v[60:63], v[116:119], v[166:169], v[60:63]
	v_mfma_f32_16x16x32_bf16 v[64:67], v[108:111], v[174:177], v[64:67]
	v_mfma_f32_16x16x32_bf16 v[68:71], v[116:119], v[174:177], v[68:71]
	v_mfma_f32_16x16x32_bf16 v[72:75], v[108:111], v[182:185], v[72:75]
	v_mfma_f32_16x16x32_bf16 v[186:189], v[116:119], v[182:185], v[76:79]
	s_setprio 0
	s_barrier
	s_mov_b32 m0, s79
	v_lshl_add_u64 v[138:139], s[62:63], 0, v[212:213]
	ds_read_b128 v[76:79], v209
	ds_read_b128 v[190:193], v209 offset:1024
	ds_read_b128 v[194:197], v209 offset:2048
	ds_read_b128 v[198:201], v209 offset:3072
	global_load_lds_dwordx4 v[138:139], off
	v_lshl_add_u64 v[210:211], s[62:63], 0, v[128:129]
	s_mov_b32 m0, s23
	s_nop 0
	global_load_lds_dwordx4 v[210:211], off
	s_barrier
	s_waitcnt lgkmcnt(0)
	s_setprio 1
	v_mfma_f32_16x16x32_bf16 v[96:99], v[76:79], v[120:123], v[96:99]
	v_mfma_f32_16x16x32_bf16 v[16:19], v[194:197], v[120:123], v[16:19]
	v_mfma_f32_16x16x32_bf16 v[20:23], v[76:79], v[162:165], v[20:23]
	v_mfma_f32_16x16x32_bf16 v[24:27], v[194:197], v[162:165], v[24:27]
	v_mfma_f32_16x16x32_bf16 v[28:31], v[76:79], v[170:173], v[28:31]
	v_mfma_f32_16x16x32_bf16 v[32:35], v[194:197], v[170:173], v[32:35]
	v_mfma_f32_16x16x32_bf16 v[36:39], v[76:79], v[178:181], v[36:39]
	v_mfma_f32_16x16x32_bf16 v[40:43], v[194:197], v[178:181], v[40:43]
	v_mfma_f32_16x16x32_bf16 v[202:205], v[190:193], v[124:127], v[96:99]
	v_mfma_f32_16x16x32_bf16 v[16:19], v[198:201], v[124:127], v[16:19]
	v_mfma_f32_16x16x32_bf16 v[20:23], v[190:193], v[166:169], v[20:23]
	v_mfma_f32_16x16x32_bf16 v[24:27], v[198:201], v[166:169], v[24:27]
	v_mfma_f32_16x16x32_bf16 v[28:31], v[190:193], v[174:177], v[28:31]
	v_mfma_f32_16x16x32_bf16 v[32:35], v[198:201], v[174:177], v[32:35]
	v_mfma_f32_16x16x32_bf16 v[36:39], v[190:193], v[182:185], v[36:39]
	v_mfma_f32_16x16x32_bf16 v[40:43], v[198:201], v[182:185], v[40:43]
	s_setprio 0
	s_mov_b32 m0, s47
	v_lshl_add_u64 v[222:223], s[64:65], 0, v[132:133]
	s_barrier
; #define PG8_STAGE(bufoff, gbase, voff) do { _Pragma("unroll") for (int _i = 0; _i < 2; ++_i) \
;         __builtin_amdgcn_global_load_lds((const unsigned*)((const char*)(gbase) + (voff)[_i]), (LAS unsigned*)(lds + (bufoff) + ldsw + _i * 8192), 16, 0, 0); } while (0)
; #define PG8_LDA(dst, b, h) do { _Pragma("unroll") for (int m = 0; m < 4; ++m) _Pragma("unroll") for (int k = 0; k < 2; ++k) dst[m][k] = *(const LAS bf16x8*)(lds + PG8_SA(b, h) + aoff + m * 2048 + k * 1024); } while (0)
; #define PG8_WAIT_V(n) asm volatile("s_waitcnt vmcnt(" #n ")" ::: "memory")
; #define PG8_WAIT_L(n) asm volatile("s_waitcnt lgkmcnt(" #n ")" ::: "memory")
; template <class Epi>
; __device__ __forceinline__ void gemm_phase(LAS unsigned char* lds, const Gemm g, const StaticOrder& S, const Epi& E, int wv) {
;     ...
;         for (int t = 0; t < nt; t += 2) {
;             const bool last = (t == nt - 2);
;             const char* a1 = cA + (size_t)(t + 1) * kstep;
;             const char* a2 = last ? nA : cA + (size_t)(t + 2) * kstep; const char* b2 = last ? nB : cB + (size_t)(t + 2) * kstep;
;             const char* a3 = a2 + kstep; const char* b3 = b2 + kstep;
;             PG8_LDB(B0, 0, 0); PG8_SCHED; PG8_LDA(At, 0, 0); PG8_STAGE(PG8_SA(1, 1), a1 + hstep, voffA);
;             PG8_WAIT_L(8); PG8_BAR; PG8_WAIT_L(0); PG8_MMA(0, 0, At, B0); PG8_BAR; PG8_SCHED;
;             PG8_LDB(B1, 0, 1); PG8_STAGE(PG8_SB(0, 0), b2, voffB);
;             PG8_BAR; PG8_WAIT_L(0); PG8_MMA(0, 1, At, B1); PG8_BAR;
;             PG8_LDA(At, 0, 1); PG8_STAGE(PG8_SA(0, 0), a2, voffA);
;             PG8_BAR; PG8_WAIT_L(0); PG8_MMA(1, 0, At, B0); PG8_BAR; PG8_SCHED;
;             PG8_STAGE(PG8_SB(0, 1), b2 + hstep, voffB);
;             PG8_WAIT_V(6); PG8_BAR; PG8_MMA(1, 1, At, B1); PG8_BAR;
;             PG8_LDB(B0, 1, 0); PG8_SCHED; PG8_LDA(At, 1, 0); PG8_STAGE(PG8_SA(0, 1), a2 + hstep, voffA);
;             PG8_WAIT_L(8); PG8_BAR; PG8_WAIT_L(0); PG8_MMA(0, 0, At, B0); PG8_BAR; PG8_SCHED;
;             PG8_LDB(B1, 1, 1); PG8_STAGE(PG8_SB(1, 0), b3, voffB);
;             PG8_BAR; PG8_WAIT_L(0); PG8_MMA(0, 1, At, B1); PG8_BAR;
;             PG8_LDA(At, 1, 1); PG8_STAGE(PG8_SA(1, 0), a3, voffA);
;             PG8_BAR; PG8_WAIT_L(0); PG8_MMA(1, 0, At, B0); PG8_BAR; PG8_SCHED;
;             PG8_STAGE(PG8_SB(1, 1), b3 + hstep, voffB);
;             PG8_WAIT_V(6); PG8_BAR; PG8_MMA(1, 1, At, B1); PG8_BAR;
	ds_read_b128 v[96:99], v141 offset:16384
	ds_read_b128 v[120:123], v141 offset:17408
	ds_read_b128 v[124:127], v141 offset:18432
	ds_read_b128 v[162:165], v141 offset:19456
	ds_read_b128 v[166:169], v141 offset:20480
	ds_read_b128 v[170:173], v141 offset:21504
	ds_read_b128 v[174:177], v141 offset:22528
	ds_read_b128 v[178:181], v141 offset:23552
	global_load_lds_dwordx4 v[222:223], off
	v_lshl_add_u64 v[228:229], s[64:65], 0, v[130:131]
	s_mov_b32 m0, s50
	s_nop 0
	global_load_lds_dwordx4 v[228:229], off
	s_barrier
	s_waitcnt lgkmcnt(0)
	s_setprio 1
	v_mfma_f32_16x16x32_bf16 v[134:137], v[104:107], v[96:99], v[134:137]
	v_mfma_f32_16x16x32_bf16 v[142:145], v[112:115], v[96:99], v[142:145]
	v_mfma_f32_16x16x32_bf16 v[146:149], v[104:107], v[124:127], v[146:149]
	v_mfma_f32_16x16x32_bf16 v[150:153], v[112:115], v[124:127], v[150:153]
	v_mfma_f32_16x16x32_bf16 v[154:157], v[104:107], v[166:169], v[154:157]
	v_mfma_f32_16x16x32_bf16 v[158:161], v[112:115], v[166:169], v[158:161]
	v_mfma_f32_16x16x32_bf16 v[0:3], v[104:107], v[174:177], v[0:3]
	v_mfma_f32_16x16x32_bf16 v[4:7], v[112:115], v[174:177], v[4:7]
	v_mfma_f32_16x16x32_bf16 v[134:137], v[108:111], v[120:123], v[134:137]
	v_mfma_f32_16x16x32_bf16 v[142:145], v[116:119], v[120:123], v[142:145]
	v_mfma_f32_16x16x32_bf16 v[146:149], v[108:111], v[162:165], v[146:149]
	v_mfma_f32_16x16x32_bf16 v[150:153], v[116:119], v[162:165], v[150:153]
	v_mfma_f32_16x16x32_bf16 v[154:157], v[108:111], v[170:173], v[154:157]
	v_mfma_f32_16x16x32_bf16 v[158:161], v[116:119], v[170:173], v[158:161]
	v_mfma_f32_16x16x32_bf16 v[0:3], v[108:111], v[178:181], v[0:3]
	v_mfma_f32_16x16x32_bf16 v[182:185], v[116:119], v[178:181], v[4:7]
	s_setprio 0
	s_barrier
	s_add_u32 s20, s62, 0x10000
	s_addc_u32 s21, s63, 0
	s_mov_b32 m0, s86
	s_nop 0
	global_load_lds_dwordx4 v212, s[20:21]
	s_mov_b32 m0, s24
	s_nop 0
	global_load_lds_dwordx4 v128, s[20:21]
	s_waitcnt vmcnt(6)
	s_barrier
	s_setprio 1
	v_mfma_f32_16x16x32_bf16 v[4:7], v[76:79], v[96:99], v[8:11]
	v_mfma_f32_16x16x32_bf16 v[8:11], v[190:193], v[120:123], v[4:7]
	v_mfma_f32_16x16x32_bf16 v[4:7], v[194:197], v[96:99], v[12:15]
	v_mfma_f32_16x16x32_bf16 v[12:15], v[198:201], v[120:123], v[4:7]
	v_mfma_f32_16x16x32_bf16 v[4:7], v[76:79], v[124:127], v[44:47]
	v_mfma_f32_16x16x32_bf16 v[206:209], v[190:193], v[162:165], v[4:7]
	v_mfma_f32_16x16x32_bf16 v[4:7], v[194:197], v[124:127], v[88:91]
	v_mfma_f32_16x16x32_bf16 v[162:165], v[198:201], v[162:165], v[4:7]
	v_mfma_f32_16x16x32_bf16 v[4:7], v[76:79], v[166:169], v[92:95]
	v_mfma_f32_16x16x32_bf16 v[214:217], v[190:193], v[170:173], v[4:7]
	v_mfma_f32_16x16x32_bf16 v[4:7], v[194:197], v[166:169], v[100:103]
	v_mfma_f32_16x16x32_bf16 v[166:169], v[198:201], v[170:173], v[4:7]
	v_mfma_f32_16x16x32_bf16 v[4:7], v[76:79], v[174:177], v[80:83]
	v_mfma_f32_16x16x32_bf16 v[170:173], v[190:193], v[178:181], v[4:7]
	v_mfma_f32_16x16x32_bf16 v[4:7], v[194:197], v[174:177], v[84:87]
	v_mfma_f32_16x16x32_bf16 v[174:177], v[198:201], v[178:181], v[4:7]
	s_setprio 0
	s_barrier
	s_nop 4
	ds_read_b128 v[4:7], v218
	ds_read_b128 v[80:83], v218 offset:1024
	ds_read_b128 v[178:181], v218 offset:2048
	ds_read_b128 v[190:193], v218 offset:3072
	s_add_u32 s20, s64, 0x10000
	s_addc_u32 s21, s65, 0
	s_mov_b32 m0, s68
	ds_read_b128 v[88:91], v141 offset:32768
	ds_read_b128 v[92:95], v141 offset:33792
	ds_read_b128 v[104:107], v141 offset:34816
	ds_read_b128 v[194:197], v141 offset:35840
	ds_read_b128 v[198:201], v141 offset:36864
	ds_read_b128 v[218:221], v141 offset:37888
	ds_read_b128 v[224:227], v141 offset:38912
	ds_read_b128 v[238:241], v141 offset:39936
	global_load_lds_dwordx4 v132, s[20:21]
	s_mov_b32 m0, s69
	s_nop 0
	global_load_lds_dwordx4 v130, s[20:21]
	s_waitcnt lgkmcnt(8)
	s_barrier
	s_waitcnt lgkmcnt(0)
	s_setprio 1
	v_mfma_f32_16x16x32_bf16 v[44:47], v[4:7], v[88:91], v[48:51]
	v_mfma_f32_16x16x32_bf16 v[124:127], v[80:83], v[92:95], v[44:47]
	v_mfma_f32_16x16x32_bf16 v[44:47], v[178:181], v[88:91], v[52:55]
	v_mfma_f32_16x16x32_bf16 v[112:115], v[190:193], v[92:95], v[44:47]
	v_mfma_f32_16x16x32_bf16 v[44:47], v[4:7], v[104:107], v[56:59]
	v_mfma_f32_16x16x32_bf16 v[100:103], v[80:83], v[194:197], v[44:47]
	v_mfma_f32_16x16x32_bf16 v[44:47], v[178:181], v[104:107], v[60:63]
	v_mfma_f32_16x16x32_bf16 v[96:99], v[190:193], v[194:197], v[44:47]
	v_mfma_f32_16x16x32_bf16 v[44:47], v[4:7], v[198:201], v[64:67]
	v_mfma_f32_16x16x32_bf16 v[84:87], v[80:83], v[218:221], v[44:47]
	v_mfma_f32_16x16x32_bf16 v[44:47], v[178:181], v[198:201], v[68:71]
	v_mfma_f32_16x16x32_bf16 v[76:79], v[190:193], v[218:221], v[44:47]
	v_mfma_f32_16x16x32_bf16 v[44:47], v[4:7], v[224:227], v[72:75]
	v_mfma_f32_16x16x32_bf16 v[52:55], v[80:83], v[238:241], v[44:47]
	v_mfma_f32_16x16x32_bf16 v[44:47], v[178:181], v[224:227], v[186:189]
	v_mfma_f32_16x16x32_bf16 v[44:47], v[190:193], v[238:241], v[44:47]
	s_setprio 0
	s_barrier
	s_mov_b32 m0, s97
	v_lshl_add_u64 v[48:49], v[138:139], 0, s[80:81]
	ds_read_b128 v[186:189], v236
	ds_read_b128 v[242:245], v236 offset:1024
	ds_read_b128 v[246:249], v236 offset:2048
	ds_read_b128 v[250:253], v236 offset:3072
	global_load_lds_dwordx4 v[48:49], off
	v_lshl_add_u64 v[48:49], v[210:211], 0, s[80:81]
	s_mov_b32 m0, s96
	s_nop 0
	global_load_lds_dwordx4 v[48:49], off
	s_barrier
; __device__ __forceinline__ int opaque_lane() { int l = __builtin_amdgcn_mbcnt_hi(~0u, __builtin_amdgcn_mbcnt_lo(~0u, 0u)); asm volatile("" : "+v"(l)); return l; }
; #define PG8_STAGE(bufoff, gbase, voff) do { _Pragma("unroll") for (int _i = 0; _i < 2; ++_i) \
;         __builtin_amdgcn_global_load_lds((const unsigned*)((const char*)(gbase) + (voff)[_i]), (LAS unsigned*)(lds + (bufoff) + ldsw + _i * 8192), 16, 0, 0); } while (0)
; #define PG8_LDA(dst, b, h) do { _Pragma("unroll") for (int m = 0; m < 4; ++m) _Pragma("unroll") for (int k = 0; k < 2; ++k) dst[m][k] = *(const LAS bf16x8*)(lds + PG8_SA(b, h) + aoff + m * 2048 + k * 1024); } while (0)
; template <class Epi>
; __device__ __forceinline__ void gemm_phase(LAS unsigned char* lds, const Gemm g, const StaticOrder& S, const Epi& E, int wv) {
;     ...
;             PG8_LDB(B0, 0, 0); PG8_SCHED; PG8_LDA(At, 0, 0); PG8_STAGE(PG8_SA(1, 1), a1 + hstep, voffA);
;             PG8_WAIT_L(8); PG8_BAR; PG8_WAIT_L(0); PG8_MMA(0, 0, At, B0); PG8_BAR; PG8_SCHED;
;             PG8_LDB(B1, 0, 1); PG8_STAGE(PG8_SB(0, 0), b2, voffB);
;             PG8_BAR; PG8_WAIT_L(0); PG8_MMA(0, 1, At, B1); PG8_BAR;
;             PG8_LDA(At, 0, 1); PG8_STAGE(PG8_SA(0, 0), a2, voffA);
;             PG8_BAR; PG8_WAIT_L(0); PG8_MMA(1, 0, At, B0); PG8_BAR; PG8_SCHED;
;             PG8_STAGE(PG8_SB(0, 1), b2 + hstep, voffB);
;             PG8_WAIT_V(6); PG8_BAR; PG8_MMA(1, 1, At, B1); PG8_BAR;
;             PG8_LDB(B0, 1, 0); PG8_SCHED; PG8_LDA(At, 1, 0); PG8_STAGE(PG8_SA(0, 1), a2 + hstep, voffA);
;             PG8_WAIT_L(8); PG8_BAR; PG8_WAIT_L(0); PG8_MMA(0, 0, At, B0); PG8_BAR; PG8_SCHED;
;             PG8_LDB(B1, 1, 1); PG8_STAGE(PG8_SB(1, 0), b3, voffB);
;             PG8_BAR; PG8_WAIT_L(0); PG8_MMA(0, 1, At, B1); PG8_BAR;
;             PG8_LDA(At, 1, 1); PG8_STAGE(PG8_SA(1, 0), a3, voffA);
;             PG8_BAR; PG8_WAIT_L(0); PG8_MMA(1, 0, At, B0); PG8_BAR; PG8_SCHED;
;             PG8_STAGE(PG8_SB(1, 1), b3 + hstep, voffB);
;             PG8_WAIT_V(6); PG8_BAR; PG8_MMA(1, 1, At, B1); PG8_BAR;
;     __device__ __forceinline__ void operator()(Acc& acc, const Unit& u, int wv) const {
;         const int wr = wv >> 2, wc = wv & 3, ln_ = opaque_lane(), fr = ln_ & 15, fq = ln_ >> 4;
;         bf16_t* base = u.pn < 8 ? KN + u.pn * 256 : V + (u.pn - 8) * 256;
;         const int row0 = u.pm * BM + wr * 64 + fr, col0 = wc * 32 + 8 * fq;
	s_waitcnt lgkmcnt(0)
	s_setprio 1
	v_mfma_f32_16x16x32_bf16 v[16:19], v[246:249], v[88:91], v[16:19]
	v_mfma_f32_16x16x32_bf16 v[116:119], v[250:253], v[92:95], v[16:19]
	v_mfma_f32_16x16x32_bf16 v[16:19], v[186:189], v[104:107], v[20:23]
	v_mfma_f32_16x16x32_bf16 v[108:111], v[242:245], v[194:197], v[16:19]
	v_mfma_f32_16x16x32_bf16 v[16:19], v[246:249], v[104:107], v[24:27]
	v_mfma_f32_16x16x32_bf16 v[48:51], v[186:189], v[88:91], v[202:205]
	v_mfma_f32_16x16x32_bf16 v[104:107], v[250:253], v[194:197], v[16:19]
	v_mfma_f32_16x16x32_bf16 v[16:19], v[186:189], v[198:201], v[28:31]
	v_mfma_f32_16x16x32_bf16 v[120:123], v[242:245], v[92:95], v[48:51]
	v_mfma_f32_16x16x32_bf16 v[92:95], v[242:245], v[218:221], v[16:19]
	v_mfma_f32_16x16x32_bf16 v[16:19], v[246:249], v[198:201], v[32:35]
	v_mfma_f32_16x16x32_bf16 v[88:91], v[250:253], v[218:221], v[16:19]
	v_mfma_f32_16x16x32_bf16 v[16:19], v[186:189], v[224:227], v[36:39]
	v_mfma_f32_16x16x32_bf16 v[60:63], v[242:245], v[238:241], v[16:19]
	v_mfma_f32_16x16x32_bf16 v[16:19], v[246:249], v[224:227], v[40:43]
	v_mfma_f32_16x16x32_bf16 v[56:59], v[250:253], v[238:241], v[16:19]
	s_setprio 0
	s_mov_b32 m0, s2
	s_nop 4
	v_lshl_add_u64 v[16:17], v[222:223], 0, s[80:81]
	s_barrier
	ds_read_b128 v[24:27], v141 offset:49152
	ds_read_b128 v[28:31], v141 offset:50176
	ds_read_b128 v[40:43], v141 offset:51200
	ds_read_b128 v[194:197], v141 offset:52224
	ds_read_b128 v[198:201], v141 offset:53248
	ds_read_b128 v[202:205], v141 offset:54272
	ds_read_b128 v[218:221], v141 offset:55296
	ds_read_b128 v[224:227], v141 offset:56320
	global_load_lds_dwordx4 v[16:17], off
	v_lshl_add_u64 v[16:17], v[228:229], 0, s[80:81]
	s_mov_b32 m0, s3
	s_nop 0
	global_load_lds_dwordx4 v[16:17], off
	s_barrier
	s_waitcnt lgkmcnt(0)
	s_setprio 1
	v_mfma_f32_16x16x32_bf16 v[16:19], v[4:7], v[24:27], v[134:137]
	v_mfma_f32_16x16x32_bf16 v[68:71], v[80:83], v[28:31], v[16:19]
	v_mfma_f32_16x16x32_bf16 v[16:19], v[178:181], v[24:27], v[142:145]
	v_mfma_f32_16x16x32_bf16 v[64:67], v[190:193], v[28:31], v[16:19]
	v_mfma_f32_16x16x32_bf16 v[16:19], v[4:7], v[40:43], v[146:149]
	v_mfma_f32_16x16x32_bf16 v[36:39], v[80:83], v[194:197], v[16:19]
	v_mfma_f32_16x16x32_bf16 v[16:19], v[178:181], v[40:43], v[150:153]
	v_mfma_f32_16x16x32_bf16 v[32:35], v[190:193], v[194:197], v[16:19]
	v_mfma_f32_16x16x32_bf16 v[16:19], v[4:7], v[198:201], v[154:157]
	v_mfma_f32_16x16x32_bf16 v[0:3], v[4:7], v[218:221], v[0:3]
	v_mfma_f32_16x16x32_bf16 v[20:23], v[80:83], v[202:205], v[16:19]
	v_mfma_f32_16x16x32_bf16 v[16:19], v[178:181], v[198:201], v[158:161]
	v_mfma_f32_16x16x32_bf16 v[4:7], v[80:83], v[224:227], v[0:3]
	v_mfma_f32_16x16x32_bf16 v[0:3], v[178:181], v[218:221], v[182:185]
	v_mfma_f32_16x16x32_bf16 v[16:19], v[190:193], v[202:205], v[16:19]
	v_mfma_f32_16x16x32_bf16 v[0:3], v[190:193], v[224:227], v[0:3]
	s_setprio 0
	s_barrier
	s_add_u32 s20, s62, 0x10080
	s_addc_u32 s21, s63, 0
	s_mov_b32 m0, s61
	s_nop 0
	global_load_lds_dwordx4 v212, s[20:21]
	s_mov_b32 m0, s60
	s_nop 0
	global_load_lds_dwordx4 v128, s[20:21]
	s_waitcnt vmcnt(6)
	s_barrier
	s_setprio 1
	v_mfma_f32_16x16x32_bf16 v[8:11], v[186:189], v[24:27], v[8:11]
	v_mfma_f32_16x16x32_bf16 v[80:83], v[242:245], v[28:31], v[8:11]
	v_mfma_f32_16x16x32_bf16 v[8:11], v[246:249], v[24:27], v[12:15]
	v_mfma_f32_16x16x32_bf16 v[72:75], v[250:253], v[28:31], v[8:11]
	v_mfma_f32_16x16x32_bf16 v[8:11], v[186:189], v[40:43], v[206:209]
	v_mfma_f32_16x16x32_bf16 v[48:51], v[242:245], v[194:197], v[8:11]
	v_mfma_f32_16x16x32_bf16 v[8:11], v[246:249], v[40:43], v[162:165]
	v_mfma_f32_16x16x32_bf16 v[40:43], v[250:253], v[194:197], v[8:11]
	v_mfma_f32_16x16x32_bf16 v[8:11], v[186:189], v[198:201], v[214:217]
	v_mfma_f32_16x16x32_bf16 v[28:31], v[242:245], v[202:205], v[8:11]
	v_mfma_f32_16x16x32_bf16 v[8:11], v[246:249], v[198:201], v[166:169]
	v_mfma_f32_16x16x32_bf16 v[24:27], v[250:253], v[202:205], v[8:11]
	v_mfma_f32_16x16x32_bf16 v[8:11], v[186:189], v[218:221], v[170:173]
	v_mfma_f32_16x16x32_bf16 v[12:15], v[242:245], v[224:227], v[8:11]
	v_mfma_f32_16x16x32_bf16 v[8:11], v[246:249], v[218:221], v[174:177]
	v_mfma_f32_16x16x32_bf16 v[8:11], v[250:253], v[224:227], v[8:11]
	s_setprio 0
	s_lshl_b32 s20, s78, 8
	s_ashr_i32 s21, s20, 31
	s_lshl_b64 s[58:59], s[20:21], 1
	s_add_u32 s13, s70, s58
	s_addc_u32 s23, s71, s59
	s_add_i32 s24, s20, 0xfffff800
	s_lshl_b64 s[20:21], s[24:25], 1
	s_add_u32 s20, s72, s20
	s_addc_u32 s21, s73, s21
	s_cmp_lt_i32 s78, 8
	s_cselect_b32 s13, s13, s20
	v_mov_b32_e32 v135, v233
	s_cselect_b32 s21, s23, s21
	v_mov_b32_e32 v136, s13
	s_lshl_b32 s13, s77, 8
	v_readlane_b32 s20, v254, 13
	s_barrier
;     __device__ __forceinline__ void operator()(Acc& acc, const Unit& u, int wv) const {
;     ...
;         float sc[8];
; #pragma unroll
;         for (int i = 0; i < 8; ++i) sc[i] = RKV[(size_t)tok0 + row0 + (i >> 2) * HALF + (i & 3) * 16];
; #pragma unroll
;         for (int i = 0; i < 8; ++i) sc[i] = rsqrtf(sc[i] * (1.f / 256.f) + EPS);
; #pragma unroll
;         for (int i = 0; i < 8; ++i) { const int row = row0 + (i >> 2) * HALF + (i & 3) * 16; bf16_t* rowp = base + (size_t)row * 2048 + col0;
; #pragma unroll
;             for (int bj = 0; bj < 2; ++bj) store8_bf16(rowp + bj * HALF, acc[i >> 2][bj][i & 3][0], acc[i >> 2][bj][i & 3][1], sc[i]); }
	s_add_i32 s13, s13, s20
	v_and_or_b32 v134, v135, 15, s13
	v_ashrrev_i32_e32 v135, 1, v135
	v_and_b32_e32 v150, -8, v135
	v_ashrrev_i32_e32 v135, 31, v134
	v_lshl_add_u64 v[138:139], v[134:135], 2, s[8:9]
	global_load_dword v142, v[138:139], off
	global_load_dword v143, v[138:139], off offset:64
	global_load_dword v144, v[138:139], off offset:128
	global_load_dword v145, v[138:139], off offset:192
	global_load_dword v151, v[138:139], off offset:512
	global_load_dword v152, v[138:139], off offset:576
	global_load_dword v153, v[138:139], off offset:640
	s_nop 0
	global_load_dword v138, v[138:139], off offset:704
	v_mov_b32_e32 v137, s21
	s_mov_b32 s13, 0x80000
	v_readlane_b32 s79, v255, 14
	s_add_i32 s76, s76, s79
	s_mov_b32 s78, s12
	s_mov_b32 s77, s22
	s_mov_b64 s[60:61], s[56:57]
	s_mov_b64 s[58:59], s[42:43]
	v_readlane_b32 s96, v255, 9
	s_movk_i32 s85, 0x1800
	v_mov_b64_e32 v[222:223], 0x14ff
	v_mov_b64_e32 v[250:251], 0x1500
	s_waitcnt vmcnt(0)
	v_fmamk_f32 v139, v142, 0x3b800000, v230
	v_cmp_gt_f32_e32 vcc, s89, v139
	v_mul_f32_e32 v142, 0x4b800000, v139
	v_fmamk_f32 v138, v138, 0x3b800000, v230
	v_cndmask_b32_e32 v139, v139, v142, vcc
	v_rsq_f32_e32 v139, v139
	s_nop 0
	v_mul_f32_e32 v142, 0x45800000, v139
	v_cndmask_b32_e32 v149, v139, v142, vcc
	v_fmamk_f32 v139, v143, 0x3b800000, v230
	v_cmp_gt_f32_e32 vcc, s89, v139
	v_mul_f32_e32 v142, 0x4b800000, v139
	v_mul_f32_e32 v124, v124, v149
	v_cndmask_b32_e32 v139, v139, v142, vcc
	v_rsq_f32_e32 v139, v139
	v_mul_f32_e32 v125, v125, v149
	v_cvt_pk_bf16_f32 v124, v124, v125
	v_mul_f32_e32 v125, v126, v149
	v_mul_f32_e32 v142, 0x45800000, v139
	v_cndmask_b32_e32 v148, v139, v142, vcc
	v_fmamk_f32 v139, v144, 0x3b800000, v230
	v_cmp_gt_f32_e32 vcc, s89, v139
	v_mul_f32_e32 v142, 0x4b800000, v139
	v_mul_f32_e32 v126, v127, v149
	v_cndmask_b32_e32 v139, v139, v142, vcc
	v_rsq_f32_e32 v139, v139
	v_mul_f32_e32 v112, v112, v149
	v_mul_f32_e32 v113, v113, v149
	v_cvt_pk_bf16_f32 v125, v125, v126
	v_mul_f32_e32 v142, 0x45800000, v139
	v_cndmask_b32_e32 v147, v139, v142, vcc
	v_fmamk_f32 v139, v145, 0x3b800000, v230
	v_cmp_gt_f32_e32 vcc, s89, v139
	v_mul_f32_e32 v142, 0x4b800000, v139
	v_cvt_pk_bf16_f32 v126, v112, v113
	v_mul_f32_e32 v112, v114, v149
	v_cndmask_b32_e32 v139, v139, v142, vcc
	v_rsq_f32_e32 v139, v139
	v_mul_f32_e32 v113, v115, v149
	v_cvt_pk_bf16_f32 v127, v112, v113
	v_mul_f32_e32 v112, v120, v149
	v_mul_f32_e32 v142, 0x45800000, v139
	v_cndmask_b32_e32 v146, v139, v142, vcc
	v_fmamk_f32 v139, v151, 0x3b800000, v230
	v_cmp_gt_f32_e32 vcc, s89, v139
	v_mul_f32_e32 v142, 0x4b800000, v139
	v_mul_f32_e32 v113, v121, v149
	v_cndmask_b32_e32 v139, v139, v142, vcc
	v_rsq_f32_e32 v139, v139
	v_mul_f32_e32 v114, v123, v149
	v_mul_f32_e32 v115, v117, v149
	v_mul_f32_e32 v100, v100, v148
	v_mul_f32_e32 v142, 0x45800000, v139
	v_cndmask_b32_e32 v145, v139, v142, vcc
	v_fmamk_f32 v139, v152, 0x3b800000, v230
	v_cmp_gt_f32_e32 vcc, s89, v139
	v_mul_f32_e32 v142, 0x4b800000, v139
	v_mul_f32_e32 v101, v101, v148
	v_cndmask_b32_e32 v139, v139, v142, vcc
	v_rsq_f32_e32 v139, v139
	v_mul_f32_e32 v96, v96, v148
	v_mul_f32_e32 v97, v97, v148
	v_mul_f32_e32 v84, v84, v147
	v_mul_f32_e32 v142, 0x45800000, v139
	v_cndmask_b32_e32 v144, v139, v142, vcc
	v_fmamk_f32 v139, v153, 0x3b800000, v230
	v_cmp_gt_f32_e32 vcc, s89, v139
	v_mul_f32_e32 v142, 0x4b800000, v139
	v_mul_f32_e32 v85, v85, v147
	v_cndmask_b32_e32 v139, v139, v142, vcc
	v_rsq_f32_e32 v139, v139
	v_mul_f32_e32 v76, v76, v147
	v_mul_f32_e32 v77, v77, v147
	v_mul_f32_e32 v52, v52, v146
	v_mul_f32_e32 v142, 0x45800000, v139
	v_cndmask_b32_e32 v143, v139, v142, vcc
	v_cmp_gt_f32_e32 vcc, s89, v138
	v_mul_f32_e32 v139, 0x4b800000, v138
	v_mul_f32_e32 v53, v53, v146
	v_cndmask_b32_e32 v138, v138, v139, vcc
	v_rsq_f32_e32 v138, v138
	v_mul_f32_e32 v44, v44, v146
	v_mul_f32_e32 v45, v45, v146
	v_mul_f32_e32 v36, v36, v144
	v_mul_f32_e32 v139, 0x45800000, v138
	v_cndmask_b32_e32 v142, v138, v139, vcc
	v_add_u32_e32 v138, s53, v150
	v_ashrrev_i32_e32 v139, 31, v138
	v_lshl_add_u64 v[136:137], v[138:139], 1, v[136:137]
	v_lshlrev_b64 v[138:139], 12, v[134:135]
	v_lshl_add_u64 v[138:139], v[136:137], 0, v[138:139]
	global_store_dwordx4 v[138:139], v[124:127], off
	v_cvt_pk_bf16_f32 v112, v112, v113
	v_mul_f32_e32 v113, v122, v149
	v_cvt_pk_bf16_f32 v113, v113, v114
	v_mul_f32_e32 v114, v116, v149
	v_cvt_pk_bf16_f32 v114, v114, v115
	v_mul_f32_e32 v115, v118, v149
	v_mul_f32_e32 v116, v119, v149
	v_cvt_pk_bf16_f32 v115, v115, v116
	global_store_dwordx4 v[138:139], v[112:115], off offset:256
	v_cvt_pk_bf16_f32 v100, v100, v101
	v_mul_f32_e32 v101, v102, v148
	v_mul_f32_e32 v102, v103, v148
	v_or_b32_e32 v112, 16, v134
	v_ashrrev_i32_e32 v113, 31, v112
	v_lshlrev_b64 v[112:113], 12, v[112:113]
	v_cvt_pk_bf16_f32 v101, v101, v102
	v_cvt_pk_bf16_f32 v102, v96, v97
	v_mul_f32_e32 v96, v98, v148
	v_mul_f32_e32 v97, v99, v148
	v_lshl_add_u64 v[112:113], v[136:137], 0, v[112:113]
	v_cvt_pk_bf16_f32 v103, v96, v97
	v_mul_f32_e32 v96, v108, v148
	v_mul_f32_e32 v97, v109, v148
	global_store_dwordx4 v[112:113], v[100:103], off
	v_cvt_pk_bf16_f32 v96, v96, v97
	v_mul_f32_e32 v97, v110, v148
	v_mul_f32_e32 v98, v111, v148
	v_cvt_pk_bf16_f32 v97, v97, v98
	v_mul_f32_e32 v98, v104, v148
	v_mul_f32_e32 v99, v105, v148
	v_cvt_pk_bf16_f32 v98, v98, v99
	v_mul_f32_e32 v99, v106, v148
	v_mul_f32_e32 v100, v107, v148
	v_cvt_pk_bf16_f32 v99, v99, v100
	global_store_dwordx4 v[112:113], v[96:99], off offset:256
	v_cvt_pk_bf16_f32 v84, v84, v85
	v_mul_f32_e32 v85, v86, v147
	v_mul_f32_e32 v86, v87, v147
	v_or_b32_e32 v96, 32, v134
;     __device__ __forceinline__ void operator()(Acc& acc, const Unit& u, int wv) const {
;     ...
;         for (int i = 0; i < 8; ++i) { const int row = row0 + (i >> 2) * HALF + (i & 3) * 16; bf16_t* rowp = base + (size_t)row * 2048 + col0;
; #pragma unroll
;             for (int bj = 0; bj < 2; ++bj) store8_bf16(rowp + bj * HALF, acc[i >> 2][bj][i & 3][0], acc[i >> 2][bj][i & 3][1], sc[i]); }
;     }
	v_ashrrev_i32_e32 v97, 31, v96
	v_lshlrev_b64 v[96:97], 12, v[96:97]
	v_cvt_pk_bf16_f32 v85, v85, v86
	v_cvt_pk_bf16_f32 v86, v76, v77
	v_mul_f32_e32 v76, v78, v147
	v_mul_f32_e32 v77, v79, v147
	v_lshl_add_u64 v[96:97], v[136:137], 0, v[96:97]
	v_cvt_pk_bf16_f32 v87, v76, v77
	v_mul_f32_e32 v76, v92, v147
	v_mul_f32_e32 v77, v93, v147
	global_store_dwordx4 v[96:97], v[84:87], off
	v_cvt_pk_bf16_f32 v76, v76, v77
	v_mul_f32_e32 v77, v94, v147
	v_mul_f32_e32 v78, v95, v147
	v_cvt_pk_bf16_f32 v77, v77, v78
	v_mul_f32_e32 v78, v88, v147
	v_mul_f32_e32 v79, v89, v147
	v_cvt_pk_bf16_f32 v78, v78, v79
	v_mul_f32_e32 v79, v90, v147
	v_mul_f32_e32 v84, v91, v147
	v_cvt_pk_bf16_f32 v79, v79, v84
	global_store_dwordx4 v[96:97], v[76:79], off offset:256
	v_cvt_pk_bf16_f32 v52, v52, v53
	v_mul_f32_e32 v53, v54, v146
	v_mul_f32_e32 v54, v55, v146
	v_or_b32_e32 v76, 48, v134
	v_ashrrev_i32_e32 v77, 31, v76
	v_lshlrev_b64 v[76:77], 12, v[76:77]
	v_cvt_pk_bf16_f32 v53, v53, v54
	v_cvt_pk_bf16_f32 v54, v44, v45
	v_mul_f32_e32 v44, v46, v146
	v_mul_f32_e32 v45, v47, v146
	v_lshl_add_u64 v[76:77], v[136:137], 0, v[76:77]
	v_cvt_pk_bf16_f32 v55, v44, v45
	v_mul_f32_e32 v44, v60, v146
	v_mul_f32_e32 v45, v61, v146
	global_store_dwordx4 v[76:77], v[52:55], off
	v_cvt_pk_bf16_f32 v44, v44, v45
	v_mul_f32_e32 v45, v62, v146
	v_mul_f32_e32 v46, v63, v146
	v_cvt_pk_bf16_f32 v45, v45, v46
	v_mul_f32_e32 v46, v56, v146
	v_mul_f32_e32 v47, v57, v146
	v_cvt_pk_bf16_f32 v46, v46, v47
	v_mul_f32_e32 v47, v58, v146
	v_mul_f32_e32 v52, v59, v146
	v_cvt_pk_bf16_f32 v47, v47, v52
	global_store_dwordx4 v[76:77], v[44:47], off offset:256
	v_mul_f32_e32 v54, v67, v145
	v_lshl_add_u64 v[52:53], v[138:139], 0, s[92:93]
	v_mul_f32_e32 v44, v68, v145
	v_mul_f32_e32 v45, v69, v145
	v_cvt_pk_bf16_f32 v44, v44, v45
	v_mul_f32_e32 v45, v70, v145
	v_mul_f32_e32 v46, v71, v145
	v_cvt_pk_bf16_f32 v45, v45, v46
	v_mul_f32_e32 v46, v64, v145
	v_mul_f32_e32 v47, v65, v145
	v_cvt_pk_bf16_f32 v46, v46, v47
	v_mul_f32_e32 v47, v66, v145
	v_cvt_pk_bf16_f32 v47, v47, v54
	v_add_co_u32_e32 v54, vcc, s13, v138
	v_mul_f32_e32 v37, v37, v144
	s_nop 0
	v_addc_co_u32_e32 v55, vcc, 0, v139, vcc
	global_store_dwordx4 v[54:55], v[44:47], off
	v_mul_f32_e32 v54, v75, v145
	v_mul_f32_e32 v32, v32, v144
	v_mul_f32_e32 v44, v80, v145
	v_mul_f32_e32 v45, v81, v145
	v_cvt_pk_bf16_f32 v44, v44, v45
	v_mul_f32_e32 v45, v82, v145
	v_mul_f32_e32 v46, v83, v145
	v_cvt_pk_bf16_f32 v45, v45, v46
	v_mul_f32_e32 v46, v72, v145
	v_mul_f32_e32 v47, v73, v145
	v_cvt_pk_bf16_f32 v46, v46, v47
	v_mul_f32_e32 v47, v74, v145
	v_cvt_pk_bf16_f32 v47, v47, v54
	global_store_dwordx4 v[52:53], v[44:47], off offset:256
	v_cvt_pk_bf16_f32 v36, v36, v37
	v_mul_f32_e32 v37, v38, v144
	v_mul_f32_e32 v38, v39, v144
	v_add_u32_e32 v44, 0x90, v134
	v_ashrrev_i32_e32 v45, 31, v44
	v_mul_f32_e32 v33, v33, v144
	v_lshlrev_b64 v[44:45], 12, v[44:45]
	v_cvt_pk_bf16_f32 v37, v37, v38
	v_cvt_pk_bf16_f32 v38, v32, v33
	v_mul_f32_e32 v32, v34, v144
	v_mul_f32_e32 v33, v35, v144
	v_lshl_add_u64 v[44:45], v[136:137], 0, v[44:45]
	v_cvt_pk_bf16_f32 v39, v32, v33
	v_mul_f32_e32 v32, v48, v144
	v_mul_f32_e32 v33, v49, v144
	global_store_dwordx4 v[44:45], v[36:39], off
	v_cvt_pk_bf16_f32 v32, v32, v33
	v_mul_f32_e32 v33, v50, v144
	v_mul_f32_e32 v34, v51, v144
	v_cvt_pk_bf16_f32 v33, v33, v34
	v_mul_f32_e32 v34, v40, v144
	v_mul_f32_e32 v35, v41, v144
	v_cvt_pk_bf16_f32 v34, v34, v35
	v_mul_f32_e32 v35, v42, v144
	v_mul_f32_e32 v36, v43, v144
	v_cvt_pk_bf16_f32 v35, v35, v36
	global_store_dwordx4 v[44:45], v[32:35], off offset:256
	v_mul_f32_e32 v20, v20, v143
	v_mul_f32_e32 v21, v21, v143
	v_add_u32_e32 v32, 0xa0, v134
	v_ashrrev_i32_e32 v33, 31, v32
	v_cvt_pk_bf16_f32 v20, v20, v21
	v_mul_f32_e32 v21, v22, v143
	v_mul_f32_e32 v22, v23, v143
	v_mul_f32_e32 v16, v16, v143
	v_mul_f32_e32 v17, v17, v143
	v_lshlrev_b64 v[32:33], 12, v[32:33]
	v_cvt_pk_bf16_f32 v21, v21, v22
	v_cvt_pk_bf16_f32 v22, v16, v17
	v_mul_f32_e32 v16, v18, v143
	v_mul_f32_e32 v17, v19, v143
	v_lshl_add_u64 v[32:33], v[136:137], 0, v[32:33]
	v_cvt_pk_bf16_f32 v23, v16, v17
	v_mul_f32_e32 v16, v28, v143
	v_mul_f32_e32 v17, v29, v143
	global_store_dwordx4 v[32:33], v[20:23], off
	v_cvt_pk_bf16_f32 v16, v16, v17
	v_mul_f32_e32 v17, v30, v143
	v_mul_f32_e32 v18, v31, v143
	v_cvt_pk_bf16_f32 v17, v17, v18
	v_mul_f32_e32 v18, v24, v143
	v_mul_f32_e32 v19, v25, v143
	v_cvt_pk_bf16_f32 v18, v18, v19
	v_mul_f32_e32 v19, v26, v143
	v_mul_f32_e32 v20, v27, v143
	v_cvt_pk_bf16_f32 v19, v19, v20
	global_store_dwordx4 v[32:33], v[16:19], off offset:256
	v_mul_f32_e32 v4, v4, v142
	v_mul_f32_e32 v5, v5, v142
	v_add_u32_e32 v16, 0xb0, v134
	v_ashrrev_i32_e32 v17, 31, v16
	v_cvt_pk_bf16_f32 v4, v4, v5
	v_mul_f32_e32 v5, v6, v142
	v_mul_f32_e32 v6, v7, v142
	v_mul_f32_e32 v0, v0, v142
	v_mul_f32_e32 v1, v1, v142
	v_lshlrev_b64 v[16:17], 12, v[16:17]
	v_cvt_pk_bf16_f32 v5, v5, v6
	v_cvt_pk_bf16_f32 v6, v0, v1
	v_mul_f32_e32 v0, v2, v142
	v_mul_f32_e32 v1, v3, v142
	v_lshl_add_u64 v[16:17], v[136:137], 0, v[16:17]
	v_cvt_pk_bf16_f32 v7, v0, v1
	v_mul_f32_e32 v0, v12, v142
	v_mul_f32_e32 v1, v13, v142
	global_store_dwordx4 v[16:17], v[4:7], off
	v_cvt_pk_bf16_f32 v0, v0, v1
	v_mul_f32_e32 v1, v14, v142
	v_mul_f32_e32 v2, v15, v142
	v_cvt_pk_bf16_f32 v1, v1, v2
	v_mul_f32_e32 v2, v8, v142
	v_mul_f32_e32 v3, v9, v142
	v_cvt_pk_bf16_f32 v2, v2, v3
	v_mul_f32_e32 v3, v10, v142
	s_andn2_b64 vcc, exec, s[6:7]
	v_mul_f32_e32 v4, v11, v142
	v_cvt_pk_bf16_f32 v3, v3, v4
	global_store_dwordx4 v[16:17], v[0:3], off offset:256
	s_cbranch_vccz .LBB0_207

; #define PG8_STAGE(bufoff, gbase, voff) do { _Pragma("unroll") for (int _i = 0; _i < 2; ++_i) \
;         __builtin_amdgcn_global_load_lds((const unsigned*)((const char*)(gbase) + (voff)[_i]), (LAS unsigned*)(lds + (bufoff) + ldsw + _i * 8192), 16, 0, 0); } while (0)
; #define PG8_WAIT_V(n) asm volatile("s_waitcnt vmcnt(" #n ")" ::: "memory")
; #define PG8_BAR __builtin_amdgcn_s_barrier()
; template <class Epi>
; __device__ __forceinline__ void gemm_phase(LAS unsigned char* lds, const Gemm g, const StaticOrder& S, const Epi& E, int wv) {
;     ...
;     const char* cA = (const char*)g.A + (size_t)cur.pm * tstep; const char* cB = (const char*)g.Bt + (size_t)cur.pn * tstep;
;     PG8_STAGE(PG8_SB(0, 0), cB, voffB); PG8_STAGE(PG8_SA(0, 0), cA, voffA); PG8_STAGE(PG8_SB(0, 1), cB + hstep, voffB); PG8_STAGE(PG8_SA(0, 1), cA + hstep, voffA);
;     if (wr == 1) PG8_BAR;
;     PG8_WAIT_V(4); PG8_BAR;
;     PG8_STAGE(PG8_SB(1, 0), cB + kstep, voffB); PG8_STAGE(PG8_SA(1, 0), cA + kstep, voffA); PG8_STAGE(PG8_SB(1, 1), cB + hstep + kstep, voffB);
;     PG8_WAIT_V(6); PG8_BAR;
.LBB0_217:
	s_add_u32 s2, s44, 0xc000000
	v_writelane_b32 v255, s2, 18
	s_addc_u32 s2, s45, 0
	s_add_u32 s22, s44, 0x3b000000
	s_addc_u32 s23, s45, 0
	s_add_u32 s42, s44, 0x38000000
	s_addc_u32 s43, s45, 0
	s_add_u32 s6, s44, 0x3e000000
	v_writelane_b32 v255, s2, 19
	s_addc_u32 s7, s45, 0
	v_writelane_b32 v255, s6, 20
	v_and_b32_e32 v15, 15, v14
	v_and_b32_e32 v17, 48, v14
	v_writelane_b32 v255, s7, 21
	v_lshlrev_b32_e32 v14, 2, v14
	v_readlane_b32 s6, v255, 10
	v_readlane_b32 s7, v255, 11
	s_lshl_b64 s[6:7], s[6:7], 19
	s_add_u32 s2, s44, s6
	s_addc_u32 s6, s45, s7
	s_add_u32 s58, s2, 0x3e800000
	s_addc_u32 s59, s6, 0
	s_add_u32 s60, s2, 0x3e840000
	s_addc_u32 s61, s6, 0
	v_readlane_b32 s2, v254, 16
	s_add_u32 s68, s44, 0x3e900000
	s_addc_u32 s69, s45, 0
	v_or_b32_e32 v16, s2, v15
	v_lshlrev_b32_e32 v18, 6, v16
	s_movk_i32 s2, 0x3c0
	v_lshlrev_b32_e32 v16, 2, v16
	s_add_u32 s70, s44, 0x3f100000
	v_and_or_b32 v18, v18, s2, v17
	v_and_b32_e32 v16, 32, v16
	v_readlane_b32 s2, v254, 7
	s_addc_u32 s71, s45, 0
	v_lshl_or_b32 v15, v15, 6, v17
	v_bitop3_b32 v16, v18, s2, v16 bitop3:0xde
	v_and_b32_e32 v14, 32, v14
	v_readlane_b32 s2, v254, 17
	v_lshl_add_u64 v[6:7], v[6:7], 0, s[80:81]
	s_add_i32 m0, s15, 0x18000
	s_ashr_i32 s97, s79, 31
	v_bitop3_b32 v148, v15, s2, v14 bitop3:0xde
	s_waitcnt vmcnt(4)
	s_barrier
	global_load_lds_dwordx4 v[6:7], off
	v_lshl_add_u64 v[2:3], v[2:3], 0, s[80:81]
	s_add_i32 m0, s15, 0x1a000
	s_add_i32 s2, s15, 0x8000
	s_add_i32 s50, s15, 0xa000
	global_load_lds_dwordx4 v[2:3], off
	v_lshl_add_u64 v[0:1], v[0:1], 0, s[80:81]
	s_mov_b32 m0, s2
	s_add_u32 s6, s10, 0x40080
	global_load_lds_dwordx4 v[0:1], off
	v_lshl_add_u64 v[0:1], v[4:5], 0, s[80:81]
	s_mov_b32 m0, s50
	s_addc_u32 s7, s11, 0
	global_load_lds_dwordx4 v[0:1], off
	s_add_i32 m0, s15, 0x1c000
	v_mov_b32_e32 v135, v213
	global_load_lds_dwordx4 v212, s[6:7]
	v_lshl_add_u64 v[0:1], s[6:7], 0, v[128:129]
	s_add_i32 m0, s15, 0x1e000
	v_readlane_b32 s6, v255, 1
	global_load_lds_dwordx4 v[0:1], off
	v_lshlrev_b32_e32 v0, 14, v11
	v_and_b32_e32 v0, 0xffff8000, v0
	v_lshl_add_u32 v0, v12, 11, v0
	v_and_b32_e32 v1, 1, v11
	v_lshl_or_b32 v0, v1, 6, v0
	v_lshl_add_u32 v134, v13, 1, v0
	v_lshlrev_b32_e32 v0, 14, v8
	v_and_b32_e32 v0, 0xffff8000, v0
	s_waitcnt vmcnt(6)
	v_lshl_add_u32 v0, v9, 11, v0
	v_and_b32_e32 v1, 1, v8
	v_lshl_or_b32 v0, v1, 6, v0
	v_lshl_add_u32 v136, v10, 1, v0
	v_mov_b32_e32 v137, v213
	s_mov_b32 s86, 0
	v_add_u32_e32 v149, 0, v16
	v_readlane_b32 s57, v254, 45
	s_mov_b32 s56, s6
	s_barrier
	v_readlane_b32 s7, v255, 2
	s_branch .LBB0_219

; #define PG8_STAGE(bufoff, gbase, voff) do { _Pragma("unroll") for (int _i = 0; _i < 2; ++_i) \
;         __builtin_amdgcn_global_load_lds((const unsigned*)((const char*)(gbase) + (voff)[_i]), (LAS unsigned*)(lds + (bufoff) + ldsw + _i * 8192), 16, 0, 0); } while (0)
; #define PG8_LDA(dst, b, h) do { _Pragma("unroll") for (int m = 0; m < 4; ++m) _Pragma("unroll") for (int k = 0; k < 2; ++k) dst[m][k] = *(const LAS bf16x8*)(lds + PG8_SA(b, h) + aoff + m * 2048 + k * 1024); } while (0)
; #define PG8_LDB(dst, b, h) do { _Pragma("unroll") for (int n = 0; n < 2; ++n) _Pragma("unroll") for (int k = 0; k < 2; ++k) dst[n][k] = *(const LAS bf16x8*)(lds + PG8_SB(b, h) + boff + n * 2048 + k * 1024); } while (0)
; #define PG8_MMA(ai, bj, At, Bt) do { __builtin_amdgcn_s_setprio(1); _Pragma("unroll") for (int m = 0; m < 4; ++m) _Pragma("unroll") for (int n = 0; n < 2; ++n) _Pragma("unroll") for (int k = 0; k < 2; ++k) \
;         acc[ai][bj][m][n] = __builtin_amdgcn_mfma_f32_16x16x32_bf16(Bt[n][k], At[m][k], acc[ai][bj][m][n], 0, 0, 0); __builtin_amdgcn_s_setprio(0); } while (0)
; #define PG8_WAIT_V(n) asm volatile("s_waitcnt vmcnt(" #n ")" ::: "memory")
; #define PG8_WAIT_L(n) asm volatile("s_waitcnt lgkmcnt(" #n ")" ::: "memory")
; template <class Epi>
; __device__ __forceinline__ void gemm_phase(LAS unsigned char* lds, const Gemm g, const StaticOrder& S, const Epi& E, int wv) {
;     ...
;         for (int t = 0; t < nt; t += 2) {
;             const bool last = (t == nt - 2);
;             const char* a1 = cA + (size_t)(t + 1) * kstep;
;             const char* a2 = last ? nA : cA + (size_t)(t + 2) * kstep; const char* b2 = last ? nB : cB + (size_t)(t + 2) * kstep;
;             const char* a3 = a2 + kstep; const char* b3 = b2 + kstep;
;             PG8_LDB(B0, 0, 0); PG8_SCHED; PG8_LDA(At, 0, 0); PG8_STAGE(PG8_SA(1, 1), a1 + hstep, voffA);
;             PG8_WAIT_L(8); PG8_BAR; PG8_WAIT_L(0); PG8_MMA(0, 0, At, B0); PG8_BAR; PG8_SCHED;
;             PG8_LDB(B1, 0, 1); PG8_STAGE(PG8_SB(0, 0), b2, voffB);
;             PG8_BAR; PG8_WAIT_L(0); PG8_MMA(0, 1, At, B1); PG8_BAR;
;             PG8_LDA(At, 0, 1); PG8_STAGE(PG8_SA(0, 0), a2, voffA);
;             PG8_BAR; PG8_WAIT_L(0); PG8_MMA(1, 0, At, B0); PG8_BAR; PG8_SCHED;
;             PG8_STAGE(PG8_SB(0, 1), b2 + hstep, voffB);
;             PG8_WAIT_V(6); PG8_BAR; PG8_MMA(1, 1, At, B1); PG8_BAR;
.LBB0_222:
	s_add_u32 s10, s8, 0xfffc0080
	s_addc_u32 s11, s9, -1
	s_add_i32 s20, 0, 0x10000
	v_add_u32_e32 v146, s20, v148
	ds_read_b128 v[138:141], v146
	ds_read_b128 v[142:145], v146 offset:1024
	ds_read_b128 v[150:153], v146 offset:2048
	ds_read_b128 v[154:157], v146 offset:3072
	s_cmp_eq_u32 s85, 12
	s_cselect_b32 s13, s34, s11
	s_cselect_b32 s12, s35, s10
	s_cselect_b32 s11, s64, s77
	s_cselect_b32 s10, s65, s73
	s_add_i32 m0, s15, 0xc000
	ds_read_b128 v[158:161], v149
	ds_read_b128 v[162:165], v149 offset:1024
	ds_read_b128 v[166:169], v149 offset:2048
	ds_read_b128 v[170:173], v149 offset:3072
	ds_read_b128 v[174:177], v149 offset:4096
	ds_read_b128 v[178:181], v149 offset:5120
	ds_read_b128 v[182:185], v149 offset:6144
	ds_read_b128 v[186:189], v149 offset:7168
	global_load_lds_dwordx4 v134, s[8:9]
	v_lshl_add_u64 v[146:147], s[8:9], 0, v[136:137]
	s_add_i32 m0, s15, 0xe000
	s_nop 0
	global_load_lds_dwordx4 v[146:147], off
	s_waitcnt lgkmcnt(8)
	s_barrier
	s_waitcnt lgkmcnt(0)
	s_setprio 1
	v_mfma_f32_16x16x32_bf16 v[124:127], v[138:141], v[158:161], v[124:127]
	v_mfma_f32_16x16x32_bf16 v[120:123], v[150:153], v[158:161], v[120:123]
	v_mfma_f32_16x16x32_bf16 v[116:119], v[138:141], v[166:169], v[116:119]
	v_mfma_f32_16x16x32_bf16 v[108:111], v[150:153], v[166:169], v[108:111]
	v_mfma_f32_16x16x32_bf16 v[100:103], v[138:141], v[174:177], v[100:103]
	v_mfma_f32_16x16x32_bf16 v[92:95], v[150:153], v[174:177], v[92:95]
	v_mfma_f32_16x16x32_bf16 v[84:87], v[138:141], v[182:185], v[84:87]
	v_mfma_f32_16x16x32_bf16 v[76:79], v[150:153], v[182:185], v[76:79]
	v_mfma_f32_16x16x32_bf16 v[124:127], v[142:145], v[162:165], v[124:127]
	v_mfma_f32_16x16x32_bf16 v[120:123], v[154:157], v[162:165], v[120:123]
	v_mfma_f32_16x16x32_bf16 v[116:119], v[142:145], v[170:173], v[116:119]
	v_mfma_f32_16x16x32_bf16 v[108:111], v[154:157], v[170:173], v[108:111]
	v_mfma_f32_16x16x32_bf16 v[100:103], v[142:145], v[178:181], v[100:103]
	v_mfma_f32_16x16x32_bf16 v[92:95], v[154:157], v[178:181], v[92:95]
	v_mfma_f32_16x16x32_bf16 v[84:87], v[142:145], v[186:189], v[84:87]
	v_mfma_f32_16x16x32_bf16 v[76:79], v[154:157], v[186:189], v[76:79]
	s_setprio 0
	s_barrier
	s_add_i32 s21, 0, 0x14000
	v_add_u32_e32 v146, s21, v148
	s_add_i32 s20, s20, s37
	ds_read_b128 v[190:193], v146
	ds_read_b128 v[194:197], v146 offset:1024
	ds_read_b128 v[198:201], v146 offset:2048
	ds_read_b128 v[202:205], v146 offset:3072
	v_lshl_add_u64 v[146:147], s[10:11], 0, v[212:213]
	s_mov_b32 m0, s20
	v_lshl_add_u64 v[206:207], s[10:11], 0, v[128:129]
	global_load_lds_dwordx4 v[146:147], off
	s_add_i32 m0, s20, 0x2000
	s_nop 0
	global_load_lds_dwordx4 v[206:207], off
	s_barrier
	s_waitcnt lgkmcnt(0)
	s_setprio 1
	v_mfma_f32_16x16x32_bf16 v[112:115], v[190:193], v[158:161], v[112:115]
	v_mfma_f32_16x16x32_bf16 v[104:107], v[198:201], v[158:161], v[104:107]
	v_mfma_f32_16x16x32_bf16 v[96:99], v[190:193], v[166:169], v[96:99]
	v_mfma_f32_16x16x32_bf16 v[88:91], v[198:201], v[166:169], v[88:91]
	v_mfma_f32_16x16x32_bf16 v[80:83], v[190:193], v[174:177], v[80:83]
	v_mfma_f32_16x16x32_bf16 v[72:75], v[198:201], v[174:177], v[72:75]
	v_mfma_f32_16x16x32_bf16 v[68:71], v[190:193], v[182:185], v[68:71]
	v_mfma_f32_16x16x32_bf16 v[64:67], v[198:201], v[182:185], v[64:67]
	v_mfma_f32_16x16x32_bf16 v[112:115], v[194:197], v[162:165], v[112:115]
	v_mfma_f32_16x16x32_bf16 v[104:107], v[202:205], v[162:165], v[104:107]
	v_mfma_f32_16x16x32_bf16 v[96:99], v[194:197], v[170:173], v[96:99]
	v_mfma_f32_16x16x32_bf16 v[88:91], v[202:205], v[170:173], v[88:91]
	v_mfma_f32_16x16x32_bf16 v[80:83], v[194:197], v[178:181], v[80:83]
	v_mfma_f32_16x16x32_bf16 v[72:75], v[202:205], v[178:181], v[72:75]
	v_mfma_f32_16x16x32_bf16 v[68:71], v[194:197], v[186:189], v[68:71]
	v_mfma_f32_16x16x32_bf16 v[64:67], v[202:205], v[186:189], v[64:67]
	s_setprio 0
	s_mov_b32 m0, s15
	v_lshl_add_u64 v[208:209], s[12:13], 0, v[132:133]
	s_barrier
	ds_read_b128 v[158:161], v149 offset:16384
	ds_read_b128 v[162:165], v149 offset:17408
	ds_read_b128 v[166:169], v149 offset:18432
	ds_read_b128 v[170:173], v149 offset:19456
	ds_read_b128 v[174:177], v149 offset:20480
	ds_read_b128 v[178:181], v149 offset:21504
	ds_read_b128 v[182:185], v149 offset:22528
	ds_read_b128 v[186:189], v149 offset:23552
	global_load_lds_dwordx4 v[208:209], off
	v_lshl_add_u64 v[210:211], s[12:13], 0, v[130:131]
	s_mov_b32 m0, s24
	s_nop 0
	global_load_lds_dwordx4 v[210:211], off
	s_barrier
	s_waitcnt lgkmcnt(0)
	s_setprio 1
	v_mfma_f32_16x16x32_bf16 v[60:63], v[138:141], v[158:161], v[60:63]
	v_mfma_f32_16x16x32_bf16 v[56:59], v[150:153], v[158:161], v[56:59]
	v_mfma_f32_16x16x32_bf16 v[52:55], v[138:141], v[166:169], v[52:55]
	v_mfma_f32_16x16x32_bf16 v[44:47], v[150:153], v[166:169], v[44:47]
	v_mfma_f32_16x16x32_bf16 v[36:39], v[138:141], v[174:177], v[36:39]
	v_mfma_f32_16x16x32_bf16 v[28:31], v[150:153], v[174:177], v[28:31]
	v_mfma_f32_16x16x32_bf16 v[20:23], v[138:141], v[182:185], v[20:23]
	v_mfma_f32_16x16x32_bf16 v[12:15], v[150:153], v[182:185], v[12:15]
	v_mfma_f32_16x16x32_bf16 v[60:63], v[142:145], v[162:165], v[60:63]
	v_mfma_f32_16x16x32_bf16 v[56:59], v[154:157], v[162:165], v[56:59]
	v_mfma_f32_16x16x32_bf16 v[52:55], v[142:145], v[170:173], v[52:55]
	v_mfma_f32_16x16x32_bf16 v[44:47], v[154:157], v[170:173], v[44:47]
	v_mfma_f32_16x16x32_bf16 v[36:39], v[142:145], v[178:181], v[36:39]
	v_mfma_f32_16x16x32_bf16 v[28:31], v[154:157], v[178:181], v[28:31]
	v_mfma_f32_16x16x32_bf16 v[20:23], v[142:145], v[186:189], v[20:23]
	v_mfma_f32_16x16x32_bf16 v[12:15], v[154:157], v[186:189], v[12:15]
	s_setprio 0
	s_barrier
; #define PG8_STAGE(bufoff, gbase, voff) do { _Pragma("unroll") for (int _i = 0; _i < 2; ++_i) \
;         __builtin_amdgcn_global_load_lds((const unsigned*)((const char*)(gbase) + (voff)[_i]), (LAS unsigned*)(lds + (bufoff) + ldsw + _i * 8192), 16, 0, 0); } while (0)
; #define PG8_LDA(dst, b, h) do { _Pragma("unroll") for (int m = 0; m < 4; ++m) _Pragma("unroll") for (int k = 0; k < 2; ++k) dst[m][k] = *(const LAS bf16x8*)(lds + PG8_SA(b, h) + aoff + m * 2048 + k * 1024); } while (0)
; #define PG8_LDB(dst, b, h) do { _Pragma("unroll") for (int n = 0; n < 2; ++n) _Pragma("unroll") for (int k = 0; k < 2; ++k) dst[n][k] = *(const LAS bf16x8*)(lds + PG8_SB(b, h) + boff + n * 2048 + k * 1024); } while (0)
; #define PG8_MMA(ai, bj, At, Bt) do { __builtin_amdgcn_s_setprio(1); _Pragma("unroll") for (int m = 0; m < 4; ++m) _Pragma("unroll") for (int n = 0; n < 2; ++n) _Pragma("unroll") for (int k = 0; k < 2; ++k) \
;         acc[ai][bj][m][n] = __builtin_amdgcn_mfma_f32_16x16x32_bf16(Bt[n][k], At[m][k], acc[ai][bj][m][n], 0, 0, 0); __builtin_amdgcn_s_setprio(0); } while (0)
; #define PG8_WAIT_V(n) asm volatile("s_waitcnt vmcnt(" #n ")" ::: "memory")
; #define PG8_WAIT_L(n) asm volatile("s_waitcnt lgkmcnt(" #n ")" ::: "memory")
; #define PG8_BAR __builtin_amdgcn_s_barrier()
; #define PG8_SCHED __builtin_amdgcn_sched_barrier(0)
; template <class Epi>
; __device__ __forceinline__ void gemm_phase(LAS unsigned char* lds, const Gemm g, const StaticOrder& S, const Epi& E, int wv) {
;     ...
;             PG8_WAIT_V(6); PG8_BAR; PG8_MMA(1, 1, At, B1); PG8_BAR;
;             PG8_LDB(B0, 1, 0); PG8_SCHED; PG8_LDA(At, 1, 0); PG8_STAGE(PG8_SA(0, 1), a2 + hstep, voffA);
;             PG8_WAIT_L(8); PG8_BAR; PG8_WAIT_L(0); PG8_MMA(0, 0, At, B0); PG8_BAR; PG8_SCHED;
;             PG8_LDB(B1, 1, 1); PG8_STAGE(PG8_SB(1, 0), b3, voffB);
;             PG8_BAR; PG8_WAIT_L(0); PG8_MMA(0, 1, At, B1); PG8_BAR;
;             PG8_LDA(At, 1, 1); PG8_STAGE(PG8_SA(1, 0), a3, voffA);
;             PG8_BAR; PG8_WAIT_L(0); PG8_MMA(1, 0, At, B0); PG8_BAR; PG8_SCHED;
	s_add_u32 vcc_lo, s10, 0x40000
	s_addc_u32 vcc_hi, s11, 0
	s_add_i32 s20, s21, s37
	v_lshl_add_u64 v[138:139], vcc, 0, v[212:213]
	s_mov_b32 m0, s20
	s_nop 0
	global_load_lds_dwordx4 v[138:139], off
	v_lshl_add_u64 v[138:139], vcc, 0, v[128:129]
	s_add_i32 m0, s20, 0x2000
	s_nop 0
	global_load_lds_dwordx4 v[138:139], off
	s_waitcnt vmcnt(6)
	s_barrier
	s_setprio 1
	v_mfma_f32_16x16x32_bf16 v[48:51], v[190:193], v[158:161], v[48:51]
	v_mfma_f32_16x16x32_bf16 v[40:43], v[198:201], v[158:161], v[40:43]
	v_mfma_f32_16x16x32_bf16 v[32:35], v[190:193], v[166:169], v[32:35]
	v_mfma_f32_16x16x32_bf16 v[24:27], v[198:201], v[166:169], v[24:27]
	v_mfma_f32_16x16x32_bf16 v[16:19], v[190:193], v[174:177], v[16:19]
	v_mfma_f32_16x16x32_bf16 v[8:11], v[198:201], v[174:177], v[8:11]
	v_mfma_f32_16x16x32_bf16 v[4:7], v[190:193], v[182:185], v[4:7]
	v_mfma_f32_16x16x32_bf16 v[0:3], v[198:201], v[182:185], v[0:3]
	v_mfma_f32_16x16x32_bf16 v[48:51], v[194:197], v[162:165], v[48:51]
	v_mfma_f32_16x16x32_bf16 v[40:43], v[202:205], v[162:165], v[40:43]
	v_mfma_f32_16x16x32_bf16 v[32:35], v[194:197], v[170:173], v[32:35]
	v_mfma_f32_16x16x32_bf16 v[24:27], v[202:205], v[170:173], v[24:27]
	v_mfma_f32_16x16x32_bf16 v[16:19], v[194:197], v[178:181], v[16:19]
	v_mfma_f32_16x16x32_bf16 v[8:11], v[202:205], v[178:181], v[8:11]
	v_mfma_f32_16x16x32_bf16 v[4:7], v[194:197], v[186:189], v[4:7]
	v_mfma_f32_16x16x32_bf16 v[0:3], v[202:205], v[186:189], v[0:3]
	s_setprio 0
	s_add_i32 s20, 0, 0x18000
	v_add_u32_e32 v154, s20, v148
	s_barrier
	ds_read_b128 v[138:141], v154
	ds_read_b128 v[142:145], v154 offset:1024
	ds_read_b128 v[150:153], v154 offset:2048
	ds_read_b128 v[154:157], v154 offset:3072
	s_add_u32 s12, s12, 0x40000
	s_addc_u32 s13, s13, 0
	s_mov_b32 m0, s46
	ds_read_b128 v[158:161], v149 offset:32768
	ds_read_b128 v[162:165], v149 offset:33792
	ds_read_b128 v[166:169], v149 offset:34816
	ds_read_b128 v[170:173], v149 offset:35840
	ds_read_b128 v[174:177], v149 offset:36864
	ds_read_b128 v[178:181], v149 offset:37888
	ds_read_b128 v[182:185], v149 offset:38912
	ds_read_b128 v[186:189], v149 offset:39936
	global_load_lds_dwordx4 v132, s[12:13]
	s_mov_b32 m0, s47
	s_nop 0
	global_load_lds_dwordx4 v130, s[12:13]
	s_waitcnt lgkmcnt(8)
	s_barrier
	s_waitcnt lgkmcnt(0)
	s_setprio 1
	v_mfma_f32_16x16x32_bf16 v[124:127], v[138:141], v[158:161], v[124:127]
	v_mfma_f32_16x16x32_bf16 v[120:123], v[150:153], v[158:161], v[120:123]
	v_mfma_f32_16x16x32_bf16 v[116:119], v[138:141], v[166:169], v[116:119]
	v_mfma_f32_16x16x32_bf16 v[108:111], v[150:153], v[166:169], v[108:111]
	v_mfma_f32_16x16x32_bf16 v[100:103], v[138:141], v[174:177], v[100:103]
	v_mfma_f32_16x16x32_bf16 v[92:95], v[150:153], v[174:177], v[92:95]
	v_mfma_f32_16x16x32_bf16 v[84:87], v[138:141], v[182:185], v[84:87]
	v_mfma_f32_16x16x32_bf16 v[76:79], v[150:153], v[182:185], v[76:79]
	v_mfma_f32_16x16x32_bf16 v[124:127], v[142:145], v[162:165], v[124:127]
	v_mfma_f32_16x16x32_bf16 v[120:123], v[154:157], v[162:165], v[120:123]
	v_mfma_f32_16x16x32_bf16 v[116:119], v[142:145], v[170:173], v[116:119]
	v_mfma_f32_16x16x32_bf16 v[108:111], v[154:157], v[170:173], v[108:111]
	v_mfma_f32_16x16x32_bf16 v[100:103], v[142:145], v[178:181], v[100:103]
	v_mfma_f32_16x16x32_bf16 v[92:95], v[154:157], v[178:181], v[92:95]
	v_mfma_f32_16x16x32_bf16 v[84:87], v[142:145], v[186:189], v[84:87]
	v_mfma_f32_16x16x32_bf16 v[76:79], v[154:157], v[186:189], v[76:79]
	s_setprio 0
	s_barrier
	s_add_i32 s12, 0, 0x1c000
	s_add_i32 s13, s20, s37
	v_add_u32_e32 v202, s12, v148
	v_lshl_add_u64 v[146:147], v[146:147], 0, s[80:81]
	s_mov_b32 m0, s13
	ds_read_b128 v[190:193], v202
	ds_read_b128 v[194:197], v202 offset:1024
	ds_read_b128 v[198:201], v202 offset:2048
	ds_read_b128 v[202:205], v202 offset:3072
	global_load_lds_dwordx4 v[146:147], off
	v_lshl_add_u64 v[146:147], v[206:207], 0, s[80:81]
	s_add_i32 m0, s13, 0x2000
	s_nop 0
	global_load_lds_dwordx4 v[146:147], off
	s_barrier
	s_waitcnt lgkmcnt(0)
	s_setprio 1
	v_mfma_f32_16x16x32_bf16 v[112:115], v[190:193], v[158:161], v[112:115]
	v_mfma_f32_16x16x32_bf16 v[104:107], v[198:201], v[158:161], v[104:107]
	v_mfma_f32_16x16x32_bf16 v[96:99], v[190:193], v[166:169], v[96:99]
	v_mfma_f32_16x16x32_bf16 v[88:91], v[198:201], v[166:169], v[88:91]
	v_mfma_f32_16x16x32_bf16 v[80:83], v[190:193], v[174:177], v[80:83]
	v_mfma_f32_16x16x32_bf16 v[72:75], v[198:201], v[174:177], v[72:75]
	v_mfma_f32_16x16x32_bf16 v[68:71], v[190:193], v[182:185], v[68:71]
	v_mfma_f32_16x16x32_bf16 v[64:67], v[198:201], v[182:185], v[64:67]
	v_mfma_f32_16x16x32_bf16 v[112:115], v[194:197], v[162:165], v[112:115]
	v_mfma_f32_16x16x32_bf16 v[104:107], v[202:205], v[162:165], v[104:107]
	v_mfma_f32_16x16x32_bf16 v[96:99], v[194:197], v[170:173], v[96:99]
	v_mfma_f32_16x16x32_bf16 v[88:91], v[202:205], v[170:173], v[88:91]
	v_mfma_f32_16x16x32_bf16 v[80:83], v[194:197], v[178:181], v[80:83]
	v_mfma_f32_16x16x32_bf16 v[72:75], v[202:205], v[178:181], v[72:75]
	v_mfma_f32_16x16x32_bf16 v[68:71], v[194:197], v[186:189], v[68:71]
	v_mfma_f32_16x16x32_bf16 v[64:67], v[202:205], v[186:189], v[64:67]
	s_setprio 0
	s_mov_b32 m0, s2
	v_lshl_add_u64 v[146:147], v[208:209], 0, s[80:81]
	s_barrier
	ds_read_b128 v[158:161], v149 offset:49152
	ds_read_b128 v[162:165], v149 offset:50176
	ds_read_b128 v[166:169], v149 offset:51200
	ds_read_b128 v[170:173], v149 offset:52224
	ds_read_b128 v[174:177], v149 offset:53248
	ds_read_b128 v[178:181], v149 offset:54272
	ds_read_b128 v[182:185], v149 offset:55296
	ds_read_b128 v[186:189], v149 offset:56320
	global_load_lds_dwordx4 v[146:147], off
	v_lshl_add_u64 v[146:147], v[210:211], 0, s[80:81]
	s_mov_b32 m0, s50
	s_nop 0
	global_load_lds_dwordx4 v[146:147], off
	s_barrier
; #define PG8_BAR __builtin_amdgcn_s_barrier()
; template <class Epi>
; __device__ __forceinline__ void gemm_phase(LAS unsigned char* lds, const Gemm g, const StaticOrder& S, const Epi& E, int wv) {
;     ...
;             PG8_BAR; PG8_WAIT_L(0); PG8_MMA(1, 0, At, B0); PG8_BAR; PG8_SCHED;
;             PG8_STAGE(PG8_SB(1, 1), b3 + hstep, voffB);
;             PG8_WAIT_V(6); PG8_BAR; PG8_MMA(1, 1, At, B1); PG8_BAR;
;     __device__ __forceinline__ void operator()(const Acc& acc, const Unit& u, int wv) const {
;         const int wr = wv >> 2, wc = wv & 3, ln_ = opaque_lane(), fr = ln_ & 15, fq = ln_ >> 4;
;         const int pn = u.pn;
;         if (pn < 8) { tile_store_bf16(acc, Z + pn * 256, 2048, u.pm, wr, wc, fr, fq, 1.f); return; }
;         const int row0 = u.pm * BM + wr * 64 + fr, col0 = wc * 32 + 8 * fq;
; #pragma unroll
;         for (int ai = 0; ai < 2; ++ai)
; #pragma unroll
;             for (int m = 0; m < 4; ++m) { const size_t row = (size_t)(row0 + ai * HALF + m * 16);
;                 float ss;
;                 if (pn == 8) { bf16_t* rp = CKV + row * 256 + col0; store8_bf16(rp, acc[ai][0][m][0], acc[ai][0][m][1], 1.f); store8_bf16(rp + HALF, acc[ai][1][m][0], acc[ai][1][m][1], 1.f);
;                     ss = sumsq8(acc[ai][0][m][0], acc[ai][0][m][1]) + sumsq8(acc[ai][1][m][0], acc[ai][1][m][1]); }
;                 else if (pn == 9) { bf16_t* rp = CQ + row * 384 + col0; store8_bf16(rp, acc[ai][0][m][0], acc[ai][0][m][1], 1.f); store8_bf16(rp + HALF, acc[ai][1][m][0], acc[ai][1][m][1], 1.f);
;                     ss = sumsq8(acc[ai][0][m][0], acc[ai][0][m][1]) + sumsq8(acc[ai][1][m][0], acc[ai][1][m][1]); }
;                 else { store8_bf16(CQ + row * 384 + 256 + col0, acc[ai][0][m][0], acc[ai][0][m][1], 1.f);
;                     ss = sumsq8(acc[ai][0][m][0], acc[ai][0][m][1]);
;                     if (wc < 2) { const int i0 = col0 >> 1; const f32x4 cs = *(const f32x4*)(COS + row * 32 + i0), sn = *(const f32x4*)(SIN + row * 32 + i0);
;                         const f32x4 v0 = acc[ai][1][m][0], v1 = acc[ai][1][m][1]; f32x4 w0, w1;
;                         w0[0] = v0[0] * cs[0] - v0[1] * sn[0]; w0[1] = v0[1] * cs[0] + v0[0] * sn[0];
;                         w0[2] = v0[2] * cs[1] - v0[3] * sn[1]; w0[3] = v0[3] * cs[1] + v0[2] * sn[1];
;                         w1[0] = v1[0] * cs[2] - v1[1] * sn[2]; w1[1] = v1[1] * cs[2] + v1[0] * sn[2];
	s_waitcnt lgkmcnt(0)
	s_setprio 1
	v_mfma_f32_16x16x32_bf16 v[60:63], v[138:141], v[158:161], v[60:63]
	v_mfma_f32_16x16x32_bf16 v[56:59], v[150:153], v[158:161], v[56:59]
	v_mfma_f32_16x16x32_bf16 v[52:55], v[138:141], v[166:169], v[52:55]
	v_mfma_f32_16x16x32_bf16 v[44:47], v[150:153], v[166:169], v[44:47]
	v_mfma_f32_16x16x32_bf16 v[36:39], v[138:141], v[174:177], v[36:39]
	v_mfma_f32_16x16x32_bf16 v[28:31], v[150:153], v[174:177], v[28:31]
	v_mfma_f32_16x16x32_bf16 v[20:23], v[138:141], v[182:185], v[20:23]
	v_mfma_f32_16x16x32_bf16 v[12:15], v[150:153], v[182:185], v[12:15]
	v_mfma_f32_16x16x32_bf16 v[60:63], v[142:145], v[162:165], v[60:63]
	v_mfma_f32_16x16x32_bf16 v[56:59], v[154:157], v[162:165], v[56:59]
	v_mfma_f32_16x16x32_bf16 v[52:55], v[142:145], v[170:173], v[52:55]
	v_mfma_f32_16x16x32_bf16 v[44:47], v[154:157], v[170:173], v[44:47]
	v_mfma_f32_16x16x32_bf16 v[36:39], v[142:145], v[178:181], v[36:39]
	v_mfma_f32_16x16x32_bf16 v[28:31], v[154:157], v[178:181], v[28:31]
	v_mfma_f32_16x16x32_bf16 v[20:23], v[142:145], v[186:189], v[20:23]
	v_mfma_f32_16x16x32_bf16 v[12:15], v[154:157], v[186:189], v[12:15]
	s_setprio 0
	s_barrier
	s_add_u32 s10, s10, 0x40080
	s_addc_u32 s11, s11, 0
	s_add_i32 s12, s12, s37
	s_mov_b32 m0, s12
	s_nop 0
	global_load_lds_dwordx4 v212, s[10:11]
	v_lshl_add_u64 v[138:139], s[10:11], 0, v[128:129]
	s_add_i32 m0, s12, 0x2000
	s_nop 0
	global_load_lds_dwordx4 v[138:139], off
	s_waitcnt vmcnt(6)
	s_barrier
	s_setprio 1
	v_mfma_f32_16x16x32_bf16 v[48:51], v[190:193], v[158:161], v[48:51]
	v_mfma_f32_16x16x32_bf16 v[40:43], v[198:201], v[158:161], v[40:43]
	v_mfma_f32_16x16x32_bf16 v[32:35], v[190:193], v[166:169], v[32:35]
	v_mfma_f32_16x16x32_bf16 v[24:27], v[198:201], v[166:169], v[24:27]
	v_mfma_f32_16x16x32_bf16 v[16:19], v[190:193], v[174:177], v[16:19]
	v_mfma_f32_16x16x32_bf16 v[8:11], v[198:201], v[174:177], v[8:11]
	v_mfma_f32_16x16x32_bf16 v[4:7], v[190:193], v[182:185], v[4:7]
	v_mfma_f32_16x16x32_bf16 v[0:3], v[198:201], v[182:185], v[0:3]
	v_mfma_f32_16x16x32_bf16 v[48:51], v[194:197], v[162:165], v[48:51]
	v_mfma_f32_16x16x32_bf16 v[40:43], v[202:205], v[162:165], v[40:43]
	v_mfma_f32_16x16x32_bf16 v[32:35], v[194:197], v[170:173], v[32:35]
	v_mfma_f32_16x16x32_bf16 v[24:27], v[202:205], v[170:173], v[24:27]
	v_mfma_f32_16x16x32_bf16 v[16:19], v[194:197], v[178:181], v[16:19]
	v_mfma_f32_16x16x32_bf16 v[8:11], v[202:205], v[178:181], v[8:11]
	v_mfma_f32_16x16x32_bf16 v[4:7], v[194:197], v[186:189], v[4:7]
	v_mfma_f32_16x16x32_bf16 v[0:3], v[202:205], v[186:189], v[0:3]
	s_setprio 0
	s_add_i32 s85, s85, 2
	s_add_u32 s8, s8, 0x100
	s_addc_u32 s9, s9, 0
	s_add_u32 s73, s73, 0x100
	s_addc_u32 s77, s77, 0
	s_cmp_gt_u32 s85, 13
	s_barrier
	s_cbranch_scc0 .LBB0_222
	v_mov_b32_e32 v146, v233
	v_readlane_b32 s10, v254, 20
	v_ashrrev_i32_e32 v138, 4, v146
	v_and_b32_e32 v150, 15, v146
	s_mov_b64 s[8:9], -1
	s_cmp_gt_i32 s57, 7
	v_lshl_add_u32 v138, v138, 3, s10
	s_movk_i32 s85, 0x1800
	s_cbranch_scc0 .LBB0_321
	s_lshl_b32 s8, s56, 8
	v_readlane_b32 s9, v254, 16
	s_add_i32 s8, s8, s9
	s_cmp_lg_u32 s57, 8
	v_or_b32_e32 v140, s8, v150
	s_cselect_b64 s[10:11], -1, 0
	s_cmp_lg_u32 s57, 9
	v_ashrrev_i32_e32 v142, 1, v138
	s_cselect_b64 s[64:65], -1, 0
	v_ashrrev_i32_e32 v139, 31, v138
	v_ashrrev_i32_e32 v143, 31, v142
	v_ashrrev_i32_e32 v141, 31, v140
	s_mov_b64 s[8:9], -1
	s_and_b64 vcc, exec, s[10:11]
	s_cbranch_vccz .LBB0_232
	v_mov_b64_e32 v[144:145], s[42:43]
	s_movk_i32 s8, 0x300
	v_mad_i64_i32 v[144:145], s[8:9], v140, s8, v[144:145]
	s_mov_b64 s[8:9], -1
	s_and_b64 vcc, exec, s[64:65]
	v_lshl_add_u64 v[144:145], v[138:139], 1, v[144:145]
	s_cbranch_vccz .LBB0_229
	v_readlane_b32 s8, v254, 21
	v_readlane_b32 s9, v254, 22
	s_andn2_b64 vcc, exec, s[8:9]
	v_cvt_pk_bf16_f32 v152, v124, v125
	v_cvt_pk_bf16_f32 v153, v126, v127
	v_cvt_pk_bf16_f32 v154, v120, v121
	v_cvt_pk_bf16_f32 v155, v122, v123
	global_store_dwordx4 v[144:145], v[152:155], off offset:512
	s_cbranch_vccnz .LBB0_228
	v_lshlrev_b64 v[160:161], 7, v[140:141]
	v_lshl_add_u64 v[152:153], s[68:69], 0, v[160:161]
	v_lshlrev_b64 v[156:157], 2, v[142:143]
	v_lshl_add_u64 v[158:159], s[70:71], 0, v[160:161]
	v_lshl_add_u64 v[152:153], v[152:153], 0, v[156:157]
	v_lshl_add_u64 v[156:157], v[158:159], 0, v[156:157]
	global_load_dwordx4 v[152:155], v[152:153], off
	v_readlane_b32 s8, v255, 20
	global_load_dwordx4 v[156:159], v[156:157], off
	v_readlane_b32 s9, v255, 21
	s_waitcnt vmcnt(0)
	v_mov_b32_e32 v162, v152
	v_mov_b32_e32 v163, v156
	v_pk_mul_f32 v[162:163], v[112:113], v[162:163]
	s_nop 0
	v_sub_f32_e32 v147, v162, v163
	v_mov_b32_e32 v162, v156
	v_mov_b32_e32 v163, v152
	v_pk_mul_f32 v[162:163], v[112:113], v[162:163]
	v_mov_b32_e32 v156, v153
	v_mov_b32_e32 v152, v157
	v_add_f32_e32 v151, v163, v162
	v_pk_mul_f32 v[162:163], v[114:115], v[156:157]
	v_pk_mul_f32 v[152:153], v[114:115], v[152:153]
	v_sub_f32_e32 v162, v162, v163
	v_add_f32_e32 v163, v153, v152
	v_mov_b32_e32 v152, v154
	v_mov_b32_e32 v153, v158
	v_pk_mul_f32 v[152:153], v[104:105], v[152:153]
	s_nop 0
	v_sub_f32_e32 v164, v152, v153
	v_mov_b32_e32 v152, v158
	v_mov_b32_e32 v153, v154
	v_pk_mul_f32 v[152:153], v[104:105], v[152:153]
	v_mov_b32_e32 v158, v155
	v_add_f32_e32 v165, v153, v152
	v_pk_mul_f32 v[152:153], v[106:107], v[158:159]
	v_mov_b32_e32 v154, v159
	v_sub_f32_e32 v158, v152, v153
	v_pk_mul_f32 v[152:153], v[106:107], v[154:155]
	s_nop 0
	v_add_f32_e32 v155, v153, v152
	v_lshl_add_u64 v[152:153], s[8:9], 0, v[160:161]
	v_lshl_add_u64 v[156:157], v[138:139], 1, v[152:153]
	v_cvt_pk_bf16_f32 v152, v147, v151
	v_cvt_pk_bf16_f32 v153, v162, v163
	v_cvt_pk_bf16_f32 v154, v164, v165
	v_cvt_pk_bf16_f32 v155, v158, v155
	global_store_dwordx4 v[156:157], v[152:155], off

; #define PG8_STAGE(bufoff, gbase, voff) do { _Pragma("unroll") for (int _i = 0; _i < 2; ++_i) \
;         __builtin_amdgcn_global_load_lds((const unsigned*)((const char*)(gbase) + (voff)[_i]), (LAS unsigned*)(lds + (bufoff) + ldsw + _i * 8192), 16, 0, 0); } while (0)
; #define PG8_WAIT_V(n) asm volatile("s_waitcnt vmcnt(" #n ")" ::: "memory")
; #define PG8_BAR __builtin_amdgcn_s_barrier()
; template <class Epi>
; __device__ __forceinline__ void gemm_phase(LAS unsigned char* lds, const Gemm g, const StaticOrder& S, const Epi& E, int wv) {
;     ...
;     const char* cA = (const char*)g.A + (size_t)cur.pm * tstep; const char* cB = (const char*)g.Bt + (size_t)cur.pn * tstep;
;     PG8_STAGE(PG8_SB(0, 0), cB, voffB); PG8_STAGE(PG8_SA(0, 0), cA, voffA); PG8_STAGE(PG8_SB(0, 1), cB + hstep, voffB); PG8_STAGE(PG8_SA(0, 1), cA + hstep, voffA);
;     if (wr == 1) PG8_BAR;
;     PG8_WAIT_V(4); PG8_BAR;
;     PG8_STAGE(PG8_SB(1, 0), cB + kstep, voffB); PG8_STAGE(PG8_SA(1, 0), cA + kstep, voffA); PG8_STAGE(PG8_SB(1, 1), cB + hstep + kstep, voffB);
;     PG8_WAIT_V(6); PG8_BAR;
.LBB0_415:
	s_add_u32 s42, s44, 0x3f910000
	s_addc_u32 s43, s45, 0
	s_lshl_b32 s6, s51, 10
	s_addk_i32 s6, 0xfc00
	s_ashr_i32 s7, s6, 31
	s_lshl_b64 s[6:7], s[6:7], 2
	s_waitcnt lgkmcnt(0)
	s_add_u32 s56, s8, s6
	s_addc_u32 s57, s9, s7
	s_add_u32 s10, s10, s6
	v_and_b32_e32 v15, 15, v14
	v_and_b32_e32 v16, 48, v14
	v_lshlrev_b32_e32 v14, 2, v14
	s_addc_u32 s11, s11, s7
	v_lshl_or_b32 v15, v15, 6, v16
	v_and_b32_e32 v14, 32, v14
	v_readlane_b32 s6, v254, 7
	v_lshl_add_u64 v[6:7], v[6:7], 0, s[80:81]
	s_add_i32 m0, s24, 0x18000
	s_ashr_i32 s51, s79, 31
	v_bitop3_b32 v16, v15, s6, v14 bitop3:0xde
	v_readlane_b32 s6, v254, 8
	s_waitcnt vmcnt(4)
	s_barrier
	global_load_lds_dwordx4 v[6:7], off
	v_lshl_add_u64 v[4:5], v[4:5], 0, s[80:81]
	s_add_i32 m0, s24, 0x1a000
	s_add_i32 s72, s24, 0x8000
	s_add_i32 s73, s24, 0xa000
	v_bitop3_b32 v192, v15, s6, v14 bitop3:0xde
	global_load_lds_dwordx4 v[4:5], off
	v_lshl_add_u64 v[0:1], v[0:1], 0, s[80:81]
	s_mov_b32 m0, s72
	s_add_u32 s6, s64, 0x80080
	global_load_lds_dwordx4 v[0:1], off
	v_lshl_add_u64 v[0:1], v[2:3], 0, s[80:81]
	s_mov_b32 m0, s73
	s_addc_u32 s7, s65, 0
	global_load_lds_dwordx4 v[0:1], off
	s_add_i32 m0, s24, 0x1c000
	v_mov_b32_e32 v167, v213
	global_load_lds_dwordx4 v212, s[6:7]
	v_lshl_add_u64 v[0:1], s[6:7], 0, v[164:165]
	s_add_i32 m0, s24, 0x1e000
	v_readlane_b32 s6, v255, 5
	global_load_lds_dwordx4 v[0:1], off
	v_lshlrev_b32_e32 v0, 15, v11
	v_and_b32_e32 v0, 0xffff0000, v0
	v_lshl_add_u32 v0, v12, 12, v0
	v_and_b32_e32 v1, 1, v11
	v_lshl_or_b32 v0, v1, 6, v0
	v_lshl_add_u32 v166, v13, 1, v0
	v_lshlrev_b32_e32 v0, 15, v8
	v_and_b32_e32 v0, 0xffff0000, v0
	s_waitcnt vmcnt(6)
	v_lshl_add_u32 v0, v9, 12, v0
	v_and_b32_e32 v1, 1, v8
	v_lshl_or_b32 v0, v1, 6, v0
	v_lshl_add_u32 v168, v10, 1, v0
	v_mov_b32_e32 v169, v213
	s_mov_b32 s76, 0
	v_add_u32_e32 v193, 0, v16
	v_readlane_b32 s77, v254, 51
	s_mov_b32 s78, s6
	s_barrier
	v_readlane_b32 s7, v255, 6
	s_branch .LBB0_417

; #define PG8_STAGE(bufoff, gbase, voff) do { _Pragma("unroll") for (int _i = 0; _i < 2; ++_i) \
;         __builtin_amdgcn_global_load_lds((const unsigned*)((const char*)(gbase) + (voff)[_i]), (LAS unsigned*)(lds + (bufoff) + ldsw + _i * 8192), 16, 0, 0); } while (0)
; #define PG8_LDA(dst, b, h) do { _Pragma("unroll") for (int m = 0; m < 4; ++m) _Pragma("unroll") for (int k = 0; k < 2; ++k) dst[m][k] = *(const LAS bf16x8*)(lds + PG8_SA(b, h) + aoff + m * 2048 + k * 1024); } while (0)
; #define PG8_LDB(dst, b, h) do { _Pragma("unroll") for (int n = 0; n < 2; ++n) _Pragma("unroll") for (int k = 0; k < 2; ++k) dst[n][k] = *(const LAS bf16x8*)(lds + PG8_SB(b, h) + boff + n * 2048 + k * 1024); } while (0)
; #define PG8_MMA(ai, bj, At, Bt) do { __builtin_amdgcn_s_setprio(1); _Pragma("unroll") for (int m = 0; m < 4; ++m) _Pragma("unroll") for (int n = 0; n < 2; ++n) _Pragma("unroll") for (int k = 0; k < 2; ++k) \
;         acc[ai][bj][m][n] = __builtin_amdgcn_mfma_f32_16x16x32_bf16(Bt[n][k], At[m][k], acc[ai][bj][m][n], 0, 0, 0); __builtin_amdgcn_s_setprio(0); } while (0)
; #define PG8_WAIT_V(n) asm volatile("s_waitcnt vmcnt(" #n ")" ::: "memory")
; #define PG8_WAIT_L(n) asm volatile("s_waitcnt lgkmcnt(" #n ")" ::: "memory")
; template <class Epi>
; __device__ __forceinline__ void gemm_phase(LAS unsigned char* lds, const Gemm g, const StaticOrder& S, const Epi& E, int wv) {
;     ...
;         for (int t = 0; t < nt; t += 2) {
;             const bool last = (t == nt - 2);
;             const char* a1 = cA + (size_t)(t + 1) * kstep;
;             const char* a2 = last ? nA : cA + (size_t)(t + 2) * kstep; const char* b2 = last ? nB : cB + (size_t)(t + 2) * kstep;
;             const char* a3 = a2 + kstep; const char* b3 = b2 + kstep;
;             PG8_LDB(B0, 0, 0); PG8_SCHED; PG8_LDA(At, 0, 0); PG8_STAGE(PG8_SA(1, 1), a1 + hstep, voffA);
;             PG8_WAIT_L(8); PG8_BAR; PG8_WAIT_L(0); PG8_MMA(0, 0, At, B0); PG8_BAR; PG8_SCHED;
;             PG8_LDB(B1, 0, 1); PG8_STAGE(PG8_SB(0, 0), b2, voffB);
;             PG8_BAR; PG8_WAIT_L(0); PG8_MMA(0, 1, At, B1); PG8_BAR;
;             PG8_LDA(At, 0, 1); PG8_STAGE(PG8_SA(0, 0), a2, voffA);
;             PG8_BAR; PG8_WAIT_L(0); PG8_MMA(1, 0, At, B0); PG8_BAR; PG8_SCHED;
;             PG8_STAGE(PG8_SB(0, 1), b2 + hstep, voffB);
;             PG8_WAIT_V(6); PG8_BAR; PG8_MMA(1, 1, At, B1); PG8_BAR;
.LBB0_424:
	s_add_u32 s64, s8, 0xfff80080
	s_addc_u32 s65, s9, -1
	s_add_i32 s96, 0, 0x10000
	v_add_u32_e32 v140, s96, v192
	ds_read_b128 v[128:131], v140
	ds_read_b128 v[132:135], v140 offset:1024
	ds_read_b128 v[136:139], v140 offset:2048
	ds_read_b128 v[140:143], v140 offset:3072
	s_cmp_eq_u32 s86, 28
	s_cselect_b32 s71, s34, s65
	s_cselect_b32 s70, s35, s64
	s_cselect_b32 s65, s59, s85
	s_cselect_b32 s64, s61, s79
	s_add_i32 m0, s24, 0xc000
	ds_read_b128 v[144:147], v193
	ds_read_b128 v[148:151], v193 offset:1024
	ds_read_b128 v[152:155], v193 offset:2048
	ds_read_b128 v[156:159], v193 offset:3072
	ds_read_b128 v[160:163], v193 offset:4096
	ds_read_b128 v[170:173], v193 offset:5120
	ds_read_b128 v[174:177], v193 offset:6144
	ds_read_b128 v[178:181], v193 offset:7168
	global_load_lds_dwordx4 v166, s[8:9]
	s_add_i32 m0, s24, 0xe000
	s_nop 0
	global_load_lds_dwordx4 v168, s[8:9]
	s_waitcnt lgkmcnt(8)
	s_barrier
	s_waitcnt lgkmcnt(0)
	s_setprio 1
	v_mfma_f32_16x16x32_bf16 v[124:127], v[128:131], v[144:147], v[124:127]
	v_mfma_f32_16x16x32_bf16 v[120:123], v[136:139], v[144:147], v[120:123]
	v_mfma_f32_16x16x32_bf16 v[108:111], v[128:131], v[152:155], v[108:111]
	v_mfma_f32_16x16x32_bf16 v[104:107], v[136:139], v[152:155], v[104:107]
	v_mfma_f32_16x16x32_bf16 v[92:95], v[128:131], v[160:163], v[92:95]
	v_mfma_f32_16x16x32_bf16 v[88:91], v[136:139], v[160:163], v[88:91]
	v_mfma_f32_16x16x32_bf16 v[76:79], v[128:131], v[174:177], v[76:79]
	v_mfma_f32_16x16x32_bf16 v[72:75], v[136:139], v[174:177], v[72:75]
	v_mfma_f32_16x16x32_bf16 v[124:127], v[132:135], v[148:151], v[124:127]
	v_mfma_f32_16x16x32_bf16 v[120:123], v[140:143], v[148:151], v[120:123]
	v_mfma_f32_16x16x32_bf16 v[108:111], v[132:135], v[156:159], v[108:111]
	v_mfma_f32_16x16x32_bf16 v[104:107], v[140:143], v[156:159], v[104:107]
	v_mfma_f32_16x16x32_bf16 v[92:95], v[132:135], v[170:173], v[92:95]
	v_mfma_f32_16x16x32_bf16 v[88:91], v[140:143], v[170:173], v[88:91]
	v_mfma_f32_16x16x32_bf16 v[76:79], v[132:135], v[178:181], v[76:79]
	v_mfma_f32_16x16x32_bf16 v[72:75], v[140:143], v[178:181], v[72:75]
	s_setprio 0
	s_barrier
	s_add_i32 vcc_lo, 0, 0x14000
	v_add_u32_e32 v190, vcc_lo, v192
	s_add_i32 s96, s96, s37
	ds_read_b128 v[182:185], v190
	ds_read_b128 v[186:189], v190 offset:1024
	ds_read_b128 v[194:197], v190 offset:2048
	ds_read_b128 v[198:201], v190 offset:3072
	v_lshl_add_u64 v[190:191], s[64:65], 0, v[212:213]
	s_mov_b32 m0, s96
	v_lshl_add_u64 v[202:203], s[64:65], 0, v[164:165]
	global_load_lds_dwordx4 v[190:191], off
	s_add_i32 m0, s96, 0x2000
	s_nop 0
	global_load_lds_dwordx4 v[202:203], off
	s_barrier
	s_waitcnt lgkmcnt(0)
	s_setprio 1
	v_mfma_f32_16x16x32_bf16 v[116:119], v[182:185], v[144:147], v[116:119]
	v_mfma_f32_16x16x32_bf16 v[112:115], v[194:197], v[144:147], v[112:115]
	v_mfma_f32_16x16x32_bf16 v[100:103], v[182:185], v[152:155], v[100:103]
	v_mfma_f32_16x16x32_bf16 v[96:99], v[194:197], v[152:155], v[96:99]
	v_mfma_f32_16x16x32_bf16 v[84:87], v[182:185], v[160:163], v[84:87]
	v_mfma_f32_16x16x32_bf16 v[80:83], v[194:197], v[160:163], v[80:83]
	v_mfma_f32_16x16x32_bf16 v[68:71], v[182:185], v[174:177], v[68:71]
	v_mfma_f32_16x16x32_bf16 v[64:67], v[194:197], v[174:177], v[64:67]
	v_mfma_f32_16x16x32_bf16 v[116:119], v[186:189], v[148:151], v[116:119]
	v_mfma_f32_16x16x32_bf16 v[112:115], v[198:201], v[148:151], v[112:115]
	v_mfma_f32_16x16x32_bf16 v[100:103], v[186:189], v[156:159], v[100:103]
	v_mfma_f32_16x16x32_bf16 v[96:99], v[198:201], v[156:159], v[96:99]
	v_mfma_f32_16x16x32_bf16 v[84:87], v[186:189], v[170:173], v[84:87]
	v_mfma_f32_16x16x32_bf16 v[80:83], v[198:201], v[170:173], v[80:83]
	v_mfma_f32_16x16x32_bf16 v[68:71], v[186:189], v[178:181], v[68:71]
	v_mfma_f32_16x16x32_bf16 v[64:67], v[198:201], v[178:181], v[64:67]
	s_setprio 0
	s_mov_b32 m0, s24
	v_lshl_add_u64 v[204:205], s[70:71], 0, v[212:213]
	s_barrier
	ds_read_b128 v[144:147], v193 offset:16384
	ds_read_b128 v[148:151], v193 offset:17408
	ds_read_b128 v[152:155], v193 offset:18432
	ds_read_b128 v[156:159], v193 offset:19456
	ds_read_b128 v[160:163], v193 offset:20480
	ds_read_b128 v[170:173], v193 offset:21504
	ds_read_b128 v[174:177], v193 offset:22528
	ds_read_b128 v[178:181], v193 offset:23552
	global_load_lds_dwordx4 v[204:205], off
	v_lshl_add_u64 v[206:207], s[70:71], 0, v[164:165]
	s_mov_b32 m0, s46
	s_nop 0
	global_load_lds_dwordx4 v[206:207], off
	s_barrier
	s_waitcnt lgkmcnt(0)
	s_setprio 1
	v_mfma_f32_16x16x32_bf16 v[60:63], v[128:131], v[144:147], v[60:63]
	v_mfma_f32_16x16x32_bf16 v[56:59], v[136:139], v[144:147], v[56:59]
	v_mfma_f32_16x16x32_bf16 v[44:47], v[128:131], v[152:155], v[44:47]
	v_mfma_f32_16x16x32_bf16 v[40:43], v[136:139], v[152:155], v[40:43]
	v_mfma_f32_16x16x32_bf16 v[28:31], v[128:131], v[160:163], v[28:31]
	v_mfma_f32_16x16x32_bf16 v[24:27], v[136:139], v[160:163], v[24:27]
	v_mfma_f32_16x16x32_bf16 v[12:15], v[128:131], v[174:177], v[12:15]
	v_mfma_f32_16x16x32_bf16 v[8:11], v[136:139], v[174:177], v[8:11]
	v_mfma_f32_16x16x32_bf16 v[60:63], v[132:135], v[148:151], v[60:63]
	v_mfma_f32_16x16x32_bf16 v[56:59], v[140:143], v[148:151], v[56:59]
	v_mfma_f32_16x16x32_bf16 v[44:47], v[132:135], v[156:159], v[44:47]
	v_mfma_f32_16x16x32_bf16 v[40:43], v[140:143], v[156:159], v[40:43]
	v_mfma_f32_16x16x32_bf16 v[28:31], v[132:135], v[170:173], v[28:31]
	v_mfma_f32_16x16x32_bf16 v[24:27], v[140:143], v[170:173], v[24:27]
	v_mfma_f32_16x16x32_bf16 v[12:15], v[132:135], v[178:181], v[12:15]
	v_mfma_f32_16x16x32_bf16 v[8:11], v[140:143], v[178:181], v[8:11]
	s_setprio 0
	s_barrier
; #define PG8_STAGE(bufoff, gbase, voff) do { _Pragma("unroll") for (int _i = 0; _i < 2; ++_i) \
;         __builtin_amdgcn_global_load_lds((const unsigned*)((const char*)(gbase) + (voff)[_i]), (LAS unsigned*)(lds + (bufoff) + ldsw + _i * 8192), 16, 0, 0); } while (0)
; #define PG8_LDA(dst, b, h) do { _Pragma("unroll") for (int m = 0; m < 4; ++m) _Pragma("unroll") for (int k = 0; k < 2; ++k) dst[m][k] = *(const LAS bf16x8*)(lds + PG8_SA(b, h) + aoff + m * 2048 + k * 1024); } while (0)
; #define PG8_LDB(dst, b, h) do { _Pragma("unroll") for (int n = 0; n < 2; ++n) _Pragma("unroll") for (int k = 0; k < 2; ++k) dst[n][k] = *(const LAS bf16x8*)(lds + PG8_SB(b, h) + boff + n * 2048 + k * 1024); } while (0)
; #define PG8_MMA(ai, bj, At, Bt) do { __builtin_amdgcn_s_setprio(1); _Pragma("unroll") for (int m = 0; m < 4; ++m) _Pragma("unroll") for (int n = 0; n < 2; ++n) _Pragma("unroll") for (int k = 0; k < 2; ++k) \
;         acc[ai][bj][m][n] = __builtin_amdgcn_mfma_f32_16x16x32_bf16(Bt[n][k], At[m][k], acc[ai][bj][m][n], 0, 0, 0); __builtin_amdgcn_s_setprio(0); } while (0)
; #define PG8_WAIT_V(n) asm volatile("s_waitcnt vmcnt(" #n ")" ::: "memory")
; #define PG8_WAIT_L(n) asm volatile("s_waitcnt lgkmcnt(" #n ")" ::: "memory")
; #define PG8_BAR __builtin_amdgcn_s_barrier()
; #define PG8_SCHED __builtin_amdgcn_sched_barrier(0)
; template <class Epi>
; __device__ __forceinline__ void gemm_phase(LAS unsigned char* lds, const Gemm g, const StaticOrder& S, const Epi& E, int wv) {
;     ...
;             PG8_WAIT_V(6); PG8_BAR; PG8_MMA(1, 1, At, B1); PG8_BAR;
;             PG8_LDB(B0, 1, 0); PG8_SCHED; PG8_LDA(At, 1, 0); PG8_STAGE(PG8_SA(0, 1), a2 + hstep, voffA);
;             PG8_WAIT_L(8); PG8_BAR; PG8_WAIT_L(0); PG8_MMA(0, 0, At, B0); PG8_BAR; PG8_SCHED;
;             PG8_LDB(B1, 1, 1); PG8_STAGE(PG8_SB(1, 0), b3, voffB);
;             PG8_BAR; PG8_WAIT_L(0); PG8_MMA(0, 1, At, B1); PG8_BAR;
;             PG8_LDA(At, 1, 1); PG8_STAGE(PG8_SA(1, 0), a3, voffA);
;             PG8_BAR; PG8_WAIT_L(0); PG8_MMA(1, 0, At, B0); PG8_BAR; PG8_SCHED;
	s_add_u32 s96, s64, 0x80000
	s_addc_u32 s97, s65, 0
	s_add_i32 vcc_lo, vcc_lo, s37
	s_mov_b32 m0, vcc_lo
	s_nop 0
	global_load_lds_dwordx4 v212, s[96:97]
	s_add_i32 m0, vcc_lo, 0x2000
	s_nop 0
	global_load_lds_dwordx4 v164, s[96:97]
	s_waitcnt vmcnt(6)
	s_barrier
	s_setprio 1
	v_mfma_f32_16x16x32_bf16 v[52:55], v[182:185], v[144:147], v[52:55]
	v_mfma_f32_16x16x32_bf16 v[48:51], v[194:197], v[144:147], v[48:51]
	v_mfma_f32_16x16x32_bf16 v[36:39], v[182:185], v[152:155], v[36:39]
	v_mfma_f32_16x16x32_bf16 v[32:35], v[194:197], v[152:155], v[32:35]
	v_mfma_f32_16x16x32_bf16 v[20:23], v[182:185], v[160:163], v[20:23]
	v_mfma_f32_16x16x32_bf16 v[16:19], v[194:197], v[160:163], v[16:19]
	v_mfma_f32_16x16x32_bf16 v[4:7], v[182:185], v[174:177], v[4:7]
	v_mfma_f32_16x16x32_bf16 v[0:3], v[194:197], v[174:177], v[0:3]
	v_mfma_f32_16x16x32_bf16 v[52:55], v[186:189], v[148:151], v[52:55]
	v_mfma_f32_16x16x32_bf16 v[48:51], v[198:201], v[148:151], v[48:51]
	v_mfma_f32_16x16x32_bf16 v[36:39], v[186:189], v[156:159], v[36:39]
	v_mfma_f32_16x16x32_bf16 v[32:35], v[198:201], v[156:159], v[32:35]
	v_mfma_f32_16x16x32_bf16 v[20:23], v[186:189], v[170:173], v[20:23]
	v_mfma_f32_16x16x32_bf16 v[16:19], v[198:201], v[170:173], v[16:19]
	v_mfma_f32_16x16x32_bf16 v[4:7], v[186:189], v[178:181], v[4:7]
	v_mfma_f32_16x16x32_bf16 v[0:3], v[198:201], v[178:181], v[0:3]
	s_setprio 0
	s_add_i32 s96, 0, 0x18000
	v_add_u32_e32 v140, s96, v192
	s_barrier
	ds_read_b128 v[128:131], v140
	ds_read_b128 v[132:135], v140 offset:1024
	ds_read_b128 v[136:139], v140 offset:2048
	ds_read_b128 v[140:143], v140 offset:3072
	s_add_u32 s70, s70, 0x80000
	s_addc_u32 s71, s71, 0
	s_mov_b32 m0, s47
	ds_read_b128 v[144:147], v193 offset:32768
	ds_read_b128 v[148:151], v193 offset:33792
	ds_read_b128 v[152:155], v193 offset:34816
	ds_read_b128 v[156:159], v193 offset:35840
	ds_read_b128 v[160:163], v193 offset:36864
	ds_read_b128 v[170:173], v193 offset:37888
	ds_read_b128 v[174:177], v193 offset:38912
	ds_read_b128 v[178:181], v193 offset:39936
	global_load_lds_dwordx4 v212, s[70:71]
	s_mov_b32 m0, s50
	s_nop 0
	global_load_lds_dwordx4 v164, s[70:71]
	s_waitcnt lgkmcnt(8)
	s_barrier
	s_waitcnt lgkmcnt(0)
	s_setprio 1
	v_mfma_f32_16x16x32_bf16 v[124:127], v[128:131], v[144:147], v[124:127]
	v_mfma_f32_16x16x32_bf16 v[120:123], v[136:139], v[144:147], v[120:123]
	v_mfma_f32_16x16x32_bf16 v[108:111], v[128:131], v[152:155], v[108:111]
	v_mfma_f32_16x16x32_bf16 v[104:107], v[136:139], v[152:155], v[104:107]
	v_mfma_f32_16x16x32_bf16 v[92:95], v[128:131], v[160:163], v[92:95]
	v_mfma_f32_16x16x32_bf16 v[88:91], v[136:139], v[160:163], v[88:91]
	v_mfma_f32_16x16x32_bf16 v[76:79], v[128:131], v[174:177], v[76:79]
	v_mfma_f32_16x16x32_bf16 v[72:75], v[136:139], v[174:177], v[72:75]
	v_mfma_f32_16x16x32_bf16 v[124:127], v[132:135], v[148:151], v[124:127]
	v_mfma_f32_16x16x32_bf16 v[120:123], v[140:143], v[148:151], v[120:123]
	v_mfma_f32_16x16x32_bf16 v[108:111], v[132:135], v[156:159], v[108:111]
	v_mfma_f32_16x16x32_bf16 v[104:107], v[140:143], v[156:159], v[104:107]
	v_mfma_f32_16x16x32_bf16 v[92:95], v[132:135], v[170:173], v[92:95]
	v_mfma_f32_16x16x32_bf16 v[88:91], v[140:143], v[170:173], v[88:91]
	v_mfma_f32_16x16x32_bf16 v[76:79], v[132:135], v[178:181], v[76:79]
	v_mfma_f32_16x16x32_bf16 v[72:75], v[140:143], v[178:181], v[72:75]
	s_setprio 0
	s_barrier
	s_add_i32 s70, 0, 0x1c000
	s_add_i32 s71, s96, s37
	v_add_u32_e32 v198, s70, v192
	v_lshl_add_u64 v[190:191], v[190:191], 0, s[80:81]
	s_mov_b32 m0, s71
	ds_read_b128 v[182:185], v198
	ds_read_b128 v[186:189], v198 offset:1024
	ds_read_b128 v[194:197], v198 offset:2048
	ds_read_b128 v[198:201], v198 offset:3072
	global_load_lds_dwordx4 v[190:191], off
	v_lshl_add_u64 v[190:191], v[202:203], 0, s[80:81]
	s_add_i32 m0, s71, 0x2000
	s_nop 0
	global_load_lds_dwordx4 v[190:191], off
	s_barrier
	s_waitcnt lgkmcnt(0)
	s_setprio 1
	v_mfma_f32_16x16x32_bf16 v[116:119], v[182:185], v[144:147], v[116:119]
	v_mfma_f32_16x16x32_bf16 v[112:115], v[194:197], v[144:147], v[112:115]
	v_mfma_f32_16x16x32_bf16 v[100:103], v[182:185], v[152:155], v[100:103]
	v_mfma_f32_16x16x32_bf16 v[96:99], v[194:197], v[152:155], v[96:99]
	v_mfma_f32_16x16x32_bf16 v[84:87], v[182:185], v[160:163], v[84:87]
	v_mfma_f32_16x16x32_bf16 v[80:83], v[194:197], v[160:163], v[80:83]
	v_mfma_f32_16x16x32_bf16 v[68:71], v[182:185], v[174:177], v[68:71]
	v_mfma_f32_16x16x32_bf16 v[64:67], v[194:197], v[174:177], v[64:67]
	v_mfma_f32_16x16x32_bf16 v[116:119], v[186:189], v[148:151], v[116:119]
	v_mfma_f32_16x16x32_bf16 v[112:115], v[198:201], v[148:151], v[112:115]
	v_mfma_f32_16x16x32_bf16 v[100:103], v[186:189], v[156:159], v[100:103]
	v_mfma_f32_16x16x32_bf16 v[96:99], v[198:201], v[156:159], v[96:99]
	v_mfma_f32_16x16x32_bf16 v[84:87], v[186:189], v[170:173], v[84:87]
	v_mfma_f32_16x16x32_bf16 v[80:83], v[198:201], v[170:173], v[80:83]
	v_mfma_f32_16x16x32_bf16 v[68:71], v[186:189], v[178:181], v[68:71]
	v_mfma_f32_16x16x32_bf16 v[64:67], v[198:201], v[178:181], v[64:67]
	s_setprio 0
	s_mov_b32 m0, s72
	v_lshl_add_u64 v[190:191], v[204:205], 0, s[80:81]
	s_barrier
	ds_read_b128 v[144:147], v193 offset:49152
	ds_read_b128 v[148:151], v193 offset:50176
	ds_read_b128 v[152:155], v193 offset:51200
	ds_read_b128 v[156:159], v193 offset:52224
	ds_read_b128 v[160:163], v193 offset:53248
	ds_read_b128 v[170:173], v193 offset:54272
	ds_read_b128 v[174:177], v193 offset:55296
	ds_read_b128 v[178:181], v193 offset:56320
	global_load_lds_dwordx4 v[190:191], off
	v_lshl_add_u64 v[190:191], v[206:207], 0, s[80:81]
	s_mov_b32 m0, s73
	s_nop 0
	global_load_lds_dwordx4 v[190:191], off
	s_barrier
; __device__ __forceinline__ int opaque_lane() { int l = __builtin_amdgcn_mbcnt_hi(~0u, __builtin_amdgcn_mbcnt_lo(~0u, 0u)); asm volatile("" : "+v"(l)); return l; }
; #define PG8_STAGE(bufoff, gbase, voff) do { _Pragma("unroll") for (int _i = 0; _i < 2; ++_i) \
;         __builtin_amdgcn_global_load_lds((const unsigned*)((const char*)(gbase) + (voff)[_i]), (LAS unsigned*)(lds + (bufoff) + ldsw + _i * 8192), 16, 0, 0); } while (0)
; #define PG8_WAIT_V(n) asm volatile("s_waitcnt vmcnt(" #n ")" ::: "memory")
; #define PG8_WAIT_L(n) asm volatile("s_waitcnt lgkmcnt(" #n ")" ::: "memory")
; #define PG8_BAR __builtin_amdgcn_s_barrier()
; template <class Epi>
; __device__ __forceinline__ void gemm_phase(LAS unsigned char* lds, const Gemm g, const StaticOrder& S, const Epi& E, int wv) {
;     ...
;             PG8_BAR; PG8_WAIT_L(0); PG8_MMA(1, 0, At, B0); PG8_BAR; PG8_SCHED;
;             PG8_STAGE(PG8_SB(1, 1), b3 + hstep, voffB);
;             PG8_WAIT_V(6); PG8_BAR; PG8_MMA(1, 1, At, B1); PG8_BAR;
;     __device__ __forceinline__ void operator()(const Acc& acc, const Unit& u, int wv) const {
;         const int wr = wv >> 2, wc = wv & 3, ln_ = opaque_lane(), fr = ln_ & 15, fq = ln_ >> 4;
;         const int row0 = u.pm * BM + wr * 64 + fr, col0 = u.pn * BM + wc * 32 + 4 * fq;
; #pragma unroll
;         for (int pr = 0; pr < 4; ++pr) {
;             f32x4 xi[2][4]; f32x2 st[2];
; #pragma unroll
;             for (int q = 0; q < 2; ++q) { const int i = pr * 2 + q, row = row0 + (i >> 2) * HALF + (i & 3) * 16; const size_t ro = (size_t)row * 1024 + col0;
;                 st[q] = (f32x2){0.f, 1.f}; if (ST) st[q] = ST[row];
; #pragma unroll
;                 for (int c4 = 0; c4 < 4; ++c4) xi[q][c4] = *(const f32x4*)(XIN + ro + (c4 >> 1) * HALF + (c4 & 1) * 16); }
; #pragma unroll
;             for (int q = 0; q < 2; ++q) { const int i = pr * 2 + q, row = row0 + (i >> 2) * HALF + (i & 3) * 16; const size_t ro = (size_t)row * 1024 + col0;
; #pragma unroll
;                 for (int c4 = 0; c4 < 4; ++c4) { const int co = (c4 >> 1) * HALF + (c4 & 1) * 16; f32x4 x = xi[q][c4];
;                     if (ST) { const f32x4 g = *(const f32x4*)(G + col0 + co), b = *(const f32x4*)(B + col0 + co); x = (x - st[q][0]) * st[q][1] * g + b; }
;                     if (!nowrite) *(f32x4*)(XRES + ro + co) = acc[i >> 2][c4 >> 1][i & 3][c4 & 1] + x * ALPHA; } }
	s_waitcnt lgkmcnt(0)
	s_setprio 1
	v_mfma_f32_16x16x32_bf16 v[60:63], v[128:131], v[144:147], v[60:63]
	v_mfma_f32_16x16x32_bf16 v[56:59], v[136:139], v[144:147], v[56:59]
	v_mfma_f32_16x16x32_bf16 v[44:47], v[128:131], v[152:155], v[44:47]
	v_mfma_f32_16x16x32_bf16 v[40:43], v[136:139], v[152:155], v[40:43]
	v_mfma_f32_16x16x32_bf16 v[28:31], v[128:131], v[160:163], v[28:31]
	v_mfma_f32_16x16x32_bf16 v[24:27], v[136:139], v[160:163], v[24:27]
	v_mfma_f32_16x16x32_bf16 v[12:15], v[128:131], v[174:177], v[12:15]
	v_mfma_f32_16x16x32_bf16 v[8:11], v[136:139], v[174:177], v[8:11]
	v_mfma_f32_16x16x32_bf16 v[60:63], v[132:135], v[148:151], v[60:63]
	v_mfma_f32_16x16x32_bf16 v[56:59], v[140:143], v[148:151], v[56:59]
	v_mfma_f32_16x16x32_bf16 v[44:47], v[132:135], v[156:159], v[44:47]
	v_mfma_f32_16x16x32_bf16 v[40:43], v[140:143], v[156:159], v[40:43]
	v_mfma_f32_16x16x32_bf16 v[28:31], v[132:135], v[170:173], v[28:31]
	v_mfma_f32_16x16x32_bf16 v[24:27], v[140:143], v[170:173], v[24:27]
	v_mfma_f32_16x16x32_bf16 v[12:15], v[132:135], v[178:181], v[12:15]
	v_mfma_f32_16x16x32_bf16 v[8:11], v[140:143], v[178:181], v[8:11]
	s_setprio 0
	s_barrier
	s_add_u32 s64, s64, 0x80080
	s_addc_u32 s65, s65, 0
	s_add_i32 s70, s70, s37
	s_mov_b32 m0, s70
	s_nop 0
	global_load_lds_dwordx4 v212, s[64:65]
	v_lshl_add_u64 v[128:129], s[64:65], 0, v[164:165]
	s_add_i32 m0, s70, 0x2000
	s_nop 0
	global_load_lds_dwordx4 v[128:129], off
	s_waitcnt vmcnt(6)
	s_barrier
	s_setprio 1
	v_mfma_f32_16x16x32_bf16 v[52:55], v[182:185], v[144:147], v[52:55]
	v_mfma_f32_16x16x32_bf16 v[48:51], v[194:197], v[144:147], v[48:51]
	v_mfma_f32_16x16x32_bf16 v[36:39], v[182:185], v[152:155], v[36:39]
	v_mfma_f32_16x16x32_bf16 v[32:35], v[194:197], v[152:155], v[32:35]
	v_mfma_f32_16x16x32_bf16 v[20:23], v[182:185], v[160:163], v[20:23]
	v_mfma_f32_16x16x32_bf16 v[16:19], v[194:197], v[160:163], v[16:19]
	v_mfma_f32_16x16x32_bf16 v[4:7], v[182:185], v[174:177], v[4:7]
	v_mfma_f32_16x16x32_bf16 v[0:3], v[194:197], v[174:177], v[0:3]
	v_mfma_f32_16x16x32_bf16 v[52:55], v[186:189], v[148:151], v[52:55]
	v_mfma_f32_16x16x32_bf16 v[48:51], v[198:201], v[148:151], v[48:51]
	v_mfma_f32_16x16x32_bf16 v[36:39], v[186:189], v[156:159], v[36:39]
	v_mfma_f32_16x16x32_bf16 v[32:35], v[198:201], v[156:159], v[32:35]
	v_mfma_f32_16x16x32_bf16 v[20:23], v[186:189], v[170:173], v[20:23]
	v_mfma_f32_16x16x32_bf16 v[16:19], v[198:201], v[170:173], v[16:19]
	v_mfma_f32_16x16x32_bf16 v[4:7], v[186:189], v[178:181], v[4:7]
	v_mfma_f32_16x16x32_bf16 v[0:3], v[198:201], v[178:181], v[0:3]
	s_setprio 0
	s_add_i32 s86, s86, 2
	s_add_u32 s8, s8, 0x100
	s_addc_u32 s9, s9, 0
	s_add_u32 s79, s79, 0x100
	s_addc_u32 s85, s85, 0
	s_cmp_gt_u32 s86, 29
	s_barrier
	s_cbranch_scc0 .LBB0_424
	s_lshl_b32 s8, s78, 8
	v_readlane_b32 s9, v254, 13
	v_mov_b32_e32 v186, v233
	s_lshl_b32 s34, s77, 8
	s_add_i32 s8, s8, s9
	s_or_b32 s34, s34, s53
	v_and_or_b32 v187, v186, 15, s8
	v_ashrrev_i32_e32 v188, 2, v186
	v_and_b32_e32 v188, -4, v188
	v_add_u32_e32 v188, s34, v188
	v_lshlrev_b32_e32 v188, 2, v188
	v_lshl_add_u32 v186, v187, 12, v188
	v_lshlrev_b32_e32 v187, 3, v187
	s_movk_i32 s85, 0x1800
	v_readlane_b32 s79, v255, 14
	v_readlane_b32 s96, v255, 9
	s_andn2_b64 vcc, exec, s[20:21]
	s_cbranch_vccnz .Lepi_res_nost
	global_load_dwordx4 v[160:163], v188, s[10:11]
	global_load_dwordx4 v[170:173], v188, s[10:11] offset:64
	global_load_dwordx4 v[174:177], v188, s[10:11] offset:512
	global_load_dwordx4 v[178:181], v188, s[10:11] offset:576
	global_load_dwordx4 v[128:131], v188, s[56:57]
	global_load_dwordx4 v[132:135], v188, s[56:57] offset:64
	global_load_dwordx4 v[136:139], v188, s[56:57] offset:512
	global_load_dwordx4 v[140:143], v188, s[56:57] offset:576
	global_load_dwordx2 v[182:183], v187, s[42:43]
	global_load_dwordx4 v[144:147], v186, s[22:23]
	global_load_dwordx4 v[148:151], v186, s[22:23] offset:64
	global_load_dwordx4 v[152:155], v186, s[22:23] offset:512
	global_load_dwordx4 v[156:159], v186, s[22:23] offset:576
	s_waitcnt vmcnt(9)
	v_pk_fma_f32 v[124:125], v[160:161], s[28:29], v[124:125] op_sel_hi:[1,0,1]
	v_pk_fma_f32 v[126:127], v[162:163], s[28:29], v[126:127] op_sel_hi:[1,0,1]
	v_pk_fma_f32 v[120:121], v[170:171], s[28:29], v[120:121] op_sel_hi:[1,0,1]
	v_pk_fma_f32 v[122:123], v[172:173], s[28:29], v[122:123] op_sel_hi:[1,0,1]
	v_pk_fma_f32 v[116:117], v[174:175], s[28:29], v[116:117] op_sel_hi:[1,0,1]
	v_pk_fma_f32 v[118:119], v[176:177], s[28:29], v[118:119] op_sel_hi:[1,0,1]
	v_pk_fma_f32 v[112:113], v[178:179], s[28:29], v[112:113] op_sel_hi:[1,0,1]
	v_pk_fma_f32 v[114:115], v[180:181], s[28:29], v[114:115] op_sel_hi:[1,0,1]
	v_pk_fma_f32 v[108:109], v[160:161], s[28:29], v[108:109] op_sel_hi:[1,0,1]
	v_pk_fma_f32 v[110:111], v[162:163], s[28:29], v[110:111] op_sel_hi:[1,0,1]
	v_pk_fma_f32 v[104:105], v[170:171], s[28:29], v[104:105] op_sel_hi:[1,0,1]
	v_pk_fma_f32 v[106:107], v[172:173], s[28:29], v[106:107] op_sel_hi:[1,0,1]
	v_pk_fma_f32 v[100:101], v[174:175], s[28:29], v[100:101] op_sel_hi:[1,0,1]
	v_pk_fma_f32 v[102:103], v[176:177], s[28:29], v[102:103] op_sel_hi:[1,0,1]
	v_pk_fma_f32 v[96:97], v[178:179], s[28:29], v[96:97] op_sel_hi:[1,0,1]
	v_pk_fma_f32 v[98:99], v[180:181], s[28:29], v[98:99] op_sel_hi:[1,0,1]
	v_pk_fma_f32 v[92:93], v[160:161], s[28:29], v[92:93] op_sel_hi:[1,0,1]
	v_pk_fma_f32 v[94:95], v[162:163], s[28:29], v[94:95] op_sel_hi:[1,0,1]
	v_pk_fma_f32 v[88:89], v[170:171], s[28:29], v[88:89] op_sel_hi:[1,0,1]
	v_pk_fma_f32 v[90:91], v[172:173], s[28:29], v[90:91] op_sel_hi:[1,0,1]
	v_pk_fma_f32 v[84:85], v[174:175], s[28:29], v[84:85] op_sel_hi:[1,0,1]
;     __device__ __forceinline__ void operator()(const Acc& acc, const Unit& u, int wv) const {
;     ...
;         for (int pr = 0; pr < 4; ++pr) {
;             f32x4 xi[2][4]; f32x2 st[2];
; #pragma unroll
;             for (int q = 0; q < 2; ++q) { const int i = pr * 2 + q, row = row0 + (i >> 2) * HALF + (i & 3) * 16; const size_t ro = (size_t)row * 1024 + col0;
;                 st[q] = (f32x2){0.f, 1.f}; if (ST) st[q] = ST[row];
; #pragma unroll
;                 for (int c4 = 0; c4 < 4; ++c4) xi[q][c4] = *(const f32x4*)(XIN + ro + (c4 >> 1) * HALF + (c4 & 1) * 16); }
; #pragma unroll
;             for (int q = 0; q < 2; ++q) { const int i = pr * 2 + q, row = row0 + (i >> 2) * HALF + (i & 3) * 16; const size_t ro = (size_t)row * 1024 + col0;
; #pragma unroll
;                 for (int c4 = 0; c4 < 4; ++c4) { const int co = (c4 >> 1) * HALF + (c4 & 1) * 16; f32x4 x = xi[q][c4];
;                     if (ST) { const f32x4 g = *(const f32x4*)(G + col0 + co), b = *(const f32x4*)(B + col0 + co); x = (x - st[q][0]) * st[q][1] * g + b; }
;                     if (!nowrite) *(f32x4*)(XRES + ro + co) = acc[i >> 2][c4 >> 1][i & 3][c4 & 1] + x * ALPHA; } }
;             __builtin_amdgcn_sched_barrier(0);
;         }
	v_pk_fma_f32 v[86:87], v[176:177], s[28:29], v[86:87] op_sel_hi:[1,0,1]
	v_pk_fma_f32 v[80:81], v[178:179], s[28:29], v[80:81] op_sel_hi:[1,0,1]
	v_pk_fma_f32 v[82:83], v[180:181], s[28:29], v[82:83] op_sel_hi:[1,0,1]
	v_pk_fma_f32 v[76:77], v[160:161], s[28:29], v[76:77] op_sel_hi:[1,0,1]
	v_pk_fma_f32 v[78:79], v[162:163], s[28:29], v[78:79] op_sel_hi:[1,0,1]
	v_pk_fma_f32 v[72:73], v[170:171], s[28:29], v[72:73] op_sel_hi:[1,0,1]
	v_pk_fma_f32 v[74:75], v[172:173], s[28:29], v[74:75] op_sel_hi:[1,0,1]
	v_pk_fma_f32 v[68:69], v[174:175], s[28:29], v[68:69] op_sel_hi:[1,0,1]
	v_pk_fma_f32 v[70:71], v[176:177], s[28:29], v[70:71] op_sel_hi:[1,0,1]
	v_pk_fma_f32 v[64:65], v[178:179], s[28:29], v[64:65] op_sel_hi:[1,0,1]
	v_pk_fma_f32 v[66:67], v[180:181], s[28:29], v[66:67] op_sel_hi:[1,0,1]
	v_pk_fma_f32 v[60:61], v[160:161], s[28:29], v[60:61] op_sel_hi:[1,0,1]
	v_pk_fma_f32 v[62:63], v[162:163], s[28:29], v[62:63] op_sel_hi:[1,0,1]
	v_pk_fma_f32 v[56:57], v[170:171], s[28:29], v[56:57] op_sel_hi:[1,0,1]
	v_pk_fma_f32 v[58:59], v[172:173], s[28:29], v[58:59] op_sel_hi:[1,0,1]
	v_pk_fma_f32 v[52:53], v[174:175], s[28:29], v[52:53] op_sel_hi:[1,0,1]
	v_pk_fma_f32 v[54:55], v[176:177], s[28:29], v[54:55] op_sel_hi:[1,0,1]
	v_pk_fma_f32 v[48:49], v[178:179], s[28:29], v[48:49] op_sel_hi:[1,0,1]
	v_pk_fma_f32 v[50:51], v[180:181], s[28:29], v[50:51] op_sel_hi:[1,0,1]
	v_pk_fma_f32 v[44:45], v[160:161], s[28:29], v[44:45] op_sel_hi:[1,0,1]
	v_pk_fma_f32 v[46:47], v[162:163], s[28:29], v[46:47] op_sel_hi:[1,0,1]
	v_pk_fma_f32 v[40:41], v[170:171], s[28:29], v[40:41] op_sel_hi:[1,0,1]
	v_pk_fma_f32 v[42:43], v[172:173], s[28:29], v[42:43] op_sel_hi:[1,0,1]
	v_pk_fma_f32 v[36:37], v[174:175], s[28:29], v[36:37] op_sel_hi:[1,0,1]
	v_pk_fma_f32 v[38:39], v[176:177], s[28:29], v[38:39] op_sel_hi:[1,0,1]
	v_pk_fma_f32 v[32:33], v[178:179], s[28:29], v[32:33] op_sel_hi:[1,0,1]
	v_pk_fma_f32 v[34:35], v[180:181], s[28:29], v[34:35] op_sel_hi:[1,0,1]
	v_pk_fma_f32 v[28:29], v[160:161], s[28:29], v[28:29] op_sel_hi:[1,0,1]
	v_pk_fma_f32 v[30:31], v[162:163], s[28:29], v[30:31] op_sel_hi:[1,0,1]
	v_pk_fma_f32 v[24:25], v[170:171], s[28:29], v[24:25] op_sel_hi:[1,0,1]
	v_pk_fma_f32 v[26:27], v[172:173], s[28:29], v[26:27] op_sel_hi:[1,0,1]
	v_pk_fma_f32 v[20:21], v[174:175], s[28:29], v[20:21] op_sel_hi:[1,0,1]
	v_pk_fma_f32 v[22:23], v[176:177], s[28:29], v[22:23] op_sel_hi:[1,0,1]
	v_pk_fma_f32 v[16:17], v[178:179], s[28:29], v[16:17] op_sel_hi:[1,0,1]
	v_pk_fma_f32 v[18:19], v[180:181], s[28:29], v[18:19] op_sel_hi:[1,0,1]
	v_pk_fma_f32 v[12:13], v[160:161], s[28:29], v[12:13] op_sel_hi:[1,0,1]
	v_pk_fma_f32 v[14:15], v[162:163], s[28:29], v[14:15] op_sel_hi:[1,0,1]
	v_pk_fma_f32 v[8:9], v[170:171], s[28:29], v[8:9] op_sel_hi:[1,0,1]
	v_pk_fma_f32 v[10:11], v[172:173], s[28:29], v[10:11] op_sel_hi:[1,0,1]
	v_pk_fma_f32 v[4:5], v[174:175], s[28:29], v[4:5] op_sel_hi:[1,0,1]
	v_pk_fma_f32 v[6:7], v[176:177], s[28:29], v[6:7] op_sel_hi:[1,0,1]
	v_pk_fma_f32 v[0:1], v[178:179], s[28:29], v[0:1] op_sel_hi:[1,0,1]
	v_pk_fma_f32 v[2:3], v[180:181], s[28:29], v[2:3] op_sel_hi:[1,0,1]
	v_add_u32_e32 v189, 0x10000, v186
	global_load_dwordx2 v[184:185], v187, s[42:43] offset:128
	global_load_dwordx4 v[160:163], v189, s[22:23]
	global_load_dwordx4 v[170:173], v189, s[22:23] offset:64
	global_load_dwordx4 v[174:177], v189, s[22:23] offset:512
	global_load_dwordx4 v[178:181], v189, s[22:23] offset:576
	s_waitcnt vmcnt(5)
	v_mov_b32_e32 v194, v183
	v_mov_b32_e32 v195, v183
	v_sub_f32_e32 v144, v144, v182
	v_sub_f32_e32 v145, v145, v182
	v_sub_f32_e32 v146, v146, v182
	v_sub_f32_e32 v147, v147, v182
	v_pk_mul_f32 v[144:145], v[194:195], v[144:145]
	v_pk_mul_f32 v[146:147], v[194:195], v[146:147]
	v_pk_mul_f32 v[144:145], v[144:145], v[128:129]
	v_pk_mul_f32 v[146:147], v[146:147], v[130:131]
	v_pk_fma_f32 v[124:125], v[144:145], s[28:29], v[124:125] op_sel_hi:[1,0,1]
	v_pk_fma_f32 v[126:127], v[146:147], s[28:29], v[126:127] op_sel_hi:[1,0,1]
	v_sub_f32_e32 v148, v148, v182
	v_sub_f32_e32 v149, v149, v182
	v_sub_f32_e32 v150, v150, v182
	v_sub_f32_e32 v151, v151, v182
	v_pk_mul_f32 v[148:149], v[194:195], v[148:149]
	v_pk_mul_f32 v[150:151], v[194:195], v[150:151]
	v_pk_mul_f32 v[148:149], v[148:149], v[132:133]
	v_pk_mul_f32 v[150:151], v[150:151], v[134:135]
	v_pk_fma_f32 v[120:121], v[148:149], s[28:29], v[120:121] op_sel_hi:[1,0,1]
	v_pk_fma_f32 v[122:123], v[150:151], s[28:29], v[122:123] op_sel_hi:[1,0,1]
	v_sub_f32_e32 v152, v152, v182
	v_sub_f32_e32 v153, v153, v182
	v_sub_f32_e32 v154, v154, v182
	v_sub_f32_e32 v155, v155, v182
	v_pk_mul_f32 v[152:153], v[194:195], v[152:153]
	v_pk_mul_f32 v[154:155], v[194:195], v[154:155]
	v_pk_mul_f32 v[152:153], v[152:153], v[136:137]
	v_pk_mul_f32 v[154:155], v[154:155], v[138:139]
	v_pk_fma_f32 v[116:117], v[152:153], s[28:29], v[116:117] op_sel_hi:[1,0,1]
	v_pk_fma_f32 v[118:119], v[154:155], s[28:29], v[118:119] op_sel_hi:[1,0,1]
	v_sub_f32_e32 v156, v156, v182
	v_sub_f32_e32 v157, v157, v182
	v_sub_f32_e32 v158, v158, v182
	v_sub_f32_e32 v159, v159, v182
	v_pk_mul_f32 v[156:157], v[194:195], v[156:157]
	v_pk_mul_f32 v[158:159], v[194:195], v[158:159]
	v_pk_mul_f32 v[156:157], v[156:157], v[140:141]
	v_pk_mul_f32 v[158:159], v[158:159], v[142:143]
	v_pk_fma_f32 v[112:113], v[156:157], s[28:29], v[112:113] op_sel_hi:[1,0,1]
	v_pk_fma_f32 v[114:115], v[158:159], s[28:29], v[114:115] op_sel_hi:[1,0,1]
	v_add_u32_e32 v189, 0x20000, v186
	global_load_dwordx2 v[182:183], v187, s[42:43] offset:256
	global_load_dwordx4 v[144:147], v189, s[22:23]
	global_load_dwordx4 v[148:151], v189, s[22:23] offset:64
	global_load_dwordx4 v[152:155], v189, s[22:23] offset:512
	global_load_dwordx4 v[156:159], v189, s[22:23] offset:576
	global_store_dwordx4 v186, v[124:127], s[18:19]
	global_store_dwordx4 v186, v[120:123], s[18:19] offset:64
	global_store_dwordx4 v186, v[116:119], s[18:19] offset:512
	global_store_dwordx4 v186, v[112:115], s[18:19] offset:576
	s_waitcnt vmcnt(9)
;     __device__ __forceinline__ void operator()(const Acc& acc, const Unit& u, int wv) const {
;     ...
;         for (int pr = 0; pr < 4; ++pr) {
;             f32x4 xi[2][4]; f32x2 st[2];
; #pragma unroll
;             for (int q = 0; q < 2; ++q) { const int i = pr * 2 + q, row = row0 + (i >> 2) * HALF + (i & 3) * 16; const size_t ro = (size_t)row * 1024 + col0;
;                 st[q] = (f32x2){0.f, 1.f}; if (ST) st[q] = ST[row];
; #pragma unroll
;                 for (int c4 = 0; c4 < 4; ++c4) xi[q][c4] = *(const f32x4*)(XIN + ro + (c4 >> 1) * HALF + (c4 & 1) * 16); }
; #pragma unroll
;             for (int q = 0; q < 2; ++q) { const int i = pr * 2 + q, row = row0 + (i >> 2) * HALF + (i & 3) * 16; const size_t ro = (size_t)row * 1024 + col0;
; #pragma unroll
;                 for (int c4 = 0; c4 < 4; ++c4) { const int co = (c4 >> 1) * HALF + (c4 & 1) * 16; f32x4 x = xi[q][c4];
;                     if (ST) { const f32x4 g = *(const f32x4*)(G + col0 + co), b = *(const f32x4*)(B + col0 + co); x = (x - st[q][0]) * st[q][1] * g + b; }
;                     if (!nowrite) *(f32x4*)(XRES + ro + co) = acc[i >> 2][c4 >> 1][i & 3][c4 & 1] + x * ALPHA; } }
;             __builtin_amdgcn_sched_barrier(0);
;         }
	v_mov_b32_e32 v194, v185
	v_mov_b32_e32 v195, v185
	v_sub_f32_e32 v160, v160, v184
	v_sub_f32_e32 v161, v161, v184
	v_sub_f32_e32 v162, v162, v184
	v_sub_f32_e32 v163, v163, v184
	v_pk_mul_f32 v[160:161], v[194:195], v[160:161]
	v_pk_mul_f32 v[162:163], v[194:195], v[162:163]
	v_pk_mul_f32 v[160:161], v[160:161], v[128:129]
	v_pk_mul_f32 v[162:163], v[162:163], v[130:131]
	v_pk_fma_f32 v[108:109], v[160:161], s[28:29], v[108:109] op_sel_hi:[1,0,1]
	v_pk_fma_f32 v[110:111], v[162:163], s[28:29], v[110:111] op_sel_hi:[1,0,1]
	v_sub_f32_e32 v170, v170, v184
	v_sub_f32_e32 v171, v171, v184
	v_sub_f32_e32 v172, v172, v184
	v_sub_f32_e32 v173, v173, v184
	v_pk_mul_f32 v[170:171], v[194:195], v[170:171]
	v_pk_mul_f32 v[172:173], v[194:195], v[172:173]
	v_pk_mul_f32 v[170:171], v[170:171], v[132:133]
	v_pk_mul_f32 v[172:173], v[172:173], v[134:135]
	v_pk_fma_f32 v[104:105], v[170:171], s[28:29], v[104:105] op_sel_hi:[1,0,1]
	v_pk_fma_f32 v[106:107], v[172:173], s[28:29], v[106:107] op_sel_hi:[1,0,1]
	v_sub_f32_e32 v174, v174, v184
	v_sub_f32_e32 v175, v175, v184
	v_sub_f32_e32 v176, v176, v184
	v_sub_f32_e32 v177, v177, v184
	v_pk_mul_f32 v[174:175], v[194:195], v[174:175]
	v_pk_mul_f32 v[176:177], v[194:195], v[176:177]
	v_pk_mul_f32 v[174:175], v[174:175], v[136:137]
	v_pk_mul_f32 v[176:177], v[176:177], v[138:139]
	v_pk_fma_f32 v[100:101], v[174:175], s[28:29], v[100:101] op_sel_hi:[1,0,1]
	v_pk_fma_f32 v[102:103], v[176:177], s[28:29], v[102:103] op_sel_hi:[1,0,1]
	v_sub_f32_e32 v178, v178, v184
	v_sub_f32_e32 v179, v179, v184
	v_sub_f32_e32 v180, v180, v184
	v_sub_f32_e32 v181, v181, v184
	v_pk_mul_f32 v[178:179], v[194:195], v[178:179]
	v_pk_mul_f32 v[180:181], v[194:195], v[180:181]
	v_pk_mul_f32 v[178:179], v[178:179], v[140:141]
	v_pk_mul_f32 v[180:181], v[180:181], v[142:143]
	v_pk_fma_f32 v[96:97], v[178:179], s[28:29], v[96:97] op_sel_hi:[1,0,1]
	v_pk_fma_f32 v[98:99], v[180:181], s[28:29], v[98:99] op_sel_hi:[1,0,1]
	v_add_u32_e32 v189, 0x30000, v186
	global_load_dwordx2 v[184:185], v187, s[42:43] offset:384
	global_load_dwordx4 v[160:163], v189, s[22:23]
	global_load_dwordx4 v[170:173], v189, s[22:23] offset:64
	global_load_dwordx4 v[174:177], v189, s[22:23] offset:512
	global_load_dwordx4 v[178:181], v189, s[22:23] offset:576
	v_add_u32_e32 v190, 0x10000, v186
	global_store_dwordx4 v190, v[108:111], s[18:19]
	global_store_dwordx4 v190, v[104:107], s[18:19] offset:64
	global_store_dwordx4 v190, v[100:103], s[18:19] offset:512
	global_store_dwordx4 v190, v[96:99], s[18:19] offset:576
	s_waitcnt vmcnt(13)
	v_mov_b32_e32 v194, v183
	v_mov_b32_e32 v195, v183
	v_sub_f32_e32 v144, v144, v182
	v_sub_f32_e32 v145, v145, v182
	v_sub_f32_e32 v146, v146, v182
	v_sub_f32_e32 v147, v147, v182
	v_pk_mul_f32 v[144:145], v[194:195], v[144:145]
	v_pk_mul_f32 v[146:147], v[194:195], v[146:147]
	v_pk_mul_f32 v[144:145], v[144:145], v[128:129]
	v_pk_mul_f32 v[146:147], v[146:147], v[130:131]
	v_pk_fma_f32 v[92:93], v[144:145], s[28:29], v[92:93] op_sel_hi:[1,0,1]
	v_pk_fma_f32 v[94:95], v[146:147], s[28:29], v[94:95] op_sel_hi:[1,0,1]
	v_sub_f32_e32 v148, v148, v182
	v_sub_f32_e32 v149, v149, v182
	v_sub_f32_e32 v150, v150, v182
	v_sub_f32_e32 v151, v151, v182
	v_pk_mul_f32 v[148:149], v[194:195], v[148:149]
	v_pk_mul_f32 v[150:151], v[194:195], v[150:151]
	v_pk_mul_f32 v[148:149], v[148:149], v[132:133]
	v_pk_mul_f32 v[150:151], v[150:151], v[134:135]
	v_pk_fma_f32 v[88:89], v[148:149], s[28:29], v[88:89] op_sel_hi:[1,0,1]
	v_pk_fma_f32 v[90:91], v[150:151], s[28:29], v[90:91] op_sel_hi:[1,0,1]
	v_sub_f32_e32 v152, v152, v182
	v_sub_f32_e32 v153, v153, v182
	v_sub_f32_e32 v154, v154, v182
	v_sub_f32_e32 v155, v155, v182
	v_pk_mul_f32 v[152:153], v[194:195], v[152:153]
	v_pk_mul_f32 v[154:155], v[194:195], v[154:155]
	v_pk_mul_f32 v[152:153], v[152:153], v[136:137]
	v_pk_mul_f32 v[154:155], v[154:155], v[138:139]
	v_pk_fma_f32 v[84:85], v[152:153], s[28:29], v[84:85] op_sel_hi:[1,0,1]
	v_pk_fma_f32 v[86:87], v[154:155], s[28:29], v[86:87] op_sel_hi:[1,0,1]
	v_sub_f32_e32 v156, v156, v182
	v_sub_f32_e32 v157, v157, v182
	v_sub_f32_e32 v158, v158, v182
	v_sub_f32_e32 v159, v159, v182
	v_pk_mul_f32 v[156:157], v[194:195], v[156:157]
	v_pk_mul_f32 v[158:159], v[194:195], v[158:159]
	v_pk_mul_f32 v[156:157], v[156:157], v[140:141]
	v_pk_mul_f32 v[158:159], v[158:159], v[142:143]
	v_pk_fma_f32 v[80:81], v[156:157], s[28:29], v[80:81] op_sel_hi:[1,0,1]
	v_pk_fma_f32 v[82:83], v[158:159], s[28:29], v[82:83] op_sel_hi:[1,0,1]
	v_add_u32_e32 v189, 0x80000, v186
	global_load_dwordx2 v[182:183], v187, s[42:43] offset:1024
	global_load_dwordx4 v[144:147], v189, s[22:23]
	global_load_dwordx4 v[148:151], v189, s[22:23] offset:64
	global_load_dwordx4 v[152:155], v189, s[22:23] offset:512
	global_load_dwordx4 v[156:159], v189, s[22:23] offset:576
	v_add_u32_e32 v190, 0x20000, v186
	global_store_dwordx4 v190, v[92:95], s[18:19]
	global_store_dwordx4 v190, v[88:91], s[18:19] offset:64
	global_store_dwordx4 v190, v[84:87], s[18:19] offset:512
	global_store_dwordx4 v190, v[80:83], s[18:19] offset:576
	s_waitcnt vmcnt(13)
;     __device__ __forceinline__ void operator()(const Acc& acc, const Unit& u, int wv) const {
;     ...
;         for (int pr = 0; pr < 4; ++pr) {
;             f32x4 xi[2][4]; f32x2 st[2];
; #pragma unroll
;             for (int q = 0; q < 2; ++q) { const int i = pr * 2 + q, row = row0 + (i >> 2) * HALF + (i & 3) * 16; const size_t ro = (size_t)row * 1024 + col0;
;                 st[q] = (f32x2){0.f, 1.f}; if (ST) st[q] = ST[row];
; #pragma unroll
;                 for (int c4 = 0; c4 < 4; ++c4) xi[q][c4] = *(const f32x4*)(XIN + ro + (c4 >> 1) * HALF + (c4 & 1) * 16); }
; #pragma unroll
;             for (int q = 0; q < 2; ++q) { const int i = pr * 2 + q, row = row0 + (i >> 2) * HALF + (i & 3) * 16; const size_t ro = (size_t)row * 1024 + col0;
; #pragma unroll
;                 for (int c4 = 0; c4 < 4; ++c4) { const int co = (c4 >> 1) * HALF + (c4 & 1) * 16; f32x4 x = xi[q][c4];
;                     if (ST) { const f32x4 g = *(const f32x4*)(G + col0 + co), b = *(const f32x4*)(B + col0 + co); x = (x - st[q][0]) * st[q][1] * g + b; }
;                     if (!nowrite) *(f32x4*)(XRES + ro + co) = acc[i >> 2][c4 >> 1][i & 3][c4 & 1] + x * ALPHA; } }
;             __builtin_amdgcn_sched_barrier(0);
;         }
	v_mov_b32_e32 v194, v185
	v_mov_b32_e32 v195, v185
	v_sub_f32_e32 v160, v160, v184
	v_sub_f32_e32 v161, v161, v184
	v_sub_f32_e32 v162, v162, v184
	v_sub_f32_e32 v163, v163, v184
	v_pk_mul_f32 v[160:161], v[194:195], v[160:161]
	v_pk_mul_f32 v[162:163], v[194:195], v[162:163]
	v_pk_mul_f32 v[160:161], v[160:161], v[128:129]
	v_pk_mul_f32 v[162:163], v[162:163], v[130:131]
	v_pk_fma_f32 v[76:77], v[160:161], s[28:29], v[76:77] op_sel_hi:[1,0,1]
	v_pk_fma_f32 v[78:79], v[162:163], s[28:29], v[78:79] op_sel_hi:[1,0,1]
	v_sub_f32_e32 v170, v170, v184
	v_sub_f32_e32 v171, v171, v184
	v_sub_f32_e32 v172, v172, v184
	v_sub_f32_e32 v173, v173, v184
	v_pk_mul_f32 v[170:171], v[194:195], v[170:171]
	v_pk_mul_f32 v[172:173], v[194:195], v[172:173]
	v_pk_mul_f32 v[170:171], v[170:171], v[132:133]
	v_pk_mul_f32 v[172:173], v[172:173], v[134:135]
	v_pk_fma_f32 v[72:73], v[170:171], s[28:29], v[72:73] op_sel_hi:[1,0,1]
	v_pk_fma_f32 v[74:75], v[172:173], s[28:29], v[74:75] op_sel_hi:[1,0,1]
	v_sub_f32_e32 v174, v174, v184
	v_sub_f32_e32 v175, v175, v184
	v_sub_f32_e32 v176, v176, v184
	v_sub_f32_e32 v177, v177, v184
	v_pk_mul_f32 v[174:175], v[194:195], v[174:175]
	v_pk_mul_f32 v[176:177], v[194:195], v[176:177]
	v_pk_mul_f32 v[174:175], v[174:175], v[136:137]
	v_pk_mul_f32 v[176:177], v[176:177], v[138:139]
	v_pk_fma_f32 v[68:69], v[174:175], s[28:29], v[68:69] op_sel_hi:[1,0,1]
	v_pk_fma_f32 v[70:71], v[176:177], s[28:29], v[70:71] op_sel_hi:[1,0,1]
	v_sub_f32_e32 v178, v178, v184
	v_sub_f32_e32 v179, v179, v184
	v_sub_f32_e32 v180, v180, v184
	v_sub_f32_e32 v181, v181, v184
	v_pk_mul_f32 v[178:179], v[194:195], v[178:179]
	v_pk_mul_f32 v[180:181], v[194:195], v[180:181]
	v_pk_mul_f32 v[178:179], v[178:179], v[140:141]
	v_pk_mul_f32 v[180:181], v[180:181], v[142:143]
	v_pk_fma_f32 v[64:65], v[178:179], s[28:29], v[64:65] op_sel_hi:[1,0,1]
	v_pk_fma_f32 v[66:67], v[180:181], s[28:29], v[66:67] op_sel_hi:[1,0,1]
	v_add_u32_e32 v189, 0x90000, v186
	global_load_dwordx2 v[184:185], v187, s[42:43] offset:1152
	global_load_dwordx4 v[160:163], v189, s[22:23]
	global_load_dwordx4 v[170:173], v189, s[22:23] offset:64
	global_load_dwordx4 v[174:177], v189, s[22:23] offset:512
	global_load_dwordx4 v[178:181], v189, s[22:23] offset:576
	v_add_u32_e32 v190, 0x30000, v186
	global_store_dwordx4 v190, v[76:79], s[18:19]
	global_store_dwordx4 v190, v[72:75], s[18:19] offset:64
	global_store_dwordx4 v190, v[68:71], s[18:19] offset:512
	global_store_dwordx4 v190, v[64:67], s[18:19] offset:576
	s_waitcnt vmcnt(13)
	v_mov_b32_e32 v194, v183
	v_mov_b32_e32 v195, v183
	v_sub_f32_e32 v144, v144, v182
	v_sub_f32_e32 v145, v145, v182
	v_sub_f32_e32 v146, v146, v182
	v_sub_f32_e32 v147, v147, v182
	v_pk_mul_f32 v[144:145], v[194:195], v[144:145]
	v_pk_mul_f32 v[146:147], v[194:195], v[146:147]
	v_pk_mul_f32 v[144:145], v[144:145], v[128:129]
	v_pk_mul_f32 v[146:147], v[146:147], v[130:131]
	v_pk_fma_f32 v[60:61], v[144:145], s[28:29], v[60:61] op_sel_hi:[1,0,1]
	v_pk_fma_f32 v[62:63], v[146:147], s[28:29], v[62:63] op_sel_hi:[1,0,1]
	v_sub_f32_e32 v148, v148, v182
	v_sub_f32_e32 v149, v149, v182
	v_sub_f32_e32 v150, v150, v182
	v_sub_f32_e32 v151, v151, v182
	v_pk_mul_f32 v[148:149], v[194:195], v[148:149]
	v_pk_mul_f32 v[150:151], v[194:195], v[150:151]
	v_pk_mul_f32 v[148:149], v[148:149], v[132:133]
	v_pk_mul_f32 v[150:151], v[150:151], v[134:135]
	v_pk_fma_f32 v[56:57], v[148:149], s[28:29], v[56:57] op_sel_hi:[1,0,1]
	v_pk_fma_f32 v[58:59], v[150:151], s[28:29], v[58:59] op_sel_hi:[1,0,1]
	v_sub_f32_e32 v152, v152, v182
	v_sub_f32_e32 v153, v153, v182
	v_sub_f32_e32 v154, v154, v182
	v_sub_f32_e32 v155, v155, v182
	v_pk_mul_f32 v[152:153], v[194:195], v[152:153]
	v_pk_mul_f32 v[154:155], v[194:195], v[154:155]
	v_pk_mul_f32 v[152:153], v[152:153], v[136:137]
	v_pk_mul_f32 v[154:155], v[154:155], v[138:139]
	v_pk_fma_f32 v[52:53], v[152:153], s[28:29], v[52:53] op_sel_hi:[1,0,1]
	v_pk_fma_f32 v[54:55], v[154:155], s[28:29], v[54:55] op_sel_hi:[1,0,1]
	v_sub_f32_e32 v156, v156, v182
	v_sub_f32_e32 v157, v157, v182
	v_sub_f32_e32 v158, v158, v182
	v_sub_f32_e32 v159, v159, v182
	v_pk_mul_f32 v[156:157], v[194:195], v[156:157]
	v_pk_mul_f32 v[158:159], v[194:195], v[158:159]
	v_pk_mul_f32 v[156:157], v[156:157], v[140:141]
	v_pk_mul_f32 v[158:159], v[158:159], v[142:143]
	v_pk_fma_f32 v[48:49], v[156:157], s[28:29], v[48:49] op_sel_hi:[1,0,1]
	v_pk_fma_f32 v[50:51], v[158:159], s[28:29], v[50:51] op_sel_hi:[1,0,1]
	v_add_u32_e32 v189, 0xa0000, v186
	global_load_dwordx2 v[182:183], v187, s[42:43] offset:1280
	global_load_dwordx4 v[144:147], v189, s[22:23]
	global_load_dwordx4 v[148:151], v189, s[22:23] offset:64
	global_load_dwordx4 v[152:155], v189, s[22:23] offset:512
	global_load_dwordx4 v[156:159], v189, s[22:23] offset:576
	v_add_u32_e32 v190, 0x80000, v186
	global_store_dwordx4 v190, v[60:63], s[18:19]
	global_store_dwordx4 v190, v[56:59], s[18:19] offset:64
	global_store_dwordx4 v190, v[52:55], s[18:19] offset:512
	global_store_dwordx4 v190, v[48:51], s[18:19] offset:576
	s_waitcnt vmcnt(13)
;     __device__ __forceinline__ void operator()(const Acc& acc, const Unit& u, int wv) const {
;     ...
;         for (int pr = 0; pr < 4; ++pr) {
;             f32x4 xi[2][4]; f32x2 st[2];
; #pragma unroll
;             for (int q = 0; q < 2; ++q) { const int i = pr * 2 + q, row = row0 + (i >> 2) * HALF + (i & 3) * 16; const size_t ro = (size_t)row * 1024 + col0;
;                 st[q] = (f32x2){0.f, 1.f}; if (ST) st[q] = ST[row];
; #pragma unroll
;                 for (int c4 = 0; c4 < 4; ++c4) xi[q][c4] = *(const f32x4*)(XIN + ro + (c4 >> 1) * HALF + (c4 & 1) * 16); }
; #pragma unroll
;             for (int q = 0; q < 2; ++q) { const int i = pr * 2 + q, row = row0 + (i >> 2) * HALF + (i & 3) * 16; const size_t ro = (size_t)row * 1024 + col0;
; #pragma unroll
;                 for (int c4 = 0; c4 < 4; ++c4) { const int co = (c4 >> 1) * HALF + (c4 & 1) * 16; f32x4 x = xi[q][c4];
;                     if (ST) { const f32x4 g = *(const f32x4*)(G + col0 + co), b = *(const f32x4*)(B + col0 + co); x = (x - st[q][0]) * st[q][1] * g + b; }
;                     if (!nowrite) *(f32x4*)(XRES + ro + co) = acc[i >> 2][c4 >> 1][i & 3][c4 & 1] + x * ALPHA; } }
;             __builtin_amdgcn_sched_barrier(0);
;         }
	v_mov_b32_e32 v194, v185
	v_mov_b32_e32 v195, v185
	v_sub_f32_e32 v160, v160, v184
	v_sub_f32_e32 v161, v161, v184
	v_sub_f32_e32 v162, v162, v184
	v_sub_f32_e32 v163, v163, v184
	v_pk_mul_f32 v[160:161], v[194:195], v[160:161]
	v_pk_mul_f32 v[162:163], v[194:195], v[162:163]
	v_pk_mul_f32 v[160:161], v[160:161], v[128:129]
	v_pk_mul_f32 v[162:163], v[162:163], v[130:131]
	v_pk_fma_f32 v[44:45], v[160:161], s[28:29], v[44:45] op_sel_hi:[1,0,1]
	v_pk_fma_f32 v[46:47], v[162:163], s[28:29], v[46:47] op_sel_hi:[1,0,1]
	v_sub_f32_e32 v170, v170, v184
	v_sub_f32_e32 v171, v171, v184
	v_sub_f32_e32 v172, v172, v184
	v_sub_f32_e32 v173, v173, v184
	v_pk_mul_f32 v[170:171], v[194:195], v[170:171]
	v_pk_mul_f32 v[172:173], v[194:195], v[172:173]
	v_pk_mul_f32 v[170:171], v[170:171], v[132:133]
	v_pk_mul_f32 v[172:173], v[172:173], v[134:135]
	v_pk_fma_f32 v[40:41], v[170:171], s[28:29], v[40:41] op_sel_hi:[1,0,1]
	v_pk_fma_f32 v[42:43], v[172:173], s[28:29], v[42:43] op_sel_hi:[1,0,1]
	v_sub_f32_e32 v174, v174, v184
	v_sub_f32_e32 v175, v175, v184
	v_sub_f32_e32 v176, v176, v184
	v_sub_f32_e32 v177, v177, v184
	v_pk_mul_f32 v[174:175], v[194:195], v[174:175]
	v_pk_mul_f32 v[176:177], v[194:195], v[176:177]
	v_pk_mul_f32 v[174:175], v[174:175], v[136:137]
	v_pk_mul_f32 v[176:177], v[176:177], v[138:139]
	v_pk_fma_f32 v[36:37], v[174:175], s[28:29], v[36:37] op_sel_hi:[1,0,1]
	v_pk_fma_f32 v[38:39], v[176:177], s[28:29], v[38:39] op_sel_hi:[1,0,1]
	v_sub_f32_e32 v178, v178, v184
	v_sub_f32_e32 v179, v179, v184
	v_sub_f32_e32 v180, v180, v184
	v_sub_f32_e32 v181, v181, v184
	v_pk_mul_f32 v[178:179], v[194:195], v[178:179]
	v_pk_mul_f32 v[180:181], v[194:195], v[180:181]
	v_pk_mul_f32 v[178:179], v[178:179], v[140:141]
	v_pk_mul_f32 v[180:181], v[180:181], v[142:143]
	v_pk_fma_f32 v[32:33], v[178:179], s[28:29], v[32:33] op_sel_hi:[1,0,1]
	v_pk_fma_f32 v[34:35], v[180:181], s[28:29], v[34:35] op_sel_hi:[1,0,1]
	v_add_u32_e32 v189, 0xb0000, v186
	global_load_dwordx2 v[184:185], v187, s[42:43] offset:1408
	global_load_dwordx4 v[160:163], v189, s[22:23]
	global_load_dwordx4 v[170:173], v189, s[22:23] offset:64
	global_load_dwordx4 v[174:177], v189, s[22:23] offset:512
	global_load_dwordx4 v[178:181], v189, s[22:23] offset:576
	v_add_u32_e32 v190, 0x90000, v186
	global_store_dwordx4 v190, v[44:47], s[18:19]
	global_store_dwordx4 v190, v[40:43], s[18:19] offset:64
	global_store_dwordx4 v190, v[36:39], s[18:19] offset:512
	global_store_dwordx4 v190, v[32:35], s[18:19] offset:576
	s_waitcnt vmcnt(13)
	v_mov_b32_e32 v194, v183
	v_mov_b32_e32 v195, v183
	v_sub_f32_e32 v144, v144, v182
	v_sub_f32_e32 v145, v145, v182
	v_sub_f32_e32 v146, v146, v182
	v_sub_f32_e32 v147, v147, v182
	v_pk_mul_f32 v[144:145], v[194:195], v[144:145]
	v_pk_mul_f32 v[146:147], v[194:195], v[146:147]
	v_pk_mul_f32 v[144:145], v[144:145], v[128:129]
	v_pk_mul_f32 v[146:147], v[146:147], v[130:131]
	v_pk_fma_f32 v[28:29], v[144:145], s[28:29], v[28:29] op_sel_hi:[1,0,1]
	v_pk_fma_f32 v[30:31], v[146:147], s[28:29], v[30:31] op_sel_hi:[1,0,1]
	v_sub_f32_e32 v148, v148, v182
	v_sub_f32_e32 v149, v149, v182
	v_sub_f32_e32 v150, v150, v182
	v_sub_f32_e32 v151, v151, v182
	v_pk_mul_f32 v[148:149], v[194:195], v[148:149]
	v_pk_mul_f32 v[150:151], v[194:195], v[150:151]
	v_pk_mul_f32 v[148:149], v[148:149], v[132:133]
	v_pk_mul_f32 v[150:151], v[150:151], v[134:135]
	v_pk_fma_f32 v[24:25], v[148:149], s[28:29], v[24:25] op_sel_hi:[1,0,1]
	v_pk_fma_f32 v[26:27], v[150:151], s[28:29], v[26:27] op_sel_hi:[1,0,1]
	v_sub_f32_e32 v152, v152, v182
	v_sub_f32_e32 v153, v153, v182
	v_sub_f32_e32 v154, v154, v182
	v_sub_f32_e32 v155, v155, v182
	v_pk_mul_f32 v[152:153], v[194:195], v[152:153]
	v_pk_mul_f32 v[154:155], v[194:195], v[154:155]
	v_pk_mul_f32 v[152:153], v[152:153], v[136:137]
	v_pk_mul_f32 v[154:155], v[154:155], v[138:139]
	v_pk_fma_f32 v[20:21], v[152:153], s[28:29], v[20:21] op_sel_hi:[1,0,1]
	v_pk_fma_f32 v[22:23], v[154:155], s[28:29], v[22:23] op_sel_hi:[1,0,1]
	v_sub_f32_e32 v156, v156, v182
	v_sub_f32_e32 v157, v157, v182
	v_sub_f32_e32 v158, v158, v182
	v_sub_f32_e32 v159, v159, v182
	v_pk_mul_f32 v[156:157], v[194:195], v[156:157]
	v_pk_mul_f32 v[158:159], v[194:195], v[158:159]
	v_pk_mul_f32 v[156:157], v[156:157], v[140:141]
	v_pk_mul_f32 v[158:159], v[158:159], v[142:143]
	v_pk_fma_f32 v[16:17], v[156:157], s[28:29], v[16:17] op_sel_hi:[1,0,1]
	v_pk_fma_f32 v[18:19], v[158:159], s[28:29], v[18:19] op_sel_hi:[1,0,1]
	v_add_u32_e32 v190, 0xa0000, v186
	global_store_dwordx4 v190, v[28:31], s[18:19]
	global_store_dwordx4 v190, v[24:27], s[18:19] offset:64
	global_store_dwordx4 v190, v[20:23], s[18:19] offset:512
	global_store_dwordx4 v190, v[16:19], s[18:19] offset:576
	s_waitcnt vmcnt(8)
	v_mov_b32_e32 v194, v185
	v_mov_b32_e32 v195, v185
	v_sub_f32_e32 v160, v160, v184
	v_sub_f32_e32 v161, v161, v184
	v_sub_f32_e32 v162, v162, v184
	v_sub_f32_e32 v163, v163, v184
	v_pk_mul_f32 v[160:161], v[194:195], v[160:161]
	v_pk_mul_f32 v[162:163], v[194:195], v[162:163]
	v_pk_mul_f32 v[160:161], v[160:161], v[128:129]
	v_pk_mul_f32 v[162:163], v[162:163], v[130:131]
	v_pk_fma_f32 v[12:13], v[160:161], s[28:29], v[12:13] op_sel_hi:[1,0,1]
	v_pk_fma_f32 v[14:15], v[162:163], s[28:29], v[14:15] op_sel_hi:[1,0,1]
	v_sub_f32_e32 v170, v170, v184
	v_sub_f32_e32 v171, v171, v184
	v_sub_f32_e32 v172, v172, v184
	v_sub_f32_e32 v173, v173, v184
	v_pk_mul_f32 v[170:171], v[194:195], v[170:171]
	v_pk_mul_f32 v[172:173], v[194:195], v[172:173]
	v_pk_mul_f32 v[170:171], v[170:171], v[132:133]
	v_pk_mul_f32 v[172:173], v[172:173], v[134:135]
	v_pk_fma_f32 v[8:9], v[170:171], s[28:29], v[8:9] op_sel_hi:[1,0,1]
	v_pk_fma_f32 v[10:11], v[172:173], s[28:29], v[10:11] op_sel_hi:[1,0,1]
	v_sub_f32_e32 v174, v174, v184
	v_sub_f32_e32 v175, v175, v184
	v_sub_f32_e32 v176, v176, v184
	v_sub_f32_e32 v177, v177, v184
	v_pk_mul_f32 v[174:175], v[194:195], v[174:175]
	v_pk_mul_f32 v[176:177], v[194:195], v[176:177]
	v_pk_mul_f32 v[174:175], v[174:175], v[136:137]
	v_pk_mul_f32 v[176:177], v[176:177], v[138:139]
	v_pk_fma_f32 v[4:5], v[174:175], s[28:29], v[4:5] op_sel_hi:[1,0,1]
	v_pk_fma_f32 v[6:7], v[176:177], s[28:29], v[6:7] op_sel_hi:[1,0,1]
	v_sub_f32_e32 v178, v178, v184
	v_sub_f32_e32 v179, v179, v184
	v_sub_f32_e32 v180, v180, v184
	v_sub_f32_e32 v181, v181, v184
	v_pk_mul_f32 v[178:179], v[194:195], v[178:179]
	v_pk_mul_f32 v[180:181], v[194:195], v[180:181]
	v_pk_mul_f32 v[178:179], v[178:179], v[140:141]
	v_pk_mul_f32 v[180:181], v[180:181], v[142:143]
	v_pk_fma_f32 v[0:1], v[178:179], s[28:29], v[0:1] op_sel_hi:[1,0,1]
	v_pk_fma_f32 v[2:3], v[180:181], s[28:29], v[2:3] op_sel_hi:[1,0,1]
	v_add_u32_e32 v190, 0xb0000, v186
	global_store_dwordx4 v190, v[12:15], s[18:19]
	global_store_dwordx4 v190, v[8:11], s[18:19] offset:64
	global_store_dwordx4 v190, v[4:7], s[18:19] offset:512
	global_store_dwordx4 v190, v[0:3], s[18:19] offset:576
	s_branch .LBB0_416

; #define LAS __attribute__((address_space(3)))
; __device__ __forceinline__ int opaque_tid(int wv) { return wv * 64 + opaque_lane(); }
; __device__ __forceinline__ int v_st(int k, int c) { const int kk = (k & ~0xC) | ((k & 4) << 1) | ((k & 8) >> 1); return ((kk >> 3) * 4 + (c >> 5)) * 512 + ((kk & 7) * 32 + (c & 31)) * 2; }
; __device__ __forceinline__ int v_rd_base(int lane) { return ((lane & 3) << 3) | (((lane >> 2) & 3) << 6) | (((lane >> 4) & 1) << 5) | (((lane >> 5) & 1) << 8); }
; #define SWRITE(b) do { *(bf16x8*)(V_lds + (b) * SHM_V + vst0) = vs0; *(bf16x8*)(V_lds + (b) * SHM_V + vst1) = vs1; const int kc = sc * 2; \
;     *(bf16x8*)(K_lds + (b) * SHM_K + KSWZ(sr, kc)) = ks0; *(bf16x8*)(K_lds + (b) * SHM_K + KSWZ(32 + sr, kc)) = ks1; \
;     *(bf16x8*)(R_lds + (b) * SHM_R + RSWZ(rr, rc * 2)) = rs0; } while (0)
; #define SWAIT() asm volatile("s_waitcnt vmcnt(0)" ::: "memory")
; __device__ __forceinline__ void attn_body(const bf16_t* __restrict__ Qb, const bf16_t* __restrict__ Kh, const bf16_t* __restrict__ Vh, const bf16_t* __restrict__ Rh,
;                                           bf16_t* __restrict__ Zb, int seq, char* lds, int wv, bool nowrite) {
;     const int tid = opaque_tid(wv), wid = wv, lane = tid & 63, r32 = lane & 31, hi = lane >> 5;
;     char* V_lds = lds + OFF_V; char* K_lds = lds + OFF_K; char* R_lds = lds + OFF_R;
;     float* ws = (float*)(lds + OFF_WS) + wid * 64; float* li_l = ws; float* al_l = ws + 32;
;     float m_reg = -1e30f, l_reg = 0; f32x16 o[4] = {}; bf16x8 qr[8];
;     const bf16_t* Qw = Qb + (long)(wid * QBLK + r32) * LDQ + hi * 8;
;     char* Qp = lds + OFF_QR + wid * 4096;
; #pragma unroll
;     for (int d0 = 0; d0 < 8; ++d0) qr[d0] = *reinterpret_cast<const bf16x8*>(Qw + d0 * 16);
; #pragma unroll
;     for (int d0 = 0; d0 < 4; ++d0) *reinterpret_cast<bf16x8*>(Qp + RSWZ(r32, (d0 * 16 + hi * 8) * 2)) = *reinterpret_cast<const bf16x8*>(Qw + 128 + d0 * 16);
;     const int sr = tid >> 4, sc = (tid & 15) * 8, vst0 = v_st(sr, sc), vst1 = v_st(32 + sr, sc);
;     const int rr = tid >> 3, rc = (tid & 7) * 8;
;     const int vb0 = (int)(uintptr_t)(LAS char*)V_lds + v_rd_base(lane);
;     bf16x8 vs0, vs1, ks0, ks1, rs0;
;     ...
;     f32x16 pA0, pA1, pB0, pB1; float mnA, mnB, alA, alB; bf16x8 pa0, pa1, pa2, pa3; const int NT = seq / KVBLK;
;     SLOAD(0); SWAIT(); SWRITE(0); __syncthreads();
.LBB0_607:
	s_ashr_i32 s56, s3, 4
	s_ashr_i32 s57, s56, 31
	s_and_b32 s8, s3, 15
	s_lshl_b64 s[6:7], s[56:57], 11
	s_add_u32 s42, s6, s68
	s_addc_u32 s43, s7, 0
	s_lshl_b32 s2, s2, 8
	s_and_b32 s24, s2, 0x700
	s_or_b32 s2, s6, s24
	s_mul_i32 s3, s7, 0x1800
	s_mul_hi_u32 s6, s2, 0x1800
	s_add_i32 s6, s6, s3
	s_mulk_i32 s2, 0x1800
	s_add_u32 s2, s35, s2
	s_addc_u32 s3, s50, s6
	s_mul_i32 s6, s8, 0x180
	s_add_u32 s2, s2, s6
	v_mov_b32_e32 v57, v233
	s_addc_u32 s3, s3, 0
	v_mov_b64_e32 v[0:1], s[2:3]
	v_and_b32_e32 v164, 31, v57
	v_bfe_u32 v165, v57, 5, 1
	v_or_b32_e32 v2, s52, v164
	v_mad_u64_u32 v[0:1], s[2:3], v2, s85, v[0:1]
	v_lshlrev_b32_e32 v212, 4, v165
	v_lshl_add_u64 v[36:37], v[0:1], 0, v[212:213]
	global_load_dwordx4 v[0:3], v[36:37], off offset:256
	global_load_dwordx4 v[4:7], v[36:37], off offset:288
	global_load_dwordx4 v[8:11], v[36:37], off offset:320
	global_load_dwordx4 v[12:15], v[36:37], off offset:352
	s_lshl_b64 s[60:61], s[56:57], 23
	s_add_u32 s6, s51, s60
	s_addc_u32 s7, s64, s61
	s_lshl_b32 s2, s8, 7
	s_lshl_b32 s3, s8, 8
	s_add_u32 s6, s6, s3
	s_addc_u32 s7, s7, 0
	s_add_u32 s8, s65, s60
	v_add_u32_e32 v56, s75, v57
	s_addc_u32 s9, s70, s61
	v_ashrrev_i32_e32 v38, 4, v56
	s_add_u32 s62, s8, s3
	v_lshlrev_b32_e32 v46, 3, v56
	v_add_u32_e32 v40, 32, v38
	s_addc_u32 s63, s9, 0
	s_lshl_b64 s[8:9], s[42:43], 7
	v_and_b32_e32 v16, 0x78, v46
	v_ashrrev_i32_e32 v39, 31, v38
	v_ashrrev_i32_e32 v41, 31, v40
	v_ashrrev_i32_e32 v42, 3, v56
	s_add_u32 s8, s71, s8
	v_lshlrev_b32_e32 v47, 1, v16
	v_lshlrev_b64 v[48:49], 12, v[38:39]
	v_lshlrev_b64 v[24:25], 12, v[40:41]
	v_ashrrev_i32_e32 v43, 31, v42
	v_or_b32_e32 v52, v48, v47
	v_mov_b32_e32 v53, v49
	v_or_b32_e32 v24, v24, v47
	s_addc_u32 s9, s76, s9
	v_lshlrev_b64 v[50:51], 7, v[42:43]
	v_lshlrev_b32_e32 v75, 4, v56
	v_lshl_add_u64 v[16:17], s[62:63], 0, v[52:53]
	v_lshl_add_u64 v[20:21], s[62:63], 0, v[24:25]
	v_lshl_add_u64 v[26:27], s[6:7], 0, v[52:53]
	v_lshl_add_u64 v[28:29], s[6:7], 0, v[24:25]
	v_lshl_add_u64 v[32:33], s[8:9], 0, v[50:51]
	v_and_b32_e32 v44, 0x70, v75
	v_mov_b32_e32 v45, v213
	global_load_dwordx4 v[16:19], v[16:17], off
	v_lshl_add_u64 v[54:55], v[32:33], 0, v[44:45]
	global_load_dwordx4 v[20:23], v[20:21], off
	s_nop 0
	global_load_dwordx4 v[24:27], v[26:27], off
	s_nop 0
	global_load_dwordx4 v[28:31], v[28:29], off
	s_nop 0
	global_load_dwordx4 v[32:35], v[54:55], off
	global_load_dwordx4 v[120:123], v[36:37], off
	global_load_dwordx4 v[124:127], v[36:37], off offset:32
	global_load_dwordx4 v[116:119], v[36:37], off offset:64
	global_load_dwordx4 v[112:115], v[36:37], off offset:96
	global_load_dwordx4 v[108:111], v[36:37], off offset:128
	global_load_dwordx4 v[104:107], v[36:37], off offset:160
	global_load_dwordx4 v[100:103], v[36:37], off offset:192
	global_load_dwordx4 v[96:99], v[36:37], off offset:224
	v_lshlrev_b32_e32 v39, 3, v57
	v_lshlrev_b32_e32 v58, 7, v164
	v_and_b32_e32 v59, 0x70, v39
	v_add_u32_e32 v41, s96, v58
	v_bitop3_b32 v39, v212, v39, s66 bitop3:0x78
	v_bitop3_b32 v43, v212, v59, 32 bitop3:0x36
	v_bitop3_b32 v45, v212, v59, 64 bitop3:0x36
	v_add_u32_e32 v39, v41, v39
	v_add_u32_e32 v43, v41, v43
	v_add_u32_e32 v45, v41, v45
	v_lshlrev_b32_e32 v60, 4, v57
	s_add_i32 s8, 0, 0x10000
	v_or_b32_e32 v61, 64, v212
	v_or_b32_e32 v62, 0x60, v212
	v_bitop3_b32 v186, v212, v58, v59 bitop3:0xde
	v_add_u32_e32 v187, s8, v186
	v_add_u32_e32 v177, s96, v186
	v_and_b32_e32 v77, 63, v57
	v_bitop3_b32 v190, v61, v58, v59 bitop3:0xde
	v_add_u32_e32 v191, s8, v190
	v_add_u32_e32 v178, s96, v190
	v_bitop3_b32 v192, v62, v58, v59 bitop3:0xde
	s_waitcnt vmcnt(0)
	ds_write_b128 v39, v[0:3]
	ds_write_b128 v43, v[4:7]
	ds_write_b128 v45, v[8:11]
	v_bitop3_b32 v0, v212, v59, s31 bitop3:0x36
	v_add_u32_e32 v0, v41, v0
	ds_write_b128 v0, v[12:15]
	v_and_b32_e32 v0, 0xfffff0, v38
	v_lshlrev_b32_e32 v1, 1, v38
	v_and_b32_e32 v4, 0xfffff0, v40
	v_lshlrev_b32_e32 v5, 1, v40
	v_and_or_b32 v0, v1, 8, v0
	v_and_or_b32 v4, v5, 8, v4
	v_lshrrev_b32_e32 v1, 1, v38
	v_lshrrev_b32_e32 v0, 1, v0
	v_bfe_u32 v2, v46, 5, 2
	v_and_b32_e32 v3, 3, v38
	v_lshrrev_b32_e32 v4, 1, v4
	v_or_b32_e32 v0, v0, v2
	v_and_or_b32 v1, v1, 4, v3
	v_or_b32_e32 v2, v4, v2
	v_lshlrev_b32_e32 v0, 9, v0
	v_lshlrev_b32_e32 v1, 6, v1
	v_and_b32_e32 v3, 48, v47
	v_lshlrev_b32_e32 v2, 9, v2
	v_or3_b32 v0, v0, v1, v3
	v_or3_b32 v1, v2, v1, v3
	v_add_u32_e32 v170, 0, v0
	v_add_u32_e32 v171, 0, v1
	v_lshlrev_b32_e32 v0, 8, v38
	v_and_b32_e32 v1, 0x70, v56
	v_bitop3_b32 v0, v47, v0, v1 bitop3:0xde
	v_add_u32_e32 v172, 0, v0
	v_lshlrev_b32_e32 v0, 8, v40
	v_bitop3_b32 v0, v47, v0, v1 bitop3:0xde
	v_add_u32_e32 v173, 0, v0
	v_lshlrev_b32_e32 v0, 7, v42
	v_bitop3_b32 v76, v44, v0, v1 bitop3:0xde
	v_add_u32_e32 v0, s8, v76
	v_lshlrev_b32_e32 v8, 8, v164
	v_and_b32_e32 v9, 0x70, v60
	s_waitcnt vmcnt(0)
	v_or_b32_e32 v12, 32, v212
	ds_write_b128 v170, v[16:19]
	v_bitop3_b32 v188, v12, v58, v59 bitop3:0xde
	ds_write_b128 v171, v[20:23]
	ds_write_b128 v172, v[24:27] offset:32768
	ds_write_b128 v173, v[28:31] offset:32768
	ds_write_b128 v0, v[32:35]
	v_bitop3_b32 v0, v212, v8, v9 bitop3:0xde
	v_add_u32_e32 v174, 0, v0
	s_waitcnt lgkmcnt(0)
	s_barrier
; __device__ __forceinline__ void qkt(f32x16& p0, f32x16& p1, const char* Ks, const char* Rs, const bf16x8* qr, const char* Qp, int r32, int hi) {
;     p0 = f32x16{}; p1 = f32x16{};
; #pragma unroll
;     for (int d0 = 0; d0 < 8; ++d0) { const int cb = (d0 * 16 + hi * 8) * 2;
;         const bf16x8 b0 = *reinterpret_cast<const bf16x8*>(Ks + KSWZ(r32, cb));
;         const bf16x8 b1 = *reinterpret_cast<const bf16x8*>(Ks + KSWZ(32 + r32, cb));
;         p0 = __builtin_amdgcn_mfma_f32_32x32x16_bf16(b0, qr[d0], p0, 0, 0, 0);
;         p1 = __builtin_amdgcn_mfma_f32_32x32x16_bf16(b1, qr[d0], p1, 0, 0, 0); }
; #pragma unroll
;     for (int d0 = 0; d0 < 4; ++d0) { const int cb = (d0 * 16 + hi * 8) * 2;
;         const bf16x8 b0 = *reinterpret_cast<const bf16x8*>(Rs + RSWZ(r32, cb));
;         const bf16x8 b1 = *reinterpret_cast<const bf16x8*>(Rs + RSWZ(32 + r32, cb));
;         const bf16x8 qq = *reinterpret_cast<const bf16x8*>(Qp + RSWZ(r32, cb));
;         p0 = __builtin_amdgcn_mfma_f32_32x32x16_bf16(b0, qq, p0, 0, 0, 0);
;         p1 = __builtin_amdgcn_mfma_f32_32x32x16_bf16(b1, qq, p1, 0, 0, 0); }
	ds_read_b128 v[0:3], v174 offset:32768
	ds_read_b128 v[4:7], v174 offset:40960
	s_waitcnt lgkmcnt(1)
	v_mfma_f32_32x32x16_bf16 v[32:47], v[0:3], v[120:123], 0
	v_bitop3_b32 v0, v12, v8, v9 bitop3:0xde
	v_add_u32_e32 v180, 0, v0
	v_add_u32_e32 v189, s8, v188
	v_add_u32_e32 v175, s96, v188
	v_add_u32_e32 v193, s8, v192
	v_add_u32_e32 v176, s96, v192
	s_mov_b32 s8, s25
	s_waitcnt lgkmcnt(0)
	v_mfma_f32_32x32x16_bf16 v[16:31], v[4:7], v[120:123], 0
	ds_read_b128 v[0:3], v180 offset:32768
	ds_read_b128 v[4:7], v180 offset:40960
	s_mov_b32 s9, s25
	s_mov_b32 s10, s25
	s_mov_b32 s11, s25
	s_mov_b32 s12, s25
	s_mov_b32 s13, s25
	s_mov_b32 s14, s25
	s_waitcnt lgkmcnt(1)
	v_mfma_f32_32x32x16_bf16 v[32:47], v[0:3], v[124:127], v[32:47]
	v_bitop3_b32 v0, v61, v8, v9 bitop3:0xde
	v_add_u32_e32 v182, 0, v0
	s_mov_b32 s15, s25
	s_mov_b32 s16, s25
	s_mov_b32 s17, s25
	s_mov_b32 s18, s25
	s_mov_b32 s19, s25
	s_waitcnt lgkmcnt(0)
	v_mfma_f32_32x32x16_bf16 v[16:31], v[4:7], v[124:127], v[16:31]
	ds_read_b128 v[0:3], v182 offset:32768
	ds_read_b128 v[4:7], v182 offset:40960
	s_mov_b32 s20, s25
	s_mov_b32 s21, s25
	s_mov_b32 s22, s25
	s_mov_b32 s23, s25
	v_add_u32_e32 v195, 0, v76
	v_add_u32_e32 v196, 0x12000, v195
	s_waitcnt lgkmcnt(1)
	v_mfma_f32_32x32x16_bf16 v[32:47], v[0:3], v[116:119], v[32:47]
	v_bitop3_b32 v0, v62, v8, v9 bitop3:0xde
	v_add_u32_e32 v184, 0, v0
	v_lshl_add_u64 v[158:159], s[60:61], 0, v[48:49]
	v_lshl_add_u32 v166, v164, 2, s1
	v_mov_b32_e32 v167, 0
	s_waitcnt lgkmcnt(0)
	v_mfma_f32_32x32x16_bf16 v[16:31], v[4:7], v[116:119], v[16:31]
	ds_read_b128 v[0:3], v184 offset:32768
	ds_read_b128 v[4:7], v184 offset:40960
	s_waitcnt lgkmcnt(1)
	v_mfma_f32_32x32x16_bf16 v[32:47], v[0:3], v[112:115], v[32:47]
	v_or_b32_e32 v0, 0x80, v212
	v_bitop3_b32 v0, v0, v8, v9 bitop3:0xde
	v_add_u32_e32 v185, 0, v0
	s_waitcnt lgkmcnt(0)
	v_mfma_f32_32x32x16_bf16 v[16:31], v[4:7], v[112:115], v[16:31]
	ds_read_b128 v[0:3], v185 offset:32768
	ds_read_b128 v[4:7], v185 offset:40960
	s_waitcnt lgkmcnt(1)
	v_mfma_f32_32x32x16_bf16 v[32:47], v[0:3], v[108:111], v[32:47]
	v_or_b32_e32 v0, 0xa0, v212
	v_bitop3_b32 v0, v0, v8, v9 bitop3:0xde
	v_add_u32_e32 v183, 0, v0
	s_waitcnt lgkmcnt(0)
	v_mfma_f32_32x32x16_bf16 v[16:31], v[4:7], v[108:111], v[16:31]
	ds_read_b128 v[0:3], v183 offset:32768
	ds_read_b128 v[4:7], v183 offset:40960
	s_waitcnt lgkmcnt(1)
	v_mfma_f32_32x32x16_bf16 v[32:47], v[0:3], v[104:107], v[32:47]
	v_or_b32_e32 v0, 0xc0, v212
	v_bitop3_b32 v0, v0, v8, v9 bitop3:0xde
	v_add_u32_e32 v181, 0, v0
	s_waitcnt lgkmcnt(0)
	v_mfma_f32_32x32x16_bf16 v[16:31], v[4:7], v[104:107], v[16:31]
	ds_read_b128 v[0:3], v181 offset:32768
	ds_read_b128 v[4:7], v181 offset:40960
	s_waitcnt lgkmcnt(1)
	v_mfma_f32_32x32x16_bf16 v[32:47], v[0:3], v[100:103], v[32:47]
	v_or_b32_e32 v0, 0xe0, v212
	v_bitop3_b32 v0, v0, v8, v9 bitop3:0xde
	v_add_u32_e32 v179, 0, v0
	s_waitcnt lgkmcnt(0)
	v_mfma_f32_32x32x16_bf16 v[16:31], v[4:7], v[100:103], v[16:31]
	ds_read_b128 v[0:3], v179 offset:32768
	ds_read_b128 v[4:7], v179 offset:40960
	s_waitcnt lgkmcnt(1)
	v_mfma_f32_32x32x16_bf16 v[32:47], v[0:3], v[96:99], v[32:47]
	ds_read_b128 v[0:3], v187
	s_waitcnt lgkmcnt(1)
	v_mfma_f32_32x32x16_bf16 v[16:31], v[4:7], v[96:99], v[16:31]
	ds_read_b128 v[4:7], v177
	ds_read_b128 v[8:11], v187 offset:4096
	ds_read_b128 v[12:15], v189
	s_waitcnt lgkmcnt(2)
	v_mfma_f32_32x32x16_bf16 v[32:47], v[0:3], v[4:7], v[32:47]
	s_waitcnt lgkmcnt(1)
	v_mfma_f32_32x32x16_bf16 v[16:31], v[8:11], v[4:7], v[16:31]
	ds_read_b128 v[0:3], v175
	ds_read_b128 v[4:7], v189 offset:4096
	v_lshlrev_b32_e32 v8, 3, v77
	v_and_b32_e32 v9, 0xc0, v60
	s_waitcnt lgkmcnt(1)
	v_mfma_f32_32x32x16_bf16 v[32:47], v[12:15], v[0:3], v[32:47]
	v_and_or_b32 v12, v8, 24, v9
	v_lshlrev_b32_e32 v9, 1, v57
	v_and_b32_e32 v13, 32, v9
	v_and_b32_e32 v14, 0x100, v8
	ds_read_b128 v[8:11], v191
	v_or3_b32 v57, v12, v13, v14
	v_add_u32_e32 v169, 0, v57
	s_waitcnt lgkmcnt(1)
	v_mfma_f32_32x32x16_bf16 v[16:31], v[4:7], v[0:3], v[16:31]
	ds_read_b128 v[0:3], v178
	ds_read_b128 v[4:7], v191 offset:4096
	ds_read_b128 v[12:15], v193
	ds_read_b128 v[58:61], v193 offset:4096
	ds_read_b128 v[62:65], v176
	s_waitcnt lgkmcnt(4)
	v_mfma_f32_32x32x16_bf16 v[32:47], v[8:11], v[0:3], v[32:47]
	s_waitcnt lgkmcnt(3)
	v_mfma_f32_32x32x16_bf16 v[16:31], v[4:7], v[0:3], v[16:31]
	s_waitcnt lgkmcnt(0)
; #define SWRITE(b) do { *(bf16x8*)(V_lds + (b) * SHM_V + vst0) = vs0; *(bf16x8*)(V_lds + (b) * SHM_V + vst1) = vs1; const int kc = sc * 2; \
;     *(bf16x8*)(K_lds + (b) * SHM_K + KSWZ(sr, kc)) = ks0; *(bf16x8*)(K_lds + (b) * SHM_K + KSWZ(32 + sr, kc)) = ks1; \
;     *(bf16x8*)(R_lds + (b) * SHM_R + RSWZ(rr, rc * 2)) = rs0; } while (0)
; #define SWAIT() asm volatile("s_waitcnt vmcnt(0)" ::: "memory")
; __device__ __forceinline__ void partialSM(f32x16& p0, f32x16& p1, float& m_reg, float& mn, float& alpha) {
;     constexpr float C = SCALE * 1.4426950408889634f;
;     float pmax = p0[0];
; #pragma unroll
;     for (int r = 1; r < 16; ++r) pmax = fmaxf(pmax, p0[r]);
; #pragma unroll
;     for (int r = 0; r < 16; ++r) pmax = fmaxf(pmax, p1[r]);
;     { auto rr = __builtin_amdgcn_permlane32_swap(__float_as_uint(pmax), __float_as_uint(pmax), false, false);
;       pmax = fmaxf(__uint_as_float(rr[0]), __uint_as_float(rr[1])); }
;     if (__builtin_expect(__all(pmax - m_reg <= THR / SCALE), 1)) { mn = m_reg; alpha = 1.f; }
;     else { mn = fmaxf(m_reg, pmax); alpha = __builtin_amdgcn_exp2f((m_reg - mn) * C); m_reg = mn; }
;     const float mnC = -mn * C;
; #pragma unroll
;     for (int r = 0; r < 16; ++r) p0[r] = fmaf(p0[r], C, mnC);
; #pragma unroll
;     for (int r = 0; r < 16; ++r) p1[r] = fmaf(p1[r], C, mnC);
; #pragma unroll
;     for (int r = 0; r < 16; ++r) p0[r] = __builtin_amdgcn_exp2f(p0[r]);
; }
; __device__ __forceinline__ void attn_body(const bf16_t* __restrict__ Qb, const bf16_t* __restrict__ Kh, const bf16_t* __restrict__ Vh, const bf16_t* __restrict__ Rh,
;                                           bf16_t* __restrict__ Zb, int seq, char* lds, int wv, bool nowrite) {
;     ...
;     f32x16 pA0, pA1, pB0, pB1; float mnA, mnB, alA, alB; bf16x8 pa0, pa1, pa2, pa3; const int NT = seq / KVBLK;
;     SLOAD(0); SWAIT(); SWRITE(0); __syncthreads();
;     qkt(pA0, pA1, K_lds, R_lds, qr, Qp, r32, hi); partialSM(pA0, pA1, m_reg, mnA, alA);
;     SLOAD(KVBLK);
;     SWAIT(); SWRITE(1); __syncthreads();
	v_mfma_f32_32x32x16_bf16 v[32:47], v[12:15], v[62:65], v[32:47]
	v_mov_b64_e32 v[0:1], s[8:9]
	v_mov_b64_e32 v[2:3], s[10:11]
	v_mov_b64_e32 v[4:5], s[12:13]
	v_mov_b64_e32 v[6:7], s[14:15]
	v_mov_b64_e32 v[8:9], s[16:17]
	v_mov_b64_e32 v[10:11], s[18:19]
	v_mov_b64_e32 v[12:13], s[20:21]
	v_mov_b64_e32 v[14:15], s[22:23]
	s_mov_b64 s[8:9], 0x40000
	v_mfma_f32_32x32x16_bf16 v[16:31], v[58:61], v[62:65], v[16:31]
	s_nop 1
	v_max_f32_e32 v58, v33, v33
	v_max_f32_e32 v59, v32, v32
	v_lshl_add_u64 v[66:67], v[52:53], 0, s[8:9]
	s_mov_b64 s[8:9], 0x60000
	v_max_f32_e32 v58, v59, v58
	v_lshl_add_u64 v[52:53], v[52:53], 0, s[8:9]
	v_max3_f32 v74, v58, v34, v35
	v_lshl_add_u64 v[58:59], s[62:63], 0, v[66:67]
	v_lshl_add_u64 v[62:63], s[62:63], 0, v[52:53]
	v_lshl_add_u64 v[66:67], s[6:7], 0, v[66:67]
	v_lshl_add_u64 v[52:53], s[6:7], 0, v[52:53]
	s_movk_i32 s6, 0x2000
	global_load_dwordx4 v[58:61], v[58:59], off
	s_nop 0
	global_load_dwordx4 v[62:65], v[62:63], off
	s_nop 0
	global_load_dwordx4 v[66:69], v[66:67], off
	s_nop 0
	global_load_dwordx4 v[70:73], v[52:53], off
	v_add_co_u32_e32 v52, vcc, s6, v54
	v_max3_f32 v74, v74, v36, v37
	s_nop 0
	v_addc_co_u32_e32 v53, vcc, 0, v55, vcc
	global_load_dwordx4 v[52:55], v[52:53], off
	v_max3_f32 v74, v74, v38, v39
	v_max3_f32 v74, v74, v40, v41
	v_max3_f32 v74, v74, v42, v43
	v_max3_f32 v74, v74, v44, v45
	v_max3_f32 v74, v74, v46, v47
	v_max3_f32 v74, v74, v16, v17
	v_max3_f32 v74, v74, v18, v19
	v_max3_f32 v74, v74, v20, v21
	v_max3_f32 v74, v74, v22, v23
	v_max3_f32 v74, v74, v24, v25
	v_max3_f32 v74, v74, v26, v27
	v_max3_f32 v74, v74, v28, v29
	v_max3_f32 v74, v74, v30, v31
	v_mov_b32_e32 v78, v74
	s_nop 1
	v_permlane32_swap_b32_e32 v74, v78
	v_max_f32_e32 v78, v78, v78
	v_max_f32_e32 v74, v74, v74
	v_max_f32_e32 v74, v74, v78
	v_add_f32_e32 v78, 0x7149f2ca, v74
	v_max_f32_e32 v74, 0xf149f2ca, v74
	v_cmp_ge_f32_e32 vcc, s88, v78
	v_sub_f32_e32 v78, 0xf149f2ca, v74
	v_mul_f32_e32 v78, 0x3dd53b94, v78
	v_exp_f32_e32 v78, v78
	s_cmp_eq_u64 vcc, exec
	s_cselect_b64 vcc, -1, 0
	v_cndmask_b32_e32 v197, v74, v235, vcc
	s_add_i32 s8, 0, 0x4000
	v_mul_f32_e32 v74, 0xbdd53b94, v197
	v_add_u32_e32 v168, s8, v57
	s_lshl_b64 s[8:9], s[56:57], 18
	v_cndmask_b32_e64 v194, v78, 1.0, vcc
	v_mov_b32_e32 v78, v74
	s_add_u32 s8, s72, s8
	v_fmamk_f32 v32, v32, 0x3dd53b94, v74
	v_fmamk_f32 v33, v33, 0x3dd53b94, v74
	v_fmamk_f32 v34, v34, 0x3dd53b94, v74
	v_fmamk_f32 v35, v35, 0x3dd53b94, v74
	v_fmamk_f32 v36, v36, 0x3dd53b94, v74
	v_fmamk_f32 v37, v37, 0x3dd53b94, v74
	v_fmamk_f32 v38, v38, 0x3dd53b94, v74
	v_fmamk_f32 v39, v39, 0x3dd53b94, v74
	v_fmamk_f32 v40, v40, 0x3dd53b94, v74
	v_fmamk_f32 v41, v41, 0x3dd53b94, v74
	v_fmamk_f32 v42, v42, 0x3dd53b94, v74
	v_fmamk_f32 v43, v43, 0x3dd53b94, v74
	v_fmamk_f32 v44, v44, 0x3dd53b94, v74
	v_fmamk_f32 v45, v45, 0x3dd53b94, v74
	v_fmamk_f32 v46, v46, 0x3dd53b94, v74
	v_fmac_f32_e32 v78, 0x3dd53b94, v47
	v_pk_fma_f32 v[138:139], v[18:19], s[36:37], v[74:75] op_sel_hi:[1,0,0]
	s_addc_u32 s9, s73, s9
	v_and_b32_e32 v18, 7, v56
	v_pk_fma_f32 v[140:141], v[16:17], s[36:37], v[74:75] op_sel_hi:[1,0,0]
	v_exp_f32_e32 v162, v32
	v_exp_f32_e32 v205, v33
	v_exp_f32_e32 v149, v34
	v_exp_f32_e32 v163, v35
	v_exp_f32_e32 v150, v36
	v_exp_f32_e32 v161, v37
	v_exp_f32_e32 v151, v38
	v_exp_f32_e32 v160, v39
	v_exp_f32_e32 v152, v40
	v_exp_f32_e32 v155, v41
	v_exp_f32_e32 v153, v42
	v_exp_f32_e32 v154, v43
	v_exp_f32_e32 v145, v44
	v_exp_f32_e32 v147, v45
	v_exp_f32_e32 v144, v46
	v_exp_f32_e32 v146, v78
	v_lshl_add_u64 v[16:17], s[8:9], 0, v[50:51]
	v_lshlrev_b32_e32 v18, 4, v18
	v_mov_b32_e32 v19, v213
	s_waitcnt vmcnt(0)
	v_lshl_add_u64 v[156:157], v[16:17], 0, v[18:19]
	v_and_b32_e32 v16, 0xf0, v75
	v_pk_fma_f32 v[134:135], v[30:31], s[36:37], v[74:75] op_sel_hi:[1,0,0]
	v_pk_fma_f32 v[136:137], v[28:29], s[36:37], v[74:75] op_sel_hi:[1,0,0]
	v_pk_fma_f32 v[142:143], v[26:27], s[36:37], v[74:75] op_sel_hi:[1,0,0]
	v_pk_fma_f32 v[128:129], v[24:25], s[36:37], v[74:75] op_sel_hi:[1,0,0]
	v_pk_fma_f32 v[130:131], v[22:23], s[36:37], v[74:75] op_sel_hi:[1,0,0]
	v_pk_fma_f32 v[132:133], v[20:21], s[36:37], v[74:75] op_sel_hi:[1,0,0]
	s_waitcnt vmcnt(4)
	ds_write_b128 v170, v[58:61] offset:16384
	s_waitcnt vmcnt(3)
	ds_write_b128 v171, v[62:65] offset:16384
	s_waitcnt vmcnt(2)
	ds_write_b128 v172, v[66:69] offset:49152
	s_waitcnt vmcnt(1)
	ds_write_b128 v173, v[70:73] offset:49152
	s_waitcnt vmcnt(0)
	ds_write_b128 v196, v[52:55]
	v_or3_b32 v158, v158, s3, v16
	v_mov_b64_e32 v[62:63], v[14:15]
	v_mov_b64_e32 v[46:47], v[14:15]
	v_mov_b64_e32 v[30:31], v[14:15]
	v_cmp_gt_u32_e64 s[6:7], 32, v77
	s_mov_b32 s3, -1
	v_mov_b64_e32 v[60:61], v[12:13]
	v_mov_b64_e32 v[58:59], v[10:11]
	v_mov_b64_e32 v[56:57], v[8:9]
	v_mov_b64_e32 v[54:55], v[6:7]
	v_mov_b64_e32 v[52:53], v[4:5]
	v_mov_b64_e32 v[50:51], v[2:3]
	v_mov_b64_e32 v[48:49], v[0:1]
	v_mov_b64_e32 v[44:45], v[12:13]
	v_mov_b64_e32 v[42:43], v[10:11]
	v_mov_b64_e32 v[40:41], v[8:9]
	v_mov_b64_e32 v[38:39], v[6:7]
	v_mov_b64_e32 v[36:37], v[4:5]
	v_mov_b64_e32 v[34:35], v[2:3]
	v_mov_b64_e32 v[32:33], v[0:1]
	v_mov_b64_e32 v[28:29], v[12:13]
	v_mov_b64_e32 v[26:27], v[10:11]
	v_mov_b64_e32 v[24:25], v[8:9]
	v_mov_b64_e32 v[22:23], v[6:7]
	v_mov_b64_e32 v[20:21], v[4:5]
	v_mov_b64_e32 v[18:19], v[2:3]
	v_mov_b64_e32 v[16:17], v[0:1]
	v_add_u32_e32 v242, 0x30080000, v158
	v_add_u32_e32 v243, 0x300a0000, v158
	v_add_u32_e32 v244, 0x28080000, v158
	v_add_u32_e32 v245, 0x280a0000, v158
	v_add_u32_e32 v246, 0x3e004000, v156
	s_waitcnt lgkmcnt(0)
	s_barrier
; #define SBAR() __builtin_amdgcn_sched_barrier(0)
; __device__ __forceinline__ void finishSM(f32x16& p0, f32x16& p1, float alpha, float& l_reg, bf16x8& pa0, bf16x8& pa1, bf16x8& pa2, bf16x8& pa3) {
; #pragma unroll
;     for (int r = 0; r < 16; ++r) p1[r] = __builtin_amdgcn_exp2f(p1[r]);
;     float ps = 0;
; #pragma unroll
;     for (int r = 0; r < 16; ++r) ps += p0[r];
; #pragma unroll
;     for (int r = 0; r < 16; ++r) ps += p1[r];
;     { auto rr = __builtin_amdgcn_permlane32_swap(__float_as_uint(ps), __float_as_uint(ps), false, false);
;       ps = __uint_as_float(rr[0]) + __uint_as_float(rr[1]); }
;     l_reg = l_reg * alpha + ps;
; __device__ __forceinline__ void qkt(f32x16& p0, f32x16& p1, const char* Ks, const char* Rs, const bf16x8* qr, const char* Qp, int r32, int hi) {
;     p0 = f32x16{}; p1 = f32x16{};
; #pragma unroll
;     for (int d0 = 0; d0 < 8; ++d0) { const int cb = (d0 * 16 + hi * 8) * 2;
;         const bf16x8 b0 = *reinterpret_cast<const bf16x8*>(Ks + KSWZ(r32, cb));
;         const bf16x8 b1 = *reinterpret_cast<const bf16x8*>(Ks + KSWZ(32 + r32, cb));
;         p0 = __builtin_amdgcn_mfma_f32_32x32x16_bf16(b0, qr[d0], p0, 0, 0, 0);
;         p1 = __builtin_amdgcn_mfma_f32_32x32x16_bf16(b1, qr[d0], p1, 0, 0, 0); }
; #pragma unroll
;     for (int d0 = 0; d0 < 4; ++d0) { const int cb = (d0 * 16 + hi * 8) * 2;
;         const bf16x8 b0 = *reinterpret_cast<const bf16x8*>(Rs + RSWZ(r32, cb));
;         const bf16x8 b1 = *reinterpret_cast<const bf16x8*>(Rs + RSWZ(32 + r32, cb));
;         const bf16x8 qq = *reinterpret_cast<const bf16x8*>(Qp + RSWZ(r32, cb));
;         p0 = __builtin_amdgcn_mfma_f32_32x32x16_bf16(b0, qq, p0, 0, 0, 0);
;         p1 = __builtin_amdgcn_mfma_f32_32x32x16_bf16(b1, qq, p1, 0, 0, 0); }
; __device__ __forceinline__ void attn_body(const bf16_t* __restrict__ Qb, const bf16_t* __restrict__ Kh, const bf16_t* __restrict__ Vh, const bf16_t* __restrict__ Rh,
;                                           bf16_t* __restrict__ Zb, int seq, char* lds, int wv, bool nowrite) {
;     ...
;     for (int j = 1; j + 1 < NT; j += 2) {
;         SBAR(); qkt(pB0, pB1, K_lds + SHM_K, R_lds + SHM_R, qr, Qp, r32, hi);
;         finishSM(pA0, pA1, alA, l_reg, pa0, pa1, pa2, pa3); SBAR();
.LBB0_608:
	ds_read_b128 v[64:67], v174 offset:49152
	ds_read_b128 v[68:71], v174 offset:57344
	ds_read_b128 v[198:201], v180 offset:49152
	ds_read_b128 v[206:209], v180 offset:57344
	s_add_i32 s8, 0, 0x12000
	v_add_f32_e32 v148, 0, v162
	s_waitcnt lgkmcnt(3)
	v_mfma_f32_32x32x16_bf16 v[80:95], v[64:67], v[120:123], 0
	v_add_f32_e32 v148, v205, v148
	v_add_f32_e32 v148, v149, v148
	v_add_f32_e32 v148, v163, v148
	v_add_f32_e32 v148, v150, v148
	v_add_f32_e32 v148, v161, v148
	v_add_f32_e32 v148, v151, v148
	v_add_f32_e32 v148, v160, v148
	s_waitcnt lgkmcnt(2)
	v_mfma_f32_32x32x16_bf16 v[64:79], v[68:71], v[120:123], 0
	v_add_f32_e32 v148, v152, v148
	v_add_f32_e32 v148, v155, v148
	v_add_f32_e32 v148, v153, v148
	v_add_f32_e32 v148, v154, v148
	v_exp_f32_e32 v140, v140
	v_add_f32_e32 v148, v145, v148
	v_exp_f32_e32 v141, v141
	s_waitcnt lgkmcnt(1)
	v_mfma_f32_32x32x16_bf16 v[80:95], v[198:201], v[124:127], v[80:95]
	v_add_f32_e32 v148, v147, v148
	v_exp_f32_e32 v138, v138
	v_add_f32_e32 v148, v144, v148
	v_exp_f32_e32 v139, v139
	v_add_f32_e32 v148, v146, v148
	v_exp_f32_e32 v132, v132
	v_add_f32_e32 v148, v140, v148
	s_waitcnt lgkmcnt(0)
	v_mfma_f32_32x32x16_bf16 v[64:79], v[206:209], v[124:127], v[64:79]
	ds_read_b128 v[198:201], v182 offset:49152
	ds_read_b128 v[206:209], v182 offset:57344
	v_exp_f32_e32 v133, v133
	v_add_f32_e32 v148, v141, v148
	v_exp_f32_e32 v130, v130
	v_add_f32_e32 v148, v138, v148
	v_exp_f32_e32 v131, v131
	v_add_f32_e32 v148, v139, v148
	s_waitcnt lgkmcnt(1)
	v_mfma_f32_32x32x16_bf16 v[80:95], v[198:201], v[116:119], v[80:95]
	v_exp_f32_e32 v128, v128
	v_add_f32_e32 v148, v132, v148
	v_exp_f32_e32 v129, v129
	v_add_f32_e32 v148, v133, v148
	v_exp_f32_e32 v142, v142
	v_add_f32_e32 v148, v130, v148
	v_exp_f32_e32 v143, v143
	s_waitcnt lgkmcnt(0)
	v_mfma_f32_32x32x16_bf16 v[64:79], v[206:209], v[116:119], v[64:79]
	ds_read_b128 v[198:201], v184 offset:49152
	ds_read_b128 v[206:209], v184 offset:57344
	v_add_f32_e32 v148, v131, v148
	v_exp_f32_e32 v136, v136
	v_add_f32_e32 v148, v128, v148
	v_exp_f32_e32 v137, v137
	v_add_f32_e32 v148, v129, v148
	v_exp_f32_e32 v134, v134
	s_waitcnt lgkmcnt(1)
	v_mfma_f32_32x32x16_bf16 v[80:95], v[198:201], v[112:115], v[80:95]
	v_add_f32_e32 v148, v142, v148
	v_exp_f32_e32 v135, v135
	v_add_f32_e32 v148, v143, v148
	v_add_f32_e32 v148, v136, v148
	v_add_f32_e32 v148, v137, v148
	v_add_f32_e32 v148, v134, v148
	s_waitcnt lgkmcnt(0)
	v_mfma_f32_32x32x16_bf16 v[64:79], v[206:209], v[112:115], v[64:79]
	ds_read_b128 v[198:201], v185 offset:49152
	ds_read_b128 v[206:209], v185 offset:57344
	s_waitcnt lgkmcnt(1)
	v_mfma_f32_32x32x16_bf16 v[80:95], v[198:201], v[108:111], v[80:95]
	s_waitcnt lgkmcnt(0)
	v_mfma_f32_32x32x16_bf16 v[64:79], v[206:209], v[108:111], v[64:79]
	ds_read_b128 v[198:201], v183 offset:49152
	ds_read_b128 v[206:209], v183 offset:57344
	s_waitcnt lgkmcnt(1)
	v_mfma_f32_32x32x16_bf16 v[80:95], v[198:201], v[104:107], v[80:95]
	s_waitcnt lgkmcnt(0)
	v_mfma_f32_32x32x16_bf16 v[64:79], v[206:209], v[104:107], v[64:79]
	ds_read_b128 v[198:201], v181 offset:49152
	ds_read_b128 v[206:209], v181 offset:57344
	s_waitcnt lgkmcnt(1)
	v_mfma_f32_32x32x16_bf16 v[80:95], v[198:201], v[100:103], v[80:95]
	s_waitcnt lgkmcnt(0)
	v_mfma_f32_32x32x16_bf16 v[64:79], v[206:209], v[100:103], v[64:79]
	ds_read_b128 v[198:201], v179 offset:49152
	ds_read_b128 v[206:209], v179 offset:57344
	s_waitcnt lgkmcnt(1)
	v_mfma_f32_32x32x16_bf16 v[80:95], v[198:201], v[96:99], v[80:95]
	v_add_u32_e32 v199, s8, v186
	v_add_u32_e32 v198, s8, v188
	s_waitcnt lgkmcnt(0)
	v_mfma_f32_32x32x16_bf16 v[64:79], v[206:209], v[96:99], v[64:79]
	ds_read_b128 v[200:203], v199
	ds_read_b128 v[206:209], v199 offset:4096
	ds_read_b128 v[214:217], v177
	s_waitcnt lgkmcnt(0)
	v_mfma_f32_32x32x16_bf16 v[80:95], v[200:203], v[214:217], v[80:95]
	v_mfma_f32_32x32x16_bf16 v[64:79], v[206:209], v[214:217], v[64:79]
	ds_read_b128 v[200:203], v198
	ds_read_b128 v[206:209], v198 offset:4096
	ds_read_b128 v[214:217], v175
	s_waitcnt lgkmcnt(0)
	v_mfma_f32_32x32x16_bf16 v[80:95], v[200:203], v[214:217], v[80:95]
	v_add_u32_e32 v200, s8, v190
	v_add_u32_e32 v201, s8, v192
	v_add_f32_e32 v202, v135, v148
	v_mov_b32_e32 v203, v202
	s_nop 1
	v_permlane32_swap_b32_e32 v202, v203
	v_mfma_f32_32x32x16_bf16 v[64:79], v[206:209], v[214:217], v[64:79]
	ds_read_b128 v[206:209], v200
	ds_read_b128 v[214:217], v200 offset:4096
	ds_read_b128 v[218:221], v178
	s_waitcnt lgkmcnt(0)
	v_mfma_f32_32x32x16_bf16 v[80:95], v[206:209], v[218:221], v[80:95]
	v_mfma_f32_32x32x16_bf16 v[64:79], v[214:217], v[218:221], v[64:79]
	ds_read_b128 v[206:209], v201
	ds_read_b128 v[214:217], v201 offset:4096
	ds_read_b128 v[218:221], v176
	v_cvt_pk_bf16_f32 v148, v162, v205
	v_cvt_pk_bf16_f32 v149, v149, v163
	v_cvt_pk_bf16_f32 v150, v150, v161
	v_cvt_pk_bf16_f32 v151, v151, v160
	v_cvt_pk_bf16_f32 v152, v152, v155
	v_cvt_pk_bf16_f32 v153, v153, v154
	s_waitcnt lgkmcnt(0)
; __device__ __forceinline__ void partialSM(f32x16& p0, f32x16& p1, float& m_reg, float& mn, float& alpha) {
;     constexpr float C = SCALE * 1.4426950408889634f;
;     float pmax = p0[0];
; #pragma unroll
;     for (int r = 1; r < 16; ++r) pmax = fmaxf(pmax, p0[r]);
; #pragma unroll
;     for (int r = 0; r < 16; ++r) pmax = fmaxf(pmax, p1[r]);
;     { auto rr = __builtin_amdgcn_permlane32_swap(__float_as_uint(pmax), __float_as_uint(pmax), false, false);
; __device__ __forceinline__ void finishSM(f32x16& p0, f32x16& p1, float alpha, float& l_reg, bf16x8& pa0, bf16x8& pa1, bf16x8& pa2, bf16x8& pa3) {
;     ...
;     PK4(p0, 0, pa0); PK4(p0, 8, pa1); PK4(p1, 0, pa2); PK4(p1, 8, pa3);
; template <int D0> __device__ __forceinline__ void pv_one(f32x16& od, int vb, bf16x8 pa0, bf16x8 pa1, bf16x8 pa2, bf16x8 pa3) {
;     const s16x4 l0 = tr_read<v_rd_off(D0, 0, 0)>(vb), h0 = tr_read<v_rd_off(D0, 0, 1)>(vb), l1 = tr_read<v_rd_off(D0, 1, 0)>(vb), h1 = tr_read<v_rd_off(D0, 1, 1)>(vb);
;     const s16x4 l2 = tr_read<v_rd_off(D0, 2, 0)>(vb), h2 = tr_read<v_rd_off(D0, 2, 1)>(vb), l3 = tr_read<v_rd_off(D0, 3, 0)>(vb), h3 = tr_read<v_rd_off(D0, 3, 1)>(vb);
;     asm volatile("s_waitcnt lgkmcnt(0)" ::: "memory"); SBAR();
;     ...
;     od = __builtin_amdgcn_mfma_f32_32x32x16_bf16(pa0, PK(l0, h0), od, 0, 0, 0);
;     od = __builtin_amdgcn_mfma_f32_32x32x16_bf16(pa1, PK(l1, h1), od, 0, 0, 0);
;     od = __builtin_amdgcn_mfma_f32_32x32x16_bf16(pa2, PK(l2, h2), od, 0, 0, 0);
;     od = __builtin_amdgcn_mfma_f32_32x32x16_bf16(pa3, PK(l3, h3), od, 0, 0, 0);
;     ...
; }
; __device__ __forceinline__ void pv_d0(f32x16* o, int vb, bf16x8 pa0, bf16x8 pa1, bf16x8 pa2, bf16x8 pa3) {
;     pv_one<0>(o[0], vb, pa0, pa1, pa2, pa3); pv_one<1>(o[1], vb, pa0, pa1, pa2, pa3); pv_one<2>(o[2], vb, pa0, pa1, pa2, pa3); pv_one<3>(o[3], vb, pa0, pa1, pa2, pa3);
; __device__ __forceinline__ void attn_body(const bf16_t* __restrict__ Qb, const bf16_t* __restrict__ Kh, const bf16_t* __restrict__ Vh, const bf16_t* __restrict__ Rh,
;                                           bf16_t* __restrict__ Zb, int seq, char* lds, int wv, bool nowrite) {
;     ...
;         finishSM(pA0, pA1, alA, l_reg, pa0, pa1, pa2, pa3); SBAR();
;         SLOAD((j + 1) * KVBLK); SBAR();
;         pv_d0(o, vb0, pa0, pa1, pa2, pa3); partialSM(pB0, pB1, m_reg, mnB, alB);
;         __syncthreads(); SWAIT(); SWRITE(0);
;         RESC(alB); __syncthreads();
	v_mfma_f32_32x32x16_bf16 v[80:95], v[206:209], v[218:221], v[80:95]
	v_cvt_pk_bf16_f32 v154, v145, v147
	v_cvt_pk_bf16_f32 v155, v144, v146
	v_cvt_pk_bf16_f32 v204, v140, v141
	v_cvt_pk_bf16_f32 v205, v138, v139
	v_cvt_pk_bf16_f32 v206, v132, v133
	v_permlane32_swap_b32_e32 v148, v150
	v_mfma_f32_32x32x16_bf16 v[64:79], v[214:217], v[218:221], v[64:79]
	v_cvt_pk_bf16_f32 v207, v130, v131
	v_permlane32_swap_b32_e32 v204, v206
	v_cvt_pk_bf16_f32 v208, v128, v129
	v_cvt_pk_bf16_f32 v209, v142, v143
	v_cvt_pk_bf16_f32 v210, v136, v137
	v_cvt_pk_bf16_f32 v211, v134, v135
	v_permlane32_swap_b32_e32 v149, v151
	v_permlane32_swap_b32_e32 v152, v154
	v_permlane32_swap_b32_e32 v153, v155
	v_permlane32_swap_b32_e32 v205, v207
	v_permlane32_swap_b32_e32 v208, v210
	v_permlane32_swap_b32_e32 v209, v211
	global_load_dwordx4 v[128:131], v242, s[44:45]
	global_load_dwordx4 v[132:135], v243, s[44:45]
	global_load_dwordx4 v[136:139], v244, s[44:45]
	global_load_dwordx4 v[140:143], v245, s[44:45]
	global_load_dwordx4 v[144:147], v246, s[44:45]
	v_add_u32_e32 v242, 0x40000, v242
	v_add_u32_e32 v243, 0x40000, v243
	v_add_u32_e32 v244, 0x40000, v244
	v_add_u32_e32 v245, 0x40000, v245
	v_add_u32_e32 v246, 0x2000, v246
	ds_read_b64_tr_b16 v[214:215], v169 offset:0
	ds_read_b64_tr_b16 v[216:217], v169 offset:0x800
	ds_read_b64_tr_b16 v[218:219], v169 offset:0x1000
	ds_read_b64_tr_b16 v[220:221], v169 offset:0x1800
	ds_read_b64_tr_b16 v[224:225], v169 offset:0x2000
	ds_read_b64_tr_b16 v[226:227], v169 offset:0x2800
	ds_read_b64_tr_b16 v[238:239], v169 offset:0x3000
	ds_read_b64_tr_b16 v[240:241], v169 offset:0x3800
	s_waitcnt lgkmcnt(0)
	s_nop 0
	v_mfma_f32_32x32x16_bf16 v[0:15], v[148:151], v[214:217], v[0:15]
	ds_read_b64_tr_b16 v[214:215], v169 offset:0x200
	ds_read_b64_tr_b16 v[216:217], v169 offset:0xa00
	v_mfma_f32_32x32x16_bf16 v[0:15], v[152:155], v[218:221], v[0:15]
	ds_read_b64_tr_b16 v[218:219], v169 offset:0x1200
	ds_read_b64_tr_b16 v[220:221], v169 offset:0x1a00
	v_mfma_f32_32x32x16_bf16 v[0:15], v[204:207], v[224:227], v[0:15]
	ds_read_b64_tr_b16 v[224:225], v169 offset:0x2200
	ds_read_b64_tr_b16 v[226:227], v169 offset:0x2a00
	v_mfma_f32_32x32x16_bf16 v[0:15], v[208:211], v[238:241], v[0:15]
	ds_read_b64_tr_b16 v[238:239], v169 offset:0x3200
	ds_read_b64_tr_b16 v[240:241], v169 offset:0x3a00
	s_waitcnt lgkmcnt(0)
	v_mfma_f32_32x32x16_bf16 v[48:63], v[148:151], v[214:217], v[48:63]
	ds_read_b64_tr_b16 v[214:215], v169 offset:0x400
	ds_read_b64_tr_b16 v[216:217], v169 offset:0xc00
	v_mfma_f32_32x32x16_bf16 v[48:63], v[152:155], v[218:221], v[48:63]
	ds_read_b64_tr_b16 v[218:219], v169 offset:0x1400
	ds_read_b64_tr_b16 v[220:221], v169 offset:0x1c00
	v_mfma_f32_32x32x16_bf16 v[48:63], v[204:207], v[224:227], v[48:63]
	ds_read_b64_tr_b16 v[224:225], v169 offset:0x2400
	ds_read_b64_tr_b16 v[226:227], v169 offset:0x2c00
	v_mfma_f32_32x32x16_bf16 v[48:63], v[208:211], v[238:241], v[48:63]
	ds_read_b64_tr_b16 v[238:239], v169 offset:0x3400
	ds_read_b64_tr_b16 v[240:241], v169 offset:0x3c00
	s_waitcnt lgkmcnt(0)
	v_mfma_f32_32x32x16_bf16 v[32:47], v[148:151], v[214:217], v[32:47]
	ds_read_b64_tr_b16 v[214:215], v169 offset:0x600
	ds_read_b64_tr_b16 v[216:217], v169 offset:0xe00
	v_mfma_f32_32x32x16_bf16 v[32:47], v[152:155], v[218:221], v[32:47]
	ds_read_b64_tr_b16 v[218:219], v169 offset:0x1600
	ds_read_b64_tr_b16 v[220:221], v169 offset:0x1e00
	v_mfma_f32_32x32x16_bf16 v[32:47], v[204:207], v[224:227], v[32:47]
	ds_read_b64_tr_b16 v[224:225], v169 offset:0x2600
	ds_read_b64_tr_b16 v[226:227], v169 offset:0x2e00
	v_mfma_f32_32x32x16_bf16 v[32:47], v[208:211], v[238:241], v[32:47]
	ds_read_b64_tr_b16 v[238:239], v169 offset:0x3600
	ds_read_b64_tr_b16 v[240:241], v169 offset:0x3e00
	s_waitcnt lgkmcnt(0)
	v_mfma_f32_32x32x16_bf16 v[16:31], v[148:151], v[214:217], v[16:31]
	v_max_f32_e32 v148, v81, v81
	v_max_f32_e32 v149, v80, v80
	v_max_f32_e32 v148, v149, v148
	v_max3_f32 v148, v148, v82, v83
	v_max3_f32 v148, v148, v84, v85
	v_max3_f32 v148, v148, v86, v87
	v_max3_f32 v148, v148, v88, v89
	v_max3_f32 v148, v148, v90, v91
	v_max3_f32 v148, v148, v92, v93
	v_mfma_f32_32x32x16_bf16 v[16:31], v[152:155], v[218:221], v[16:31]
	v_max3_f32 v148, v148, v94, v95
	v_max3_f32 v148, v148, v64, v65
	v_max3_f32 v148, v148, v66, v67
	v_max3_f32 v148, v148, v68, v69
	v_max3_f32 v148, v148, v70, v71
	v_max3_f32 v148, v148, v72, v73
	v_max3_f32 v148, v148, v74, v75
	v_max3_f32 v148, v148, v76, v77
	v_mfma_f32_32x32x16_bf16 v[16:31], v[204:207], v[224:227], v[16:31]
	v_max3_f32 v148, v148, v78, v79
	v_mov_b32_e32 v149, v148
	s_nop 1
	v_permlane32_swap_b32_e32 v148, v149
	v_max_f32_e32 v149, v149, v149
	v_max_f32_e32 v148, v148, v148
	v_max_f32_e32 v148, v148, v149
	v_sub_f32_e32 v149, v148, v197
	v_cmp_ge_f32_e32 vcc, s88, v149
	v_max_f32_e32 v149, v197, v197
	v_max_f32_e32 v148, v149, v148
	v_mfma_f32_32x32x16_bf16 v[16:31], v[208:211], v[238:241], v[16:31]
	v_sub_f32_e32 v149, v197, v148
	v_mul_f32_e32 v149, 0x3dd53b94, v149
	v_exp_f32_e32 v149, v149
	s_cmp_eq_u64 vcc, exec
	s_cselect_b64 s[8:9], -1, 0
	s_barrier
	s_waitcnt vmcnt(0)
	v_cndmask_b32_e64 v204, v149, 1.0, s[8:9]
	ds_write_b128 v170, v[128:131]
	ds_write_b128 v171, v[132:135]
	ds_write_b128 v172, v[136:139] offset:32768
	ds_write_b128 v173, v[140:143] offset:32768
	v_add_u32_e32 v128, 0x10000, v195
	v_cmp_gt_f32_e32 vcc, 1.0, v204
	ds_write_b128 v128, v[144:147]
	s_cbranch_vccz .LBB0_612
; #define SBAR() __builtin_amdgcn_sched_barrier(0)
; #define SWAIT() asm volatile("s_waitcnt vmcnt(0)" ::: "memory")
; __device__ __forceinline__ void qkt(f32x16& p0, f32x16& p1, const char* Ks, const char* Rs, const bf16x8* qr, const char* Qp, int r32, int hi) {
;     p0 = f32x16{}; p1 = f32x16{};
; #pragma unroll
;     for (int d0 = 0; d0 < 8; ++d0) { const int cb = (d0 * 16 + hi * 8) * 2;
;         const bf16x8 b0 = *reinterpret_cast<const bf16x8*>(Ks + KSWZ(r32, cb));
;         const bf16x8 b1 = *reinterpret_cast<const bf16x8*>(Ks + KSWZ(32 + r32, cb));
;         p0 = __builtin_amdgcn_mfma_f32_32x32x16_bf16(b0, qr[d0], p0, 0, 0, 0);
;         p1 = __builtin_amdgcn_mfma_f32_32x32x16_bf16(b1, qr[d0], p1, 0, 0, 0); }
; #pragma unroll
;     for (int d0 = 0; d0 < 4; ++d0) { const int cb = (d0 * 16 + hi * 8) * 2;
;         const bf16x8 b0 = *reinterpret_cast<const bf16x8*>(Rs + RSWZ(r32, cb));
;         const bf16x8 b1 = *reinterpret_cast<const bf16x8*>(Rs + RSWZ(32 + r32, cb));
;         const bf16x8 qq = *reinterpret_cast<const bf16x8*>(Qp + RSWZ(r32, cb));
;         p0 = __builtin_amdgcn_mfma_f32_32x32x16_bf16(b0, qq, p0, 0, 0, 0);
;         p1 = __builtin_amdgcn_mfma_f32_32x32x16_bf16(b1, qq, p1, 0, 0, 0); }
; __device__ __forceinline__ void attn_body(const bf16_t* __restrict__ Qb, const bf16_t* __restrict__ Kh, const bf16_t* __restrict__ Vh, const bf16_t* __restrict__ Rh,
;                                           bf16_t* __restrict__ Zb, int seq, char* lds, int wv, bool nowrite) {
;     ...
;     f32x16 pA0, pA1, pB0, pB1; float mnA, mnB, alA, alB; bf16x8 pa0, pa1, pa2, pa3; const int NT = seq / KVBLK;
;     SLOAD(0); SWAIT(); SWRITE(0); __syncthreads();
;     qkt(pA0, pA1, K_lds, R_lds, qr, Qp, r32, hi); partialSM(pA0, pA1, m_reg, mnA, alA);
;     SLOAD(KVBLK);
;     SWAIT(); SWRITE(1); __syncthreads();
;     for (int j = 1; j + 1 < NT; j += 2) {
;         SBAR(); qkt(pB0, pB1, K_lds + SHM_K, R_lds + SHM_R, qr, Qp, r32, hi);
;         finishSM(pA0, pA1, alA, l_reg, pa0, pa1, pa2, pa3); SBAR();
;         SLOAD((j + 1) * KVBLK); SBAR();
;         pv_d0(o, vb0, pa0, pa1, pa2, pa3); partialSM(pB0, pB1, m_reg, mnB, alB);
;         __syncthreads(); SWAIT(); SWRITE(0);
;         RESC(alB); __syncthreads();
;         SBAR(); qkt(pA0, pA1, K_lds, R_lds, qr, Qp, r32, hi);
	s_and_saveexec_b64 s[10:11], s[6:7]
	ds_write_b32 v166, v204 offset:128
	s_or_b64 exec, exec, s[10:11]
	s_waitcnt lgkmcnt(0)
	v_add_u32_e32 v140, s1, v212
	ds_read_b128 v[128:131], v140 offset:224
	ds_read_b128 v[132:135], v140 offset:192
	ds_read_b128 v[136:139], v140 offset:160
	ds_read_b128 v[140:143], v140 offset:128
	s_waitcnt lgkmcnt(3)
	v_pk_mul_f32 v[12:13], v[12:13], v[128:129]
	s_waitcnt lgkmcnt(2)
	v_pk_mul_f32 v[8:9], v[8:9], v[132:133]
	s_waitcnt lgkmcnt(1)
	v_pk_mul_f32 v[4:5], v[4:5], v[136:137]
	v_pk_mul_f32 v[14:15], v[14:15], v[130:131]
	v_pk_mul_f32 v[10:11], v[10:11], v[134:135]
	v_pk_mul_f32 v[6:7], v[6:7], v[138:139]
	s_waitcnt lgkmcnt(0)
	v_pk_mul_f32 v[2:3], v[2:3], v[142:143]
	v_pk_mul_f32 v[0:1], v[0:1], v[140:141]
	v_pk_mul_f32 v[60:61], v[60:61], v[128:129]
	v_pk_mul_f32 v[56:57], v[56:57], v[132:133]
	v_pk_mul_f32 v[52:53], v[52:53], v[136:137]
	v_pk_mul_f32 v[62:63], v[62:63], v[130:131]
	v_pk_mul_f32 v[58:59], v[58:59], v[134:135]
	v_pk_mul_f32 v[54:55], v[54:55], v[138:139]
	v_pk_mul_f32 v[50:51], v[50:51], v[142:143]
	v_pk_mul_f32 v[48:49], v[48:49], v[140:141]
	v_pk_mul_f32 v[44:45], v[44:45], v[128:129]
	v_pk_mul_f32 v[40:41], v[40:41], v[132:133]
	v_pk_mul_f32 v[36:37], v[36:37], v[136:137]
	v_pk_mul_f32 v[46:47], v[46:47], v[130:131]
	v_pk_mul_f32 v[42:43], v[42:43], v[134:135]
	v_pk_mul_f32 v[38:39], v[38:39], v[138:139]
	v_pk_mul_f32 v[34:35], v[34:35], v[142:143]
	v_pk_mul_f32 v[32:33], v[32:33], v[140:141]
	v_pk_mul_f32 v[28:29], v[28:29], v[128:129]
	v_pk_mul_f32 v[24:25], v[24:25], v[132:133]
	v_pk_mul_f32 v[20:21], v[20:21], v[136:137]
	v_pk_mul_f32 v[30:31], v[30:31], v[130:131]
	v_pk_mul_f32 v[26:27], v[26:27], v[134:135]
	v_pk_mul_f32 v[22:23], v[22:23], v[138:139]
	v_pk_mul_f32 v[18:19], v[18:19], v[142:143]
	v_pk_mul_f32 v[16:17], v[16:17], v[140:141]
.LBB0_612:
	v_cndmask_b32_e64 v197, v148, v197, s[8:9]
	v_mul_f32_e32 v144, 0xbdd53b94, v197
	v_fmamk_f32 v80, v80, 0x3dd53b94, v144
	v_fmamk_f32 v81, v81, 0x3dd53b94, v144
	v_fmamk_f32 v82, v82, 0x3dd53b94, v144
	v_fmamk_f32 v83, v83, 0x3dd53b94, v144
	v_fmamk_f32 v84, v84, 0x3dd53b94, v144
	v_fmamk_f32 v85, v85, 0x3dd53b94, v144
	v_fmamk_f32 v86, v86, 0x3dd53b94, v144
	v_fmamk_f32 v87, v87, 0x3dd53b94, v144
	v_fmamk_f32 v88, v88, 0x3dd53b94, v144
	v_fmamk_f32 v89, v89, 0x3dd53b94, v144
	v_fmamk_f32 v90, v90, 0x3dd53b94, v144
	v_fmamk_f32 v91, v91, 0x3dd53b94, v144
	v_fmamk_f32 v92, v92, 0x3dd53b94, v144
	v_fmamk_f32 v93, v93, 0x3dd53b94, v144
	v_fmamk_f32 v94, v94, 0x3dd53b94, v144
	v_fmamk_f32 v95, v95, 0x3dd53b94, v144
	v_fmamk_f32 v206, v68, 0x3dd53b94, v144
	v_fmamk_f32 v148, v71, 0x3dd53b94, v144
	v_fmamk_f32 v149, v72, 0x3dd53b94, v144
	v_fmamk_f32 v207, v77, 0x3dd53b94, v144
	v_fmamk_f32 v153, v64, 0x3dd53b94, v144
	v_fmamk_f32 v154, v65, 0x3dd53b94, v144
	v_fmamk_f32 v155, v66, 0x3dd53b94, v144
	v_fmamk_f32 v205, v67, 0x3dd53b94, v144
	v_fmamk_f32 v146, v69, 0x3dd53b94, v144
	v_fmamk_f32 v147, v70, 0x3dd53b94, v144
	v_fmamk_f32 v150, v73, 0x3dd53b94, v144
	v_fmamk_f32 v151, v74, 0x3dd53b94, v144
	v_fmamk_f32 v152, v75, 0x3dd53b94, v144
	v_fmamk_f32 v145, v76, 0x3dd53b94, v144
	v_exp_f32_e32 v141, v80
	v_exp_f32_e32 v143, v81
	v_exp_f32_e32 v139, v82
	v_exp_f32_e32 v142, v83
	v_exp_f32_e32 v138, v84
	v_exp_f32_e32 v140, v85
	v_exp_f32_e32 v136, v86
	v_exp_f32_e32 v137, v87
	v_exp_f32_e32 v133, v88
	v_exp_f32_e32 v135, v89
	v_exp_f32_e32 v132, v90
	v_exp_f32_e32 v134, v91
	v_exp_f32_e32 v129, v92
	v_exp_f32_e32 v131, v93
	v_exp_f32_e32 v128, v94
	v_exp_f32_e32 v130, v95
	v_fmamk_f32 v208, v78, 0x3dd53b94, v144
	v_fmac_f32_e32 v144, 0x3dd53b94, v79
	s_waitcnt lgkmcnt(0)
	s_barrier
	ds_read_b128 v[64:67], v174 offset:32768
	ds_read_b128 v[68:71], v174 offset:40960
	ds_read_b128 v[214:217], v180 offset:32768
	ds_read_b128 v[218:221], v180 offset:40960
	v_exp_f32_e32 v209, v153
	v_exp_f32_e32 v210, v154
	s_waitcnt lgkmcnt(3)
	v_mfma_f32_32x32x16_bf16 v[80:95], v[64:67], v[120:123], 0
	v_exp_f32_e32 v211, v155
	v_exp_f32_e32 v205, v205
	v_exp_f32_e32 v146, v146
	v_exp_f32_e32 v147, v147
	v_exp_f32_e32 v145, v145
	v_exp_f32_e32 v144, v144
	s_waitcnt lgkmcnt(2)
	v_mfma_f32_32x32x16_bf16 v[64:79], v[68:71], v[120:123], 0
	s_waitcnt lgkmcnt(1)
	v_mfma_f32_32x32x16_bf16 v[80:95], v[214:217], v[124:127], v[80:95]
	s_waitcnt lgkmcnt(0)
	v_mfma_f32_32x32x16_bf16 v[64:79], v[218:221], v[124:127], v[64:79]
	ds_read_b128 v[214:217], v182 offset:32768
	ds_read_b128 v[218:221], v182 offset:40960
	s_waitcnt lgkmcnt(1)
	v_mfma_f32_32x32x16_bf16 v[80:95], v[214:217], v[116:119], v[80:95]
	s_waitcnt lgkmcnt(0)
	v_mfma_f32_32x32x16_bf16 v[64:79], v[218:221], v[116:119], v[64:79]
	ds_read_b128 v[214:217], v184 offset:32768
	ds_read_b128 v[218:221], v184 offset:40960
	s_waitcnt lgkmcnt(1)
	v_mfma_f32_32x32x16_bf16 v[80:95], v[214:217], v[112:115], v[80:95]
	s_waitcnt lgkmcnt(0)
	v_mfma_f32_32x32x16_bf16 v[64:79], v[218:221], v[112:115], v[64:79]
	ds_read_b128 v[214:217], v185 offset:32768
	ds_read_b128 v[218:221], v185 offset:40960
	s_waitcnt lgkmcnt(1)
	v_mfma_f32_32x32x16_bf16 v[80:95], v[214:217], v[108:111], v[80:95]
	s_waitcnt lgkmcnt(0)
	v_mfma_f32_32x32x16_bf16 v[64:79], v[218:221], v[108:111], v[64:79]
	ds_read_b128 v[214:217], v183 offset:32768
	ds_read_b128 v[218:221], v183 offset:40960
	s_waitcnt lgkmcnt(1)
	v_mfma_f32_32x32x16_bf16 v[80:95], v[214:217], v[104:107], v[80:95]
	s_waitcnt lgkmcnt(0)
	v_mfma_f32_32x32x16_bf16 v[64:79], v[218:221], v[104:107], v[64:79]
	ds_read_b128 v[214:217], v181 offset:32768
	ds_read_b128 v[218:221], v181 offset:40960
	s_waitcnt lgkmcnt(1)
	v_mfma_f32_32x32x16_bf16 v[80:95], v[214:217], v[100:103], v[80:95]
	s_waitcnt lgkmcnt(0)
; __device__ __forceinline__ void qkt(f32x16& p0, f32x16& p1, const char* Ks, const char* Rs, const bf16x8* qr, const char* Qp, int r32, int hi) {
;     p0 = f32x16{}; p1 = f32x16{};
; #pragma unroll
;     for (int d0 = 0; d0 < 8; ++d0) { const int cb = (d0 * 16 + hi * 8) * 2;
;         const bf16x8 b0 = *reinterpret_cast<const bf16x8*>(Ks + KSWZ(r32, cb));
;         const bf16x8 b1 = *reinterpret_cast<const bf16x8*>(Ks + KSWZ(32 + r32, cb));
;         p0 = __builtin_amdgcn_mfma_f32_32x32x16_bf16(b0, qr[d0], p0, 0, 0, 0);
;         p1 = __builtin_amdgcn_mfma_f32_32x32x16_bf16(b1, qr[d0], p1, 0, 0, 0); }
; #pragma unroll
;     for (int d0 = 0; d0 < 4; ++d0) { const int cb = (d0 * 16 + hi * 8) * 2;
;         const bf16x8 b0 = *reinterpret_cast<const bf16x8*>(Rs + RSWZ(r32, cb));
;         const bf16x8 b1 = *reinterpret_cast<const bf16x8*>(Rs + RSWZ(32 + r32, cb));
;         const bf16x8 qq = *reinterpret_cast<const bf16x8*>(Qp + RSWZ(r32, cb));
;         p0 = __builtin_amdgcn_mfma_f32_32x32x16_bf16(b0, qq, p0, 0, 0, 0);
;         p1 = __builtin_amdgcn_mfma_f32_32x32x16_bf16(b1, qq, p1, 0, 0, 0); }
; }
; __device__ __forceinline__ int v_st(int k, int c) { const int kk = (k & ~0xC) | ((k & 4) << 1) | ((k & 8) >> 1); return ((kk >> 3) * 4 + (c >> 5)) * 512 + ((kk & 7) * 32 + (c & 31)) * 2; }
; __device__ __forceinline__ int v_rd_base(int lane) { return ((lane & 3) << 3) | (((lane >> 2) & 3) << 6) | (((lane >> 4) & 1) << 5) | (((lane >> 5) & 1) << 8); }
; template <int OFF> __device__ __forceinline__ s16x4 tr_read(int vb) {
;     s16x4 r; asm volatile("ds_read_b64_tr_b16 %0, %1 offset:%2" : "=&v"(r) : "v"(vb), "i"(OFF) : "memory"); return r;
; }
; template <int D0> __device__ __forceinline__ void pv_one(f32x16& od, int vb, bf16x8 pa0, bf16x8 pa1, bf16x8 pa2, bf16x8 pa3) {
;     const s16x4 l0 = tr_read<v_rd_off(D0, 0, 0)>(vb), h0 = tr_read<v_rd_off(D0, 0, 1)>(vb), l1 = tr_read<v_rd_off(D0, 1, 0)>(vb), h1 = tr_read<v_rd_off(D0, 1, 1)>(vb);
;     const s16x4 l2 = tr_read<v_rd_off(D0, 2, 0)>(vb), h2 = tr_read<v_rd_off(D0, 2, 1)>(vb), l3 = tr_read<v_rd_off(D0, 3, 0)>(vb), h3 = tr_read<v_rd_off(D0, 3, 1)>(vb);
;     asm volatile("s_waitcnt lgkmcnt(0)" ::: "memory"); SBAR();
;     ...
;     od = __builtin_amdgcn_mfma_f32_32x32x16_bf16(pa0, PK(l0, h0), od, 0, 0, 0);
;     od = __builtin_amdgcn_mfma_f32_32x32x16_bf16(pa1, PK(l1, h1), od, 0, 0, 0);
	v_mfma_f32_32x32x16_bf16 v[64:79], v[218:221], v[100:103], v[64:79]
	ds_read_b128 v[214:217], v179 offset:32768
	ds_read_b128 v[218:221], v179 offset:40960
	s_waitcnt lgkmcnt(1)
	v_mfma_f32_32x32x16_bf16 v[80:95], v[214:217], v[96:99], v[80:95]
	s_waitcnt lgkmcnt(0)
	v_mfma_f32_32x32x16_bf16 v[64:79], v[218:221], v[96:99], v[64:79]
	ds_read_b128 v[214:217], v187
	ds_read_b128 v[218:221], v187 offset:4096
	ds_read_b128 v[224:227], v177
	s_waitcnt lgkmcnt(0)
	v_mfma_f32_32x32x16_bf16 v[80:95], v[214:217], v[224:227], v[80:95]
	v_mfma_f32_32x32x16_bf16 v[64:79], v[218:221], v[224:227], v[64:79]
	ds_read_b128 v[214:217], v189
	ds_read_b128 v[218:221], v189 offset:4096
	ds_read_b128 v[224:227], v175
	s_waitcnt lgkmcnt(0)
	v_mfma_f32_32x32x16_bf16 v[80:95], v[214:217], v[224:227], v[80:95]
	v_mfma_f32_32x32x16_bf16 v[64:79], v[218:221], v[224:227], v[64:79]
	ds_read_b128 v[214:217], v191
	ds_read_b128 v[218:221], v191 offset:4096
	ds_read_b128 v[224:227], v178
	s_waitcnt lgkmcnt(0)
	v_mfma_f32_32x32x16_bf16 v[80:95], v[214:217], v[224:227], v[80:95]
	v_mfma_f32_32x32x16_bf16 v[64:79], v[218:221], v[224:227], v[64:79]
	ds_read_b128 v[214:217], v193
	ds_read_b128 v[218:221], v193 offset:4096
	ds_read_b128 v[224:227], v176
	s_waitcnt lgkmcnt(0)
	v_mfma_f32_32x32x16_bf16 v[80:95], v[214:217], v[224:227], v[80:95]
	v_exp_f32_e32 v215, v148
	v_add_f32_e32 v148, 0, v141
	v_add_f32_e32 v148, v143, v148
	v_add_f32_e32 v148, v139, v148
	v_add_f32_e32 v148, v142, v148
	v_add_f32_e32 v148, v138, v148
	v_add_f32_e32 v148, v140, v148
	v_add_f32_e32 v148, v136, v148
	v_add_f32_e32 v148, v137, v148
	v_add_f32_e32 v148, v133, v148
	v_add_f32_e32 v148, v135, v148
	v_add_f32_e32 v148, v132, v148
	v_add_f32_e32 v148, v134, v148
	v_add_f32_e32 v148, v129, v148
	v_add_f32_e32 v148, v131, v148
	v_add_f32_e32 v148, v128, v148
	v_add_f32_e32 v148, v130, v148
	v_exp_f32_e32 v214, v206
	v_add_f32_e32 v148, v209, v148
	v_add_f32_e32 v148, v210, v148
	v_add_f32_e32 v148, v211, v148
	v_add_f32_e32 v148, v205, v148
	v_exp_f32_e32 v216, v149
	v_add_f32_e32 v148, v214, v148
	v_exp_f32_e32 v217, v150
	v_add_f32_e32 v148, v146, v148
	v_mfma_f32_32x32x16_bf16 v[64:79], v[218:221], v[224:227], v[64:79]
	v_exp_f32_e32 v218, v151
	v_add_f32_e32 v148, v147, v148
	v_exp_f32_e32 v219, v152
	v_add_f32_e32 v148, v215, v148
	v_add_f32_e32 v148, v216, v148
	v_exp_f32_e32 v220, v207
	v_add_f32_e32 v148, v217, v148
	v_exp_f32_e32 v221, v208
	v_add_f32_e32 v148, v218, v148
	v_add_f32_e32 v148, v219, v148
	v_add_f32_e32 v148, v145, v148
	v_add_f32_e32 v148, v220, v148
	v_add_f32_e32 v148, v221, v148
	v_add_f32_e32 v206, v144, v148
	v_mov_b32_e32 v207, v206
	v_cvt_pk_bf16_f32 v148, v141, v143
	v_cvt_pk_bf16_f32 v149, v139, v142
	v_cvt_pk_bf16_f32 v150, v138, v140
	v_cvt_pk_bf16_f32 v151, v136, v137
	s_nop 1
	v_permlane32_swap_b32_e32 v206, v207
	v_permlane32_swap_b32_e32 v148, v150
	v_permlane32_swap_b32_e32 v149, v151
	v_cvt_pk_bf16_f32 v152, v133, v135
	v_cvt_pk_bf16_f32 v153, v132, v134
	v_cvt_pk_bf16_f32 v154, v129, v131
	v_cvt_pk_bf16_f32 v155, v128, v130
	v_cvt_pk_bf16_f32 v208, v209, v210
	v_cvt_pk_bf16_f32 v209, v211, v205
	v_cvt_pk_bf16_f32 v210, v214, v146
	v_cvt_pk_bf16_f32 v211, v147, v215
	v_cvt_pk_bf16_f32 v214, v216, v217
	v_cvt_pk_bf16_f32 v215, v218, v219
	v_cvt_pk_bf16_f32 v216, v145, v220
	v_cvt_pk_bf16_f32 v217, v221, v144
	s_nop 0
	v_permlane32_swap_b32_e32 v152, v154
	v_permlane32_swap_b32_e32 v153, v155
	v_permlane32_swap_b32_e32 v208, v210
	v_permlane32_swap_b32_e32 v209, v211
	v_permlane32_swap_b32_e32 v214, v216
	v_permlane32_swap_b32_e32 v215, v217
	global_load_dwordx4 v[128:131], v242, s[44:45]
	global_load_dwordx4 v[132:135], v243, s[44:45]
	global_load_dwordx4 v[136:139], v244, s[44:45]
	global_load_dwordx4 v[140:143], v245, s[44:45]
	global_load_dwordx4 v[144:147], v246, s[44:45]
	v_add_u32_e32 v242, 0x40000, v242
	v_add_u32_e32 v243, 0x40000, v243
	v_add_u32_e32 v244, 0x40000, v244
	v_add_u32_e32 v245, 0x40000, v245
	v_add_u32_e32 v246, 0x2000, v246
	ds_read_b64_tr_b16 v[160:161], v168 offset:0
	ds_read_b64_tr_b16 v[162:163], v168 offset:0x800
	ds_read_b64_tr_b16 v[218:219], v168 offset:0x1000
	ds_read_b64_tr_b16 v[220:221], v168 offset:0x1800
	ds_read_b64_tr_b16 v[224:225], v168 offset:0x2000
	ds_read_b64_tr_b16 v[226:227], v168 offset:0x2800
	ds_read_b64_tr_b16 v[238:239], v168 offset:0x3000
	ds_read_b64_tr_b16 v[240:241], v168 offset:0x3800
	s_waitcnt lgkmcnt(0)
	s_nop 0
	v_mfma_f32_32x32x16_bf16 v[0:15], v[148:151], v[160:163], v[0:15]
	ds_read_b64_tr_b16 v[160:161], v168 offset:0x200
	ds_read_b64_tr_b16 v[162:163], v168 offset:0xa00
	v_mfma_f32_32x32x16_bf16 v[0:15], v[152:155], v[218:221], v[0:15]
	ds_read_b64_tr_b16 v[218:219], v168 offset:0x1200
	ds_read_b64_tr_b16 v[220:221], v168 offset:0x1a00
	v_mfma_f32_32x32x16_bf16 v[0:15], v[208:211], v[224:227], v[0:15]
	ds_read_b64_tr_b16 v[224:225], v168 offset:0x2200
	ds_read_b64_tr_b16 v[226:227], v168 offset:0x2a00
	v_mfma_f32_32x32x16_bf16 v[0:15], v[214:217], v[238:241], v[0:15]
	ds_read_b64_tr_b16 v[238:239], v168 offset:0x3200
	ds_read_b64_tr_b16 v[240:241], v168 offset:0x3a00
	s_waitcnt lgkmcnt(0)
	v_mfma_f32_32x32x16_bf16 v[48:63], v[148:151], v[160:163], v[48:63]
	ds_read_b64_tr_b16 v[160:161], v168 offset:0x400
	ds_read_b64_tr_b16 v[162:163], v168 offset:0xc00
	v_mfma_f32_32x32x16_bf16 v[48:63], v[152:155], v[218:221], v[48:63]
	ds_read_b64_tr_b16 v[218:219], v168 offset:0x1400
	ds_read_b64_tr_b16 v[220:221], v168 offset:0x1c00
	v_mfma_f32_32x32x16_bf16 v[48:63], v[208:211], v[224:227], v[48:63]
	ds_read_b64_tr_b16 v[224:225], v168 offset:0x2400
	ds_read_b64_tr_b16 v[226:227], v168 offset:0x2c00
	v_mfma_f32_32x32x16_bf16 v[48:63], v[214:217], v[238:241], v[48:63]
	ds_read_b64_tr_b16 v[238:239], v168 offset:0x3400
	ds_read_b64_tr_b16 v[240:241], v168 offset:0x3c00
	s_waitcnt lgkmcnt(0)
; #define SBAR() __builtin_amdgcn_sched_barrier(0)
; #define SWAIT() asm volatile("s_waitcnt vmcnt(0)" ::: "memory")
; __device__ __forceinline__ void partialSM(f32x16& p0, f32x16& p1, float& m_reg, float& mn, float& alpha) {
;     constexpr float C = SCALE * 1.4426950408889634f;
;     float pmax = p0[0];
; #pragma unroll
;     for (int r = 1; r < 16; ++r) pmax = fmaxf(pmax, p0[r]);
; #pragma unroll
;     for (int r = 0; r < 16; ++r) pmax = fmaxf(pmax, p1[r]);
;     { auto rr = __builtin_amdgcn_permlane32_swap(__float_as_uint(pmax), __float_as_uint(pmax), false, false);
;       pmax = fmaxf(__uint_as_float(rr[0]), __uint_as_float(rr[1])); }
;     if (__builtin_expect(__all(pmax - m_reg <= THR / SCALE), 1)) { mn = m_reg; alpha = 1.f; }
;     else { mn = fmaxf(m_reg, pmax); alpha = __builtin_amdgcn_exp2f((m_reg - mn) * C); m_reg = mn; }
;     const float mnC = -mn * C;
; #pragma unroll
;     for (int r = 0; r < 16; ++r) p0[r] = fmaf(p0[r], C, mnC);
; #pragma unroll
;     for (int r = 0; r < 16; ++r) p1[r] = fmaf(p1[r], C, mnC);
; #pragma unroll
;     for (int r = 0; r < 16; ++r) p0[r] = __builtin_amdgcn_exp2f(p0[r]);
; }
; __device__ __forceinline__ void attn_body(const bf16_t* __restrict__ Qb, const bf16_t* __restrict__ Kh, const bf16_t* __restrict__ Vh, const bf16_t* __restrict__ Rh,
;                                           bf16_t* __restrict__ Zb, int seq, char* lds, int wv, bool nowrite) {
;     ...
;     for (int j = 1; j + 1 < NT; j += 2) {
;         SBAR(); qkt(pB0, pB1, K_lds + SHM_K, R_lds + SHM_R, qr, Qp, r32, hi);
;         finishSM(pA0, pA1, alA, l_reg, pa0, pa1, pa2, pa3); SBAR();
;         SLOAD((j + 1) * KVBLK); SBAR();
;         pv_d0(o, vb0, pa0, pa1, pa2, pa3); partialSM(pB0, pB1, m_reg, mnB, alB);
;         __syncthreads(); SWAIT(); SWRITE(0);
;         RESC(alB); __syncthreads();
;         SBAR(); qkt(pA0, pA1, K_lds, R_lds, qr, Qp, r32, hi);
;         finishSM(pB0, pB1, alB, l_reg, pa0, pa1, pa2, pa3); SBAR();
;         SLOAD((j + 2) * KVBLK); SBAR();
;         pv_d0(o, vb0 + SHM_V, pa0, pa1, pa2, pa3); partialSM(pA0, pA1, m_reg, mnA, alA);
;         __syncthreads(); SWAIT(); SWRITE(1);
;         RESC(alA); __syncthreads();
;     }
	v_mfma_f32_32x32x16_bf16 v[32:47], v[148:151], v[160:163], v[32:47]
	ds_read_b64_tr_b16 v[160:161], v168 offset:0x600
	ds_read_b64_tr_b16 v[162:163], v168 offset:0xe00
	v_mfma_f32_32x32x16_bf16 v[32:47], v[152:155], v[218:221], v[32:47]
	ds_read_b64_tr_b16 v[218:219], v168 offset:0x1600
	ds_read_b64_tr_b16 v[220:221], v168 offset:0x1e00
	v_mfma_f32_32x32x16_bf16 v[32:47], v[208:211], v[224:227], v[32:47]
	ds_read_b64_tr_b16 v[224:225], v168 offset:0x2600
	ds_read_b64_tr_b16 v[226:227], v168 offset:0x2e00
	v_mfma_f32_32x32x16_bf16 v[32:47], v[214:217], v[238:241], v[32:47]
	ds_read_b64_tr_b16 v[238:239], v168 offset:0x3600
	ds_read_b64_tr_b16 v[240:241], v168 offset:0x3e00
	s_waitcnt lgkmcnt(0)
	v_mfma_f32_32x32x16_bf16 v[16:31], v[148:151], v[160:163], v[16:31]
	v_max_f32_e32 v148, v81, v81
	v_max_f32_e32 v149, v80, v80
	v_max_f32_e32 v148, v149, v148
	v_max3_f32 v148, v148, v82, v83
	v_max3_f32 v148, v148, v84, v85
	v_max3_f32 v148, v148, v86, v87
	v_max3_f32 v148, v148, v88, v89
	v_max3_f32 v148, v148, v90, v91
	v_max3_f32 v148, v148, v92, v93
	v_mfma_f32_32x32x16_bf16 v[16:31], v[152:155], v[218:221], v[16:31]
	v_max3_f32 v148, v148, v94, v95
	v_max3_f32 v148, v148, v64, v65
	v_max3_f32 v148, v148, v66, v67
	v_max3_f32 v148, v148, v68, v69
	v_max3_f32 v148, v148, v70, v71
	v_max3_f32 v148, v148, v72, v73
	v_max3_f32 v148, v148, v74, v75
	v_max3_f32 v148, v148, v76, v77
	v_mfma_f32_32x32x16_bf16 v[16:31], v[208:211], v[224:227], v[16:31]
	v_max3_f32 v148, v148, v78, v79
	v_mov_b32_e32 v149, v148
	s_nop 1
	v_permlane32_swap_b32_e32 v148, v149
	v_max_f32_e32 v149, v149, v149
	v_max_f32_e32 v148, v148, v148
	v_max_f32_e32 v148, v148, v149
	v_sub_f32_e32 v149, v148, v197
	v_cmp_ge_f32_e32 vcc, s88, v149
	v_max_f32_e32 v149, v197, v197
	v_max_f32_e32 v149, v149, v148
	v_mfma_f32_32x32x16_bf16 v[16:31], v[214:217], v[238:241], v[16:31]
	v_sub_f32_e32 v148, v197, v149
	v_mul_f32_e32 v148, 0x3dd53b94, v148
	v_exp_f32_e32 v148, v148
	s_cmp_eq_u64 vcc, exec
	s_cselect_b64 s[8:9], -1, 0
	s_barrier
	s_waitcnt vmcnt(0)
	v_cndmask_b32_e64 v148, v148, 1.0, s[8:9]
	v_cmp_gt_f32_e32 vcc, 1.0, v148
	ds_write_b128 v170, v[128:131] offset:16384
	ds_write_b128 v171, v[132:135] offset:16384
	ds_write_b128 v172, v[136:139] offset:49152
	ds_write_b128 v173, v[140:143] offset:49152
	ds_write_b128 v196, v[144:147]
	s_cbranch_vccz .LBB0_616
	s_and_saveexec_b64 s[10:11], s[6:7]
	ds_write_b32 v166, v148 offset:128
	s_or_b64 exec, exec, s[10:11]
	s_waitcnt lgkmcnt(0)
	v_add_u32_e32 v140, s1, v212
	ds_read_b128 v[128:131], v140 offset:224
	ds_read_b128 v[132:135], v140 offset:192
	ds_read_b128 v[136:139], v140 offset:160
	ds_read_b128 v[140:143], v140 offset:128
	s_waitcnt lgkmcnt(3)
	v_pk_mul_f32 v[12:13], v[12:13], v[128:129]
	s_waitcnt lgkmcnt(2)
	v_pk_mul_f32 v[8:9], v[8:9], v[132:133]
	s_waitcnt lgkmcnt(1)
	v_pk_mul_f32 v[4:5], v[4:5], v[136:137]
	v_pk_mul_f32 v[14:15], v[14:15], v[130:131]
	v_pk_mul_f32 v[10:11], v[10:11], v[134:135]
	v_pk_mul_f32 v[6:7], v[6:7], v[138:139]
	s_waitcnt lgkmcnt(0)
	v_pk_mul_f32 v[2:3], v[2:3], v[142:143]
	v_pk_mul_f32 v[0:1], v[0:1], v[140:141]
	v_pk_mul_f32 v[60:61], v[60:61], v[128:129]
	v_pk_mul_f32 v[56:57], v[56:57], v[132:133]
	v_pk_mul_f32 v[52:53], v[52:53], v[136:137]
	v_pk_mul_f32 v[62:63], v[62:63], v[130:131]
	v_pk_mul_f32 v[58:59], v[58:59], v[134:135]
	v_pk_mul_f32 v[54:55], v[54:55], v[138:139]
	v_pk_mul_f32 v[50:51], v[50:51], v[142:143]
	v_pk_mul_f32 v[48:49], v[48:49], v[140:141]
	v_pk_mul_f32 v[44:45], v[44:45], v[128:129]
	v_pk_mul_f32 v[40:41], v[40:41], v[132:133]
	v_pk_mul_f32 v[36:37], v[36:37], v[136:137]
	v_pk_mul_f32 v[46:47], v[46:47], v[130:131]
	v_pk_mul_f32 v[42:43], v[42:43], v[134:135]
	v_pk_mul_f32 v[38:39], v[38:39], v[138:139]
	v_pk_mul_f32 v[34:35], v[34:35], v[142:143]
	v_pk_mul_f32 v[32:33], v[32:33], v[140:141]
	v_pk_mul_f32 v[28:29], v[28:29], v[128:129]
	v_pk_mul_f32 v[24:25], v[24:25], v[132:133]
	v_pk_mul_f32 v[20:21], v[20:21], v[136:137]
	v_pk_mul_f32 v[30:31], v[30:31], v[130:131]
	v_pk_mul_f32 v[26:27], v[26:27], v[134:135]
	v_pk_mul_f32 v[22:23], v[22:23], v[138:139]
	v_pk_mul_f32 v[18:19], v[18:19], v[142:143]
	v_pk_mul_f32 v[16:17], v[16:17], v[140:141]
.LBB0_616:
	v_cndmask_b32_e64 v197, v149, v197, s[8:9]
	v_mul_f32_e32 v134, 0xbdd53b94, v197
	v_mov_b32_e32 v135, v134
	v_fmamk_f32 v80, v80, 0x3dd53b94, v134
	v_fmamk_f32 v81, v81, 0x3dd53b94, v134
	v_fmamk_f32 v82, v82, 0x3dd53b94, v134
	v_fmamk_f32 v83, v83, 0x3dd53b94, v134
	v_fmamk_f32 v84, v84, 0x3dd53b94, v134
	v_fmamk_f32 v85, v85, 0x3dd53b94, v134
	v_fmamk_f32 v86, v86, 0x3dd53b94, v134
	v_fmamk_f32 v87, v87, 0x3dd53b94, v134
	v_fmamk_f32 v88, v88, 0x3dd53b94, v134
	v_fmamk_f32 v89, v89, 0x3dd53b94, v134
	v_fmamk_f32 v90, v90, 0x3dd53b94, v134
	v_fmamk_f32 v91, v91, 0x3dd53b94, v134
	v_fmamk_f32 v92, v92, 0x3dd53b94, v134
	v_fmamk_f32 v93, v93, 0x3dd53b94, v134
	v_fmamk_f32 v94, v94, 0x3dd53b94, v134
	v_fmac_f32_e32 v135, 0x3dd53b94, v95
	v_exp_f32_e32 v162, v80
	v_exp_f32_e32 v205, v81
	v_exp_f32_e32 v149, v82
	v_exp_f32_e32 v163, v83
	v_exp_f32_e32 v150, v84
	v_exp_f32_e32 v161, v85
	v_exp_f32_e32 v151, v86
	v_exp_f32_e32 v160, v87
	v_exp_f32_e32 v152, v88
	v_exp_f32_e32 v155, v89
	v_exp_f32_e32 v153, v90
	v_exp_f32_e32 v154, v91
	v_exp_f32_e32 v145, v92
	v_exp_f32_e32 v147, v93
	v_exp_f32_e32 v144, v94
	v_exp_f32_e32 v146, v135
	v_pk_fma_f32 v[140:141], v[64:65], s[36:37], v[134:135] op_sel_hi:[1,0,0]
	v_add_f32_e32 v64, v202, v203
	v_fmac_f32_e32 v64, v194, v167
	v_add_f32_e32 v167, v206, v207
	s_add_i32 s3, s3, 2
	v_pk_fma_f32 v[138:139], v[66:67], s[36:37], v[134:135] op_sel_hi:[1,0,0]
	v_pk_fma_f32 v[132:133], v[68:69], s[36:37], v[134:135] op_sel_hi:[1,0,0]
	v_pk_fma_f32 v[130:131], v[70:71], s[36:37], v[134:135] op_sel_hi:[1,0,0]
	v_pk_fma_f32 v[128:129], v[72:73], s[36:37], v[134:135] op_sel_hi:[1,0,0]
	v_pk_fma_f32 v[142:143], v[74:75], s[36:37], v[134:135] op_sel_hi:[1,0,0]
	v_pk_fma_f32 v[136:137], v[76:77], s[36:37], v[134:135] op_sel_hi:[1,0,0]
	v_pk_fma_f32 v[134:135], v[78:79], s[36:37], v[134:135] op_sel_hi:[1,0,0]
	v_fmac_f32_e32 v167, v64, v204
	s_cmp_gt_u32 s3, 28
	s_waitcnt lgkmcnt(0)
	s_barrier
	s_cbranch_scc1 .LBB0_618
	v_mov_b32_e32 v194, v148
	s_branch .LBB0_608

; #define PG8_STAGE(bufoff, gbase, voff) do { _Pragma("unroll") for (int _i = 0; _i < 2; ++_i) \
;         __builtin_amdgcn_global_load_lds((const unsigned*)((const char*)(gbase) + (voff)[_i]), (LAS unsigned*)(lds + (bufoff) + ldsw + _i * 8192), 16, 0, 0); } while (0)
; #define PG8_WAIT_V(n) asm volatile("s_waitcnt vmcnt(" #n ")" ::: "memory")
; #define PG8_BAR __builtin_amdgcn_s_barrier()
; template <class Epi>
; __device__ __forceinline__ void gemm_phase(LAS unsigned char* lds, const Gemm g, const StaticOrder& S, const Epi& E, int wv) {
;     ...
;     for (int i = 0; i < 2; ++i) { int R, C; stage_rc(tid * 16 + i * 8192, R, C); const int Rb = Epi::PERM ? ((R & ~31) + perm32(R & 31)) : R;
;         voffA[i] = (unsigned)(R * K + C) * 2u; voffB[i] = (unsigned)(Rb * K + C) * 2u; }
;     const size_t kstep = (size_t)(BK * 2);
;     const size_t hstep = (size_t)HALF * K * 2;
;     const size_t tstep = 2 * hstep;
;     const unsigned ldsw = (unsigned)wid * 1024u;
;     const int aoff = lds_byte(wr * 64 + fr, fq * 8), boff = lds_byte(wc * 32 + fr, fq * 8);
;     ...
;     Unit cur, nxt; int ui = 0;
;     if (!S.next(0, cur)) return;
;     f32x4 acc[2][2][4][2];
; #pragma unroll
;     for (int a = 0; a < 2; ++a)
; #pragma unroll
;         for (int b = 0; b < 2; ++b)
; #pragma unroll
;             for (int m = 0; m < 4; ++m)
; #pragma unroll
;                 for (int n = 0; n < 2; ++n) acc[a][b][m][n] = (f32x4){0.f, 0.f, 0.f, 0.f};
;     bf16x8 At[4][2], B0[2][2], B1[2][2];
;     const char* cA = (const char*)g.A + (size_t)cur.pm * tstep; const char* cB = (const char*)g.Bt + (size_t)cur.pn * tstep;
;     PG8_STAGE(PG8_SB(0, 0), cB, voffB); PG8_STAGE(PG8_SA(0, 0), cA, voffA); PG8_STAGE(PG8_SB(0, 1), cB + hstep, voffB); PG8_STAGE(PG8_SA(0, 1), cA + hstep, voffA);
;     if (wr == 1) PG8_BAR;
;     PG8_WAIT_V(4); PG8_BAR;
;     PG8_STAGE(PG8_SB(1, 0), cB + kstep, voffB); PG8_STAGE(PG8_SA(1, 0), cA + kstep, voffA); PG8_STAGE(PG8_SB(1, 1), cB + hstep + kstep, voffB);
;     PG8_WAIT_V(6); PG8_BAR;
.LBB0_629:
	s_add_u32 s43, s44, 0x14000000
	s_addc_u32 s46, s45, 0
	s_add_u32 s8, s44, 0x3c000000
	s_addc_u32 s9, s45, 0
	v_lshl_add_u64 v[6:7], v[6:7], 0, s[80:81]
	s_add_i32 m0, s24, 0x18000
	s_ashr_i32 s47, s79, 31
	s_waitcnt vmcnt(4)
	s_barrier
	global_load_lds_dwordx4 v[6:7], off
	v_lshl_add_u64 v[2:3], v[2:3], 0, s[80:81]
	s_add_i32 m0, s24, 0x1a000
	s_add_i32 s50, s24, 0x8000
	s_add_i32 s51, s24, 0xa000
	global_load_lds_dwordx4 v[2:3], off
	v_lshl_add_u64 v[0:1], v[0:1], 0, s[80:81]
	s_mov_b32 m0, s50
	s_add_u32 s6, s20, 0x40080
	global_load_lds_dwordx4 v[0:1], off
	v_lshl_add_u64 v[0:1], v[4:5], 0, s[80:81]
	s_mov_b32 m0, s51
	s_addc_u32 s7, s21, 0
	global_load_lds_dwordx4 v[0:1], off
	s_add_i32 m0, s24, 0x1c000
	v_and_b32_e32 v2, 48, v8
	global_load_lds_dwordx4 v212, s[6:7]
	v_lshl_add_u64 v[0:1], s[6:7], 0, v[128:129]
	s_add_i32 m0, s24, 0x1e000
	v_readlane_b32 s6, v254, 16
	global_load_lds_dwordx4 v[0:1], off
	v_and_b32_e32 v0, 15, v8
	v_or_b32_e32 v1, s6, v0
	v_lshlrev_b32_e32 v3, 6, v1
	s_movk_i32 s6, 0x3c0
	v_lshlrev_b32_e32 v1, 2, v1
	v_and_or_b32 v3, v3, s6, v2
	v_and_b32_e32 v1, 32, v1
	v_readlane_b32 s6, v254, 7
	v_lshl_or_b32 v0, v0, 6, v2
	v_lshlrev_b32_e32 v2, 2, v8
	v_bitop3_b32 v1, v3, s6, v1 bitop3:0xde
	v_and_b32_e32 v2, 32, v2
	v_readlane_b32 s6, v254, 17
	s_waitcnt vmcnt(6)
	v_mov_b32_e32 v135, v213
	v_mov_b32_e32 v137, v213
	v_bitop3_b32 v140, v0, s6, v2 bitop3:0xde
	v_lshlrev_b32_e32 v0, 14, v12
	v_and_b32_e32 v0, 0xffff8000, v0
	v_lshl_add_u32 v0, v13, 11, v0
	v_and_b32_e32 v2, 1, v12
	v_lshl_or_b32 v0, v2, 6, v0
	v_lshl_add_u32 v134, v14, 1, v0
	v_lshlrev_b32_e32 v0, 14, v9
	v_and_b32_e32 v0, 0xffff8000, v0
	v_lshl_add_u32 v0, v10, 11, v0
	v_and_b32_e32 v2, 1, v9
	v_lshl_or_b32 v0, v2, 6, v0
	v_readlane_b32 s6, v254, 61
	v_lshl_add_u32 v136, v11, 1, v0
	s_mov_b32 s56, 0
	v_add_u32_e32 v141, 0, v1
	v_readlane_b32 s58, v254, 46
	s_mov_b32 s57, s6
	s_barrier
	v_readlane_b32 s7, v254, 62
	s_branch .LBB0_631

; #define PG8_STAGE(bufoff, gbase, voff) do { _Pragma("unroll") for (int _i = 0; _i < 2; ++_i) \
;         __builtin_amdgcn_global_load_lds((const unsigned*)((const char*)(gbase) + (voff)[_i]), (LAS unsigned*)(lds + (bufoff) + ldsw + _i * 8192), 16, 0, 0); } while (0)
; #define PG8_LDA(dst, b, h) do { _Pragma("unroll") for (int m = 0; m < 4; ++m) _Pragma("unroll") for (int k = 0; k < 2; ++k) dst[m][k] = *(const LAS bf16x8*)(lds + PG8_SA(b, h) + aoff + m * 2048 + k * 1024); } while (0)
; #define PG8_LDB(dst, b, h) do { _Pragma("unroll") for (int n = 0; n < 2; ++n) _Pragma("unroll") for (int k = 0; k < 2; ++k) dst[n][k] = *(const LAS bf16x8*)(lds + PG8_SB(b, h) + boff + n * 2048 + k * 1024); } while (0)
; #define PG8_MMA(ai, bj, At, Bt) do { __builtin_amdgcn_s_setprio(1); _Pragma("unroll") for (int m = 0; m < 4; ++m) _Pragma("unroll") for (int n = 0; n < 2; ++n) _Pragma("unroll") for (int k = 0; k < 2; ++k) \
;         acc[ai][bj][m][n] = __builtin_amdgcn_mfma_f32_16x16x32_bf16(Bt[n][k], At[m][k], acc[ai][bj][m][n], 0, 0, 0); __builtin_amdgcn_s_setprio(0); } while (0)
; #define PG8_WAIT_V(n) asm volatile("s_waitcnt vmcnt(" #n ")" ::: "memory")
; #define PG8_WAIT_L(n) asm volatile("s_waitcnt lgkmcnt(" #n ")" ::: "memory")
; template <class Epi>
; __device__ __forceinline__ void gemm_phase(LAS unsigned char* lds, const Gemm g, const StaticOrder& S, const Epi& E, int wv) {
;     ...
;         for (int t = 0; t < nt; t += 2) {
;             const bool last = (t == nt - 2);
;             const char* a1 = cA + (size_t)(t + 1) * kstep;
;             const char* a2 = last ? nA : cA + (size_t)(t + 2) * kstep; const char* b2 = last ? nB : cB + (size_t)(t + 2) * kstep;
;             const char* a3 = a2 + kstep; const char* b3 = b2 + kstep;
;             PG8_LDB(B0, 0, 0); PG8_SCHED; PG8_LDA(At, 0, 0); PG8_STAGE(PG8_SA(1, 1), a1 + hstep, voffA);
;             PG8_WAIT_L(8); PG8_BAR; PG8_WAIT_L(0); PG8_MMA(0, 0, At, B0); PG8_BAR; PG8_SCHED;
;             PG8_LDB(B1, 0, 1); PG8_STAGE(PG8_SB(0, 0), b2, voffB);
;             PG8_BAR; PG8_WAIT_L(0); PG8_MMA(0, 1, At, B1); PG8_BAR;
;             PG8_LDA(At, 0, 1); PG8_STAGE(PG8_SA(0, 0), a2, voffA);
;             PG8_BAR; PG8_WAIT_L(0); PG8_MMA(1, 0, At, B0); PG8_BAR; PG8_SCHED;
;             PG8_STAGE(PG8_SB(0, 1), b2 + hstep, voffB);
;             PG8_WAIT_V(6); PG8_BAR; PG8_MMA(1, 1, At, B1); PG8_BAR;
.LBB0_634:
	s_add_u32 s20, s18, 0xfffc0080
	s_addc_u32 s21, s19, -1
	s_add_i32 s64, 0, 0x10000
	v_add_u32_e32 v138, s64, v140
	ds_read_b128 v[142:145], v138
	ds_read_b128 v[146:149], v138 offset:1024
	ds_read_b128 v[150:153], v138 offset:2048
	ds_read_b128 v[154:157], v138 offset:3072
	s_cmp_eq_u32 s63, 12
	s_cselect_b32 s23, s13, s21
	s_cselect_b32 s22, s59, s20
	s_cselect_b32 s21, s11, s62
	s_cselect_b32 s20, s60, s61
	s_add_i32 m0, s24, 0xc000
	ds_read_b128 v[158:161], v141
	ds_read_b128 v[162:165], v141 offset:1024
	ds_read_b128 v[166:169], v141 offset:2048
	ds_read_b128 v[170:173], v141 offset:3072
	ds_read_b128 v[174:177], v141 offset:4096
	ds_read_b128 v[178:181], v141 offset:5120
	ds_read_b128 v[182:185], v141 offset:6144
	ds_read_b128 v[186:189], v141 offset:7168
	global_load_lds_dwordx4 v134, s[18:19]
	v_lshl_add_u64 v[138:139], s[18:19], 0, v[136:137]
	s_add_i32 m0, s24, 0xe000
	s_nop 0
	global_load_lds_dwordx4 v[138:139], off
	s_waitcnt lgkmcnt(8)
	s_barrier
	s_waitcnt lgkmcnt(0)
	s_setprio 1
	v_mfma_f32_16x16x32_bf16 v[124:127], v[142:145], v[158:161], v[124:127]
	v_mfma_f32_16x16x32_bf16 v[120:123], v[150:153], v[158:161], v[120:123]
	v_mfma_f32_16x16x32_bf16 v[116:119], v[142:145], v[166:169], v[116:119]
	v_mfma_f32_16x16x32_bf16 v[108:111], v[150:153], v[166:169], v[108:111]
	v_mfma_f32_16x16x32_bf16 v[100:103], v[142:145], v[174:177], v[100:103]
	v_mfma_f32_16x16x32_bf16 v[92:95], v[150:153], v[174:177], v[92:95]
	v_mfma_f32_16x16x32_bf16 v[84:87], v[142:145], v[182:185], v[84:87]
	v_mfma_f32_16x16x32_bf16 v[76:79], v[150:153], v[182:185], v[76:79]
	v_mfma_f32_16x16x32_bf16 v[124:127], v[146:149], v[162:165], v[124:127]
	v_mfma_f32_16x16x32_bf16 v[120:123], v[154:157], v[162:165], v[120:123]
	v_mfma_f32_16x16x32_bf16 v[116:119], v[146:149], v[170:173], v[116:119]
	v_mfma_f32_16x16x32_bf16 v[108:111], v[154:157], v[170:173], v[108:111]
	v_mfma_f32_16x16x32_bf16 v[100:103], v[146:149], v[178:181], v[100:103]
	v_mfma_f32_16x16x32_bf16 v[92:95], v[154:157], v[178:181], v[92:95]
	v_mfma_f32_16x16x32_bf16 v[84:87], v[146:149], v[186:189], v[84:87]
	v_mfma_f32_16x16x32_bf16 v[76:79], v[154:157], v[186:189], v[76:79]
	s_setprio 0
	s_barrier
	s_add_i32 s68, 0, 0x14000
	v_add_u32_e32 v138, s68, v140
	s_add_i32 s64, s64, s37
	ds_read_b128 v[190:193], v138
	ds_read_b128 v[194:197], v138 offset:1024
	ds_read_b128 v[198:201], v138 offset:2048
	ds_read_b128 v[202:205], v138 offset:3072
	v_lshl_add_u64 v[138:139], s[20:21], 0, v[212:213]
	s_mov_b32 m0, s64
	v_lshl_add_u64 v[206:207], s[20:21], 0, v[128:129]
	global_load_lds_dwordx4 v[138:139], off
	s_add_i32 m0, s64, 0x2000
	s_nop 0
	global_load_lds_dwordx4 v[206:207], off
	s_barrier
	s_waitcnt lgkmcnt(0)
	s_setprio 1
	v_mfma_f32_16x16x32_bf16 v[112:115], v[190:193], v[158:161], v[112:115]
	v_mfma_f32_16x16x32_bf16 v[104:107], v[198:201], v[158:161], v[104:107]
	v_mfma_f32_16x16x32_bf16 v[96:99], v[190:193], v[166:169], v[96:99]
	v_mfma_f32_16x16x32_bf16 v[88:91], v[198:201], v[166:169], v[88:91]
	v_mfma_f32_16x16x32_bf16 v[80:83], v[190:193], v[174:177], v[80:83]
	v_mfma_f32_16x16x32_bf16 v[72:75], v[198:201], v[174:177], v[72:75]
	v_mfma_f32_16x16x32_bf16 v[68:71], v[190:193], v[182:185], v[68:71]
	v_mfma_f32_16x16x32_bf16 v[64:67], v[198:201], v[182:185], v[64:67]
	v_mfma_f32_16x16x32_bf16 v[112:115], v[194:197], v[162:165], v[112:115]
	v_mfma_f32_16x16x32_bf16 v[104:107], v[202:205], v[162:165], v[104:107]
	v_mfma_f32_16x16x32_bf16 v[96:99], v[194:197], v[170:173], v[96:99]
	v_mfma_f32_16x16x32_bf16 v[88:91], v[202:205], v[170:173], v[88:91]
	v_mfma_f32_16x16x32_bf16 v[80:83], v[194:197], v[178:181], v[80:83]
	v_mfma_f32_16x16x32_bf16 v[72:75], v[202:205], v[178:181], v[72:75]
	v_mfma_f32_16x16x32_bf16 v[68:71], v[194:197], v[186:189], v[68:71]
	v_mfma_f32_16x16x32_bf16 v[64:67], v[202:205], v[186:189], v[64:67]
	s_setprio 0
	s_mov_b32 m0, s24
	v_lshl_add_u64 v[208:209], s[22:23], 0, v[132:133]
	s_barrier
	ds_read_b128 v[158:161], v141 offset:16384
	ds_read_b128 v[162:165], v141 offset:17408
	ds_read_b128 v[166:169], v141 offset:18432
	ds_read_b128 v[170:173], v141 offset:19456
	ds_read_b128 v[174:177], v141 offset:20480
	ds_read_b128 v[178:181], v141 offset:21504
	ds_read_b128 v[182:185], v141 offset:22528
	ds_read_b128 v[186:189], v141 offset:23552
	global_load_lds_dwordx4 v[208:209], off
	v_lshl_add_u64 v[210:211], s[22:23], 0, v[130:131]
	s_mov_b32 m0, s34
	s_nop 0
	global_load_lds_dwordx4 v[210:211], off
	s_barrier
	s_waitcnt lgkmcnt(0)
	s_setprio 1
	v_mfma_f32_16x16x32_bf16 v[60:63], v[142:145], v[158:161], v[60:63]
	v_mfma_f32_16x16x32_bf16 v[56:59], v[150:153], v[158:161], v[56:59]
	v_mfma_f32_16x16x32_bf16 v[52:55], v[142:145], v[166:169], v[52:55]
	v_mfma_f32_16x16x32_bf16 v[44:47], v[150:153], v[166:169], v[44:47]
	v_mfma_f32_16x16x32_bf16 v[36:39], v[142:145], v[174:177], v[36:39]
	v_mfma_f32_16x16x32_bf16 v[28:31], v[150:153], v[174:177], v[28:31]
	v_mfma_f32_16x16x32_bf16 v[20:23], v[142:145], v[182:185], v[20:23]
	v_mfma_f32_16x16x32_bf16 v[12:15], v[150:153], v[182:185], v[12:15]
	v_mfma_f32_16x16x32_bf16 v[60:63], v[146:149], v[162:165], v[60:63]
	v_mfma_f32_16x16x32_bf16 v[56:59], v[154:157], v[162:165], v[56:59]
	v_mfma_f32_16x16x32_bf16 v[52:55], v[146:149], v[170:173], v[52:55]
	v_mfma_f32_16x16x32_bf16 v[44:47], v[154:157], v[170:173], v[44:47]
	v_mfma_f32_16x16x32_bf16 v[36:39], v[146:149], v[178:181], v[36:39]
	v_mfma_f32_16x16x32_bf16 v[28:31], v[154:157], v[178:181], v[28:31]
	v_mfma_f32_16x16x32_bf16 v[20:23], v[146:149], v[186:189], v[20:23]
	v_mfma_f32_16x16x32_bf16 v[12:15], v[154:157], v[186:189], v[12:15]
	s_setprio 0
	s_barrier
; #define PG8_STAGE(bufoff, gbase, voff) do { _Pragma("unroll") for (int _i = 0; _i < 2; ++_i) \
;         __builtin_amdgcn_global_load_lds((const unsigned*)((const char*)(gbase) + (voff)[_i]), (LAS unsigned*)(lds + (bufoff) + ldsw + _i * 8192), 16, 0, 0); } while (0)
; #define PG8_LDA(dst, b, h) do { _Pragma("unroll") for (int m = 0; m < 4; ++m) _Pragma("unroll") for (int k = 0; k < 2; ++k) dst[m][k] = *(const LAS bf16x8*)(lds + PG8_SA(b, h) + aoff + m * 2048 + k * 1024); } while (0)
; #define PG8_LDB(dst, b, h) do { _Pragma("unroll") for (int n = 0; n < 2; ++n) _Pragma("unroll") for (int k = 0; k < 2; ++k) dst[n][k] = *(const LAS bf16x8*)(lds + PG8_SB(b, h) + boff + n * 2048 + k * 1024); } while (0)
; #define PG8_MMA(ai, bj, At, Bt) do { __builtin_amdgcn_s_setprio(1); _Pragma("unroll") for (int m = 0; m < 4; ++m) _Pragma("unroll") for (int n = 0; n < 2; ++n) _Pragma("unroll") for (int k = 0; k < 2; ++k) \
;         acc[ai][bj][m][n] = __builtin_amdgcn_mfma_f32_16x16x32_bf16(Bt[n][k], At[m][k], acc[ai][bj][m][n], 0, 0, 0); __builtin_amdgcn_s_setprio(0); } while (0)
; #define PG8_WAIT_V(n) asm volatile("s_waitcnt vmcnt(" #n ")" ::: "memory")
; #define PG8_WAIT_L(n) asm volatile("s_waitcnt lgkmcnt(" #n ")" ::: "memory")
; #define PG8_BAR __builtin_amdgcn_s_barrier()
; #define PG8_SCHED __builtin_amdgcn_sched_barrier(0)
; template <class Epi>
; __device__ __forceinline__ void gemm_phase(LAS unsigned char* lds, const Gemm g, const StaticOrder& S, const Epi& E, int wv) {
;     ...
;             PG8_LDA(At, 0, 1); PG8_STAGE(PG8_SA(0, 0), a2, voffA);
;             PG8_BAR; PG8_WAIT_L(0); PG8_MMA(1, 0, At, B0); PG8_BAR; PG8_SCHED;
;             PG8_STAGE(PG8_SB(0, 1), b2 + hstep, voffB);
;             PG8_WAIT_V(6); PG8_BAR; PG8_MMA(1, 1, At, B1); PG8_BAR;
;             PG8_LDB(B0, 1, 0); PG8_SCHED; PG8_LDA(At, 1, 0); PG8_STAGE(PG8_SA(0, 1), a2 + hstep, voffA);
;             PG8_WAIT_L(8); PG8_BAR; PG8_WAIT_L(0); PG8_MMA(0, 0, At, B0); PG8_BAR; PG8_SCHED;
;             PG8_LDB(B1, 1, 1); PG8_STAGE(PG8_SB(1, 0), b3, voffB);
;             PG8_BAR; PG8_WAIT_L(0); PG8_MMA(0, 1, At, B1); PG8_BAR;
;             PG8_LDA(At, 1, 1); PG8_STAGE(PG8_SA(1, 0), a3, voffA);
;             PG8_BAR; PG8_WAIT_L(0); PG8_MMA(1, 0, At, B0); PG8_BAR; PG8_SCHED;
	s_add_u32 s64, s20, 0x40000
	s_addc_u32 s65, s21, 0
	s_add_i32 s68, s68, s37
	s_mov_b32 m0, s68
	s_nop 0
	global_load_lds_dwordx4 v212, s[64:65]
	s_add_i32 m0, s68, 0x2000
	s_nop 0
	global_load_lds_dwordx4 v128, s[64:65]
	s_waitcnt vmcnt(6)
	s_barrier
	s_setprio 1
	v_mfma_f32_16x16x32_bf16 v[48:51], v[190:193], v[158:161], v[48:51]
	v_mfma_f32_16x16x32_bf16 v[40:43], v[198:201], v[158:161], v[40:43]
	v_mfma_f32_16x16x32_bf16 v[32:35], v[190:193], v[166:169], v[32:35]
	v_mfma_f32_16x16x32_bf16 v[24:27], v[198:201], v[166:169], v[24:27]
	v_mfma_f32_16x16x32_bf16 v[16:19], v[190:193], v[174:177], v[16:19]
	v_mfma_f32_16x16x32_bf16 v[8:11], v[198:201], v[174:177], v[8:11]
	v_mfma_f32_16x16x32_bf16 v[4:7], v[190:193], v[182:185], v[4:7]
	v_mfma_f32_16x16x32_bf16 v[0:3], v[198:201], v[182:185], v[0:3]
	v_mfma_f32_16x16x32_bf16 v[48:51], v[194:197], v[162:165], v[48:51]
	v_mfma_f32_16x16x32_bf16 v[40:43], v[202:205], v[162:165], v[40:43]
	v_mfma_f32_16x16x32_bf16 v[32:35], v[194:197], v[170:173], v[32:35]
	v_mfma_f32_16x16x32_bf16 v[24:27], v[202:205], v[170:173], v[24:27]
	v_mfma_f32_16x16x32_bf16 v[16:19], v[194:197], v[178:181], v[16:19]
	v_mfma_f32_16x16x32_bf16 v[8:11], v[202:205], v[178:181], v[8:11]
	v_mfma_f32_16x16x32_bf16 v[4:7], v[194:197], v[186:189], v[4:7]
	v_mfma_f32_16x16x32_bf16 v[0:3], v[202:205], v[186:189], v[0:3]
	s_setprio 0
	s_add_i32 s64, 0, 0x18000
	v_add_u32_e32 v154, s64, v140
	s_barrier
	ds_read_b128 v[142:145], v154
	ds_read_b128 v[146:149], v154 offset:1024
	ds_read_b128 v[150:153], v154 offset:2048
	ds_read_b128 v[154:157], v154 offset:3072
	s_add_u32 s22, s22, 0x40000
	s_addc_u32 s23, s23, 0
	s_mov_b32 m0, s35
	ds_read_b128 v[158:161], v141 offset:32768
	ds_read_b128 v[162:165], v141 offset:33792
	ds_read_b128 v[166:169], v141 offset:34816
	ds_read_b128 v[170:173], v141 offset:35840
	ds_read_b128 v[174:177], v141 offset:36864
	ds_read_b128 v[178:181], v141 offset:37888
	ds_read_b128 v[182:185], v141 offset:38912
	ds_read_b128 v[186:189], v141 offset:39936
	global_load_lds_dwordx4 v132, s[22:23]
	s_mov_b32 m0, s42
	s_nop 0
	global_load_lds_dwordx4 v130, s[22:23]
	s_waitcnt lgkmcnt(8)
	s_barrier
	s_waitcnt lgkmcnt(0)
	s_setprio 1
	v_mfma_f32_16x16x32_bf16 v[124:127], v[142:145], v[158:161], v[124:127]
	v_mfma_f32_16x16x32_bf16 v[120:123], v[150:153], v[158:161], v[120:123]
	v_mfma_f32_16x16x32_bf16 v[116:119], v[142:145], v[166:169], v[116:119]
	v_mfma_f32_16x16x32_bf16 v[108:111], v[150:153], v[166:169], v[108:111]
	v_mfma_f32_16x16x32_bf16 v[100:103], v[142:145], v[174:177], v[100:103]
	v_mfma_f32_16x16x32_bf16 v[92:95], v[150:153], v[174:177], v[92:95]
	v_mfma_f32_16x16x32_bf16 v[84:87], v[142:145], v[182:185], v[84:87]
	v_mfma_f32_16x16x32_bf16 v[76:79], v[150:153], v[182:185], v[76:79]
	v_mfma_f32_16x16x32_bf16 v[124:127], v[146:149], v[162:165], v[124:127]
	v_mfma_f32_16x16x32_bf16 v[120:123], v[154:157], v[162:165], v[120:123]
	v_mfma_f32_16x16x32_bf16 v[116:119], v[146:149], v[170:173], v[116:119]
	v_mfma_f32_16x16x32_bf16 v[108:111], v[154:157], v[170:173], v[108:111]
	v_mfma_f32_16x16x32_bf16 v[100:103], v[146:149], v[178:181], v[100:103]
	v_mfma_f32_16x16x32_bf16 v[92:95], v[154:157], v[178:181], v[92:95]
	v_mfma_f32_16x16x32_bf16 v[84:87], v[146:149], v[186:189], v[84:87]
	v_mfma_f32_16x16x32_bf16 v[76:79], v[154:157], v[186:189], v[76:79]
	s_setprio 0
	s_barrier
	s_add_i32 s22, 0, 0x1c000
	s_add_i32 s23, s64, s37
	v_add_u32_e32 v202, s22, v140
	v_lshl_add_u64 v[138:139], v[138:139], 0, s[80:81]
	s_mov_b32 m0, s23
	ds_read_b128 v[190:193], v202
	ds_read_b128 v[194:197], v202 offset:1024
	ds_read_b128 v[198:201], v202 offset:2048
	ds_read_b128 v[202:205], v202 offset:3072
	global_load_lds_dwordx4 v[138:139], off
	v_lshl_add_u64 v[138:139], v[206:207], 0, s[80:81]
	s_add_i32 m0, s23, 0x2000
	s_nop 0
	global_load_lds_dwordx4 v[138:139], off
	s_barrier
	s_waitcnt lgkmcnt(0)
	s_setprio 1
	v_mfma_f32_16x16x32_bf16 v[112:115], v[190:193], v[158:161], v[112:115]
	v_mfma_f32_16x16x32_bf16 v[104:107], v[198:201], v[158:161], v[104:107]
	v_mfma_f32_16x16x32_bf16 v[96:99], v[190:193], v[166:169], v[96:99]
	v_mfma_f32_16x16x32_bf16 v[88:91], v[198:201], v[166:169], v[88:91]
	v_mfma_f32_16x16x32_bf16 v[80:83], v[190:193], v[174:177], v[80:83]
	v_mfma_f32_16x16x32_bf16 v[72:75], v[198:201], v[174:177], v[72:75]
	v_mfma_f32_16x16x32_bf16 v[68:71], v[190:193], v[182:185], v[68:71]
	v_mfma_f32_16x16x32_bf16 v[64:67], v[198:201], v[182:185], v[64:67]
	v_mfma_f32_16x16x32_bf16 v[112:115], v[194:197], v[162:165], v[112:115]
	v_mfma_f32_16x16x32_bf16 v[104:107], v[202:205], v[162:165], v[104:107]
	v_mfma_f32_16x16x32_bf16 v[96:99], v[194:197], v[170:173], v[96:99]
	v_mfma_f32_16x16x32_bf16 v[88:91], v[202:205], v[170:173], v[88:91]
	v_mfma_f32_16x16x32_bf16 v[80:83], v[194:197], v[178:181], v[80:83]
	v_mfma_f32_16x16x32_bf16 v[72:75], v[202:205], v[178:181], v[72:75]
	v_mfma_f32_16x16x32_bf16 v[68:71], v[194:197], v[186:189], v[68:71]
	v_mfma_f32_16x16x32_bf16 v[64:67], v[202:205], v[186:189], v[64:67]
	s_setprio 0
	s_mov_b32 m0, s50
	v_lshl_add_u64 v[138:139], v[208:209], 0, s[80:81]
	s_barrier
	ds_read_b128 v[158:161], v141 offset:49152
	ds_read_b128 v[162:165], v141 offset:50176
	ds_read_b128 v[166:169], v141 offset:51200
	ds_read_b128 v[170:173], v141 offset:52224
	ds_read_b128 v[174:177], v141 offset:53248
	ds_read_b128 v[178:181], v141 offset:54272
	ds_read_b128 v[182:185], v141 offset:55296
	ds_read_b128 v[186:189], v141 offset:56320
	global_load_lds_dwordx4 v[138:139], off
	v_lshl_add_u64 v[138:139], v[210:211], 0, s[80:81]
	s_mov_b32 m0, s51
	s_nop 0
	global_load_lds_dwordx4 v[138:139], off
	s_barrier
; __device__ __forceinline__ int opaque_lane() { int l = __builtin_amdgcn_mbcnt_hi(~0u, __builtin_amdgcn_mbcnt_lo(~0u, 0u)); asm volatile("" : "+v"(l)); return l; }
; #define PG8_STAGE(bufoff, gbase, voff) do { _Pragma("unroll") for (int _i = 0; _i < 2; ++_i) \
;         __builtin_amdgcn_global_load_lds((const unsigned*)((const char*)(gbase) + (voff)[_i]), (LAS unsigned*)(lds + (bufoff) + ldsw + _i * 8192), 16, 0, 0); } while (0)
; #define PG8_WAIT_V(n) asm volatile("s_waitcnt vmcnt(" #n ")" ::: "memory")
; #define PG8_BAR __builtin_amdgcn_s_barrier()
; template <class Epi>
; __device__ __forceinline__ void gemm_phase(LAS unsigned char* lds, const Gemm g, const StaticOrder& S, const Epi& E, int wv) {
;     ...
;             PG8_WAIT_V(6); PG8_BAR; PG8_MMA(1, 1, At, B1); PG8_BAR;
;             PG8_LDB(B0, 1, 0); PG8_SCHED; PG8_LDA(At, 1, 0); PG8_STAGE(PG8_SA(0, 1), a2 + hstep, voffA);
;             PG8_WAIT_L(8); PG8_BAR; PG8_WAIT_L(0); PG8_MMA(0, 0, At, B0); PG8_BAR; PG8_SCHED;
;             PG8_LDB(B1, 1, 1); PG8_STAGE(PG8_SB(1, 0), b3, voffB);
;             PG8_BAR; PG8_WAIT_L(0); PG8_MMA(0, 1, At, B1); PG8_BAR;
;             PG8_LDA(At, 1, 1); PG8_STAGE(PG8_SA(1, 0), a3, voffA);
;             PG8_BAR; PG8_WAIT_L(0); PG8_MMA(1, 0, At, B0); PG8_BAR; PG8_SCHED;
;             PG8_STAGE(PG8_SB(1, 1), b3 + hstep, voffB);
;             PG8_WAIT_V(6); PG8_BAR; PG8_MMA(1, 1, At, B1); PG8_BAR;
;         }
;         E(acc, cur, wv);
;     __device__ __forceinline__ void operator()(const Acc& acc, const Unit& u, int wv) const {
;         const int wr = wv >> 2, wc = wv & 3, ln_ = opaque_lane(), fr = ln_ & 15, fq = ln_ >> 4;
;         const int pn = u.pn;
;         if (pn < 4) tile_store_bf16(acc, QK + pn * 256, 1024, u.pm, wr, wc, fr, fq, pn < 2 ? 0.08838834764831845f : 1.f);
;         else if (pn < 12) tile_store_bf16(acc, V + (pn - 4) * 256, 2048, u.pm, wr, wc, fr, fq, 1.f);
;         else if (pn < 20) tile_store_bf16(acc, Z + (pn - 12) * 256, 2048, u.pm, wr, wc, fr, fq, 1.f);
;         else if (wc == 0) {
;             const int row0 = u.pm * BM + wr * 64 + fr;
; #pragma unroll
;             for (int ai = 0; ai < 2; ++ai)
; #pragma unroll
;                 for (int m = 0; m < 4; ++m) { float* rowp = GLR + (size_t)(row0 + ai * HALF + m * 16) * 32 + 8 * fq;
;                     *(f32x4*)rowp = acc[ai][0][m][0]; *(f32x4*)(rowp + 4) = acc[ai][0][m][1]; }
;         }
	s_waitcnt lgkmcnt(0)
	s_setprio 1
	v_mfma_f32_16x16x32_bf16 v[60:63], v[142:145], v[158:161], v[60:63]
	v_mfma_f32_16x16x32_bf16 v[56:59], v[150:153], v[158:161], v[56:59]
	v_mfma_f32_16x16x32_bf16 v[52:55], v[142:145], v[166:169], v[52:55]
	v_mfma_f32_16x16x32_bf16 v[44:47], v[150:153], v[166:169], v[44:47]
	v_mfma_f32_16x16x32_bf16 v[36:39], v[142:145], v[174:177], v[36:39]
	v_mfma_f32_16x16x32_bf16 v[28:31], v[150:153], v[174:177], v[28:31]
	v_mfma_f32_16x16x32_bf16 v[20:23], v[142:145], v[182:185], v[20:23]
	v_mfma_f32_16x16x32_bf16 v[12:15], v[150:153], v[182:185], v[12:15]
	v_mfma_f32_16x16x32_bf16 v[60:63], v[146:149], v[162:165], v[60:63]
	v_mfma_f32_16x16x32_bf16 v[56:59], v[154:157], v[162:165], v[56:59]
	v_mfma_f32_16x16x32_bf16 v[52:55], v[146:149], v[170:173], v[52:55]
	v_mfma_f32_16x16x32_bf16 v[44:47], v[154:157], v[170:173], v[44:47]
	v_mfma_f32_16x16x32_bf16 v[36:39], v[146:149], v[178:181], v[36:39]
	v_mfma_f32_16x16x32_bf16 v[28:31], v[154:157], v[178:181], v[28:31]
	v_mfma_f32_16x16x32_bf16 v[20:23], v[146:149], v[186:189], v[20:23]
	v_mfma_f32_16x16x32_bf16 v[12:15], v[154:157], v[186:189], v[12:15]
	s_setprio 0
	s_barrier
	s_add_u32 s20, s20, 0x40080
	s_addc_u32 s21, s21, 0
	s_add_i32 s22, s22, s37
	s_mov_b32 m0, s22
	s_nop 0
	global_load_lds_dwordx4 v212, s[20:21]
	v_lshl_add_u64 v[138:139], s[20:21], 0, v[128:129]
	s_add_i32 m0, s22, 0x2000
	s_nop 0
	global_load_lds_dwordx4 v[138:139], off
	s_waitcnt vmcnt(6)
	s_barrier
	s_setprio 1
	v_mfma_f32_16x16x32_bf16 v[48:51], v[190:193], v[158:161], v[48:51]
	v_mfma_f32_16x16x32_bf16 v[40:43], v[198:201], v[158:161], v[40:43]
	v_mfma_f32_16x16x32_bf16 v[32:35], v[190:193], v[166:169], v[32:35]
	v_mfma_f32_16x16x32_bf16 v[24:27], v[198:201], v[166:169], v[24:27]
	v_mfma_f32_16x16x32_bf16 v[16:19], v[190:193], v[174:177], v[16:19]
	v_mfma_f32_16x16x32_bf16 v[8:11], v[198:201], v[174:177], v[8:11]
	v_mfma_f32_16x16x32_bf16 v[4:7], v[190:193], v[182:185], v[4:7]
	v_mfma_f32_16x16x32_bf16 v[0:3], v[198:201], v[182:185], v[0:3]
	v_mfma_f32_16x16x32_bf16 v[48:51], v[194:197], v[162:165], v[48:51]
	v_mfma_f32_16x16x32_bf16 v[40:43], v[202:205], v[162:165], v[40:43]
	v_mfma_f32_16x16x32_bf16 v[32:35], v[194:197], v[170:173], v[32:35]
	v_mfma_f32_16x16x32_bf16 v[24:27], v[202:205], v[170:173], v[24:27]
	v_mfma_f32_16x16x32_bf16 v[16:19], v[194:197], v[178:181], v[16:19]
	v_mfma_f32_16x16x32_bf16 v[8:11], v[202:205], v[178:181], v[8:11]
	v_mfma_f32_16x16x32_bf16 v[4:7], v[194:197], v[186:189], v[4:7]
	v_mfma_f32_16x16x32_bf16 v[0:3], v[202:205], v[186:189], v[0:3]
	s_setprio 0
	s_add_i32 s63, s63, 2
	s_add_u32 s18, s18, 0x100
	s_addc_u32 s19, s19, 0
	s_add_u32 s61, s61, 0x100
	s_addc_u32 s62, s62, 0
	s_cmp_gt_u32 s63, 13
	s_barrier
	s_cbranch_scc0 .LBB0_634
	v_mov_b32_e32 v138, v233
	s_cmp_gt_i32 s58, 3
	v_and_b32_e32 v143, 15, v138
	v_ashrrev_i32_e32 v142, 4, v138
	s_mov_b64 s[18:19], -1
	s_cbranch_scc0 .LBB0_647
	s_cmp_gt_u32 s58, 11
	s_cbranch_scc0 .LBB0_644
	s_cmp_gt_u32 s58, 19
	s_cbranch_scc0 .LBB0_641
	v_readlane_b32 s18, v254, 34
	v_readlane_b32 s19, v254, 35
	s_andn2_b64 vcc, exec, s[18:19]
	s_cbranch_vccnz .LBB0_640
	s_lshl_b32 s11, s57, 8
	v_readlane_b32 s13, v254, 16
	s_add_i32 s11, s11, s13
	v_or_b32_e32 v138, s11, v143
	v_or_b32_e32 v148, 16, v138
	v_lshlrev_b32_e32 v144, 3, v142
	v_ashrrev_i32_e32 v139, 31, v138
	v_ashrrev_i32_e32 v149, 31, v148
	v_ashrrev_i32_e32 v145, 31, v144
	v_lshlrev_b64 v[146:147], 7, v[138:139]
	v_lshlrev_b64 v[148:149], 7, v[148:149]
	v_lshl_add_u64 v[146:147], s[8:9], 0, v[146:147]
	v_lshlrev_b64 v[144:145], 2, v[144:145]
	v_lshl_add_u64 v[148:149], s[8:9], 0, v[148:149]
	v_lshl_add_u64 v[146:147], v[146:147], 0, v[144:145]
	v_lshl_add_u64 v[148:149], v[148:149], 0, v[144:145]
	global_store_dwordx4 v[146:147], v[124:127], off
	global_store_dwordx4 v[146:147], v[120:123], off offset:16
	global_store_dwordx4 v[148:149], v[116:119], off
	global_store_dwordx4 v[148:149], v[108:111], off offset:16
	v_or_b32_e32 v148, 32, v138
	v_or_b32_e32 v138, 48, v138
	v_ashrrev_i32_e32 v149, 31, v148
	v_ashrrev_i32_e32 v139, 31, v138
	v_lshlrev_b64 v[148:149], 7, v[148:149]
	v_lshlrev_b64 v[138:139], 7, v[138:139]
	v_lshl_add_u64 v[148:149], s[8:9], 0, v[148:149]
	v_lshl_add_u64 v[138:139], s[8:9], 0, v[138:139]
	s_movk_i32 s11, 0x4000
	v_lshl_add_u64 v[148:149], v[148:149], 0, v[144:145]
	v_lshl_add_u64 v[138:139], v[138:139], 0, v[144:145]
	v_add_co_u32_e32 v144, vcc, s11, v146
	global_store_dwordx4 v[148:149], v[100:103], off
	global_store_dwordx4 v[148:149], v[92:95], off offset:16
	global_store_dwordx4 v[138:139], v[84:87], off
	global_store_dwordx4 v[138:139], v[76:79], off offset:16
	v_lshl_add_u64 v[138:139], v[146:147], 0, s[38:39]
	v_addc_co_u32_e32 v145, vcc, 0, v147, vcc
	s_mov_b64 s[18:19], 0x4800
	global_store_dwordx4 v[144:145], v[60:63], off
	global_store_dwordx4 v[138:139], v[56:59], off offset:16
	v_lshl_add_u64 v[138:139], v[146:147], 0, s[18:19]
	global_store_dwordx4 v[144:145], v[52:55], off offset:2048
	global_store_dwordx4 v[138:139], v[44:47], off offset:16
	s_mov_b64 s[18:19], 0x5000
	v_add_co_u32_e32 v144, vcc, 0x5000, v146
	v_lshl_add_u64 v[138:139], v[146:147], 0, s[18:19]
	s_nop 0
	v_addc_co_u32_e32 v145, vcc, 0, v147, vcc
	s_mov_b64 s[18:19], 0x5800
	global_store_dwordx4 v[144:145], v[36:39], off
	global_store_dwordx4 v[138:139], v[28:31], off offset:16
	v_lshl_add_u64 v[138:139], v[146:147], 0, s[18:19]
	global_store_dwordx4 v[144:145], v[20:23], off offset:2048
	global_store_dwordx4 v[138:139], v[12:15], off offset:16
